# c3sp with the static prio kept through GEMM epilogues and tile setup, reset only at phase ends
# baseline (speedup 1.0000x reference)
; #define PG8_STAGE(bufoff, gbase, voff) do { _Pragma("unroll") for (int _i = 0; _i < 2; ++_i) \
;         __builtin_amdgcn_global_load_lds((const unsigned*)((const char*)(gbase) + (voff)[_i]), (PG8_LAS unsigned*)(lds + (bufoff) + ldsw + _i * 8192), 16, 0, 0); } while (0)
; #define PG8_LDA(dst, b, h) do { _Pragma("unroll") for (int m = 0; m < 4; ++m) _Pragma("unroll") for (int k = 0; k < 2; ++k) dst[m][k] = *(const PG8_LAS bf16x8*)(lds + PG8_SA(b, h) + aoff + m * 2048 + k * 1024); } while (0)
; #define PG8_LDB(dst, b, h) do { _Pragma("unroll") for (int n = 0; n < 2; ++n) _Pragma("unroll") for (int k = 0; k < 2; ++k) dst[n][k] = *(const PG8_LAS bf16x8*)(lds + PG8_SB(b, h) + boff + n * 2048 + k * 1024); } while (0)
; #define PG8_MMA(ai, bj, At, Bt) do { __builtin_amdgcn_s_setprio(1); _Pragma("unroll") for (int m = 0; m < 4; ++m) _Pragma("unroll") for (int n = 0; n < 2; ++n) _Pragma("unroll") for (int k = 0; k < 2; ++k) \
;         acc[ai][bj][m][n] = __builtin_amdgcn_mfma_f32_16x16x32_bf16(Bt[n][k], At[m][k], acc[ai][bj][m][n], 0, 0, 0); __builtin_amdgcn_s_setprio(0); } while (0)
; #define PG8_WAIT_V(n) asm volatile("s_waitcnt vmcnt(" #n ")" ::: "memory")
; #define PG8_WAIT_L(n) asm volatile("s_waitcnt lgkmcnt(" #n ")" ::: "memory")
; template <class Epi>
; __device__ __forceinline__ void gemm_phase(PG8_LAS unsigned char* lds, const Gemm g, const StaticOrder& S, const Epi& E) {
;     ...
;         for (int t = 0; t < nt; t += 2) {
;             const bool last = (t == nt - 2);
;             const char* a1 = cA + (size_t)(t + 1) * kstep;
;             const char* a2 = last ? nA : cA + (size_t)(t + 2) * kstep; const char* b2 = last ? nB : cB + (size_t)(t + 2) * kstep;
;             const char* a3 = a2 + kstep; const char* b3 = b2 + kstep;
;             PG8_LDB(B0, 0, 0); PG8_SCHED; PG8_LDA(At, 0, 0); PG8_STAGE(PG8_SA(1, 1), a1 + hstepA, voffA);
;             PG8_WAIT_L(8); PG8_BAR; PG8_WAIT_L(0); PG8_MMA(0, 0, At, B0); PG8_BAR; PG8_SCHED;
;             PG8_LDB(B1, 0, 1); PG8_STAGE(PG8_SB(0, 0), b2, voffB);
;             PG8_BAR; PG8_WAIT_L(0); PG8_MMA(0, 1, At, B1); PG8_BAR;
;             PG8_LDA(At, 0, 1); PG8_STAGE(PG8_SA(0, 0), a2, voffA);
;             PG8_BAR; PG8_WAIT_L(0); PG8_MMA(1, 0, At, B0); PG8_BAR; PG8_SCHED;
;             PG8_STAGE(PG8_SB(0, 1), b2 + hstepB, voffB);
;             PG8_WAIT_V(6); PG8_BAR; PG8_MMA(1, 1, At, B1); PG8_BAR;
.Lsp_0:
.LBB0_226:
	ds_read_b128 v[0:3], v174
	ds_read_b128 v[4:7], v174 offset:1024
	ds_read_b128 v[156:159], v174 offset:2048
	ds_read_b128 v[160:163], v174 offset:3072
	ds_read_b128 v[164:167], v175
	ds_read_b128 v[178:181], v175 offset:1024
	ds_read_b128 v[182:185], v175 offset:2048
	ds_read_b128 v[186:189], v175 offset:3072
	ds_read_b128 v[190:193], v175 offset:4096
	ds_read_b128 v[194:197], v175 offset:5120
	ds_read_b128 v[198:201], v175 offset:6144
	ds_read_b128 v[202:205], v175 offset:7168
	ds_read_b128 v[206:209], v176
	ds_read_b128 v[210:213], v176 offset:1024
	ds_read_b128 v[214:217], v176 offset:2048
	ds_read_b128 v[218:221], v176 offset:3072
	s_add_u32 s4, s0, 0xfff80080
	s_addc_u32 s5, s1, -1
	s_cmp_eq_u32 s62, 28
	s_cselect_b32 s7, s47, s5
	s_cselect_b32 s6, s49, s4
	s_cselect_b32 s5, s51, s61
	s_cselect_b32 s4, s53, s60
	v_lshl_add_u64 v[170:171], s[0:1], 0, v[148:149]
	s_add_i32 m0, s14, 0xc000
	s_nop 0
	global_load_lds_dwordx4 v[170:171], off
	v_lshl_add_u64 v[170:171], s[0:1], 0, v[150:151]
	s_add_i32 m0, s14, 0xe000
	s_nop 0
	global_load_lds_dwordx4 v[170:171], off
	s_waitcnt lgkmcnt(0)
	s_waitcnt vmcnt(8)
	s_barrier
	v_mfma_f32_16x16x32_bf16 v[132:135], v[0:3], v[164:167], v[132:135]
	v_mfma_f32_16x16x32_bf16 v[124:127], v[156:159], v[164:167], v[124:127]
	v_mfma_f32_16x16x32_bf16 v[116:119], v[0:3], v[182:185], v[116:119]
	v_mfma_f32_16x16x32_bf16 v[108:111], v[156:159], v[182:185], v[108:111]
	v_mfma_f32_16x16x32_bf16 v[100:103], v[0:3], v[190:193], v[100:103]
	v_mfma_f32_16x16x32_bf16 v[92:95], v[156:159], v[190:193], v[92:95]
	v_mfma_f32_16x16x32_bf16 v[84:87], v[0:3], v[198:201], v[84:87]
	v_mfma_f32_16x16x32_bf16 v[76:79], v[156:159], v[198:201], v[76:79]
	v_mfma_f32_16x16x32_bf16 v[132:135], v[4:7], v[178:181], v[132:135]
	v_mfma_f32_16x16x32_bf16 v[124:127], v[160:163], v[178:181], v[124:127]
	v_mfma_f32_16x16x32_bf16 v[116:119], v[4:7], v[186:189], v[116:119]
	v_mfma_f32_16x16x32_bf16 v[108:111], v[160:163], v[186:189], v[108:111]
	v_mfma_f32_16x16x32_bf16 v[100:103], v[4:7], v[194:197], v[100:103]
	v_mfma_f32_16x16x32_bf16 v[92:95], v[160:163], v[194:197], v[92:95]
	v_mfma_f32_16x16x32_bf16 v[84:87], v[4:7], v[202:205], v[84:87]
	v_mfma_f32_16x16x32_bf16 v[76:79], v[160:163], v[202:205], v[76:79]
	v_mfma_f32_16x16x32_bf16 v[128:131], v[206:209], v[164:167], v[128:131]
	v_mfma_f32_16x16x32_bf16 v[120:123], v[214:217], v[164:167], v[120:123]
	v_mfma_f32_16x16x32_bf16 v[112:115], v[206:209], v[182:185], v[112:115]
	v_mfma_f32_16x16x32_bf16 v[104:107], v[214:217], v[182:185], v[104:107]
	v_mfma_f32_16x16x32_bf16 v[96:99], v[206:209], v[190:193], v[96:99]
	v_mfma_f32_16x16x32_bf16 v[88:91], v[214:217], v[190:193], v[88:91]
	v_mfma_f32_16x16x32_bf16 v[80:83], v[206:209], v[198:201], v[80:83]
	v_mfma_f32_16x16x32_bf16 v[72:75], v[214:217], v[198:201], v[72:75]
	v_mfma_f32_16x16x32_bf16 v[128:131], v[210:213], v[178:181], v[128:131]
	v_mfma_f32_16x16x32_bf16 v[120:123], v[218:221], v[178:181], v[120:123]
	v_mfma_f32_16x16x32_bf16 v[112:115], v[210:213], v[186:189], v[112:115]
	v_mfma_f32_16x16x32_bf16 v[104:107], v[218:221], v[186:189], v[104:107]
	v_mfma_f32_16x16x32_bf16 v[96:99], v[210:213], v[194:197], v[96:99]
	v_mfma_f32_16x16x32_bf16 v[88:91], v[218:221], v[194:197], v[88:91]
	v_mfma_f32_16x16x32_bf16 v[80:83], v[210:213], v[202:205], v[80:83]
	v_mfma_f32_16x16x32_bf16 v[72:75], v[218:221], v[202:205], v[72:75]
	s_barrier
	ds_read_b128 v[164:167], v175 offset:16384
	ds_read_b128 v[178:181], v175 offset:17408
	ds_read_b128 v[182:185], v175 offset:18432
	ds_read_b128 v[186:189], v175 offset:19456
	ds_read_b128 v[190:193], v175 offset:20480
	ds_read_b128 v[194:197], v175 offset:21504
	ds_read_b128 v[198:201], v175 offset:22528
	ds_read_b128 v[202:205], v175 offset:23552
	s_add_i32 s63, s37, s11
	v_lshl_add_u64 v[170:171], s[4:5], 0, v[142:143]
	s_mov_b32 m0, s63
	s_nop 0
	global_load_lds_dwordx4 v[170:171], off
	v_lshl_add_u64 v[222:223], s[4:5], 0, v[138:139]
	s_add_i32 m0, s63, 0x2000
	s_nop 0
	global_load_lds_dwordx4 v[222:223], off
	s_mov_b32 m0, s14
	v_lshl_add_u64 v[224:225], s[6:7], 0, v[144:145]
	global_load_lds_dwordx4 v[224:225], off
	v_lshl_add_u64 v[226:227], s[6:7], 0, v[140:141]
	s_mov_b32 m0, s15
	s_nop 0
	global_load_lds_dwordx4 v[226:227], off
	s_add_u32 s64, s4, 0x80000
	s_addc_u32 s65, s5, 0
	s_add_i32 s63, s38, s11
	v_lshl_add_u64 v[228:229], s[64:65], 0, v[142:143]
	s_mov_b32 m0, s63
	s_nop 0
	global_load_lds_dwordx4 v[228:229], off
	v_lshl_add_u64 v[228:229], s[64:65], 0, v[138:139]
	s_add_i32 m0, s63, 0x2000
	s_nop 0
	global_load_lds_dwordx4 v[228:229], off
	s_waitcnt lgkmcnt(0)
	s_waitcnt vmcnt(8)
	s_barrier
; #define PG8_STAGE(bufoff, gbase, voff) do { _Pragma("unroll") for (int _i = 0; _i < 2; ++_i) \
;         __builtin_amdgcn_global_load_lds((const unsigned*)((const char*)(gbase) + (voff)[_i]), (PG8_LAS unsigned*)(lds + (bufoff) + ldsw + _i * 8192), 16, 0, 0); } while (0)
; #define PG8_LDA(dst, b, h) do { _Pragma("unroll") for (int m = 0; m < 4; ++m) _Pragma("unroll") for (int k = 0; k < 2; ++k) dst[m][k] = *(const PG8_LAS bf16x8*)(lds + PG8_SA(b, h) + aoff + m * 2048 + k * 1024); } while (0)
; #define PG8_LDB(dst, b, h) do { _Pragma("unroll") for (int n = 0; n < 2; ++n) _Pragma("unroll") for (int k = 0; k < 2; ++k) dst[n][k] = *(const PG8_LAS bf16x8*)(lds + PG8_SB(b, h) + boff + n * 2048 + k * 1024); } while (0)
; #define PG8_MMA(ai, bj, At, Bt) do { __builtin_amdgcn_s_setprio(1); _Pragma("unroll") for (int m = 0; m < 4; ++m) _Pragma("unroll") for (int n = 0; n < 2; ++n) _Pragma("unroll") for (int k = 0; k < 2; ++k) \
;         acc[ai][bj][m][n] = __builtin_amdgcn_mfma_f32_16x16x32_bf16(Bt[n][k], At[m][k], acc[ai][bj][m][n], 0, 0, 0); __builtin_amdgcn_s_setprio(0); } while (0)
; #define PG8_WAIT_V(n) asm volatile("s_waitcnt vmcnt(" #n ")" ::: "memory")
; #define PG8_WAIT_L(n) asm volatile("s_waitcnt lgkmcnt(" #n ")" ::: "memory")
; #define PG8_BAR __builtin_amdgcn_s_barrier()
; #define PG8_SCHED __builtin_amdgcn_sched_barrier(0)
; template <class Epi>
; __device__ __forceinline__ void gemm_phase(PG8_LAS unsigned char* lds, const Gemm g, const StaticOrder& S, const Epi& E) {
;     ...
;             PG8_WAIT_V(6); PG8_BAR; PG8_MMA(1, 1, At, B1); PG8_BAR;
;             PG8_LDB(B0, 1, 0); PG8_SCHED; PG8_LDA(At, 1, 0); PG8_STAGE(PG8_SA(0, 1), a2 + hstepA, voffA);
;             PG8_WAIT_L(8); PG8_BAR; PG8_WAIT_L(0); PG8_MMA(0, 0, At, B0); PG8_BAR; PG8_SCHED;
;             PG8_LDB(B1, 1, 1); PG8_STAGE(PG8_SB(1, 0), b3, voffB);
;             PG8_BAR; PG8_WAIT_L(0); PG8_MMA(0, 1, At, B1); PG8_BAR;
;             PG8_LDA(At, 1, 1); PG8_STAGE(PG8_SA(1, 0), a3, voffA);
;             PG8_BAR; PG8_WAIT_L(0); PG8_MMA(1, 0, At, B0); PG8_BAR; PG8_SCHED;
	v_mfma_f32_16x16x32_bf16 v[68:71], v[0:3], v[164:167], v[68:71]
	v_mfma_f32_16x16x32_bf16 v[60:63], v[156:159], v[164:167], v[60:63]
	v_mfma_f32_16x16x32_bf16 v[52:55], v[0:3], v[182:185], v[52:55]
	v_mfma_f32_16x16x32_bf16 v[44:47], v[156:159], v[182:185], v[44:47]
	v_mfma_f32_16x16x32_bf16 v[36:39], v[0:3], v[190:193], v[36:39]
	v_mfma_f32_16x16x32_bf16 v[28:31], v[156:159], v[190:193], v[28:31]
	v_mfma_f32_16x16x32_bf16 v[0:3], v[0:3], v[198:201], v[20:23]
	v_mfma_f32_16x16x32_bf16 v[68:71], v[4:7], v[178:181], v[68:71]
	v_mfma_f32_16x16x32_bf16 v[60:63], v[160:163], v[178:181], v[60:63]
	v_mfma_f32_16x16x32_bf16 v[52:55], v[4:7], v[186:189], v[52:55]
	v_mfma_f32_16x16x32_bf16 v[44:47], v[160:163], v[186:189], v[44:47]
	v_mfma_f32_16x16x32_bf16 v[36:39], v[4:7], v[194:197], v[36:39]
	v_mfma_f32_16x16x32_bf16 v[28:31], v[160:163], v[194:197], v[28:31]
	v_mfma_f32_16x16x32_bf16 v[0:3], v[4:7], v[202:205], v[0:3]
	v_mfma_f32_16x16x32_bf16 v[4:7], v[156:159], v[198:201], v[12:15]
	v_mfma_f32_16x16x32_bf16 v[4:7], v[160:163], v[202:205], v[4:7]
	v_mfma_f32_16x16x32_bf16 v[12:15], v[206:209], v[164:167], v[64:67]
	v_mfma_f32_16x16x32_bf16 v[64:67], v[210:213], v[178:181], v[12:15]
	v_mfma_f32_16x16x32_bf16 v[12:15], v[214:217], v[164:167], v[56:59]
	v_mfma_f32_16x16x32_bf16 v[56:59], v[218:221], v[178:181], v[12:15]
	v_mfma_f32_16x16x32_bf16 v[12:15], v[206:209], v[182:185], v[48:51]
	v_mfma_f32_16x16x32_bf16 v[48:51], v[210:213], v[186:189], v[12:15]
	v_mfma_f32_16x16x32_bf16 v[12:15], v[214:217], v[182:185], v[40:43]
	v_mfma_f32_16x16x32_bf16 v[40:43], v[218:221], v[186:189], v[12:15]
	v_mfma_f32_16x16x32_bf16 v[12:15], v[206:209], v[190:193], v[32:35]
	v_mfma_f32_16x16x32_bf16 v[32:35], v[210:213], v[194:197], v[12:15]
	v_mfma_f32_16x16x32_bf16 v[12:15], v[214:217], v[190:193], v[24:27]
	v_mfma_f32_16x16x32_bf16 v[24:27], v[218:221], v[194:197], v[12:15]
	v_mfma_f32_16x16x32_bf16 v[12:15], v[206:209], v[198:201], v[16:19]
	v_mfma_f32_16x16x32_bf16 v[8:11], v[214:217], v[198:201], v[8:11]
	v_mfma_f32_16x16x32_bf16 v[16:19], v[210:213], v[202:205], v[12:15]
	v_mfma_f32_16x16x32_bf16 v[8:11], v[218:221], v[202:205], v[8:11]
	s_add_i32 s63, 0, 0x18000
	v_add_u32_e32 v160, s63, v169
	s_barrier
	s_nop 0
	s_nop 0
	ds_read_b128 v[12:15], v160
	ds_read_b128 v[20:23], v160 offset:1024
	ds_read_b128 v[156:159], v160 offset:2048
	ds_read_b128 v[160:163], v160 offset:3072
	ds_read_b128 v[164:167], v175 offset:32768
	ds_read_b128 v[178:181], v175 offset:33792
	ds_read_b128 v[182:185], v175 offset:34816
	ds_read_b128 v[186:189], v175 offset:35840
	ds_read_b128 v[190:193], v175 offset:36864
	ds_read_b128 v[194:197], v175 offset:37888
	ds_read_b128 v[198:201], v175 offset:38912
	ds_read_b128 v[202:205], v175 offset:39936
	v_add_u32_e32 v218, 0x1c000, v169
	ds_read_b128 v[206:209], v218
	ds_read_b128 v[210:213], v218 offset:1024
	ds_read_b128 v[214:217], v218 offset:2048
	ds_read_b128 v[218:221], v218 offset:3072
	s_add_u32 s6, s6, 0x80000
	s_addc_u32 s7, s7, 0
	s_mov_b32 m0, s17
	v_lshl_add_u64 v[228:229], s[6:7], 0, v[144:145]
	global_load_lds_dwordx4 v[228:229], off
	v_lshl_add_u64 v[228:229], s[6:7], 0, v[140:141]
	s_mov_b32 m0, s22
	s_nop 0
	global_load_lds_dwordx4 v[228:229], off
	s_waitcnt lgkmcnt(0)
	s_waitcnt vmcnt(8)
	s_barrier
	v_mfma_f32_16x16x32_bf16 v[132:135], v[12:15], v[164:167], v[132:135]
	v_mfma_f32_16x16x32_bf16 v[124:127], v[156:159], v[164:167], v[124:127]
	v_mfma_f32_16x16x32_bf16 v[116:119], v[12:15], v[182:185], v[116:119]
	v_mfma_f32_16x16x32_bf16 v[108:111], v[156:159], v[182:185], v[108:111]
	v_mfma_f32_16x16x32_bf16 v[100:103], v[12:15], v[190:193], v[100:103]
	v_mfma_f32_16x16x32_bf16 v[92:95], v[156:159], v[190:193], v[92:95]
	v_mfma_f32_16x16x32_bf16 v[84:87], v[12:15], v[198:201], v[84:87]
	v_mfma_f32_16x16x32_bf16 v[76:79], v[156:159], v[198:201], v[76:79]
	v_mfma_f32_16x16x32_bf16 v[132:135], v[20:23], v[178:181], v[132:135]
	v_mfma_f32_16x16x32_bf16 v[124:127], v[160:163], v[178:181], v[124:127]
	v_mfma_f32_16x16x32_bf16 v[116:119], v[20:23], v[186:189], v[116:119]
	v_mfma_f32_16x16x32_bf16 v[108:111], v[160:163], v[186:189], v[108:111]
	v_mfma_f32_16x16x32_bf16 v[100:103], v[20:23], v[194:197], v[100:103]
	v_mfma_f32_16x16x32_bf16 v[92:95], v[160:163], v[194:197], v[92:95]
	v_mfma_f32_16x16x32_bf16 v[84:87], v[20:23], v[202:205], v[84:87]
	v_mfma_f32_16x16x32_bf16 v[76:79], v[160:163], v[202:205], v[76:79]
	v_mfma_f32_16x16x32_bf16 v[128:131], v[206:209], v[164:167], v[128:131]
	v_mfma_f32_16x16x32_bf16 v[120:123], v[214:217], v[164:167], v[120:123]
	v_mfma_f32_16x16x32_bf16 v[112:115], v[206:209], v[182:185], v[112:115]
	v_mfma_f32_16x16x32_bf16 v[104:107], v[214:217], v[182:185], v[104:107]
	v_mfma_f32_16x16x32_bf16 v[96:99], v[206:209], v[190:193], v[96:99]
	v_mfma_f32_16x16x32_bf16 v[88:91], v[214:217], v[190:193], v[88:91]
	v_mfma_f32_16x16x32_bf16 v[80:83], v[206:209], v[198:201], v[80:83]
	v_mfma_f32_16x16x32_bf16 v[72:75], v[214:217], v[198:201], v[72:75]
	v_mfma_f32_16x16x32_bf16 v[128:131], v[210:213], v[178:181], v[128:131]
	v_mfma_f32_16x16x32_bf16 v[120:123], v[218:221], v[178:181], v[120:123]
	v_mfma_f32_16x16x32_bf16 v[112:115], v[210:213], v[186:189], v[112:115]
	v_mfma_f32_16x16x32_bf16 v[104:107], v[218:221], v[186:189], v[104:107]
	v_mfma_f32_16x16x32_bf16 v[96:99], v[210:213], v[194:197], v[96:99]
	v_mfma_f32_16x16x32_bf16 v[88:91], v[218:221], v[194:197], v[88:91]
	v_mfma_f32_16x16x32_bf16 v[80:83], v[210:213], v[202:205], v[80:83]
	v_mfma_f32_16x16x32_bf16 v[72:75], v[218:221], v[202:205], v[72:75]
	s_barrier
; #define PG8_STAGE(bufoff, gbase, voff) do { _Pragma("unroll") for (int _i = 0; _i < 2; ++_i) \
;         __builtin_amdgcn_global_load_lds((const unsigned*)((const char*)(gbase) + (voff)[_i]), (PG8_LAS unsigned*)(lds + (bufoff) + ldsw + _i * 8192), 16, 0, 0); } while (0)
; #define PG8_MMA(ai, bj, At, Bt) do { __builtin_amdgcn_s_setprio(1); _Pragma("unroll") for (int m = 0; m < 4; ++m) _Pragma("unroll") for (int n = 0; n < 2; ++n) _Pragma("unroll") for (int k = 0; k < 2; ++k) \
;         acc[ai][bj][m][n] = __builtin_amdgcn_mfma_f32_16x16x32_bf16(Bt[n][k], At[m][k], acc[ai][bj][m][n], 0, 0, 0); __builtin_amdgcn_s_setprio(0); } while (0)
; #define PG8_WAIT_V(n) asm volatile("s_waitcnt vmcnt(" #n ")" ::: "memory")
; #define PG8_WAIT_L(n) asm volatile("s_waitcnt lgkmcnt(" #n ")" ::: "memory")
; #define PG8_BAR __builtin_amdgcn_s_barrier()
; #define PG8_SCHED __builtin_amdgcn_sched_barrier(0)
; __device__ __forceinline__ void rstd8(const float* part, int row0, int fq, float (&rs)[8]) {
;     f32x4 v[8][2];
; #pragma unroll
;     for (int k = 0; k < 8; ++k) { const f32x4* p = (const f32x4*)(part + (size_t)(row0 + (k >> 2) * 128 + (k & 3) * 16) * 32 + fq * 8); v[k][0] = p[0]; v[k][1] = p[1]; }
; template <class Epi>
; __device__ __forceinline__ void gemm_phase(PG8_LAS unsigned char* lds, const Gemm g, const StaticOrder& S, const Epi& E) {
;     ...
;             PG8_BAR; PG8_WAIT_L(0); PG8_MMA(1, 0, At, B0); PG8_BAR; PG8_SCHED;
;             PG8_STAGE(PG8_SB(1, 1), b3 + hstepB, voffB);
;             PG8_WAIT_V(6); PG8_BAR; PG8_MMA(1, 1, At, B1); PG8_BAR;
	ds_read_b128 v[164:167], v175 offset:49152
	ds_read_b128 v[178:181], v175 offset:50176
	ds_read_b128 v[182:185], v175 offset:51200
	ds_read_b128 v[186:189], v175 offset:52224
	ds_read_b128 v[190:193], v175 offset:53248
	ds_read_b128 v[194:197], v175 offset:54272
	ds_read_b128 v[198:201], v175 offset:55296
	ds_read_b128 v[202:205], v175 offset:56320
	s_add_i32 s6, 0, 0x1c000
	s_add_i32 s7, s63, s11
	v_lshl_add_u64 v[170:171], v[170:171], 0, s[18:19]
	s_mov_b32 m0, s7
	s_nop 0
	global_load_lds_dwordx4 v[170:171], off
	v_lshl_add_u64 v[170:171], v[222:223], 0, s[18:19]
	s_add_i32 m0, s7, 0x2000
	s_nop 0
	global_load_lds_dwordx4 v[170:171], off
	s_mov_b32 m0, s31
	v_lshl_add_u64 v[170:171], v[224:225], 0, s[18:19]
	global_load_lds_dwordx4 v[170:171], off
	v_lshl_add_u64 v[170:171], v[226:227], 0, s[18:19]
	s_mov_b32 m0, s34
	s_nop 0
	global_load_lds_dwordx4 v[170:171], off
	s_add_u32 s4, s4, 0x80080
	s_addc_u32 s5, s5, 0
	s_add_i32 s6, s6, s11
	v_lshl_add_u64 v[228:229], s[4:5], 0, v[142:143]
	s_mov_b32 m0, s6
	s_nop 0
	global_load_lds_dwordx4 v[228:229], off
	v_lshl_add_u64 v[228:229], s[4:5], 0, v[138:139]
	s_add_i32 m0, s6, 0x2000
	s_nop 0
	global_load_lds_dwordx4 v[228:229], off
	s_waitcnt lgkmcnt(0)
	s_waitcnt vmcnt(8)
	s_barrier
	v_mfma_f32_16x16x32_bf16 v[68:71], v[12:15], v[164:167], v[68:71]
	v_mfma_f32_16x16x32_bf16 v[52:55], v[12:15], v[182:185], v[52:55]
	v_mfma_f32_16x16x32_bf16 v[36:39], v[12:15], v[190:193], v[36:39]
	v_mfma_f32_16x16x32_bf16 v[0:3], v[12:15], v[198:201], v[0:3]
	v_mfma_f32_16x16x32_bf16 v[68:71], v[20:23], v[178:181], v[68:71]
	v_mfma_f32_16x16x32_bf16 v[60:63], v[156:159], v[164:167], v[60:63]
	v_mfma_f32_16x16x32_bf16 v[52:55], v[20:23], v[186:189], v[52:55]
	v_mfma_f32_16x16x32_bf16 v[44:47], v[156:159], v[182:185], v[44:47]
	v_mfma_f32_16x16x32_bf16 v[36:39], v[20:23], v[194:197], v[36:39]
	v_mfma_f32_16x16x32_bf16 v[28:31], v[156:159], v[190:193], v[28:31]
	v_mfma_f32_16x16x32_bf16 v[20:23], v[20:23], v[202:205], v[0:3]
	v_mfma_f32_16x16x32_bf16 v[0:3], v[156:159], v[198:201], v[4:7]
	v_mfma_f32_16x16x32_bf16 v[60:63], v[160:163], v[178:181], v[60:63]
	v_mfma_f32_16x16x32_bf16 v[44:47], v[160:163], v[186:189], v[44:47]
	v_mfma_f32_16x16x32_bf16 v[28:31], v[160:163], v[194:197], v[28:31]
	v_mfma_f32_16x16x32_bf16 v[12:15], v[160:163], v[202:205], v[0:3]
	v_mfma_f32_16x16x32_bf16 v[0:3], v[206:209], v[164:167], v[64:67]
	v_mfma_f32_16x16x32_bf16 v[64:67], v[210:213], v[178:181], v[0:3]
	v_mfma_f32_16x16x32_bf16 v[0:3], v[214:217], v[164:167], v[56:59]
	v_mfma_f32_16x16x32_bf16 v[56:59], v[218:221], v[178:181], v[0:3]
	v_mfma_f32_16x16x32_bf16 v[0:3], v[206:209], v[182:185], v[48:51]
	v_mfma_f32_16x16x32_bf16 v[48:51], v[210:213], v[186:189], v[0:3]
	v_mfma_f32_16x16x32_bf16 v[0:3], v[214:217], v[182:185], v[40:43]
	v_mfma_f32_16x16x32_bf16 v[40:43], v[218:221], v[186:189], v[0:3]
	v_mfma_f32_16x16x32_bf16 v[0:3], v[206:209], v[190:193], v[32:35]
	v_mfma_f32_16x16x32_bf16 v[32:35], v[210:213], v[194:197], v[0:3]
	v_mfma_f32_16x16x32_bf16 v[0:3], v[214:217], v[190:193], v[24:27]
	v_mfma_f32_16x16x32_bf16 v[24:27], v[218:221], v[194:197], v[0:3]
	v_mfma_f32_16x16x32_bf16 v[0:3], v[206:209], v[198:201], v[16:19]
	v_mfma_f32_16x16x32_bf16 v[16:19], v[210:213], v[202:205], v[0:3]
	v_mfma_f32_16x16x32_bf16 v[0:3], v[214:217], v[198:201], v[8:11]
	v_mfma_f32_16x16x32_bf16 v[8:11], v[218:221], v[202:205], v[0:3]
	s_add_i32 s62, s62, 2
	s_add_u32 s0, s0, 0x100
	s_addc_u32 s1, s1, 0
	s_add_u32 s60, s60, 0x100
	s_addc_u32 s61, s61, 0
	s_cmp_gt_u32 s62, 29
	s_barrier
	s_cbranch_scc0 .LBB0_226
	v_lshl_add_u32 v166, s16, 8, v137
	v_or_b32_e32 v162, 16, v166
	v_or_b32_e32 v160, 32, v166
	v_or_b32_e32 v158, 48, v166
	s_mov_b64 s[0:1], -1
	s_cmp_lg_u32 s16, s43
	v_ashrrev_i32_e32 v167, 31, v166
	v_ashrrev_i32_e32 v163, 31, v162
	v_ashrrev_i32_e32 v161, 31, v160
	v_ashrrev_i32_e32 v159, 31, v158
	v_add_u32_e32 v170, 0x80, v166
	s_cbranch_scc0 .LBB0_229
	v_lshlrev_b64 v[0:1], 7, v[166:167]
	v_lshlrev_b64 v[4:5], 7, v[162:163]
	v_lshl_add_u64 v[6:7], v[146:147], 0, v[0:1]
	v_lshl_add_u64 v[4:5], v[146:147], 0, v[4:5]
	global_load_dwordx4 v[0:3], v[6:7], off
	global_load_dwordx4 v[178:181], v[4:5], off
	global_load_dwordx4 v[182:185], v[6:7], off offset:16
	global_load_dwordx4 v[186:189], v[4:5], off offset:16
	v_lshlrev_b64 v[4:5], 7, v[160:161]
	v_lshlrev_b64 v[156:157], 7, v[158:159]
	v_lshl_add_u64 v[4:5], v[146:147], 0, v[4:5]
	v_lshl_add_u64 v[156:157], v[146:147], 0, v[156:157]
	global_load_dwordx4 v[190:193], v[4:5], off
	global_load_dwordx4 v[194:197], v[156:157], off
	global_load_dwordx4 v[198:201], v[4:5], off offset:16
	global_load_dwordx4 v[202:205], v[156:157], off offset:16
	v_add_u32_e32 v156, 0x80, v166
	s_movk_i32 s4, 0x4000
	v_and_b32_e32 v164, 64, v177
	v_ashrrev_i32_e32 v157, 31, v156
	v_add_co_u32_e32 v206, vcc, s4, v6
	v_add_u32_e32 v221, 64, v164
	v_lshlrev_b64 v[164:165], 7, v[156:157]
	v_addc_co_u32_e32 v207, vcc, 0, v7, vcc
	v_lshl_add_u64 v[164:165], v[146:147], 0, v[164:165]
	global_load_dwordx4 v[206:209], v[206:207], off offset:2048
	s_nop 0
	global_load_dwordx4 v[210:213], v[164:165], off offset:16
	global_load_dwordx4 v[214:217], v[164:165], off
	v_add_co_u32_e32 v230, vcc, s39, v6
	v_xor_b32_e32 v171, 16, v177
	s_nop 0
	v_addc_co_u32_e32 v231, vcc, 0, v7, vcc
	v_xor_b32_e32 v220, 32, v177
	s_mov_b64 s[0:1], 0x4800
	v_cmp_lt_i32_e32 vcc, v171, v221
	v_lshl_add_u64 v[218:219], v[6:7], 0, s[0:1]
	v_lshl_add_u64 v[226:227], v[6:7], 0, s[20:21]
	v_cndmask_b32_e32 v164, v177, v171, vcc
	v_cmp_lt_i32_e32 vcc, v220, v221
	v_lshl_add_u64 v[6:7], v[6:7], 0, s[28:29]
	v_lshlrev_b32_e32 v171, 2, v164
	v_cndmask_b32_e32 v165, v177, v220, vcc
	global_load_dwordx4 v[218:221], v[218:219], off offset:16
	s_nop 0
	global_load_dwordx4 v[222:225], v[230:231], off
	s_nop 0
	global_load_dwordx4 v[226:229], v[226:227], off offset:16
	s_nop 0
	global_load_dwordx4 v[230:233], v[230:231], off offset:2048
	s_nop 0
	global_load_dwordx4 v[234:237], v[6:7], off offset:16
	v_lshlrev_b32_e32 v238, 2, v165
	v_mov_b64_e32 v[4:5], s[46:47]
	s_waitcnt vmcnt(0)
; __device__ __forceinline__ void rstd8(const float* part, int row0, int fq, float (&rs)[8]) {
;     f32x4 v[8][2];
; #pragma unroll
;     for (int k = 0; k < 8; ++k) { const f32x4* p = (const f32x4*)(part + (size_t)(row0 + (k >> 2) * 128 + (k & 3) * 16) * 32 + fq * 8); v[k][0] = p[0]; v[k][1] = p[1]; }
; #pragma unroll
;     for (int k = 0; k < 8; ++k) { float s = ((v[k][0][0] + v[k][0][1]) + (v[k][0][2] + v[k][0][3])) + ((v[k][1][0] + v[k][1][1]) + (v[k][1][2] + v[k][1][3]));
;         s += __shfl_xor(s, 16); s += __shfl_xor(s, 32); rs[k] = rsqrtf(s * (1.0f / 2048.0f) + EPS); }
;     __device__ __forceinline__ void operator()(const f32x4 (&acc)[2][2][4][2], const pg8::Unit& u, int wr, int wc, int fr, int fq) const {
;     ...
;         if (u.pm != cached_pm) { rstd8(part, row0, fq, rsv);
; #pragma unroll
;             for (int k = 0; k < 8; ++k) mine[k * 64] = rsv[k];
;             cached_pm = u.pm; }
	v_mov_b32_e32 v7, v178
	v_mov_b32_e32 v6, v0
	v_mov_b32_e32 v178, v1
	v_mov_b32_e32 v0, v2
	v_mov_b32_e32 v1, v180
	v_mov_b32_e32 v180, v3
	v_mov_b32_e32 v2, v182
	v_mov_b32_e32 v3, v186
	v_mov_b32_e32 v186, v183
	v_mov_b32_e32 v164, v184
	v_mov_b32_e32 v165, v188
	v_mov_b32_e32 v188, v185
	v_pk_add_f32 v[6:7], v[6:7], v[178:179]
	v_pk_add_f32 v[0:1], v[0:1], v[180:181]
	v_pk_add_f32 v[2:3], v[2:3], v[186:187]
	v_pk_add_f32 v[164:165], v[164:165], v[188:189]
	v_pk_add_f32 v[0:1], v[6:7], v[0:1]
	v_pk_add_f32 v[2:3], v[2:3], v[164:165]
	v_mov_b32_e32 v182, v190
	v_pk_add_f32 v[0:1], v[0:1], v[2:3]
	ds_bpermute_b32 v2, v171, v0
	ds_bpermute_b32 v3, v171, v1
	v_mov_b32_e32 v183, v194
	v_mov_b32_e32 v194, v191
	v_mov_b32_e32 v184, v192
	v_mov_b32_e32 v185, v196
	v_mov_b32_e32 v196, v193
	v_mov_b32_e32 v190, v198
	v_mov_b32_e32 v191, v202
	v_mov_b32_e32 v202, v199
	v_mov_b32_e32 v192, v200
	v_mov_b32_e32 v193, v204
	v_mov_b32_e32 v204, v201
	s_waitcnt lgkmcnt(0)
	v_pk_add_f32 v[0:1], v[0:1], v[2:3]
	v_pk_add_f32 v[178:179], v[182:183], v[194:195]
	v_pk_add_f32 v[6:7], v[184:185], v[196:197]
	v_pk_add_f32 v[164:165], v[190:191], v[202:203]
	v_pk_add_f32 v[180:181], v[192:193], v[204:205]
	ds_bpermute_b32 v2, v238, v0
	ds_bpermute_b32 v3, v238, v1
	v_pk_add_f32 v[6:7], v[178:179], v[6:7]
	v_pk_add_f32 v[164:165], v[164:165], v[180:181]
	v_mov_b32_e32 v178, v216
	v_pk_add_f32 v[6:7], v[6:7], v[164:165]
	ds_bpermute_b32 v164, v171, v6
	ds_bpermute_b32 v165, v171, v7
	s_waitcnt lgkmcnt(2)
	v_pk_add_f32 v[0:1], v[0:1], v[2:3]
	v_mov_b32_e32 v179, v208
	v_pk_fma_f32 v[0:1], v[0:1], s[30:31], v[4:5] op_sel_hi:[1,0,0]
	v_mov_b32_e32 v208, v217
	v_mul_f32_e32 v2, 0x4b800000, v0
	v_mul_f32_e32 v3, 0x4b800000, v1
	v_cmp_gt_f32_e32 vcc, s40, v0
	v_cmp_gt_f32_e64 s[0:1], s40, v1
	v_pk_add_f32 v[178:179], v[178:179], v[208:209]
	v_cndmask_b32_e32 v0, v0, v2, vcc
	v_cndmask_b32_e64 v1, v1, v3, s[0:1]
	s_waitcnt lgkmcnt(0)
	v_pk_add_f32 v[2:3], v[6:7], v[164:165]
	ds_bpermute_b32 v6, v238, v2
	ds_bpermute_b32 v7, v238, v3
	v_rsq_f32_e32 v0, v0
	v_rsq_f32_e32 v1, v1
	v_mov_b32_e32 v180, v212
	v_mov_b32_e32 v181, v220
	s_waitcnt lgkmcnt(0)
	v_pk_add_f32 v[2:3], v[2:3], v[6:7]
	v_pk_mul_f32 v[164:165], v[0:1], s[48:49] op_sel_hi:[1,0]
	v_pk_fma_f32 v[2:3], v[2:3], s[30:31], v[4:5] op_sel_hi:[1,0,0]
	v_cndmask_b32_e64 v1, v1, v165, s[0:1]
	v_mul_f32_e32 v6, 0x4b800000, v2
	v_cmp_gt_f32_e64 s[0:1], s40, v2
	v_mov_b32_e32 v7, v206
	v_mov_b32_e32 v206, v215
	v_cndmask_b32_e64 v2, v2, v6, s[0:1]
	v_mov_b32_e32 v6, v214
	v_pk_add_f32 v[6:7], v[6:7], v[206:207]
	v_mov_b32_e32 v220, v213
	v_pk_add_f32 v[6:7], v[6:7], v[178:179]
	v_mov_b32_e32 v178, v210
	v_mov_b32_e32 v179, v218
	v_mov_b32_e32 v218, v211
	v_pk_add_f32 v[178:179], v[178:179], v[218:219]
	v_pk_add_f32 v[180:181], v[180:181], v[220:221]
	v_mul_f32_e32 v165, 0x4b800000, v3
	v_pk_add_f32 v[178:179], v[178:179], v[180:181]
	v_cmp_gt_f32_e64 s[4:5], s40, v3
	v_pk_add_f32 v[6:7], v[6:7], v[178:179]
	ds_bpermute_b32 v178, v171, v6
	ds_bpermute_b32 v179, v171, v7
	v_cndmask_b32_e64 v3, v3, v165, s[4:5]
	v_rsq_f32_e32 v2, v2
	v_rsq_f32_e32 v3, v3
	v_cndmask_b32_e32 v0, v0, v164, vcc
	s_waitcnt lgkmcnt(0)
	v_pk_add_f32 v[6:7], v[6:7], v[178:179]
	ds_bpermute_b32 v178, v238, v6
	ds_bpermute_b32 v179, v238, v7
	v_pk_mul_f32 v[164:165], v[2:3], s[48:49] op_sel_hi:[1,0]
	v_mov_b32_e32 v180, v230
	v_cndmask_b32_e64 v3, v3, v165, s[4:5]
	v_cndmask_b32_e64 v2, v2, v164, s[0:1]
	s_waitcnt lgkmcnt(0)
	v_pk_add_f32 v[6:7], v[6:7], v[178:179]
	v_mov_b32_e32 v164, v223
	v_mov_b32_e32 v165, v224
	v_mov_b32_e32 v223, v225
	v_mov_b32_e32 v178, v227
	v_mov_b32_e32 v179, v228
	v_mov_b32_e32 v227, v229
	v_mov_b32_e32 v181, v234
	v_mov_b32_e32 v234, v231
	v_mov_b32_e32 v182, v232
	v_mov_b32_e32 v183, v236
	v_mov_b32_e32 v236, v233
	v_pk_add_f32 v[164:165], v[164:165], v[222:223]
	v_pk_add_f32 v[178:179], v[178:179], v[226:227]
	v_pk_add_f32 v[180:181], v[180:181], v[234:235]
	v_pk_add_f32 v[182:183], v[182:183], v[236:237]
	v_pk_add_f32 v[164:165], v[164:165], v[164:165] op_sel:[0,1] op_sel_hi:[1,0]
	v_pk_add_f32 v[178:179], v[178:179], v[178:179] op_sel:[0,1] op_sel_hi:[1,0]
	v_pk_add_f32 v[180:181], v[180:181], v[182:183]
	v_pk_fma_f32 v[6:7], v[6:7], s[30:31], v[4:5] op_sel_hi:[1,0,0]
	v_mov_b32_e32 v165, v180
	v_mov_b32_e32 v179, v181
	v_pk_add_f32 v[164:165], v[164:165], v[178:179]
	ds_bpermute_b32 v178, v171, v164
	ds_bpermute_b32 v179, v171, v165
	v_mul_f32_e32 v171, 0x4b800000, v6
	v_cmp_gt_f32_e32 vcc, s40, v6
	v_cmp_gt_f32_e64 s[0:1], s40, v7
	s_waitcnt lgkmcnt(0)
	v_pk_add_f32 v[164:165], v[164:165], v[178:179]
	ds_bpermute_b32 v178, v238, v164
	ds_bpermute_b32 v179, v238, v165
	v_cndmask_b32_e32 v6, v6, v171, vcc
	v_mul_f32_e32 v171, 0x4b800000, v7
	v_cndmask_b32_e64 v7, v7, v171, s[0:1]
	v_rsq_f32_e32 v6, v6
	s_waitcnt lgkmcnt(0)
	v_pk_add_f32 v[164:165], v[164:165], v[178:179]
	v_rsq_f32_e32 v7, v7
	v_pk_fma_f32 v[4:5], v[164:165], s[30:31], v[4:5] op_sel_hi:[1,0,0]
	s_nop 0
	v_mul_f32_e32 v164, 0x4b800000, v4
	v_cmp_gt_f32_e64 s[4:5], s40, v4
	v_cmp_gt_f32_e64 s[6:7], s40, v5
	s_nop 0
	v_cndmask_b32_e64 v4, v4, v164, s[4:5]
	v_rsq_f32_e32 v164, v4
	v_mul_f32_e32 v4, 0x4b800000, v5
	v_cndmask_b32_e64 v4, v5, v4, s[6:7]
	v_rsq_f32_e32 v165, v4
	v_pk_mul_f32 v[4:5], v[6:7], s[48:49] op_sel_hi:[1,0]
	s_nop 0
	v_cndmask_b32_e64 v5, v7, v5, s[0:1]
	v_cndmask_b32_e32 v4, v6, v4, vcc
	v_pk_mul_f32 v[6:7], v[164:165], s[48:49] op_sel_hi:[1,0]
	s_mov_b64 s[0:1], 0
	v_cndmask_b32_e64 v7, v165, v7, s[6:7]
	v_cndmask_b32_e64 v6, v164, v6, s[4:5]
	ds_write2st64_b32 v172, v0, v1 offset1:1
	ds_write2st64_b32 v172, v2, v3 offset0:2 offset1:3
	ds_write2st64_b32 v172, v4, v5 offset0:4 offset1:5
	ds_write2st64_b32 v172, v6, v7 offset0:6 offset1:7
	v_mov_b64_e32 v[164:165], v[156:157]

; __device__ __forceinline__ void xcd_barrier(const XcdBarrier& b) {
;     asm volatile("s_waitcnt vmcnt(0)" ::: "memory");
;     __syncthreads();
;     if (threadIdx.x == 0) {
;         unsigned* bar = b.bar;
;         __builtin_amdgcn_s_waitcnt(0);
;         unsigned nloc = b.st[0], nx = b.st[1];
;         if (nloc == 0u) { xcd_barrier_complete(bar, b.x, nloc, nx); b.st[0] = nloc; b.st[1] = nx; }
.LBB0_239:
	s_setprio 0
	s_cmp_gt_i32 s75, 2
	s_cselect_b64 s[0:1], -1, 0
	s_and_b64 s[2:3], s[8:9], s[0:1]
	s_andn2_b64 vcc, exec, s[2:3]
	s_cbranch_vccnz .LBB0_293
	s_waitcnt vmcnt(0)
	s_waitcnt vmcnt(0) lgkmcnt(0)
	s_barrier
	s_mov_b64 s[2:3], exec
	v_readlane_b32 s4, v253, 8
	v_readlane_b32 s5, v253, 9
	s_and_b64 s[4:5], s[2:3], s[4:5]
	s_mov_b64 exec, s[4:5]
	s_cbranch_execz .LBB0_292
	s_add_i32 s4, 0, 0x24000
	v_mov_b32_e32 v0, s4
	s_waitcnt vmcnt(0) expcnt(0) lgkmcnt(0)
	ds_read_b32 v2, v0
	s_add_i32 s4, 0, 0x24004
	v_mov_b32_e32 v0, s4
	ds_read_b32 v0, v0
	s_waitcnt lgkmcnt(1)
	v_cmp_ne_u32_e32 vcc, 0, v2
	s_cbranch_vccnz .LBB0_256
	s_add_u32 s4, s80, 0x1e7fae00
	s_addc_u32 s5, s81, 0
	s_add_u32 s6, s80, 0x1e7fb000
	s_addc_u32 s7, s81, 0
	s_add_u32 s8, s80, 0x1e7fb100
	s_addc_u32 s9, s81, 0
	s_add_u32 s10, s80, 0x1e7fb200
	s_addc_u32 s11, s81, 0
	s_add_u32 s12, s80, 0x1e7fb300
	s_addc_u32 s13, s81, 0
	s_add_u32 s14, s80, 0x1e7fb400
	s_addc_u32 s15, s81, 0
	s_add_u32 s16, s80, 0x1e7fb500
	s_addc_u32 s17, s81, 0
	s_add_u32 s18, s80, 0x1e7fb600
	s_addc_u32 s19, s81, 0
	s_add_u32 s20, s80, 0x1e7fb700
	s_addc_u32 s21, s81, 0
	s_add_u32 s22, s80, 0x1e7fb800
	s_addc_u32 s23, s81, 0
	s_add_u32 s28, s80, 0x1e7fb900
	s_addc_u32 s29, s81, 0
	s_add_u32 s30, s80, 0x1e7fba00
	s_addc_u32 s31, s81, 0
	s_add_u32 s34, s80, 0x1e7fbb00
	s_addc_u32 s35, s81, 0
	s_add_u32 s36, s80, 0x1e7fbc00
	s_addc_u32 s37, s81, 0
	s_add_u32 s38, s80, 0x1e7fbd00
	s_addc_u32 s39, s81, 0
	s_add_u32 s40, s80, 0x1e7fbe00
	s_addc_u32 s41, s81, 0
	s_mul_i32 s52, s27, s33
	s_add_u32 s42, s80, 0x1e7fbf00
	s_mul_i32 s52, s52, s26
	s_addc_u32 s43, s81, 0
	s_mov_b32 s53, 1
	v_mov_b32_e32 v16, 0
	s_branch .LBB0_244

; #define PG8_STAGE(bufoff, gbase, voff) do { _Pragma("unroll") for (int _i = 0; _i < 2; ++_i) \
;         __builtin_amdgcn_global_load_lds((const unsigned*)((const char*)(gbase) + (voff)[_i]), (PG8_LAS unsigned*)(lds + (bufoff) + ldsw + _i * 8192), 16, 0, 0); } while (0)
; #define PG8_LDA(dst, b, h) do { _Pragma("unroll") for (int m = 0; m < 4; ++m) _Pragma("unroll") for (int k = 0; k < 2; ++k) dst[m][k] = *(const PG8_LAS bf16x8*)(lds + PG8_SA(b, h) + aoff + m * 2048 + k * 1024); } while (0)
; #define PG8_LDB(dst, b, h) do { _Pragma("unroll") for (int n = 0; n < 2; ++n) _Pragma("unroll") for (int k = 0; k < 2; ++k) dst[n][k] = *(const PG8_LAS bf16x8*)(lds + PG8_SB(b, h) + boff + n * 2048 + k * 1024); } while (0)
; #define PG8_MMA(ai, bj, At, Bt) do { __builtin_amdgcn_s_setprio(1); _Pragma("unroll") for (int m = 0; m < 4; ++m) _Pragma("unroll") for (int n = 0; n < 2; ++n) _Pragma("unroll") for (int k = 0; k < 2; ++k) \
;         acc[ai][bj][m][n] = __builtin_amdgcn_mfma_f32_16x16x32_bf16(Bt[n][k], At[m][k], acc[ai][bj][m][n], 0, 0, 0); __builtin_amdgcn_s_setprio(0); } while (0)
; #define PG8_WAIT_V(n) asm volatile("s_waitcnt vmcnt(" #n ")" ::: "memory")
; #define PG8_WAIT_L(n) asm volatile("s_waitcnt lgkmcnt(" #n ")" ::: "memory")
; template <class Epi>
; __device__ __forceinline__ void gemm_phase(PG8_LAS unsigned char* lds, const Gemm g, const StaticOrder& S, const Epi& E) {
;     ...
;         for (int t = 0; t < nt; t += 2) {
;             const bool last = (t == nt - 2);
;             const char* a1 = cA + (size_t)(t + 1) * kstep;
;             const char* a2 = last ? nA : cA + (size_t)(t + 2) * kstep; const char* b2 = last ? nB : cB + (size_t)(t + 2) * kstep;
;             const char* a3 = a2 + kstep; const char* b3 = b2 + kstep;
;             PG8_LDB(B0, 0, 0); PG8_SCHED; PG8_LDA(At, 0, 0); PG8_STAGE(PG8_SA(1, 1), a1 + hstepA, voffA);
;             PG8_WAIT_L(8); PG8_BAR; PG8_WAIT_L(0); PG8_MMA(0, 0, At, B0); PG8_BAR; PG8_SCHED;
;             PG8_LDB(B1, 0, 1); PG8_STAGE(PG8_SB(0, 0), b2, voffB);
;             PG8_BAR; PG8_WAIT_L(0); PG8_MMA(0, 1, At, B1); PG8_BAR;
;             PG8_LDA(At, 0, 1); PG8_STAGE(PG8_SA(0, 0), a2, voffA);
;             PG8_BAR; PG8_WAIT_L(0); PG8_MMA(1, 0, At, B0); PG8_BAR; PG8_SCHED;
;             PG8_STAGE(PG8_SB(0, 1), b2 + hstepB, voffB);
;             PG8_WAIT_V(6); PG8_BAR; PG8_MMA(1, 1, At, B1); PG8_BAR;
.Lsp_1:
.LBB0_317:
	ds_read_b128 v[128:131], v191
	ds_read_b128 v[132:135], v191 offset:1024
	ds_read_b128 v[136:139], v191 offset:2048
	ds_read_b128 v[140:143], v191 offset:3072
	ds_read_b128 v[144:147], v192
	ds_read_b128 v[148:151], v192 offset:1024
	ds_read_b128 v[170:173], v192 offset:2048
	ds_read_b128 v[174:177], v192 offset:3072
	ds_read_b128 v[178:181], v192 offset:4096
	ds_read_b128 v[182:185], v192 offset:5120
	ds_read_b128 v[196:199], v192 offset:6144
	ds_read_b128 v[200:203], v192 offset:7168
	ds_read_b128 v[204:207], v193
	ds_read_b128 v[208:211], v193 offset:1024
	ds_read_b128 v[212:215], v193 offset:2048
	ds_read_b128 v[216:219], v193 offset:3072
	s_add_u32 s10, s20, 0xffea0080
	s_addc_u32 s11, s21, -1
	s_cmpk_eq_i32 s50, 0x54
	s_cselect_b32 s13, s1, s11
	s_cselect_b32 s12, s0, s10
	s_cselect_b32 s11, s7, s49
	s_cselect_b32 s10, s6, s48
	v_lshl_add_u64 v[186:187], s[20:21], 0, v[160:161]
	s_add_i32 m0, s28, 0xc000
	s_nop 0
	global_load_lds_dwordx4 v[186:187], off
	v_lshl_add_u64 v[186:187], s[20:21], 0, v[162:163]
	s_add_i32 m0, s28, 0xe000
	s_nop 0
	global_load_lds_dwordx4 v[186:187], off
	s_waitcnt lgkmcnt(0)
	s_waitcnt vmcnt(8)
	s_barrier
	v_mfma_f32_16x16x32_bf16 v[124:127], v[128:131], v[144:147], v[124:127]
	v_mfma_f32_16x16x32_bf16 v[120:123], v[136:139], v[144:147], v[120:123]
	v_mfma_f32_16x16x32_bf16 v[104:107], v[128:131], v[170:173], v[104:107]
	v_mfma_f32_16x16x32_bf16 v[108:111], v[136:139], v[170:173], v[108:111]
	v_mfma_f32_16x16x32_bf16 v[88:91], v[128:131], v[178:181], v[88:91]
	v_mfma_f32_16x16x32_bf16 v[92:95], v[136:139], v[178:181], v[92:95]
	v_mfma_f32_16x16x32_bf16 v[72:75], v[128:131], v[196:199], v[72:75]
	v_mfma_f32_16x16x32_bf16 v[76:79], v[136:139], v[196:199], v[76:79]
	v_mfma_f32_16x16x32_bf16 v[124:127], v[132:135], v[148:151], v[124:127]
	v_mfma_f32_16x16x32_bf16 v[120:123], v[140:143], v[148:151], v[120:123]
	v_mfma_f32_16x16x32_bf16 v[104:107], v[132:135], v[174:177], v[104:107]
	v_mfma_f32_16x16x32_bf16 v[108:111], v[140:143], v[174:177], v[108:111]
	v_mfma_f32_16x16x32_bf16 v[88:91], v[132:135], v[182:185], v[88:91]
	v_mfma_f32_16x16x32_bf16 v[92:95], v[140:143], v[182:185], v[92:95]
	v_mfma_f32_16x16x32_bf16 v[72:75], v[132:135], v[200:203], v[72:75]
	v_mfma_f32_16x16x32_bf16 v[76:79], v[140:143], v[200:203], v[76:79]
	v_mfma_f32_16x16x32_bf16 v[116:119], v[204:207], v[144:147], v[116:119]
	v_mfma_f32_16x16x32_bf16 v[112:115], v[212:215], v[144:147], v[112:115]
	v_mfma_f32_16x16x32_bf16 v[100:103], v[204:207], v[170:173], v[100:103]
	v_mfma_f32_16x16x32_bf16 v[96:99], v[212:215], v[170:173], v[96:99]
	v_mfma_f32_16x16x32_bf16 v[84:87], v[204:207], v[178:181], v[84:87]
	v_mfma_f32_16x16x32_bf16 v[80:83], v[212:215], v[178:181], v[80:83]
	v_mfma_f32_16x16x32_bf16 v[68:71], v[204:207], v[196:199], v[68:71]
	v_mfma_f32_16x16x32_bf16 v[64:67], v[212:215], v[196:199], v[64:67]
	v_mfma_f32_16x16x32_bf16 v[116:119], v[208:211], v[148:151], v[116:119]
	v_mfma_f32_16x16x32_bf16 v[112:115], v[216:219], v[148:151], v[112:115]
	v_mfma_f32_16x16x32_bf16 v[100:103], v[208:211], v[174:177], v[100:103]
	v_mfma_f32_16x16x32_bf16 v[96:99], v[216:219], v[174:177], v[96:99]
	v_mfma_f32_16x16x32_bf16 v[84:87], v[208:211], v[182:185], v[84:87]
	v_mfma_f32_16x16x32_bf16 v[80:83], v[216:219], v[182:185], v[80:83]
	v_mfma_f32_16x16x32_bf16 v[68:71], v[208:211], v[200:203], v[68:71]
	v_mfma_f32_16x16x32_bf16 v[64:67], v[216:219], v[200:203], v[64:67]
	s_barrier
	ds_read_b128 v[144:147], v192 offset:16384
	ds_read_b128 v[148:151], v192 offset:17408
	ds_read_b128 v[170:173], v192 offset:18432
	ds_read_b128 v[174:177], v192 offset:19456
	ds_read_b128 v[178:181], v192 offset:20480
	ds_read_b128 v[182:185], v192 offset:21504
	ds_read_b128 v[196:199], v192 offset:22528
	ds_read_b128 v[200:203], v192 offset:23552
	s_add_i32 s51, s40, s23
	v_lshl_add_u64 v[186:187], s[10:11], 0, v[154:155]
	s_mov_b32 m0, s51
	s_nop 0
	global_load_lds_dwordx4 v[186:187], off
	v_lshl_add_u64 v[220:221], s[10:11], 0, v[158:159]
	s_add_i32 m0, s51, 0x2000
	s_nop 0
	global_load_lds_dwordx4 v[220:221], off
	s_mov_b32 m0, s28
	v_lshl_add_u64 v[222:223], s[12:13], 0, v[152:153]
	global_load_lds_dwordx4 v[222:223], off
	v_lshl_add_u64 v[224:225], s[12:13], 0, v[156:157]
	s_mov_b32 m0, s29
	s_nop 0
	global_load_lds_dwordx4 v[224:225], off
	s_add_u32 s52, s10, 0x160000
	s_addc_u32 s53, s11, 0
	s_add_i32 s51, s41, s23
	v_lshl_add_u64 v[226:227], s[52:53], 0, v[154:155]
	s_mov_b32 m0, s51
	s_nop 0
	global_load_lds_dwordx4 v[226:227], off
	v_lshl_add_u64 v[226:227], s[52:53], 0, v[158:159]
	s_add_i32 m0, s51, 0x2000
	s_nop 0
	global_load_lds_dwordx4 v[226:227], off
	s_waitcnt lgkmcnt(0)
	s_waitcnt vmcnt(8)
	s_barrier
; #define PG8_STAGE(bufoff, gbase, voff) do { _Pragma("unroll") for (int _i = 0; _i < 2; ++_i) \
;         __builtin_amdgcn_global_load_lds((const unsigned*)((const char*)(gbase) + (voff)[_i]), (PG8_LAS unsigned*)(lds + (bufoff) + ldsw + _i * 8192), 16, 0, 0); } while (0)
; #define PG8_LDA(dst, b, h) do { _Pragma("unroll") for (int m = 0; m < 4; ++m) _Pragma("unroll") for (int k = 0; k < 2; ++k) dst[m][k] = *(const PG8_LAS bf16x8*)(lds + PG8_SA(b, h) + aoff + m * 2048 + k * 1024); } while (0)
; #define PG8_LDB(dst, b, h) do { _Pragma("unroll") for (int n = 0; n < 2; ++n) _Pragma("unroll") for (int k = 0; k < 2; ++k) dst[n][k] = *(const PG8_LAS bf16x8*)(lds + PG8_SB(b, h) + boff + n * 2048 + k * 1024); } while (0)
; #define PG8_MMA(ai, bj, At, Bt) do { __builtin_amdgcn_s_setprio(1); _Pragma("unroll") for (int m = 0; m < 4; ++m) _Pragma("unroll") for (int n = 0; n < 2; ++n) _Pragma("unroll") for (int k = 0; k < 2; ++k) \
;         acc[ai][bj][m][n] = __builtin_amdgcn_mfma_f32_16x16x32_bf16(Bt[n][k], At[m][k], acc[ai][bj][m][n], 0, 0, 0); __builtin_amdgcn_s_setprio(0); } while (0)
; #define PG8_WAIT_V(n) asm volatile("s_waitcnt vmcnt(" #n ")" ::: "memory")
; #define PG8_WAIT_L(n) asm volatile("s_waitcnt lgkmcnt(" #n ")" ::: "memory")
; #define PG8_BAR __builtin_amdgcn_s_barrier()
; #define PG8_SCHED __builtin_amdgcn_sched_barrier(0)
; template <class Epi>
; __device__ __forceinline__ void gemm_phase(PG8_LAS unsigned char* lds, const Gemm g, const StaticOrder& S, const Epi& E) {
;     ...
;             PG8_WAIT_V(6); PG8_BAR; PG8_MMA(1, 1, At, B1); PG8_BAR;
;             PG8_LDB(B0, 1, 0); PG8_SCHED; PG8_LDA(At, 1, 0); PG8_STAGE(PG8_SA(0, 1), a2 + hstepA, voffA);
;             PG8_WAIT_L(8); PG8_BAR; PG8_WAIT_L(0); PG8_MMA(0, 0, At, B0); PG8_BAR; PG8_SCHED;
;             PG8_LDB(B1, 1, 1); PG8_STAGE(PG8_SB(1, 0), b3, voffB);
;             PG8_BAR; PG8_WAIT_L(0); PG8_MMA(0, 1, At, B1); PG8_BAR;
;             PG8_LDA(At, 1, 1); PG8_STAGE(PG8_SA(1, 0), a3, voffA);
;             PG8_BAR; PG8_WAIT_L(0); PG8_MMA(1, 0, At, B0); PG8_BAR; PG8_SCHED;
	v_mfma_f32_16x16x32_bf16 v[60:63], v[128:131], v[144:147], v[60:63]
	v_mfma_f32_16x16x32_bf16 v[56:59], v[136:139], v[144:147], v[56:59]
	v_mfma_f32_16x16x32_bf16 v[40:43], v[128:131], v[170:173], v[40:43]
	v_mfma_f32_16x16x32_bf16 v[44:47], v[136:139], v[170:173], v[44:47]
	v_mfma_f32_16x16x32_bf16 v[24:27], v[128:131], v[178:181], v[24:27]
	v_mfma_f32_16x16x32_bf16 v[28:31], v[136:139], v[178:181], v[28:31]
	v_mfma_f32_16x16x32_bf16 v[8:11], v[128:131], v[196:199], v[8:11]
	v_mfma_f32_16x16x32_bf16 v[12:15], v[136:139], v[196:199], v[12:15]
	v_mfma_f32_16x16x32_bf16 v[60:63], v[132:135], v[148:151], v[60:63]
	v_mfma_f32_16x16x32_bf16 v[56:59], v[140:143], v[148:151], v[56:59]
	v_mfma_f32_16x16x32_bf16 v[40:43], v[132:135], v[174:177], v[40:43]
	v_mfma_f32_16x16x32_bf16 v[44:47], v[140:143], v[174:177], v[44:47]
	v_mfma_f32_16x16x32_bf16 v[24:27], v[132:135], v[182:185], v[24:27]
	v_mfma_f32_16x16x32_bf16 v[28:31], v[140:143], v[182:185], v[28:31]
	v_mfma_f32_16x16x32_bf16 v[8:11], v[132:135], v[200:203], v[8:11]
	v_mfma_f32_16x16x32_bf16 v[12:15], v[140:143], v[200:203], v[12:15]
	v_mfma_f32_16x16x32_bf16 v[52:55], v[204:207], v[144:147], v[52:55]
	v_mfma_f32_16x16x32_bf16 v[48:51], v[212:215], v[144:147], v[48:51]
	v_mfma_f32_16x16x32_bf16 v[36:39], v[204:207], v[170:173], v[36:39]
	v_mfma_f32_16x16x32_bf16 v[32:35], v[212:215], v[170:173], v[32:35]
	v_mfma_f32_16x16x32_bf16 v[20:23], v[204:207], v[178:181], v[20:23]
	v_mfma_f32_16x16x32_bf16 v[16:19], v[212:215], v[178:181], v[16:19]
	v_mfma_f32_16x16x32_bf16 v[4:7], v[204:207], v[196:199], v[4:7]
	v_mfma_f32_16x16x32_bf16 v[0:3], v[212:215], v[196:199], v[0:3]
	v_mfma_f32_16x16x32_bf16 v[52:55], v[208:211], v[148:151], v[52:55]
	v_mfma_f32_16x16x32_bf16 v[48:51], v[216:219], v[148:151], v[48:51]
	v_mfma_f32_16x16x32_bf16 v[36:39], v[208:211], v[174:177], v[36:39]
	v_mfma_f32_16x16x32_bf16 v[32:35], v[216:219], v[174:177], v[32:35]
	v_mfma_f32_16x16x32_bf16 v[20:23], v[208:211], v[182:185], v[20:23]
	v_mfma_f32_16x16x32_bf16 v[16:19], v[216:219], v[182:185], v[16:19]
	v_mfma_f32_16x16x32_bf16 v[4:7], v[208:211], v[200:203], v[4:7]
	v_mfma_f32_16x16x32_bf16 v[0:3], v[216:219], v[200:203], v[0:3]
	s_add_i32 s51, 0, 0x18000
	v_add_u32_e32 v140, s51, v189
	s_barrier
	ds_read_b128 v[128:131], v140
	ds_read_b128 v[132:135], v140 offset:1024
	ds_read_b128 v[136:139], v140 offset:2048
	ds_read_b128 v[140:143], v140 offset:3072
	ds_read_b128 v[144:147], v192 offset:32768
	ds_read_b128 v[148:151], v192 offset:33792
	ds_read_b128 v[170:173], v192 offset:34816
	ds_read_b128 v[174:177], v192 offset:35840
	ds_read_b128 v[178:181], v192 offset:36864
	ds_read_b128 v[182:185], v192 offset:37888
	ds_read_b128 v[196:199], v192 offset:38912
	ds_read_b128 v[200:203], v192 offset:39936
	v_add_u32_e32 v195, 0x1c000, v189
	ds_read_b128 v[204:207], v195
	ds_read_b128 v[208:211], v195 offset:1024
	ds_read_b128 v[212:215], v195 offset:2048
	ds_read_b128 v[216:219], v195 offset:3072
	s_add_u32 s12, s12, 0x160000
	s_addc_u32 s13, s13, 0
	s_mov_b32 m0, s30
	v_lshl_add_u64 v[226:227], s[12:13], 0, v[152:153]
	global_load_lds_dwordx4 v[226:227], off
	v_lshl_add_u64 v[226:227], s[12:13], 0, v[156:157]
	s_mov_b32 m0, s31
	s_nop 0
	global_load_lds_dwordx4 v[226:227], off
	s_waitcnt lgkmcnt(0)
	s_waitcnt vmcnt(8)
	s_barrier
	v_mfma_f32_16x16x32_bf16 v[124:127], v[128:131], v[144:147], v[124:127]
	v_mfma_f32_16x16x32_bf16 v[120:123], v[136:139], v[144:147], v[120:123]
	v_mfma_f32_16x16x32_bf16 v[104:107], v[128:131], v[170:173], v[104:107]
	v_mfma_f32_16x16x32_bf16 v[108:111], v[136:139], v[170:173], v[108:111]
	v_mfma_f32_16x16x32_bf16 v[88:91], v[128:131], v[178:181], v[88:91]
	v_mfma_f32_16x16x32_bf16 v[92:95], v[136:139], v[178:181], v[92:95]
	v_mfma_f32_16x16x32_bf16 v[72:75], v[128:131], v[196:199], v[72:75]
	v_mfma_f32_16x16x32_bf16 v[76:79], v[136:139], v[196:199], v[76:79]
	v_mfma_f32_16x16x32_bf16 v[124:127], v[132:135], v[148:151], v[124:127]
	v_mfma_f32_16x16x32_bf16 v[120:123], v[140:143], v[148:151], v[120:123]
	v_mfma_f32_16x16x32_bf16 v[104:107], v[132:135], v[174:177], v[104:107]
	v_mfma_f32_16x16x32_bf16 v[108:111], v[140:143], v[174:177], v[108:111]
	v_mfma_f32_16x16x32_bf16 v[88:91], v[132:135], v[182:185], v[88:91]
	v_mfma_f32_16x16x32_bf16 v[92:95], v[140:143], v[182:185], v[92:95]
	v_mfma_f32_16x16x32_bf16 v[72:75], v[132:135], v[200:203], v[72:75]
	v_mfma_f32_16x16x32_bf16 v[76:79], v[140:143], v[200:203], v[76:79]
	v_mfma_f32_16x16x32_bf16 v[116:119], v[204:207], v[144:147], v[116:119]
	v_mfma_f32_16x16x32_bf16 v[112:115], v[212:215], v[144:147], v[112:115]
	v_mfma_f32_16x16x32_bf16 v[100:103], v[204:207], v[170:173], v[100:103]
	v_mfma_f32_16x16x32_bf16 v[96:99], v[212:215], v[170:173], v[96:99]
	v_mfma_f32_16x16x32_bf16 v[84:87], v[204:207], v[178:181], v[84:87]
	v_mfma_f32_16x16x32_bf16 v[80:83], v[212:215], v[178:181], v[80:83]
	v_mfma_f32_16x16x32_bf16 v[68:71], v[204:207], v[196:199], v[68:71]
	v_mfma_f32_16x16x32_bf16 v[64:67], v[212:215], v[196:199], v[64:67]
	v_mfma_f32_16x16x32_bf16 v[116:119], v[208:211], v[148:151], v[116:119]
	v_mfma_f32_16x16x32_bf16 v[112:115], v[216:219], v[148:151], v[112:115]
	v_mfma_f32_16x16x32_bf16 v[100:103], v[208:211], v[174:177], v[100:103]
	v_mfma_f32_16x16x32_bf16 v[96:99], v[216:219], v[174:177], v[96:99]
	v_mfma_f32_16x16x32_bf16 v[84:87], v[208:211], v[182:185], v[84:87]
	v_mfma_f32_16x16x32_bf16 v[80:83], v[216:219], v[182:185], v[80:83]
	v_mfma_f32_16x16x32_bf16 v[68:71], v[208:211], v[200:203], v[68:71]
	v_mfma_f32_16x16x32_bf16 v[64:67], v[216:219], v[200:203], v[64:67]
	s_barrier
; #define PG8_STAGE(bufoff, gbase, voff) do { _Pragma("unroll") for (int _i = 0; _i < 2; ++_i) \
;         __builtin_amdgcn_global_load_lds((const unsigned*)((const char*)(gbase) + (voff)[_i]), (PG8_LAS unsigned*)(lds + (bufoff) + ldsw + _i * 8192), 16, 0, 0); } while (0)
; #define PG8_MMA(ai, bj, At, Bt) do { __builtin_amdgcn_s_setprio(1); _Pragma("unroll") for (int m = 0; m < 4; ++m) _Pragma("unroll") for (int n = 0; n < 2; ++n) _Pragma("unroll") for (int k = 0; k < 2; ++k) \
;         acc[ai][bj][m][n] = __builtin_amdgcn_mfma_f32_16x16x32_bf16(Bt[n][k], At[m][k], acc[ai][bj][m][n], 0, 0, 0); __builtin_amdgcn_s_setprio(0); } while (0)
; #define PG8_WAIT_V(n) asm volatile("s_waitcnt vmcnt(" #n ")" ::: "memory")
; #define PG8_WAIT_L(n) asm volatile("s_waitcnt lgkmcnt(" #n ")" ::: "memory")
; #define PG8_BAR __builtin_amdgcn_s_barrier()
; #define PG8_SCHED __builtin_amdgcn_sched_barrier(0)
; template <class Epi>
; __device__ __forceinline__ void gemm_phase(PG8_LAS unsigned char* lds, const Gemm g, const StaticOrder& S, const Epi& E) {
;     ...
;             PG8_BAR; PG8_WAIT_L(0); PG8_MMA(1, 0, At, B0); PG8_BAR; PG8_SCHED;
;             PG8_STAGE(PG8_SB(1, 1), b3 + hstepB, voffB);
;             PG8_WAIT_V(6); PG8_BAR; PG8_MMA(1, 1, At, B1); PG8_BAR;
	ds_read_b128 v[144:147], v192 offset:49152
	ds_read_b128 v[148:151], v192 offset:50176
	ds_read_b128 v[170:173], v192 offset:51200
	ds_read_b128 v[174:177], v192 offset:52224
	ds_read_b128 v[178:181], v192 offset:53248
	ds_read_b128 v[182:185], v192 offset:54272
	ds_read_b128 v[196:199], v192 offset:55296
	ds_read_b128 v[200:203], v192 offset:56320
	s_add_i32 s12, 0, 0x1c000
	s_add_i32 s13, s51, s23
	v_lshl_add_u64 v[186:187], v[186:187], 0, s[18:19]
	s_mov_b32 m0, s13
	s_nop 0
	global_load_lds_dwordx4 v[186:187], off
	v_lshl_add_u64 v[186:187], v[220:221], 0, s[18:19]
	s_add_i32 m0, s13, 0x2000
	s_nop 0
	global_load_lds_dwordx4 v[186:187], off
	s_mov_b32 m0, s35
	v_lshl_add_u64 v[186:187], v[222:223], 0, s[18:19]
	global_load_lds_dwordx4 v[186:187], off
	v_lshl_add_u64 v[186:187], v[224:225], 0, s[18:19]
	s_mov_b32 m0, s36
	s_nop 0
	global_load_lds_dwordx4 v[186:187], off
	s_add_u32 s10, s10, 0x160080
	s_addc_u32 s11, s11, 0
	s_add_i32 s12, s12, s23
	v_lshl_add_u64 v[226:227], s[10:11], 0, v[154:155]
	s_mov_b32 m0, s12
	s_nop 0
	global_load_lds_dwordx4 v[226:227], off
	v_lshl_add_u64 v[226:227], s[10:11], 0, v[158:159]
	s_add_i32 m0, s12, 0x2000
	s_nop 0
	global_load_lds_dwordx4 v[226:227], off
	s_waitcnt lgkmcnt(0)
	s_waitcnt vmcnt(8)
	s_barrier
	v_mfma_f32_16x16x32_bf16 v[60:63], v[128:131], v[144:147], v[60:63]
	v_mfma_f32_16x16x32_bf16 v[56:59], v[136:139], v[144:147], v[56:59]
	v_mfma_f32_16x16x32_bf16 v[40:43], v[128:131], v[170:173], v[40:43]
	v_mfma_f32_16x16x32_bf16 v[44:47], v[136:139], v[170:173], v[44:47]
	v_mfma_f32_16x16x32_bf16 v[24:27], v[128:131], v[178:181], v[24:27]
	v_mfma_f32_16x16x32_bf16 v[28:31], v[136:139], v[178:181], v[28:31]
	v_mfma_f32_16x16x32_bf16 v[8:11], v[128:131], v[196:199], v[8:11]
	v_mfma_f32_16x16x32_bf16 v[12:15], v[136:139], v[196:199], v[12:15]
	v_mfma_f32_16x16x32_bf16 v[60:63], v[132:135], v[148:151], v[60:63]
	v_mfma_f32_16x16x32_bf16 v[56:59], v[140:143], v[148:151], v[56:59]
	v_mfma_f32_16x16x32_bf16 v[40:43], v[132:135], v[174:177], v[40:43]
	v_mfma_f32_16x16x32_bf16 v[44:47], v[140:143], v[174:177], v[44:47]
	v_mfma_f32_16x16x32_bf16 v[24:27], v[132:135], v[182:185], v[24:27]
	v_mfma_f32_16x16x32_bf16 v[28:31], v[140:143], v[182:185], v[28:31]
	v_mfma_f32_16x16x32_bf16 v[8:11], v[132:135], v[200:203], v[8:11]
	v_mfma_f32_16x16x32_bf16 v[12:15], v[140:143], v[200:203], v[12:15]
	v_mfma_f32_16x16x32_bf16 v[52:55], v[204:207], v[144:147], v[52:55]
	v_mfma_f32_16x16x32_bf16 v[48:51], v[212:215], v[144:147], v[48:51]
	v_mfma_f32_16x16x32_bf16 v[36:39], v[204:207], v[170:173], v[36:39]
	v_mfma_f32_16x16x32_bf16 v[32:35], v[212:215], v[170:173], v[32:35]
	v_mfma_f32_16x16x32_bf16 v[20:23], v[204:207], v[178:181], v[20:23]
	v_mfma_f32_16x16x32_bf16 v[16:19], v[212:215], v[178:181], v[16:19]
	v_mfma_f32_16x16x32_bf16 v[4:7], v[204:207], v[196:199], v[4:7]
	v_mfma_f32_16x16x32_bf16 v[0:3], v[212:215], v[196:199], v[0:3]
	v_mfma_f32_16x16x32_bf16 v[52:55], v[208:211], v[148:151], v[52:55]
	v_mfma_f32_16x16x32_bf16 v[48:51], v[216:219], v[148:151], v[48:51]
	v_mfma_f32_16x16x32_bf16 v[36:39], v[208:211], v[174:177], v[36:39]
	v_mfma_f32_16x16x32_bf16 v[32:35], v[216:219], v[174:177], v[32:35]
	v_mfma_f32_16x16x32_bf16 v[20:23], v[208:211], v[182:185], v[20:23]
	v_mfma_f32_16x16x32_bf16 v[16:19], v[216:219], v[182:185], v[16:19]
	v_mfma_f32_16x16x32_bf16 v[4:7], v[208:211], v[200:203], v[4:7]
	v_mfma_f32_16x16x32_bf16 v[0:3], v[216:219], v[200:203], v[0:3]
	s_add_i32 s50, s50, 2
	s_add_u32 s20, s20, 0x100
	s_addc_u32 s21, s21, 0
	s_add_u32 s48, s48, 0x100
	s_addc_u32 s49, s49, 0
	s_cmpk_gt_u32 s50, 0x55
	s_barrier
	s_cbranch_scc0 .LBB0_317
; __device__ __forceinline__ u32x4 pack8(const float (&f)[8]) { u32x4 w; w.x = cvt_pk_bf16(f[0], f[1]); w.y = cvt_pk_bf16(f[2], f[3]); w.z = cvt_pk_bf16(f[4], f[5]); w.w = cvt_pk_bf16(f[6], f[7]); return w; }
;     __device__ __forceinline__ void operator()(const f32x4 (&acc)[2][2][4][2], const pg8::Unit& u, int wr, int wc, int fr, int fq) const {
;         const int row0 = u.pm * 256 + wr * 64 + fr, col0 = u.pn * 256 + wc * 32 + 8 * fq;
; #pragma unroll
;         for (int ai = 0; ai < 2; ++ai) {
;             u32x4 rb[4][2];
; #pragma unroll
;             for (int m = 0; m < 4; ++m)
; #pragma unroll
;                 for (int bj = 0; bj < 2; ++bj) rb[m][bj] = *(const u32x4*)(resb + (size_t)(row0 + ai * 128 + m * 16) * DM + col0 + bj * 128);
; #pragma unroll
;             for (int m = 0; m < 4; ++m) {
;                 const int r = row0 + ai * 128 + m * 16; float ss = 0.f;
; #pragma unroll
;                 for (int bj = 0; bj < 2; ++bj) {
;                     const size_t off = (size_t)r * DM + col0 + bj * 128;
;                     float rv[8], o[8]; unpack8(rb[m][bj], rv);
; #pragma unroll
;                     for (int n = 0; n < 2; ++n)
; #pragma unroll
;                         for (int i = 0; i < 4; ++i) o[n * 4 + i] = rv[n * 4 + i] + coef * acc[ai][bj][m][n][i];
;                     if (outf) { *(f32x4*)(outf + off) = (f32x4){o[0], o[1], o[2], o[3]}; *(f32x4*)(outf + off + 4) = (f32x4){o[4], o[5], o[6], o[7]}; }
;                     if (hb) { *(u32x4*)(hb + off) = pack8(o);
; #pragma unroll
;                         for (int i = 0; i < 8; ++i) ss += o[i] * o[i]; }
;                 }
;                 if (hb) { ss += __shfl_xor(ss, 16); ss += __shfl_xor(ss, 32); if (fq == 0) part[(size_t)r * 32 + u.pn * 4 + wc] = ss; }
	v_lshl_or_b32 v170, s16, 8, v190
	v_lshl_add_u32 v172, s47, 8, v188
	v_ashrrev_i32_e32 v171, 31, v170
	v_lshlrev_b64 v[204:205], 1, v[170:171]
	v_ashrrev_i32_e32 v173, 31, v172
	v_lshl_add_u64 v[174:175], s[76:77], 0, v[204:205]
	v_lshlrev_b64 v[206:207], 12, v[172:173]
	v_lshl_add_u64 v[128:129], v[174:175], 0, v[206:207]
	global_load_dwordx4 v[196:199], v[128:129], off
	global_load_dwordx4 v[200:203], v[128:129], off offset:256
	v_or_b32_e32 v184, 16, v172
	v_or_b32_e32 v180, 32, v172
	v_or_b32_e32 v176, 48, v172
	v_ashrrev_i32_e32 v185, 31, v184
	v_ashrrev_i32_e32 v181, 31, v180
	v_ashrrev_i32_e32 v177, 31, v176
	v_lshlrev_b64 v[186:187], 12, v[184:185]
	v_lshlrev_b64 v[182:183], 12, v[180:181]
	v_lshlrev_b64 v[178:179], 12, v[176:177]
	v_lshl_add_u64 v[128:129], v[174:175], 0, v[186:187]
	v_lshl_add_u64 v[130:131], v[174:175], 0, v[182:183]
	v_lshl_add_u64 v[208:209], v[174:175], 0, v[178:179]
	global_load_dwordx4 v[148:151], v[128:129], off
	global_load_dwordx4 v[144:147], v[128:129], off offset:256
	global_load_dwordx4 v[140:143], v[130:131], off
	global_load_dwordx4 v[136:139], v[130:131], off offset:256
	global_load_dwordx4 v[132:135], v[208:209], off
	s_nop 0
	global_load_dwordx4 v[128:131], v[208:209], off offset:256
	v_lshl_add_u64 v[206:207], s[76:77], 0, v[206:207]
	v_and_b32_e32 v208, 64, v194
	v_lshl_add_u64 v[204:205], v[206:207], 0, v[204:205]
	v_xor_b32_e32 v195, 16, v194
	v_add_u32_e32 v208, 64, v208
	v_xor_b32_e32 v209, 32, v194
	v_cmp_lt_i32_e32 vcc, v195, v208
	s_lshl_b32 s20, s16, 2
	s_ashr_i32 s21, s20, 31
	v_cndmask_b32_e32 v195, v194, v195, vcc
	v_cmp_lt_i32_e32 vcc, v209, v208
	v_lshlrev_b32_e32 v195, 2, v195
	s_waitcnt vmcnt(0)
	v_lshlrev_b32_e32 v206, 16, v196
	v_and_b32_e32 v196, 0xffff0000, v196
	v_lshlrev_b32_e32 v211, 16, v200
	v_and_b32_e32 v200, 0xffff0000, v200
	v_fmac_f32_e32 v196, 0.5, v125
	v_lshlrev_b32_e32 v207, 16, v197
	v_fmac_f32_e32 v206, 0.5, v124
	v_fmac_f32_e32 v200, 0.5, v117
	v_mul_f32_e32 v117, v196, v196
	v_and_b32_e32 v197, 0xffff0000, v197
	v_fmac_f32_e32 v207, 0.5, v126
	v_fmac_f32_e32 v117, v206, v206
	v_cndmask_b32_e32 v208, v194, v209, vcc
	v_lshlrev_b32_e32 v209, 16, v198
	v_fmac_f32_e32 v197, 0.5, v127
	v_fmac_f32_e32 v117, v207, v207
	v_and_b32_e32 v198, 0xffff0000, v198
	v_fmac_f32_e32 v209, 0.5, v120
	v_fmac_f32_e32 v117, v197, v197
	v_lshlrev_b32_e32 v210, 16, v199
	v_fmac_f32_e32 v198, 0.5, v121
	v_fmac_f32_e32 v117, v209, v209
	v_and_b32_e32 v199, 0xffff0000, v199
	v_fmac_f32_e32 v210, 0.5, v122
	v_fmac_f32_e32 v117, v198, v198
	v_fmac_f32_e32 v199, 0.5, v123
	v_fmac_f32_e32 v117, v210, v210
	v_fmac_f32_e32 v211, 0.5, v116
	v_fmac_f32_e32 v117, v199, v199
	v_lshlrev_b32_e32 v212, 16, v201
	v_fmac_f32_e32 v117, v211, v211
	v_and_b32_e32 v201, 0xffff0000, v201
	v_fmac_f32_e32 v212, 0.5, v118
	v_fmac_f32_e32 v117, v200, v200
	v_lshlrev_b32_e32 v213, 16, v202
	v_fmac_f32_e32 v201, 0.5, v119
	v_fmac_f32_e32 v117, v212, v212
	v_and_b32_e32 v202, 0xffff0000, v202
	v_fmac_f32_e32 v213, 0.5, v112
	v_fmac_f32_e32 v117, v201, v201
	v_lshlrev_b32_e32 v214, 16, v203
	v_fmac_f32_e32 v202, 0.5, v113
	v_fmac_f32_e32 v117, v213, v213
	v_and_b32_e32 v203, 0xffff0000, v203
	v_fmac_f32_e32 v214, 0.5, v114
	v_fmac_f32_e32 v117, v202, v202
	v_fmac_f32_e32 v203, 0.5, v115
	v_fmac_f32_e32 v117, v214, v214
	v_fmac_f32_e32 v117, v203, v203
	ds_bpermute_b32 v118, v195, v117
	v_cvt_pk_bf16_f32 v112, v206, v196
	v_cvt_pk_bf16_f32 v113, v207, v197
	v_cvt_pk_bf16_f32 v114, v209, v198
	v_cvt_pk_bf16_f32 v115, v210, v199
	global_store_dwordx4 v[204:205], v[112:115], off
	v_cvt_pk_bf16_f32 v116, v211, v200
	s_waitcnt lgkmcnt(0)
	s_nop 0
	v_add_f32_e32 v113, v117, v118
	v_lshlrev_b32_e32 v112, 2, v208
	ds_bpermute_b32 v114, v112, v113
	v_cvt_pk_bf16_f32 v117, v212, v201
	v_cvt_pk_bf16_f32 v118, v213, v202
	v_cvt_pk_bf16_f32 v119, v214, v203
	global_store_dwordx4 v[204:205], v[116:119], off offset:256
	s_and_saveexec_b64 s[10:11], s[2:3]
	s_cbranch_execz .LBB0_320
	v_lshlrev_b64 v[116:117], 7, v[172:173]
	v_lshl_add_u64 v[116:117], s[8:9], 0, v[116:117]
	v_lshl_add_u64 v[116:117], s[20:21], 2, v[116:117]
	s_lshl_b32 s16, s34, 2
	v_lshl_add_u64 v[116:117], v[116:117], 0, s[16:17]
	s_waitcnt lgkmcnt(0)
	v_add_f32_e32 v113, v113, v114
	global_store_dword v[116:117], v113, off

; __device__ __forceinline__ void xcd_barrier(const XcdBarrier& b) {
;     asm volatile("s_waitcnt vmcnt(0)" ::: "memory");
;     __syncthreads();
;     if (threadIdx.x == 0) {
;         unsigned* bar = b.bar;
;         __builtin_amdgcn_s_waitcnt(0);
;         unsigned nloc = b.st[0], nx = b.st[1];
;         if (nloc == 0u) { xcd_barrier_complete(bar, b.x, nloc, nx); b.st[0] = nloc; b.st[1] = nx; }
.LBB0_348:
	s_setprio 0
	s_cmp_gt_i32 s75, 3
	s_cselect_b64 s[0:1], -1, 0
	s_and_b64 s[2:3], s[14:15], s[0:1]
	s_andn2_b64 vcc, exec, s[2:3]
	s_cbranch_vccnz .LBB0_402
	s_waitcnt vmcnt(0)
	s_waitcnt vmcnt(0) lgkmcnt(0)
	s_barrier
	s_mov_b64 s[2:3], exec
	v_readlane_b32 s4, v253, 8
	v_readlane_b32 s5, v253, 9
	s_and_b64 s[4:5], s[2:3], s[4:5]
	s_mov_b64 exec, s[4:5]
	s_cbranch_execz .LBB0_401
	s_add_i32 s4, 0, 0x24000
	v_mov_b32_e32 v0, s4
	s_waitcnt vmcnt(0) expcnt(0) lgkmcnt(0)
	ds_read_b32 v2, v0
	s_add_i32 s4, 0, 0x24004
	v_mov_b32_e32 v0, s4
	ds_read_b32 v0, v0
	s_waitcnt lgkmcnt(1)
	v_cmp_ne_u32_e32 vcc, 0, v2
	s_cbranch_vccnz .LBB0_365
	s_add_u32 s4, s80, 0x1e7fae00
	s_addc_u32 s5, s81, 0
	s_add_u32 s6, s80, 0x1e7fb000
	s_addc_u32 s7, s81, 0
	s_add_u32 s10, s80, 0x1e7fb100
	s_addc_u32 s11, s81, 0
	s_add_u32 s12, s80, 0x1e7fb200
	s_addc_u32 s13, s81, 0
	s_add_u32 s14, s80, 0x1e7fb300
	s_addc_u32 s15, s81, 0
	s_add_u32 s16, s80, 0x1e7fb400
	s_addc_u32 s17, s81, 0
	s_add_u32 s18, s80, 0x1e7fb500
	s_addc_u32 s19, s81, 0
	s_add_u32 s20, s80, 0x1e7fb600
	s_addc_u32 s21, s81, 0
	s_add_u32 s22, s80, 0x1e7fb700
	s_addc_u32 s23, s81, 0
	s_add_u32 s28, s80, 0x1e7fb800
	s_addc_u32 s29, s81, 0
	s_add_u32 s30, s80, 0x1e7fb900
	s_addc_u32 s31, s81, 0
	s_add_u32 s34, s80, 0x1e7fba00
	s_addc_u32 s35, s81, 0
	s_add_u32 s36, s80, 0x1e7fbb00
	s_addc_u32 s37, s81, 0
	s_add_u32 s38, s80, 0x1e7fbc00
	s_addc_u32 s39, s81, 0
	s_add_u32 s40, s80, 0x1e7fbd00
	s_addc_u32 s41, s81, 0
	s_add_u32 s42, s80, 0x1e7fbe00
	s_addc_u32 s43, s81, 0
	s_mul_i32 s54, s27, s33
	s_add_u32 s46, s80, 0x1e7fbf00
	s_mul_i32 s54, s54, s26
	s_addc_u32 s47, s81, 0
	s_mov_b32 s55, 1
	v_mov_b32_e32 v16, 0
	s_branch .LBB0_353

; #define PG8_STAGE(bufoff, gbase, voff) do { _Pragma("unroll") for (int _i = 0; _i < 2; ++_i) \
;         __builtin_amdgcn_global_load_lds((const unsigned*)((const char*)(gbase) + (voff)[_i]), (PG8_LAS unsigned*)(lds + (bufoff) + ldsw + _i * 8192), 16, 0, 0); } while (0)
; #define PG8_LDA(dst, b, h) do { _Pragma("unroll") for (int m = 0; m < 4; ++m) _Pragma("unroll") for (int k = 0; k < 2; ++k) dst[m][k] = *(const PG8_LAS bf16x8*)(lds + PG8_SA(b, h) + aoff + m * 2048 + k * 1024); } while (0)
; #define PG8_LDB(dst, b, h) do { _Pragma("unroll") for (int n = 0; n < 2; ++n) _Pragma("unroll") for (int k = 0; k < 2; ++k) dst[n][k] = *(const PG8_LAS bf16x8*)(lds + PG8_SB(b, h) + boff + n * 2048 + k * 1024); } while (0)
; #define PG8_MMA(ai, bj, At, Bt) do { __builtin_amdgcn_s_setprio(1); _Pragma("unroll") for (int m = 0; m < 4; ++m) _Pragma("unroll") for (int n = 0; n < 2; ++n) _Pragma("unroll") for (int k = 0; k < 2; ++k) \
;         acc[ai][bj][m][n] = __builtin_amdgcn_mfma_f32_16x16x32_bf16(Bt[n][k], At[m][k], acc[ai][bj][m][n], 0, 0, 0); __builtin_amdgcn_s_setprio(0); } while (0)
; #define PG8_WAIT_V(n) asm volatile("s_waitcnt vmcnt(" #n ")" ::: "memory")
; #define PG8_WAIT_L(n) asm volatile("s_waitcnt lgkmcnt(" #n ")" ::: "memory")
; template <class Epi>
; __device__ __forceinline__ void gemm_phase(PG8_LAS unsigned char* lds, const Gemm g, const StaticOrder& S, const Epi& E) {
;     ...
;         for (int t = 0; t < nt; t += 2) {
;             const bool last = (t == nt - 2);
;             const char* a1 = cA + (size_t)(t + 1) * kstep;
;             const char* a2 = last ? nA : cA + (size_t)(t + 2) * kstep; const char* b2 = last ? nB : cB + (size_t)(t + 2) * kstep;
;             const char* a3 = a2 + kstep; const char* b3 = b2 + kstep;
;             PG8_LDB(B0, 0, 0); PG8_SCHED; PG8_LDA(At, 0, 0); PG8_STAGE(PG8_SA(1, 1), a1 + hstepA, voffA);
;             PG8_WAIT_L(8); PG8_BAR; PG8_WAIT_L(0); PG8_MMA(0, 0, At, B0); PG8_BAR; PG8_SCHED;
;             PG8_LDB(B1, 0, 1); PG8_STAGE(PG8_SB(0, 0), b2, voffB);
;             PG8_BAR; PG8_WAIT_L(0); PG8_MMA(0, 1, At, B1); PG8_BAR;
;             PG8_LDA(At, 0, 1); PG8_STAGE(PG8_SA(0, 0), a2, voffA);
;             PG8_BAR; PG8_WAIT_L(0); PG8_MMA(1, 0, At, B0); PG8_BAR; PG8_SCHED;
;             PG8_STAGE(PG8_SB(0, 1), b2 + hstepB, voffB);
;             PG8_WAIT_V(6); PG8_BAR; PG8_MMA(1, 1, At, B1); PG8_BAR;
.Lsp_2:
.LBB0_413:
	ds_read_b128 v[148:151], v166
	ds_read_b128 v[152:155], v166 offset:1024
	ds_read_b128 v[156:159], v166 offset:2048
	ds_read_b128 v[172:175], v166 offset:3072
	ds_read_b128 v[176:179], v167
	ds_read_b128 v[180:183], v167 offset:1024
	ds_read_b128 v[184:187], v167 offset:2048
	ds_read_b128 v[188:191], v167 offset:3072
	ds_read_b128 v[192:195], v167 offset:4096
	ds_read_b128 v[196:199], v167 offset:5120
	ds_read_b128 v[200:203], v167 offset:6144
	ds_read_b128 v[204:207], v167 offset:7168
	ds_read_b128 v[208:211], v169
	ds_read_b128 v[212:215], v169 offset:1024
	ds_read_b128 v[216:219], v169 offset:2048
	ds_read_b128 v[220:223], v169 offset:3072
	s_add_u32 s4, s0, 0xfff80080
	s_addc_u32 s5, s1, -1
	s_cmp_eq_u32 s67, 28
	s_cselect_b32 s7, s53, s5
	s_cselect_b32 s6, s57, s4
	s_cselect_b32 s5, s55, s66
	s_cselect_b32 s4, s63, s65
	v_lshl_add_u64 v[160:161], s[0:1], 0, v[140:141]
	s_add_i32 m0, s11, 0xc000
	s_nop 0
	global_load_lds_dwordx4 v[160:161], off
	v_lshl_add_u64 v[160:161], s[0:1], 0, v[142:143]
	s_add_i32 m0, s11, 0xe000
	s_nop 0
	global_load_lds_dwordx4 v[160:161], off
	s_waitcnt lgkmcnt(0)
	s_waitcnt vmcnt(8)
	s_barrier
	v_mfma_f32_16x16x32_bf16 v[124:127], v[148:151], v[176:179], v[124:127]
	v_mfma_f32_16x16x32_bf16 v[120:123], v[156:159], v[176:179], v[120:123]
	v_mfma_f32_16x16x32_bf16 v[108:111], v[148:151], v[184:187], v[108:111]
	v_mfma_f32_16x16x32_bf16 v[104:107], v[156:159], v[184:187], v[104:107]
	v_mfma_f32_16x16x32_bf16 v[92:95], v[148:151], v[192:195], v[92:95]
	v_mfma_f32_16x16x32_bf16 v[88:91], v[156:159], v[192:195], v[88:91]
	v_mfma_f32_16x16x32_bf16 v[76:79], v[148:151], v[200:203], v[76:79]
	v_mfma_f32_16x16x32_bf16 v[72:75], v[156:159], v[200:203], v[72:75]
	v_mfma_f32_16x16x32_bf16 v[124:127], v[152:155], v[180:183], v[124:127]
	v_mfma_f32_16x16x32_bf16 v[120:123], v[172:175], v[180:183], v[120:123]
	v_mfma_f32_16x16x32_bf16 v[108:111], v[152:155], v[188:191], v[108:111]
	v_mfma_f32_16x16x32_bf16 v[104:107], v[172:175], v[188:191], v[104:107]
	v_mfma_f32_16x16x32_bf16 v[92:95], v[152:155], v[196:199], v[92:95]
	v_mfma_f32_16x16x32_bf16 v[88:91], v[172:175], v[196:199], v[88:91]
	v_mfma_f32_16x16x32_bf16 v[76:79], v[152:155], v[204:207], v[76:79]
	v_mfma_f32_16x16x32_bf16 v[72:75], v[172:175], v[204:207], v[72:75]
	v_mfma_f32_16x16x32_bf16 v[116:119], v[208:211], v[176:179], v[116:119]
	v_mfma_f32_16x16x32_bf16 v[112:115], v[216:219], v[176:179], v[112:115]
	v_mfma_f32_16x16x32_bf16 v[100:103], v[208:211], v[184:187], v[100:103]
	v_mfma_f32_16x16x32_bf16 v[96:99], v[216:219], v[184:187], v[96:99]
	v_mfma_f32_16x16x32_bf16 v[84:87], v[208:211], v[192:195], v[84:87]
	v_mfma_f32_16x16x32_bf16 v[80:83], v[216:219], v[192:195], v[80:83]
	v_mfma_f32_16x16x32_bf16 v[68:71], v[208:211], v[200:203], v[68:71]
	v_mfma_f32_16x16x32_bf16 v[64:67], v[216:219], v[200:203], v[64:67]
	v_mfma_f32_16x16x32_bf16 v[116:119], v[212:215], v[180:183], v[116:119]
	v_mfma_f32_16x16x32_bf16 v[112:115], v[220:223], v[180:183], v[112:115]
	v_mfma_f32_16x16x32_bf16 v[100:103], v[212:215], v[188:191], v[100:103]
	v_mfma_f32_16x16x32_bf16 v[96:99], v[220:223], v[188:191], v[96:99]
	v_mfma_f32_16x16x32_bf16 v[84:87], v[212:215], v[196:199], v[84:87]
	v_mfma_f32_16x16x32_bf16 v[80:83], v[220:223], v[196:199], v[80:83]
	v_mfma_f32_16x16x32_bf16 v[68:71], v[212:215], v[204:207], v[68:71]
	v_mfma_f32_16x16x32_bf16 v[64:67], v[220:223], v[204:207], v[64:67]
	s_barrier
	ds_read_b128 v[176:179], v167 offset:16384
	ds_read_b128 v[180:183], v167 offset:17408
	ds_read_b128 v[184:187], v167 offset:18432
	ds_read_b128 v[188:191], v167 offset:19456
	ds_read_b128 v[192:195], v167 offset:20480
	ds_read_b128 v[196:199], v167 offset:21504
	ds_read_b128 v[200:203], v167 offset:22528
	ds_read_b128 v[204:207], v167 offset:23552
	s_add_i32 s68, s9, s10
	v_lshl_add_u64 v[160:161], s[4:5], 0, v[130:131]
	s_mov_b32 m0, s68
	s_nop 0
	global_load_lds_dwordx4 v[160:161], off
	v_lshl_add_u64 v[224:225], s[4:5], 0, v[134:135]
	s_add_i32 m0, s68, 0x2000
	s_nop 0
	global_load_lds_dwordx4 v[224:225], off
	s_mov_b32 m0, s11
	v_lshl_add_u64 v[226:227], s[6:7], 0, v[128:129]
	global_load_lds_dwordx4 v[226:227], off
	v_lshl_add_u64 v[228:229], s[6:7], 0, v[132:133]
	s_mov_b32 m0, s19
	s_nop 0
	global_load_lds_dwordx4 v[228:229], off
	s_add_u32 s68, s4, 0x80000
	s_addc_u32 s69, s5, 0
	s_add_i32 s70, s40, s10
	v_lshl_add_u64 v[230:231], s[68:69], 0, v[130:131]
	s_mov_b32 m0, s70
	s_nop 0
	global_load_lds_dwordx4 v[230:231], off
	v_lshl_add_u64 v[230:231], s[68:69], 0, v[134:135]
	s_add_i32 m0, s70, 0x2000
	s_nop 0
	global_load_lds_dwordx4 v[230:231], off
	s_waitcnt lgkmcnt(0)
	s_waitcnt vmcnt(8)
	s_barrier
; #define PG8_STAGE(bufoff, gbase, voff) do { _Pragma("unroll") for (int _i = 0; _i < 2; ++_i) \
;         __builtin_amdgcn_global_load_lds((const unsigned*)((const char*)(gbase) + (voff)[_i]), (PG8_LAS unsigned*)(lds + (bufoff) + ldsw + _i * 8192), 16, 0, 0); } while (0)
; #define PG8_LDA(dst, b, h) do { _Pragma("unroll") for (int m = 0; m < 4; ++m) _Pragma("unroll") for (int k = 0; k < 2; ++k) dst[m][k] = *(const PG8_LAS bf16x8*)(lds + PG8_SA(b, h) + aoff + m * 2048 + k * 1024); } while (0)
; #define PG8_LDB(dst, b, h) do { _Pragma("unroll") for (int n = 0; n < 2; ++n) _Pragma("unroll") for (int k = 0; k < 2; ++k) dst[n][k] = *(const PG8_LAS bf16x8*)(lds + PG8_SB(b, h) + boff + n * 2048 + k * 1024); } while (0)
; #define PG8_MMA(ai, bj, At, Bt) do { __builtin_amdgcn_s_setprio(1); _Pragma("unroll") for (int m = 0; m < 4; ++m) _Pragma("unroll") for (int n = 0; n < 2; ++n) _Pragma("unroll") for (int k = 0; k < 2; ++k) \
;         acc[ai][bj][m][n] = __builtin_amdgcn_mfma_f32_16x16x32_bf16(Bt[n][k], At[m][k], acc[ai][bj][m][n], 0, 0, 0); __builtin_amdgcn_s_setprio(0); } while (0)
; #define PG8_WAIT_V(n) asm volatile("s_waitcnt vmcnt(" #n ")" ::: "memory")
; #define PG8_WAIT_L(n) asm volatile("s_waitcnt lgkmcnt(" #n ")" ::: "memory")
; #define PG8_BAR __builtin_amdgcn_s_barrier()
; #define PG8_SCHED __builtin_amdgcn_sched_barrier(0)
; template <class Epi>
; __device__ __forceinline__ void gemm_phase(PG8_LAS unsigned char* lds, const Gemm g, const StaticOrder& S, const Epi& E) {
;     ...
;             PG8_WAIT_V(6); PG8_BAR; PG8_MMA(1, 1, At, B1); PG8_BAR;
;             PG8_LDB(B0, 1, 0); PG8_SCHED; PG8_LDA(At, 1, 0); PG8_STAGE(PG8_SA(0, 1), a2 + hstepA, voffA);
;             PG8_WAIT_L(8); PG8_BAR; PG8_WAIT_L(0); PG8_MMA(0, 0, At, B0); PG8_BAR; PG8_SCHED;
;             PG8_LDB(B1, 1, 1); PG8_STAGE(PG8_SB(1, 0), b3, voffB);
;             PG8_BAR; PG8_WAIT_L(0); PG8_MMA(0, 1, At, B1); PG8_BAR;
;             PG8_LDA(At, 1, 1); PG8_STAGE(PG8_SA(1, 0), a3, voffA);
;             PG8_BAR; PG8_WAIT_L(0); PG8_MMA(1, 0, At, B0); PG8_BAR; PG8_SCHED;
	v_mfma_f32_16x16x32_bf16 v[60:63], v[148:151], v[176:179], v[60:63]
	v_mfma_f32_16x16x32_bf16 v[56:59], v[156:159], v[176:179], v[56:59]
	v_mfma_f32_16x16x32_bf16 v[44:47], v[148:151], v[184:187], v[44:47]
	v_mfma_f32_16x16x32_bf16 v[40:43], v[156:159], v[184:187], v[40:43]
	v_mfma_f32_16x16x32_bf16 v[28:31], v[148:151], v[192:195], v[28:31]
	v_mfma_f32_16x16x32_bf16 v[24:27], v[156:159], v[192:195], v[24:27]
	v_mfma_f32_16x16x32_bf16 v[12:15], v[148:151], v[200:203], v[12:15]
	v_mfma_f32_16x16x32_bf16 v[8:11], v[156:159], v[200:203], v[8:11]
	v_mfma_f32_16x16x32_bf16 v[60:63], v[152:155], v[180:183], v[60:63]
	v_mfma_f32_16x16x32_bf16 v[56:59], v[172:175], v[180:183], v[56:59]
	v_mfma_f32_16x16x32_bf16 v[44:47], v[152:155], v[188:191], v[44:47]
	v_mfma_f32_16x16x32_bf16 v[40:43], v[172:175], v[188:191], v[40:43]
	v_mfma_f32_16x16x32_bf16 v[28:31], v[152:155], v[196:199], v[28:31]
	v_mfma_f32_16x16x32_bf16 v[24:27], v[172:175], v[196:199], v[24:27]
	v_mfma_f32_16x16x32_bf16 v[12:15], v[152:155], v[204:207], v[12:15]
	v_mfma_f32_16x16x32_bf16 v[8:11], v[172:175], v[204:207], v[8:11]
	v_mfma_f32_16x16x32_bf16 v[52:55], v[208:211], v[176:179], v[52:55]
	v_mfma_f32_16x16x32_bf16 v[48:51], v[216:219], v[176:179], v[48:51]
	v_mfma_f32_16x16x32_bf16 v[36:39], v[208:211], v[184:187], v[36:39]
	v_mfma_f32_16x16x32_bf16 v[32:35], v[216:219], v[184:187], v[32:35]
	v_mfma_f32_16x16x32_bf16 v[20:23], v[208:211], v[192:195], v[20:23]
	v_mfma_f32_16x16x32_bf16 v[16:19], v[216:219], v[192:195], v[16:19]
	v_mfma_f32_16x16x32_bf16 v[4:7], v[208:211], v[200:203], v[4:7]
	v_mfma_f32_16x16x32_bf16 v[0:3], v[216:219], v[200:203], v[0:3]
	v_mfma_f32_16x16x32_bf16 v[52:55], v[212:215], v[180:183], v[52:55]
	v_mfma_f32_16x16x32_bf16 v[48:51], v[220:223], v[180:183], v[48:51]
	v_mfma_f32_16x16x32_bf16 v[36:39], v[212:215], v[188:191], v[36:39]
	v_mfma_f32_16x16x32_bf16 v[32:35], v[220:223], v[188:191], v[32:35]
	v_mfma_f32_16x16x32_bf16 v[20:23], v[212:215], v[196:199], v[20:23]
	v_mfma_f32_16x16x32_bf16 v[16:19], v[220:223], v[196:199], v[16:19]
	v_mfma_f32_16x16x32_bf16 v[4:7], v[212:215], v[204:207], v[4:7]
	v_mfma_f32_16x16x32_bf16 v[0:3], v[220:223], v[204:207], v[0:3]
	s_add_i32 s68, 0, 0x18000
	v_add_u32_e32 v172, s68, v163
	s_barrier
	ds_read_b128 v[148:151], v172
	ds_read_b128 v[152:155], v172 offset:1024
	ds_read_b128 v[156:159], v172 offset:2048
	ds_read_b128 v[172:175], v172 offset:3072
	ds_read_b128 v[176:179], v167 offset:32768
	ds_read_b128 v[180:183], v167 offset:33792
	ds_read_b128 v[184:187], v167 offset:34816
	ds_read_b128 v[188:191], v167 offset:35840
	ds_read_b128 v[192:195], v167 offset:36864
	ds_read_b128 v[196:199], v167 offset:37888
	ds_read_b128 v[200:203], v167 offset:38912
	ds_read_b128 v[204:207], v167 offset:39936
	v_add_u32_e32 v220, 0x1c000, v163
	ds_read_b128 v[208:211], v220
	ds_read_b128 v[212:215], v220 offset:1024
	ds_read_b128 v[216:219], v220 offset:2048
	ds_read_b128 v[220:223], v220 offset:3072
	s_add_u32 s6, s6, 0x80000
	s_addc_u32 s7, s7, 0
	s_mov_b32 m0, s22
	v_lshl_add_u64 v[230:231], s[6:7], 0, v[128:129]
	global_load_lds_dwordx4 v[230:231], off
	v_lshl_add_u64 v[230:231], s[6:7], 0, v[132:133]
	s_mov_b32 m0, s23
	s_nop 0
	global_load_lds_dwordx4 v[230:231], off
	s_waitcnt lgkmcnt(0)
	s_waitcnt vmcnt(8)
	s_barrier
	v_mfma_f32_16x16x32_bf16 v[124:127], v[148:151], v[176:179], v[124:127]
	v_mfma_f32_16x16x32_bf16 v[120:123], v[156:159], v[176:179], v[120:123]
	v_mfma_f32_16x16x32_bf16 v[108:111], v[148:151], v[184:187], v[108:111]
	v_mfma_f32_16x16x32_bf16 v[104:107], v[156:159], v[184:187], v[104:107]
	v_mfma_f32_16x16x32_bf16 v[92:95], v[148:151], v[192:195], v[92:95]
	v_mfma_f32_16x16x32_bf16 v[88:91], v[156:159], v[192:195], v[88:91]
	v_mfma_f32_16x16x32_bf16 v[76:79], v[148:151], v[200:203], v[76:79]
	v_mfma_f32_16x16x32_bf16 v[72:75], v[156:159], v[200:203], v[72:75]
	v_mfma_f32_16x16x32_bf16 v[124:127], v[152:155], v[180:183], v[124:127]
	v_mfma_f32_16x16x32_bf16 v[120:123], v[172:175], v[180:183], v[120:123]
	v_mfma_f32_16x16x32_bf16 v[108:111], v[152:155], v[188:191], v[108:111]
	v_mfma_f32_16x16x32_bf16 v[104:107], v[172:175], v[188:191], v[104:107]
	v_mfma_f32_16x16x32_bf16 v[92:95], v[152:155], v[196:199], v[92:95]
	v_mfma_f32_16x16x32_bf16 v[88:91], v[172:175], v[196:199], v[88:91]
	v_mfma_f32_16x16x32_bf16 v[76:79], v[152:155], v[204:207], v[76:79]
	v_mfma_f32_16x16x32_bf16 v[72:75], v[172:175], v[204:207], v[72:75]
	v_mfma_f32_16x16x32_bf16 v[116:119], v[208:211], v[176:179], v[116:119]
	v_mfma_f32_16x16x32_bf16 v[112:115], v[216:219], v[176:179], v[112:115]
	v_mfma_f32_16x16x32_bf16 v[100:103], v[208:211], v[184:187], v[100:103]
	v_mfma_f32_16x16x32_bf16 v[96:99], v[216:219], v[184:187], v[96:99]
	v_mfma_f32_16x16x32_bf16 v[84:87], v[208:211], v[192:195], v[84:87]
	v_mfma_f32_16x16x32_bf16 v[80:83], v[216:219], v[192:195], v[80:83]
	v_mfma_f32_16x16x32_bf16 v[68:71], v[208:211], v[200:203], v[68:71]
	v_mfma_f32_16x16x32_bf16 v[64:67], v[216:219], v[200:203], v[64:67]
	v_mfma_f32_16x16x32_bf16 v[116:119], v[212:215], v[180:183], v[116:119]
	v_mfma_f32_16x16x32_bf16 v[112:115], v[220:223], v[180:183], v[112:115]
	v_mfma_f32_16x16x32_bf16 v[100:103], v[212:215], v[188:191], v[100:103]
	v_mfma_f32_16x16x32_bf16 v[96:99], v[220:223], v[188:191], v[96:99]
	v_mfma_f32_16x16x32_bf16 v[84:87], v[212:215], v[196:199], v[84:87]
	v_mfma_f32_16x16x32_bf16 v[80:83], v[220:223], v[196:199], v[80:83]
	v_mfma_f32_16x16x32_bf16 v[68:71], v[212:215], v[204:207], v[68:71]
	v_mfma_f32_16x16x32_bf16 v[64:67], v[220:223], v[204:207], v[64:67]
	s_barrier
; #define PG8_STAGE(bufoff, gbase, voff) do { _Pragma("unroll") for (int _i = 0; _i < 2; ++_i) \
;         __builtin_amdgcn_global_load_lds((const unsigned*)((const char*)(gbase) + (voff)[_i]), (PG8_LAS unsigned*)(lds + (bufoff) + ldsw + _i * 8192), 16, 0, 0); } while (0)
; #define PG8_LDA(dst, b, h) do { _Pragma("unroll") for (int m = 0; m < 4; ++m) _Pragma("unroll") for (int k = 0; k < 2; ++k) dst[m][k] = *(const PG8_LAS bf16x8*)(lds + PG8_SA(b, h) + aoff + m * 2048 + k * 1024); } while (0)
; #define PG8_LDB(dst, b, h) do { _Pragma("unroll") for (int n = 0; n < 2; ++n) _Pragma("unroll") for (int k = 0; k < 2; ++k) dst[n][k] = *(const PG8_LAS bf16x8*)(lds + PG8_SB(b, h) + boff + n * 2048 + k * 1024); } while (0)
; #define PG8_MMA(ai, bj, At, Bt) do { __builtin_amdgcn_s_setprio(1); _Pragma("unroll") for (int m = 0; m < 4; ++m) _Pragma("unroll") for (int n = 0; n < 2; ++n) _Pragma("unroll") for (int k = 0; k < 2; ++k) \
;         acc[ai][bj][m][n] = __builtin_amdgcn_mfma_f32_16x16x32_bf16(Bt[n][k], At[m][k], acc[ai][bj][m][n], 0, 0, 0); __builtin_amdgcn_s_setprio(0); } while (0)
; #define PG8_WAIT_V(n) asm volatile("s_waitcnt vmcnt(" #n ")" ::: "memory")
; #define PG8_WAIT_L(n) asm volatile("s_waitcnt lgkmcnt(" #n ")" ::: "memory")
; template <class Epi>
; __device__ __forceinline__ void gemm_phase(PG8_LAS unsigned char* lds, const Gemm g, const StaticOrder& S, const Epi& E) {
;     ...
;             PG8_LDB(B1, 1, 1); PG8_STAGE(PG8_SB(1, 0), b3, voffB);
;             PG8_BAR; PG8_WAIT_L(0); PG8_MMA(0, 1, At, B1); PG8_BAR;
;             PG8_LDA(At, 1, 1); PG8_STAGE(PG8_SA(1, 0), a3, voffA);
;             PG8_BAR; PG8_WAIT_L(0); PG8_MMA(1, 0, At, B0); PG8_BAR; PG8_SCHED;
;             PG8_STAGE(PG8_SB(1, 1), b3 + hstepB, voffB);
;             PG8_WAIT_V(6); PG8_BAR; PG8_MMA(1, 1, At, B1); PG8_BAR;
;         }
;         E(acc, cur, wr, wc, fr, fq);
;         if (!has_next) break;
;     __device__ __forceinline__ void operator()(const f32x4 (&acc)[2][2][4][2], const pg8::Unit& u, int wr, int wc, int fr, int fq) const {
;     ...
;         bf16_t* base; int ld, cb; const bool paired = (pn >= 11 && pn < 19);
;         if (pn < 11) { base = Z1; ld = LDZ; cb = pn * 256; } else if (pn < 19) { base = XCC; ld = LDX; cb = (pn - 11) * 128; } else if (pn < 23) { base = BB; ld = LDX; cb = (pn - 19) * 256; } else { base = G; ld = LDG; cb = (pn - 23) * 256; }
	ds_read_b128 v[176:179], v167 offset:49152
	ds_read_b128 v[180:183], v167 offset:50176
	ds_read_b128 v[184:187], v167 offset:51200
	ds_read_b128 v[188:191], v167 offset:52224
	ds_read_b128 v[192:195], v167 offset:53248
	ds_read_b128 v[196:199], v167 offset:54272
	ds_read_b128 v[200:203], v167 offset:55296
	ds_read_b128 v[204:207], v167 offset:56320
	s_add_i32 s6, 0, 0x1c000
	s_add_i32 s7, s68, s10
	v_lshl_add_u64 v[160:161], v[160:161], 0, s[14:15]
	s_mov_b32 m0, s7
	s_nop 0
	global_load_lds_dwordx4 v[160:161], off
	v_lshl_add_u64 v[160:161], v[224:225], 0, s[14:15]
	s_add_i32 m0, s7, 0x2000
	s_nop 0
	global_load_lds_dwordx4 v[160:161], off
	s_mov_b32 m0, s35
	v_lshl_add_u64 v[160:161], v[226:227], 0, s[14:15]
	global_load_lds_dwordx4 v[160:161], off
	v_lshl_add_u64 v[160:161], v[228:229], 0, s[14:15]
	s_mov_b32 m0, s36
	s_nop 0
	global_load_lds_dwordx4 v[160:161], off
	s_add_u32 s4, s4, 0x80080
	s_addc_u32 s5, s5, 0
	s_add_i32 s6, s6, s10
	v_lshl_add_u64 v[230:231], s[4:5], 0, v[130:131]
	s_mov_b32 m0, s6
	s_nop 0
	global_load_lds_dwordx4 v[230:231], off
	v_lshl_add_u64 v[230:231], s[4:5], 0, v[134:135]
	s_add_i32 m0, s6, 0x2000
	s_nop 0
	global_load_lds_dwordx4 v[230:231], off
	s_waitcnt lgkmcnt(0)
	s_waitcnt vmcnt(8)
	s_barrier
	v_mfma_f32_16x16x32_bf16 v[60:63], v[148:151], v[176:179], v[60:63]
	v_mfma_f32_16x16x32_bf16 v[56:59], v[156:159], v[176:179], v[56:59]
	v_mfma_f32_16x16x32_bf16 v[44:47], v[148:151], v[184:187], v[44:47]
	v_mfma_f32_16x16x32_bf16 v[40:43], v[156:159], v[184:187], v[40:43]
	v_mfma_f32_16x16x32_bf16 v[28:31], v[148:151], v[192:195], v[28:31]
	v_mfma_f32_16x16x32_bf16 v[24:27], v[156:159], v[192:195], v[24:27]
	v_mfma_f32_16x16x32_bf16 v[12:15], v[148:151], v[200:203], v[12:15]
	v_mfma_f32_16x16x32_bf16 v[8:11], v[156:159], v[200:203], v[8:11]
	v_mfma_f32_16x16x32_bf16 v[60:63], v[152:155], v[180:183], v[60:63]
	v_mfma_f32_16x16x32_bf16 v[56:59], v[172:175], v[180:183], v[56:59]
	v_mfma_f32_16x16x32_bf16 v[44:47], v[152:155], v[188:191], v[44:47]
	v_mfma_f32_16x16x32_bf16 v[40:43], v[172:175], v[188:191], v[40:43]
	v_mfma_f32_16x16x32_bf16 v[28:31], v[152:155], v[196:199], v[28:31]
	v_mfma_f32_16x16x32_bf16 v[24:27], v[172:175], v[196:199], v[24:27]
	v_mfma_f32_16x16x32_bf16 v[12:15], v[152:155], v[204:207], v[12:15]
	v_mfma_f32_16x16x32_bf16 v[8:11], v[172:175], v[204:207], v[8:11]
	v_mfma_f32_16x16x32_bf16 v[52:55], v[208:211], v[176:179], v[52:55]
	v_mfma_f32_16x16x32_bf16 v[48:51], v[216:219], v[176:179], v[48:51]
	v_mfma_f32_16x16x32_bf16 v[36:39], v[208:211], v[184:187], v[36:39]
	v_mfma_f32_16x16x32_bf16 v[32:35], v[216:219], v[184:187], v[32:35]
	v_mfma_f32_16x16x32_bf16 v[20:23], v[208:211], v[192:195], v[20:23]
	v_mfma_f32_16x16x32_bf16 v[16:19], v[216:219], v[192:195], v[16:19]
	v_mfma_f32_16x16x32_bf16 v[4:7], v[208:211], v[200:203], v[4:7]
	v_mfma_f32_16x16x32_bf16 v[0:3], v[216:219], v[200:203], v[0:3]
	v_mfma_f32_16x16x32_bf16 v[52:55], v[212:215], v[180:183], v[52:55]
	v_mfma_f32_16x16x32_bf16 v[48:51], v[220:223], v[180:183], v[48:51]
	v_mfma_f32_16x16x32_bf16 v[36:39], v[212:215], v[188:191], v[36:39]
	v_mfma_f32_16x16x32_bf16 v[32:35], v[220:223], v[188:191], v[32:35]
	v_mfma_f32_16x16x32_bf16 v[20:23], v[212:215], v[196:199], v[20:23]
	v_mfma_f32_16x16x32_bf16 v[16:19], v[220:223], v[196:199], v[16:19]
	v_mfma_f32_16x16x32_bf16 v[4:7], v[212:215], v[204:207], v[4:7]
	v_mfma_f32_16x16x32_bf16 v[0:3], v[220:223], v[204:207], v[0:3]
	s_add_i32 s67, s67, 2
	s_add_u32 s0, s0, 0x100
	s_addc_u32 s1, s1, 0
	s_add_u32 s65, s65, 0x100
	s_addc_u32 s66, s66, 0
	s_cmp_gt_u32 s67, 29
	s_barrier
	s_cbranch_scc0 .LBB0_413
	s_cmp_gt_i32 s62, 10
	s_mov_b64 s[0:1], -1
	s_cbranch_scc0 .LBB0_424
	s_cmp_gt_u32 s62, 18
	s_cbranch_scc0 .LBB0_421
	s_lshl_b32 s4, s62, 8
	s_cmp_gt_u32 s62, 22
	s_cbranch_scc0 .LBB0_418
	s_add_i32 s53, s4, 0xffffe900
	s_mov_b64 s[0:1], 0

; __device__ __forceinline__ unsigned xb_ld(unsigned* p)              { return __hip_atomic_load(p, __ATOMIC_RELAXED, __HIP_MEMORY_SCOPE_AGENT); }
; __device__ __forceinline__ void xcd_barrier_complete(unsigned* bar, unsigned x, unsigned& nloc, unsigned& nx) {
;     const unsigned G = gridDim.x * gridDim.y * gridDim.z;
;     unsigned sum, cnt, mine, sp = 0u;
;     for (;;) {
;         sum = 0u; cnt = 0u; mine = 0u;
; #pragma unroll
;         for (unsigned j = 0; j < 16; ++j) { const unsigned c = xb_ld(&bar[XB_XCNT(j)]); sum += c; cnt += (c > 0u) ? 1u : 0u; mine = (j == x) ? c : mine; }
; __device__ __forceinline__ void xcd_barrier(const XcdBarrier& b) {
;     asm volatile("s_waitcnt vmcnt(0)" ::: "memory");
;     __syncthreads();
;     if (threadIdx.x == 0) {
;         unsigned* bar = b.bar;
;         __builtin_amdgcn_s_waitcnt(0);
;         unsigned nloc = b.st[0], nx = b.st[1];
;         if (nloc == 0u) { xcd_barrier_complete(bar, b.x, nloc, nx); b.st[0] = nloc; b.st[1] = nx; }
.LBB0_471:
	s_setprio 0
	s_cmp_gt_i32 s75, 4
	s_cselect_b64 s[2:3], -1, 0
	s_and_b64 s[0:1], s[12:13], s[2:3]
	v_readlane_b32 s64, v253, 36
	s_andn2_b64 vcc, exec, s[0:1]
	v_readlane_b32 s65, v253, 37
	s_cbranch_vccnz .LBB0_525
	s_waitcnt vmcnt(0)
	s_waitcnt vmcnt(0) lgkmcnt(0)
	s_barrier
	s_mov_b64 s[0:1], exec
	v_readlane_b32 s4, v253, 8
	v_readlane_b32 s5, v253, 9
	s_and_b64 s[4:5], s[0:1], s[4:5]
	s_mov_b64 exec, s[4:5]
	s_cbranch_execz .LBB0_524
	s_add_i32 s4, 0, 0x24000
	v_mov_b32_e32 v0, s4
	s_waitcnt vmcnt(0) expcnt(0) lgkmcnt(0)
	ds_read_b32 v2, v0
	s_add_i32 s4, 0, 0x24004
	v_mov_b32_e32 v0, s4
	ds_read_b32 v0, v0
	s_waitcnt lgkmcnt(1)
	v_cmp_ne_u32_e32 vcc, 0, v2
	s_cbranch_vccnz .LBB0_488
	s_add_u32 s4, s80, 0x1e7fae00
	s_addc_u32 s5, s81, 0
	s_add_u32 s6, s80, 0x1e7fb000
	s_addc_u32 s7, s81, 0
	s_add_u32 s8, s80, 0x1e7fb100
	s_addc_u32 s9, s81, 0
	s_add_u32 s10, s80, 0x1e7fb200
	s_addc_u32 s11, s81, 0
	s_add_u32 s12, s80, 0x1e7fb300
	s_addc_u32 s13, s81, 0
	s_add_u32 s14, s80, 0x1e7fb400
	s_addc_u32 s15, s81, 0
	s_add_u32 s16, s80, 0x1e7fb500
	s_addc_u32 s17, s81, 0
	s_add_u32 s18, s80, 0x1e7fb600
	s_addc_u32 s19, s81, 0
	s_add_u32 s20, s80, 0x1e7fb700
	s_addc_u32 s21, s81, 0
	s_add_u32 s22, s80, 0x1e7fb800
	s_addc_u32 s23, s81, 0
	s_add_u32 s28, s80, 0x1e7fb900
	s_addc_u32 s29, s81, 0
	s_add_u32 s30, s80, 0x1e7fba00
	s_addc_u32 s31, s81, 0
	s_add_u32 s34, s80, 0x1e7fbb00
	s_addc_u32 s35, s81, 0
	s_add_u32 s36, s80, 0x1e7fbc00
	s_addc_u32 s37, s81, 0
	s_add_u32 s38, s80, 0x1e7fbd00
	s_addc_u32 s39, s81, 0
	s_add_u32 s40, s80, 0x1e7fbe00
	s_addc_u32 s41, s81, 0
	s_mul_i32 s56, s27, s33
	s_add_u32 s42, s80, 0x1e7fbf00
	s_mul_i32 s56, s56, s26
	s_addc_u32 s43, s81, 0
	s_mov_b32 s57, 1
	v_mov_b32_e32 v16, 0
	s_branch .LBB0_476

; __device__ __forceinline__ unsigned xb_ld(unsigned* p)              { return __hip_atomic_load(p, __ATOMIC_RELAXED, __HIP_MEMORY_SCOPE_AGENT); }
; __device__ __forceinline__ void xcd_barrier_complete(unsigned* bar, unsigned x, unsigned& nloc, unsigned& nx) {
;     const unsigned G = gridDim.x * gridDim.y * gridDim.z;
;     unsigned sum, cnt, mine, sp = 0u;
;     for (;;) {
;         sum = 0u; cnt = 0u; mine = 0u;
; #pragma unroll
;         for (unsigned j = 0; j < 16; ++j) { const unsigned c = xb_ld(&bar[XB_XCNT(j)]); sum += c; cnt += (c > 0u) ? 1u : 0u; mine = (j == x) ? c : mine; }
; __device__ __forceinline__ void xcd_barrier(const XcdBarrier& b) {
;     asm volatile("s_waitcnt vmcnt(0)" ::: "memory");
;     __syncthreads();
;     if (threadIdx.x == 0) {
;         unsigned* bar = b.bar;
;         __builtin_amdgcn_s_waitcnt(0);
;         unsigned nloc = b.st[0], nx = b.st[1];
;         if (nloc == 0u) { xcd_barrier_complete(bar, b.x, nloc, nx); b.st[0] = nloc; b.st[1] = nx; }
.LBB0_562:
	s_setprio 0
	s_cmp_gt_i32 s75, 5
	s_cselect_b64 s[2:3], -1, 0
	s_and_b64 s[0:1], s[0:1], s[2:3]
	s_andn2_b64 vcc, exec, s[0:1]
	s_cbranch_vccnz .LBB0_616
	s_waitcnt vmcnt(0)
	s_waitcnt vmcnt(0) lgkmcnt(0)
	s_barrier
	s_mov_b64 s[0:1], exec
	v_readlane_b32 s4, v253, 8
	v_readlane_b32 s5, v253, 9
	s_and_b64 s[4:5], s[0:1], s[4:5]
	s_mov_b64 exec, s[4:5]
	s_cbranch_execz .LBB0_615
	s_add_i32 s4, 0, 0x24000
	v_mov_b32_e32 v0, s4
	s_waitcnt vmcnt(0) expcnt(0) lgkmcnt(0)
	ds_read_b32 v2, v0
	s_add_i32 s4, 0, 0x24004
	v_mov_b32_e32 v0, s4
	ds_read_b32 v0, v0
	s_waitcnt lgkmcnt(1)
	v_cmp_ne_u32_e32 vcc, 0, v2
	s_cbranch_vccnz .LBB0_579
	s_add_u32 s4, s80, 0x1e7fae00
	s_addc_u32 s5, s81, 0
	s_add_u32 s6, s80, 0x1e7fb000
	s_addc_u32 s7, s81, 0
	s_add_u32 s8, s80, 0x1e7fb100
	s_addc_u32 s9, s81, 0
	s_add_u32 s10, s80, 0x1e7fb200
	s_addc_u32 s11, s81, 0
	s_add_u32 s12, s80, 0x1e7fb300
	s_addc_u32 s13, s81, 0
	s_add_u32 s14, s80, 0x1e7fb400
	s_addc_u32 s15, s81, 0
	s_add_u32 s16, s80, 0x1e7fb500
	s_addc_u32 s17, s81, 0
	s_add_u32 s18, s80, 0x1e7fb600
	s_addc_u32 s19, s81, 0
	s_add_u32 s20, s80, 0x1e7fb700
	s_addc_u32 s21, s81, 0
	s_add_u32 s22, s80, 0x1e7fb800
	s_addc_u32 s23, s81, 0
	s_add_u32 s28, s80, 0x1e7fb900
	s_addc_u32 s29, s81, 0
	s_add_u32 s30, s80, 0x1e7fba00
	s_addc_u32 s31, s81, 0
	s_add_u32 s34, s80, 0x1e7fbb00
	s_addc_u32 s35, s81, 0
	s_add_u32 s36, s80, 0x1e7fbc00
	s_addc_u32 s37, s81, 0
	s_add_u32 s38, s80, 0x1e7fbd00
	s_addc_u32 s39, s81, 0
	s_add_u32 s40, s80, 0x1e7fbe00
	s_addc_u32 s41, s81, 0
	s_mul_i32 s56, s27, s33
	s_add_u32 s42, s80, 0x1e7fbf00
	s_mul_i32 s56, s56, s26
	s_addc_u32 s43, s81, 0
	s_mov_b32 s57, 1
	v_mov_b32_e32 v16, 0
	s_branch .LBB0_567

; __device__ __forceinline__ unsigned xb_ld(unsigned* p)              { return __hip_atomic_load(p, __ATOMIC_RELAXED, __HIP_MEMORY_SCOPE_AGENT); }
; __device__ __forceinline__ void xcd_barrier_complete(unsigned* bar, unsigned x, unsigned& nloc, unsigned& nx) {
;     const unsigned G = gridDim.x * gridDim.y * gridDim.z;
;     unsigned sum, cnt, mine, sp = 0u;
;     for (;;) {
;         sum = 0u; cnt = 0u; mine = 0u;
; #pragma unroll
;         for (unsigned j = 0; j < 16; ++j) { const unsigned c = xb_ld(&bar[XB_XCNT(j)]); sum += c; cnt += (c > 0u) ? 1u : 0u; mine = (j == x) ? c : mine; }
; __device__ __forceinline__ void xcd_barrier(const XcdBarrier& b) {
;     asm volatile("s_waitcnt vmcnt(0)" ::: "memory");
;     __syncthreads();
;     if (threadIdx.x == 0) {
;         unsigned* bar = b.bar;
;         __builtin_amdgcn_s_waitcnt(0);
;         unsigned nloc = b.st[0], nx = b.st[1];
;         if (nloc == 0u) { xcd_barrier_complete(bar, b.x, nloc, nx); b.st[0] = nloc; b.st[1] = nx; }
.LBB0_834:
	s_setprio 0
	s_cmp_gt_i32 s75, 6
	s_cselect_b64 s[0:1], -1, 0
	s_and_b64 s[2:3], s[28:29], s[0:1]
	s_andn2_b64 vcc, exec, s[2:3]
	s_cbranch_vccnz .LBB0_888
	s_waitcnt vmcnt(0)
	s_waitcnt vmcnt(0) lgkmcnt(0)
	s_barrier
	s_mov_b64 s[2:3], exec
	v_readlane_b32 s4, v253, 8
	v_readlane_b32 s5, v253, 9
	s_and_b64 s[4:5], s[2:3], s[4:5]
	s_mov_b64 exec, s[4:5]
	s_cbranch_execz .LBB0_887
	s_add_i32 s4, 0, 0x24000
	v_mov_b32_e32 v0, s4
	s_waitcnt vmcnt(0) expcnt(0) lgkmcnt(0)
	ds_read_b32 v2, v0
	s_add_i32 s4, 0, 0x24004
	v_mov_b32_e32 v0, s4
	ds_read_b32 v0, v0
	s_waitcnt lgkmcnt(1)
	v_cmp_ne_u32_e32 vcc, 0, v2
	s_cbranch_vccnz .LBB0_851
	s_add_u32 s4, s80, 0x1e7fae00
	s_addc_u32 s5, s81, 0
	s_add_u32 s6, s80, 0x1e7fb000
	s_addc_u32 s7, s81, 0
	s_add_u32 s8, s80, 0x1e7fb100
	s_addc_u32 s9, s81, 0
	s_add_u32 s10, s80, 0x1e7fb200
	s_addc_u32 s11, s81, 0
	s_add_u32 s12, s80, 0x1e7fb300
	s_addc_u32 s13, s81, 0
	s_add_u32 s14, s80, 0x1e7fb400
	s_addc_u32 s15, s81, 0
	s_add_u32 s16, s80, 0x1e7fb500
	s_addc_u32 s17, s81, 0
	s_add_u32 s18, s80, 0x1e7fb600
	s_addc_u32 s19, s81, 0
	s_add_u32 s20, s80, 0x1e7fb700
	s_addc_u32 s21, s81, 0
	s_add_u32 s22, s80, 0x1e7fb800
	s_addc_u32 s23, s81, 0
	s_add_u32 s28, s80, 0x1e7fb900
	s_addc_u32 s29, s81, 0
	s_add_u32 s30, s80, 0x1e7fba00
	s_addc_u32 s31, s81, 0
	s_add_u32 s34, s80, 0x1e7fbb00
	s_addc_u32 s35, s81, 0
	s_add_u32 s36, s80, 0x1e7fbc00
	s_addc_u32 s37, s81, 0
	s_add_u32 s38, s80, 0x1e7fbd00
	s_addc_u32 s39, s81, 0
	s_add_u32 s40, s80, 0x1e7fbe00
	s_addc_u32 s41, s81, 0
	s_mul_i32 s56, s27, s33
	s_add_u32 s42, s80, 0x1e7fbf00
	s_mul_i32 s56, s56, s26
	s_addc_u32 s43, s81, 0
	s_mov_b32 s57, 1
	v_mov_b32_e32 v16, 0
	s_branch .LBB0_839

; #define PG8_STAGE(bufoff, gbase, voff) do { _Pragma("unroll") for (int _i = 0; _i < 2; ++_i) \
;         __builtin_amdgcn_global_load_lds((const unsigned*)((const char*)(gbase) + (voff)[_i]), (PG8_LAS unsigned*)(lds + (bufoff) + ldsw + _i * 8192), 16, 0, 0); } while (0)
; #define PG8_LDA(dst, b, h) do { _Pragma("unroll") for (int m = 0; m < 4; ++m) _Pragma("unroll") for (int k = 0; k < 2; ++k) dst[m][k] = *(const PG8_LAS bf16x8*)(lds + PG8_SA(b, h) + aoff + m * 2048 + k * 1024); } while (0)
; #define PG8_LDB(dst, b, h) do { _Pragma("unroll") for (int n = 0; n < 2; ++n) _Pragma("unroll") for (int k = 0; k < 2; ++k) dst[n][k] = *(const PG8_LAS bf16x8*)(lds + PG8_SB(b, h) + boff + n * 2048 + k * 1024); } while (0)
; #define PG8_MMA(ai, bj, At, Bt) do { __builtin_amdgcn_s_setprio(1); _Pragma("unroll") for (int m = 0; m < 4; ++m) _Pragma("unroll") for (int n = 0; n < 2; ++n) _Pragma("unroll") for (int k = 0; k < 2; ++k) \
;         acc[ai][bj][m][n] = __builtin_amdgcn_mfma_f32_16x16x32_bf16(Bt[n][k], At[m][k], acc[ai][bj][m][n], 0, 0, 0); __builtin_amdgcn_s_setprio(0); } while (0)
; #define PG8_BAR __builtin_amdgcn_s_barrier()
; template <class Epi>
; __device__ __forceinline__ void gemm_phase(PG8_LAS unsigned char* lds, const Gemm g, const StaticOrder& S, const Epi& E) {
;     ...
;             const char* a1 = cA + (size_t)(t + 1) * kstep;
;             const char* a2 = last ? nA : cA + (size_t)(t + 2) * kstep; const char* b2 = last ? nB : cB + (size_t)(t + 2) * kstep;
;             const char* a3 = a2 + kstep; const char* b3 = b2 + kstep;
;             PG8_LDB(B0, 0, 0); PG8_SCHED; PG8_LDA(At, 0, 0); PG8_STAGE(PG8_SA(1, 1), a1 + hstepA, voffA);
;             PG8_WAIT_L(8); PG8_BAR; PG8_WAIT_L(0); PG8_MMA(0, 0, At, B0); PG8_BAR; PG8_SCHED;
;             PG8_LDB(B1, 0, 1); PG8_STAGE(PG8_SB(0, 0), b2, voffB);
;             PG8_BAR; PG8_WAIT_L(0); PG8_MMA(0, 1, At, B1); PG8_BAR;
;             PG8_LDA(At, 0, 1); PG8_STAGE(PG8_SA(0, 0), a2, voffA);
;             PG8_BAR; PG8_WAIT_L(0); PG8_MMA(1, 0, At, B0); PG8_BAR; PG8_SCHED;
;             PG8_STAGE(PG8_SB(0, 1), b2 + hstepB, voffB);
;             PG8_WAIT_V(6); PG8_BAR; PG8_MMA(1, 1, At, B1); PG8_BAR;
;             PG8_LDB(B0, 1, 0); PG8_SCHED; PG8_LDA(At, 1, 0); PG8_STAGE(PG8_SA(0, 1), a2 + hstepA, voffA);
;             PG8_WAIT_L(8); PG8_BAR; PG8_WAIT_L(0); PG8_MMA(0, 0, At, B0); PG8_BAR; PG8_SCHED;
.Lsp_3:
.LBB0_904:
	ds_read_b128 v[128:131], v178
	ds_read_b128 v[132:135], v178 offset:1024
	ds_read_b128 v[136:139], v178 offset:2048
	ds_read_b128 v[140:143], v178 offset:3072
	ds_read_b128 v[144:147], v179
	ds_read_b128 v[164:167], v179 offset:1024
	ds_read_b128 v[170:173], v179 offset:2048
	ds_read_b128 v[182:185], v179 offset:3072
	ds_read_b128 v[186:189], v179 offset:4096
	ds_read_b128 v[190:193], v179 offset:5120
	ds_read_b128 v[194:197], v179 offset:6144
	ds_read_b128 v[198:201], v179 offset:7168
	ds_read_b128 v[202:205], v180
	ds_read_b128 v[206:209], v180 offset:1024
	ds_read_b128 v[210:213], v180 offset:2048
	ds_read_b128 v[214:217], v180 offset:3072
	s_add_u32 s22, s28, 0xfffc0080
	s_addc_u32 s23, s29, -1
	s_cmp_eq_u32 s58, 12
	s_cselect_b32 s31, s15, s23
	s_cselect_b32 s30, s54, s22
	s_cselect_b32 s23, s13, s57
	s_cselect_b32 s22, s55, s56
	v_lshl_add_u64 v[174:175], s[28:29], 0, v[156:157]
	s_add_i32 m0, s21, 0xc000
	s_nop 0
	global_load_lds_dwordx4 v[174:175], off
	v_lshl_add_u64 v[174:175], s[28:29], 0, v[158:159]
	s_add_i32 m0, s21, 0xe000
	s_nop 0
	global_load_lds_dwordx4 v[174:175], off
	s_waitcnt lgkmcnt(0)
	s_waitcnt vmcnt(8)
	s_barrier
	v_mfma_f32_16x16x32_bf16 v[124:127], v[128:131], v[144:147], v[124:127]
	v_mfma_f32_16x16x32_bf16 v[120:123], v[136:139], v[144:147], v[120:123]
	v_mfma_f32_16x16x32_bf16 v[108:111], v[128:131], v[170:173], v[108:111]
	v_mfma_f32_16x16x32_bf16 v[104:107], v[136:139], v[170:173], v[104:107]
	v_mfma_f32_16x16x32_bf16 v[92:95], v[128:131], v[186:189], v[92:95]
	v_mfma_f32_16x16x32_bf16 v[88:91], v[136:139], v[186:189], v[88:91]
	v_mfma_f32_16x16x32_bf16 v[76:79], v[128:131], v[194:197], v[76:79]
	v_mfma_f32_16x16x32_bf16 v[72:75], v[136:139], v[194:197], v[72:75]
	v_mfma_f32_16x16x32_bf16 v[124:127], v[132:135], v[164:167], v[124:127]
	v_mfma_f32_16x16x32_bf16 v[120:123], v[140:143], v[164:167], v[120:123]
	v_mfma_f32_16x16x32_bf16 v[108:111], v[132:135], v[182:185], v[108:111]
	v_mfma_f32_16x16x32_bf16 v[104:107], v[140:143], v[182:185], v[104:107]
	v_mfma_f32_16x16x32_bf16 v[92:95], v[132:135], v[190:193], v[92:95]
	v_mfma_f32_16x16x32_bf16 v[88:91], v[140:143], v[190:193], v[88:91]
	v_mfma_f32_16x16x32_bf16 v[76:79], v[132:135], v[198:201], v[76:79]
	v_mfma_f32_16x16x32_bf16 v[72:75], v[140:143], v[198:201], v[72:75]
	v_mfma_f32_16x16x32_bf16 v[116:119], v[202:205], v[144:147], v[116:119]
	v_mfma_f32_16x16x32_bf16 v[112:115], v[210:213], v[144:147], v[112:115]
	v_mfma_f32_16x16x32_bf16 v[100:103], v[202:205], v[170:173], v[100:103]
	v_mfma_f32_16x16x32_bf16 v[96:99], v[210:213], v[170:173], v[96:99]
	v_mfma_f32_16x16x32_bf16 v[84:87], v[202:205], v[186:189], v[84:87]
	v_mfma_f32_16x16x32_bf16 v[80:83], v[210:213], v[186:189], v[80:83]
	v_mfma_f32_16x16x32_bf16 v[68:71], v[202:205], v[194:197], v[68:71]
	v_mfma_f32_16x16x32_bf16 v[64:67], v[210:213], v[194:197], v[64:67]
	v_mfma_f32_16x16x32_bf16 v[116:119], v[206:209], v[164:167], v[116:119]
	v_mfma_f32_16x16x32_bf16 v[112:115], v[214:217], v[164:167], v[112:115]
	v_mfma_f32_16x16x32_bf16 v[100:103], v[206:209], v[182:185], v[100:103]
	v_mfma_f32_16x16x32_bf16 v[96:99], v[214:217], v[182:185], v[96:99]
	v_mfma_f32_16x16x32_bf16 v[84:87], v[206:209], v[190:193], v[84:87]
	v_mfma_f32_16x16x32_bf16 v[80:83], v[214:217], v[190:193], v[80:83]
	v_mfma_f32_16x16x32_bf16 v[68:71], v[206:209], v[198:201], v[68:71]
	v_mfma_f32_16x16x32_bf16 v[64:67], v[214:217], v[198:201], v[64:67]
	s_barrier
	ds_read_b128 v[144:147], v179 offset:16384
	ds_read_b128 v[164:167], v179 offset:17408
	ds_read_b128 v[170:173], v179 offset:18432
	ds_read_b128 v[182:185], v179 offset:19456
	ds_read_b128 v[186:189], v179 offset:20480
	ds_read_b128 v[190:193], v179 offset:21504
	ds_read_b128 v[194:197], v179 offset:22528
	ds_read_b128 v[198:201], v179 offset:23552
	s_add_i32 s59, s51, s36
	v_lshl_add_u64 v[174:175], s[22:23], 0, v[150:151]
	s_mov_b32 m0, s59
	s_nop 0
	global_load_lds_dwordx4 v[174:175], off
	v_lshl_add_u64 v[218:219], s[22:23], 0, v[154:155]
	s_add_i32 m0, s59, 0x2000
	s_nop 0
	global_load_lds_dwordx4 v[218:219], off
	s_mov_b32 m0, s21
	v_lshl_add_u64 v[220:221], s[30:31], 0, v[148:149]
	global_load_lds_dwordx4 v[220:221], off
	v_lshl_add_u64 v[222:223], s[30:31], 0, v[152:153]
	s_mov_b32 m0, s37
	s_nop 0
	global_load_lds_dwordx4 v[222:223], off
	s_add_u32 s60, s22, 0x40000
	s_addc_u32 s61, s23, 0
	s_add_i32 s59, s52, s36
	v_lshl_add_u64 v[224:225], s[60:61], 0, v[150:151]
	s_mov_b32 m0, s59
	s_nop 0
	global_load_lds_dwordx4 v[224:225], off
	v_lshl_add_u64 v[224:225], s[60:61], 0, v[154:155]
	s_add_i32 m0, s59, 0x2000
	s_nop 0
	global_load_lds_dwordx4 v[224:225], off
	s_waitcnt lgkmcnt(0)
	s_waitcnt vmcnt(8)
	s_barrier
; #define PG8_STAGE(bufoff, gbase, voff) do { _Pragma("unroll") for (int _i = 0; _i < 2; ++_i) \
;         __builtin_amdgcn_global_load_lds((const unsigned*)((const char*)(gbase) + (voff)[_i]), (PG8_LAS unsigned*)(lds + (bufoff) + ldsw + _i * 8192), 16, 0, 0); } while (0)
; #define PG8_LDA(dst, b, h) do { _Pragma("unroll") for (int m = 0; m < 4; ++m) _Pragma("unroll") for (int k = 0; k < 2; ++k) dst[m][k] = *(const PG8_LAS bf16x8*)(lds + PG8_SA(b, h) + aoff + m * 2048 + k * 1024); } while (0)
; #define PG8_LDB(dst, b, h) do { _Pragma("unroll") for (int n = 0; n < 2; ++n) _Pragma("unroll") for (int k = 0; k < 2; ++k) dst[n][k] = *(const PG8_LAS bf16x8*)(lds + PG8_SB(b, h) + boff + n * 2048 + k * 1024); } while (0)
; #define PG8_MMA(ai, bj, At, Bt) do { __builtin_amdgcn_s_setprio(1); _Pragma("unroll") for (int m = 0; m < 4; ++m) _Pragma("unroll") for (int n = 0; n < 2; ++n) _Pragma("unroll") for (int k = 0; k < 2; ++k) \
;         acc[ai][bj][m][n] = __builtin_amdgcn_mfma_f32_16x16x32_bf16(Bt[n][k], At[m][k], acc[ai][bj][m][n], 0, 0, 0); __builtin_amdgcn_s_setprio(0); } while (0)
; #define PG8_WAIT_V(n) asm volatile("s_waitcnt vmcnt(" #n ")" ::: "memory")
; #define PG8_WAIT_L(n) asm volatile("s_waitcnt lgkmcnt(" #n ")" ::: "memory")
; #define PG8_BAR __builtin_amdgcn_s_barrier()
; #define PG8_SCHED __builtin_amdgcn_sched_barrier(0)
; template <class Epi>
; __device__ __forceinline__ void gemm_phase(PG8_LAS unsigned char* lds, const Gemm g, const StaticOrder& S, const Epi& E) {
;     ...
;             PG8_BAR; PG8_WAIT_L(0); PG8_MMA(0, 1, At, B1); PG8_BAR;
;             PG8_LDA(At, 0, 1); PG8_STAGE(PG8_SA(0, 0), a2, voffA);
;             PG8_BAR; PG8_WAIT_L(0); PG8_MMA(1, 0, At, B0); PG8_BAR; PG8_SCHED;
;             PG8_STAGE(PG8_SB(0, 1), b2 + hstepB, voffB);
;             PG8_WAIT_V(6); PG8_BAR; PG8_MMA(1, 1, At, B1); PG8_BAR;
;             PG8_LDB(B0, 1, 0); PG8_SCHED; PG8_LDA(At, 1, 0); PG8_STAGE(PG8_SA(0, 1), a2 + hstepA, voffA);
;             PG8_WAIT_L(8); PG8_BAR; PG8_WAIT_L(0); PG8_MMA(0, 0, At, B0); PG8_BAR; PG8_SCHED;
	v_mfma_f32_16x16x32_bf16 v[60:63], v[128:131], v[144:147], v[60:63]
	v_mfma_f32_16x16x32_bf16 v[56:59], v[136:139], v[144:147], v[56:59]
	v_mfma_f32_16x16x32_bf16 v[44:47], v[128:131], v[170:173], v[44:47]
	v_mfma_f32_16x16x32_bf16 v[40:43], v[136:139], v[170:173], v[40:43]
	v_mfma_f32_16x16x32_bf16 v[28:31], v[128:131], v[186:189], v[28:31]
	v_mfma_f32_16x16x32_bf16 v[24:27], v[136:139], v[186:189], v[24:27]
	v_mfma_f32_16x16x32_bf16 v[12:15], v[128:131], v[194:197], v[12:15]
	v_mfma_f32_16x16x32_bf16 v[8:11], v[136:139], v[194:197], v[8:11]
	v_mfma_f32_16x16x32_bf16 v[60:63], v[132:135], v[164:167], v[60:63]
	v_mfma_f32_16x16x32_bf16 v[56:59], v[140:143], v[164:167], v[56:59]
	v_mfma_f32_16x16x32_bf16 v[44:47], v[132:135], v[182:185], v[44:47]
	v_mfma_f32_16x16x32_bf16 v[40:43], v[140:143], v[182:185], v[40:43]
	v_mfma_f32_16x16x32_bf16 v[28:31], v[132:135], v[190:193], v[28:31]
	v_mfma_f32_16x16x32_bf16 v[24:27], v[140:143], v[190:193], v[24:27]
	v_mfma_f32_16x16x32_bf16 v[12:15], v[132:135], v[198:201], v[12:15]
	v_mfma_f32_16x16x32_bf16 v[8:11], v[140:143], v[198:201], v[8:11]
	v_mfma_f32_16x16x32_bf16 v[52:55], v[202:205], v[144:147], v[52:55]
	v_mfma_f32_16x16x32_bf16 v[48:51], v[210:213], v[144:147], v[48:51]
	v_mfma_f32_16x16x32_bf16 v[36:39], v[202:205], v[170:173], v[36:39]
	v_mfma_f32_16x16x32_bf16 v[32:35], v[210:213], v[170:173], v[32:35]
	v_mfma_f32_16x16x32_bf16 v[20:23], v[202:205], v[186:189], v[20:23]
	v_mfma_f32_16x16x32_bf16 v[16:19], v[210:213], v[186:189], v[16:19]
	v_mfma_f32_16x16x32_bf16 v[4:7], v[202:205], v[194:197], v[4:7]
	v_mfma_f32_16x16x32_bf16 v[0:3], v[210:213], v[194:197], v[0:3]
	v_mfma_f32_16x16x32_bf16 v[52:55], v[206:209], v[164:167], v[52:55]
	v_mfma_f32_16x16x32_bf16 v[48:51], v[214:217], v[164:167], v[48:51]
	v_mfma_f32_16x16x32_bf16 v[36:39], v[206:209], v[182:185], v[36:39]
	v_mfma_f32_16x16x32_bf16 v[32:35], v[214:217], v[182:185], v[32:35]
	v_mfma_f32_16x16x32_bf16 v[20:23], v[206:209], v[190:193], v[20:23]
	v_mfma_f32_16x16x32_bf16 v[16:19], v[214:217], v[190:193], v[16:19]
	v_mfma_f32_16x16x32_bf16 v[4:7], v[206:209], v[198:201], v[4:7]
	v_mfma_f32_16x16x32_bf16 v[0:3], v[214:217], v[198:201], v[0:3]
	s_add_i32 s59, 0, 0x18000
	v_add_u32_e32 v140, s59, v176
	s_barrier
	ds_read_b128 v[128:131], v140
	ds_read_b128 v[132:135], v140 offset:1024
	ds_read_b128 v[136:139], v140 offset:2048
	ds_read_b128 v[140:143], v140 offset:3072
	ds_read_b128 v[144:147], v179 offset:32768
	ds_read_b128 v[164:167], v179 offset:33792
	ds_read_b128 v[170:173], v179 offset:34816
	ds_read_b128 v[182:185], v179 offset:35840
	ds_read_b128 v[186:189], v179 offset:36864
	ds_read_b128 v[190:193], v179 offset:37888
	ds_read_b128 v[194:197], v179 offset:38912
	ds_read_b128 v[198:201], v179 offset:39936
	v_add_u32_e32 v181, 0x1c000, v176
	ds_read_b128 v[202:205], v181
	ds_read_b128 v[206:209], v181 offset:1024
	ds_read_b128 v[210:213], v181 offset:2048
	ds_read_b128 v[214:217], v181 offset:3072
	s_add_u32 s30, s30, 0x40000
	s_addc_u32 s31, s31, 0
	s_mov_b32 m0, s38
	v_lshl_add_u64 v[224:225], s[30:31], 0, v[148:149]
	global_load_lds_dwordx4 v[224:225], off
	v_lshl_add_u64 v[224:225], s[30:31], 0, v[152:153]
	s_mov_b32 m0, s39
	s_nop 0
	global_load_lds_dwordx4 v[224:225], off
	s_waitcnt lgkmcnt(0)
	s_waitcnt vmcnt(8)
	s_barrier
	v_mfma_f32_16x16x32_bf16 v[124:127], v[128:131], v[144:147], v[124:127]
	v_mfma_f32_16x16x32_bf16 v[120:123], v[136:139], v[144:147], v[120:123]
	v_mfma_f32_16x16x32_bf16 v[108:111], v[128:131], v[170:173], v[108:111]
	v_mfma_f32_16x16x32_bf16 v[104:107], v[136:139], v[170:173], v[104:107]
	v_mfma_f32_16x16x32_bf16 v[92:95], v[128:131], v[186:189], v[92:95]
	v_mfma_f32_16x16x32_bf16 v[88:91], v[136:139], v[186:189], v[88:91]
	v_mfma_f32_16x16x32_bf16 v[76:79], v[128:131], v[194:197], v[76:79]
	v_mfma_f32_16x16x32_bf16 v[72:75], v[136:139], v[194:197], v[72:75]
	v_mfma_f32_16x16x32_bf16 v[124:127], v[132:135], v[164:167], v[124:127]
	v_mfma_f32_16x16x32_bf16 v[120:123], v[140:143], v[164:167], v[120:123]
	v_mfma_f32_16x16x32_bf16 v[108:111], v[132:135], v[182:185], v[108:111]
	v_mfma_f32_16x16x32_bf16 v[104:107], v[140:143], v[182:185], v[104:107]
	v_mfma_f32_16x16x32_bf16 v[92:95], v[132:135], v[190:193], v[92:95]
	v_mfma_f32_16x16x32_bf16 v[88:91], v[140:143], v[190:193], v[88:91]
	v_mfma_f32_16x16x32_bf16 v[76:79], v[132:135], v[198:201], v[76:79]
	v_mfma_f32_16x16x32_bf16 v[72:75], v[140:143], v[198:201], v[72:75]
	v_mfma_f32_16x16x32_bf16 v[116:119], v[202:205], v[144:147], v[116:119]
	v_mfma_f32_16x16x32_bf16 v[112:115], v[210:213], v[144:147], v[112:115]
	v_mfma_f32_16x16x32_bf16 v[100:103], v[202:205], v[170:173], v[100:103]
	v_mfma_f32_16x16x32_bf16 v[96:99], v[210:213], v[170:173], v[96:99]
	v_mfma_f32_16x16x32_bf16 v[84:87], v[202:205], v[186:189], v[84:87]
	v_mfma_f32_16x16x32_bf16 v[80:83], v[210:213], v[186:189], v[80:83]
	v_mfma_f32_16x16x32_bf16 v[68:71], v[202:205], v[194:197], v[68:71]
	v_mfma_f32_16x16x32_bf16 v[64:67], v[210:213], v[194:197], v[64:67]
	v_mfma_f32_16x16x32_bf16 v[116:119], v[206:209], v[164:167], v[116:119]
	v_mfma_f32_16x16x32_bf16 v[112:115], v[214:217], v[164:167], v[112:115]
	v_mfma_f32_16x16x32_bf16 v[100:103], v[206:209], v[182:185], v[100:103]
	v_mfma_f32_16x16x32_bf16 v[96:99], v[214:217], v[182:185], v[96:99]
	v_mfma_f32_16x16x32_bf16 v[84:87], v[206:209], v[190:193], v[84:87]
	v_mfma_f32_16x16x32_bf16 v[80:83], v[214:217], v[190:193], v[80:83]
	v_mfma_f32_16x16x32_bf16 v[68:71], v[206:209], v[198:201], v[68:71]
	v_mfma_f32_16x16x32_bf16 v[64:67], v[214:217], v[198:201], v[64:67]
	s_barrier
; #define PG8_STAGE(bufoff, gbase, voff) do { _Pragma("unroll") for (int _i = 0; _i < 2; ++_i) \
;         __builtin_amdgcn_global_load_lds((const unsigned*)((const char*)(gbase) + (voff)[_i]), (PG8_LAS unsigned*)(lds + (bufoff) + ldsw + _i * 8192), 16, 0, 0); } while (0)
; #define PG8_MMA(ai, bj, At, Bt) do { __builtin_amdgcn_s_setprio(1); _Pragma("unroll") for (int m = 0; m < 4; ++m) _Pragma("unroll") for (int n = 0; n < 2; ++n) _Pragma("unroll") for (int k = 0; k < 2; ++k) \
;         acc[ai][bj][m][n] = __builtin_amdgcn_mfma_f32_16x16x32_bf16(Bt[n][k], At[m][k], acc[ai][bj][m][n], 0, 0, 0); __builtin_amdgcn_s_setprio(0); } while (0)
; #define PG8_WAIT_V(n) asm volatile("s_waitcnt vmcnt(" #n ")" ::: "memory")
; #define PG8_WAIT_L(n) asm volatile("s_waitcnt lgkmcnt(" #n ")" ::: "memory")
; #define PG8_BAR __builtin_amdgcn_s_barrier()
; #define PG8_SCHED __builtin_amdgcn_sched_barrier(0)
; template <class Epi>
; __device__ __forceinline__ void gemm_phase(PG8_LAS unsigned char* lds, const Gemm g, const StaticOrder& S, const Epi& E) {
;     ...
;             PG8_BAR; PG8_WAIT_L(0); PG8_MMA(1, 0, At, B0); PG8_BAR; PG8_SCHED;
;             PG8_STAGE(PG8_SB(1, 1), b3 + hstepB, voffB);
;             PG8_WAIT_V(6); PG8_BAR; PG8_MMA(1, 1, At, B1); PG8_BAR;
;         }
;         E(acc, cur, wr, wc, fr, fq);
;         if (!has_next) break;
;     __device__ __forceinline__ void operator()(const f32x4 (&acc)[2][2][4][2], const pg8::Unit& u, int wr, int wc, int fr, int fq) const {
;         const int row0 = u.pm * 256 + wr * 64 + fr, col0 = u.pn * 256 + wc * 32 + 8 * fq;
; #pragma unroll
;         for (int ai = 0; ai < 2; ++ai) {
;             u32x4 la[4][2], lg[4][2];
; #pragma unroll
;             for (int m = 0; m < 4; ++m)
; #pragma unroll
;                 for (int bj = 0; bj < 2; ++bj) { const bf16_t* p = G + (size_t)(row0 + ai * 128 + m * 16) * LDG + col0 + bj * 128;
;                     la[m][bj] = *(const u32x4*)p; if (mode != 0) lg[m][bj] = *(const u32x4*)(p + 2048); else lg[m][bj] = la[m][bj]; }
	ds_read_b128 v[144:147], v179 offset:49152
	ds_read_b128 v[164:167], v179 offset:50176
	ds_read_b128 v[170:173], v179 offset:51200
	ds_read_b128 v[182:185], v179 offset:52224
	ds_read_b128 v[186:189], v179 offset:53248
	ds_read_b128 v[190:193], v179 offset:54272
	ds_read_b128 v[194:197], v179 offset:55296
	ds_read_b128 v[198:201], v179 offset:56320
	s_add_i32 s30, 0, 0x1c000
	s_add_i32 s31, s59, s36
	v_lshl_add_u64 v[174:175], v[174:175], 0, s[0:1]
	s_mov_b32 m0, s31
	s_nop 0
	global_load_lds_dwordx4 v[174:175], off
	v_lshl_add_u64 v[174:175], v[218:219], 0, s[0:1]
	s_add_i32 m0, s31, 0x2000
	s_nop 0
	global_load_lds_dwordx4 v[174:175], off
	s_mov_b32 m0, s41
	v_lshl_add_u64 v[174:175], v[220:221], 0, s[0:1]
	global_load_lds_dwordx4 v[174:175], off
	v_lshl_add_u64 v[174:175], v[222:223], 0, s[0:1]
	s_mov_b32 m0, s42
	s_nop 0
	global_load_lds_dwordx4 v[174:175], off
	s_add_u32 s22, s22, 0x40080
	s_addc_u32 s23, s23, 0
	s_add_i32 s30, s30, s36
	v_lshl_add_u64 v[224:225], s[22:23], 0, v[150:151]
	s_mov_b32 m0, s30
	s_nop 0
	global_load_lds_dwordx4 v[224:225], off
	v_lshl_add_u64 v[224:225], s[22:23], 0, v[154:155]
	s_add_i32 m0, s30, 0x2000
	s_nop 0
	global_load_lds_dwordx4 v[224:225], off
	s_waitcnt lgkmcnt(0)
	s_waitcnt vmcnt(8)
	s_barrier
	v_mfma_f32_16x16x32_bf16 v[60:63], v[128:131], v[144:147], v[60:63]
	v_mfma_f32_16x16x32_bf16 v[56:59], v[136:139], v[144:147], v[56:59]
	v_mfma_f32_16x16x32_bf16 v[44:47], v[128:131], v[170:173], v[44:47]
	v_mfma_f32_16x16x32_bf16 v[40:43], v[136:139], v[170:173], v[40:43]
	v_mfma_f32_16x16x32_bf16 v[28:31], v[128:131], v[186:189], v[28:31]
	v_mfma_f32_16x16x32_bf16 v[24:27], v[136:139], v[186:189], v[24:27]
	v_mfma_f32_16x16x32_bf16 v[12:15], v[128:131], v[194:197], v[12:15]
	v_mfma_f32_16x16x32_bf16 v[8:11], v[136:139], v[194:197], v[8:11]
	v_mfma_f32_16x16x32_bf16 v[60:63], v[132:135], v[164:167], v[60:63]
	v_mfma_f32_16x16x32_bf16 v[56:59], v[140:143], v[164:167], v[56:59]
	v_mfma_f32_16x16x32_bf16 v[44:47], v[132:135], v[182:185], v[44:47]
	v_mfma_f32_16x16x32_bf16 v[40:43], v[140:143], v[182:185], v[40:43]
	v_mfma_f32_16x16x32_bf16 v[28:31], v[132:135], v[190:193], v[28:31]
	v_mfma_f32_16x16x32_bf16 v[24:27], v[140:143], v[190:193], v[24:27]
	v_mfma_f32_16x16x32_bf16 v[12:15], v[132:135], v[198:201], v[12:15]
	v_mfma_f32_16x16x32_bf16 v[8:11], v[140:143], v[198:201], v[8:11]
	v_mfma_f32_16x16x32_bf16 v[52:55], v[202:205], v[144:147], v[52:55]
	v_mfma_f32_16x16x32_bf16 v[48:51], v[210:213], v[144:147], v[48:51]
	v_mfma_f32_16x16x32_bf16 v[36:39], v[202:205], v[170:173], v[36:39]
	v_mfma_f32_16x16x32_bf16 v[32:35], v[210:213], v[170:173], v[32:35]
	v_mfma_f32_16x16x32_bf16 v[20:23], v[202:205], v[186:189], v[20:23]
	v_mfma_f32_16x16x32_bf16 v[16:19], v[210:213], v[186:189], v[16:19]
	v_mfma_f32_16x16x32_bf16 v[4:7], v[202:205], v[194:197], v[4:7]
	v_mfma_f32_16x16x32_bf16 v[0:3], v[210:213], v[194:197], v[0:3]
	v_mfma_f32_16x16x32_bf16 v[52:55], v[206:209], v[164:167], v[52:55]
	v_mfma_f32_16x16x32_bf16 v[48:51], v[214:217], v[164:167], v[48:51]
	v_mfma_f32_16x16x32_bf16 v[36:39], v[206:209], v[182:185], v[36:39]
	v_mfma_f32_16x16x32_bf16 v[32:35], v[214:217], v[182:185], v[32:35]
	v_mfma_f32_16x16x32_bf16 v[20:23], v[206:209], v[190:193], v[20:23]
	v_mfma_f32_16x16x32_bf16 v[16:19], v[214:217], v[190:193], v[16:19]
	v_mfma_f32_16x16x32_bf16 v[4:7], v[206:209], v[198:201], v[4:7]
	v_mfma_f32_16x16x32_bf16 v[0:3], v[214:217], v[198:201], v[0:3]
	s_add_i32 s58, s58, 2
	s_add_u32 s28, s28, 0x100
	s_addc_u32 s29, s29, 0
	s_add_u32 s56, s56, 0x100
	s_addc_u32 s57, s57, 0
	s_cmp_gt_u32 s58, 13
	s_barrier
	s_cbranch_scc0 .LBB0_904
	v_lshl_or_b32 v130, s53, 8, v177
	v_lshl_add_u32 v128, s20, 8, v169
	v_ashrrev_i32_e32 v131, 31, v130
	v_lshlrev_b64 v[164:165], 1, v[130:131]
	v_ashrrev_i32_e32 v129, 31, v128
	v_lshl_add_u64 v[166:167], s[46:47], 0, v[164:165]
	v_lshlrev_b64 v[170:171], 13, v[128:129]
	v_lshl_add_u64 v[130:131], v[166:167], 0, v[170:171]
	global_load_dwordx4 v[182:185], v[130:131], off
	global_load_dwordx4 v[186:189], v[130:131], off offset:256
	v_or_b32_e32 v130, 16, v128
	v_or_b32_e32 v132, 32, v128
	v_or_b32_e32 v128, 48, v128
	v_ashrrev_i32_e32 v131, 31, v130
	v_ashrrev_i32_e32 v133, 31, v132
	v_ashrrev_i32_e32 v129, 31, v128
	v_lshlrev_b64 v[194:195], 13, v[130:131]
	v_lshlrev_b64 v[174:175], 13, v[132:133]
	v_lshlrev_b64 v[172:173], 13, v[128:129]
	v_lshl_add_u64 v[128:129], s[46:47], 0, v[170:171]
	v_lshl_add_u64 v[130:131], v[166:167], 0, v[194:195]
	v_lshl_add_u64 v[132:133], v[166:167], 0, v[174:175]
	v_lshl_add_u64 v[196:197], v[166:167], 0, v[172:173]
	v_lshl_add_u64 v[198:199], v[128:129], 0, v[164:165]
	global_load_dwordx4 v[190:193], v[130:131], off
	global_load_dwordx4 v[144:147], v[130:131], off offset:256
	global_load_dwordx4 v[140:143], v[132:133], off
	global_load_dwordx4 v[136:139], v[132:133], off offset:256
	s_nop 0
	global_load_dwordx4 v[132:135], v[196:197], off
	global_load_dwordx4 v[128:131], v[196:197], off offset:256
	s_and_b64 vcc, exec, s[2:3]
	s_mov_b32 s53, s12
	s_mov_b32 s20, s14
	s_mov_b64 s[22:23], s[18:19]
	s_mov_b64 s[28:29], s[16:17]
	s_waitcnt vmcnt(0)
; __device__ __forceinline__ float sigmoidf_(float x) { return __builtin_amdgcn_rcpf(1.0f + __expf(-x)); }
; __device__ __forceinline__ u32x4 pack8(const float (&f)[8]) { u32x4 w; w.x = cvt_pk_bf16(f[0], f[1]); w.y = cvt_pk_bf16(f[2], f[3]); w.z = cvt_pk_bf16(f[4], f[5]); w.w = cvt_pk_bf16(f[6], f[7]); return w; }
;     __device__ __forceinline__ void operator()(const f32x4 (&acc)[2][2][4][2], const pg8::Unit& u, int wr, int wc, int fr, int fq) const {
;     ...
;                     float a[8], gt[8], o[8];
;                     unpack8(la[m][bj], a);
;                     if (mode == 0) {
; #pragma unroll
;                         for (int n = 0; n < 2; ++n)
; #pragma unroll
;                             for (int i = 0; i < 4; ++i) o[n * 4 + i] = sigmoidf_(a[n * 4 + i]) * acc[ai][bj][m][n][i];
;                     } else {
;                         unpack8(lg[m][bj], gt);
; #pragma unroll
;                         for (int n = 0; n < 2; ++n)
; #pragma unroll
;                             for (int i = 0; i < 4; ++i) o[n * 4 + i] = a[n * 4 + i] + sigmoidf_(gt[n * 4 + i]) * acc[ai][bj][m][n][i];
;                     }
;                     *(u32x4*)p = pack8(o);
	v_lshlrev_b32_e32 v181, 16, v182
	v_and_b32_e32 v182, 0xffff0000, v182
	v_lshlrev_b32_e32 v196, 16, v183
	v_and_b32_e32 v183, 0xffff0000, v183
	v_lshlrev_b32_e32 v197, 16, v184
	v_and_b32_e32 v184, 0xffff0000, v184
	v_lshlrev_b32_e32 v200, 16, v185
	v_and_b32_e32 v185, 0xffff0000, v185
	v_mul_f32_e32 v181, 0xbfb8aa3b, v181
	v_mul_f32_e32 v182, 0xbfb8aa3b, v182
	v_mul_f32_e32 v196, 0xbfb8aa3b, v196
	v_mul_f32_e32 v183, 0xbfb8aa3b, v183
	v_mul_f32_e32 v197, 0xbfb8aa3b, v197
	v_mul_f32_e32 v184, 0xbfb8aa3b, v184
	v_mul_f32_e32 v200, 0xbfb8aa3b, v200
	v_mul_f32_e32 v185, 0xbfb8aa3b, v185
	v_exp_f32_e32 v181, v181
	v_exp_f32_e32 v182, v182
	v_exp_f32_e32 v196, v196
	v_exp_f32_e32 v183, v183
	v_exp_f32_e32 v197, v197
	v_exp_f32_e32 v184, v184
	v_exp_f32_e32 v200, v200
	v_exp_f32_e32 v185, v185
	v_lshlrev_b32_e32 v201, 16, v186
	v_and_b32_e32 v186, 0xffff0000, v186
	v_lshlrev_b32_e32 v202, 16, v187
	v_add_f32_e32 v181, 1.0, v181
	v_add_f32_e32 v182, 1.0, v182
	v_add_f32_e32 v196, 1.0, v196
	v_add_f32_e32 v183, 1.0, v183
	v_add_f32_e32 v197, 1.0, v197
	v_add_f32_e32 v184, 1.0, v184
	v_add_f32_e32 v200, 1.0, v200
	v_add_f32_e32 v185, 1.0, v185
	v_mul_f32_e32 v186, 0xbfb8aa3b, v186
	v_mul_f32_e32 v202, 0xbfb8aa3b, v202
	v_rcp_f32_e32 v181, v181
	v_rcp_f32_e32 v182, v182
	v_rcp_f32_e32 v196, v196
	v_rcp_f32_e32 v183, v183
	v_rcp_f32_e32 v197, v197
	v_rcp_f32_e32 v184, v184
	v_rcp_f32_e32 v200, v200
	v_rcp_f32_e32 v185, v185
	v_exp_f32_e32 v186, v186
	v_exp_f32_e32 v202, v202
	v_and_b32_e32 v187, 0xffff0000, v187
	v_mul_f32_e32 v124, v124, v181
	v_mul_f32_e32 v125, v125, v182
	v_mul_f32_e32 v126, v126, v196
	v_mul_f32_e32 v127, v127, v183
	v_mul_f32_e32 v181, v120, v197
	v_mul_f32_e32 v182, v121, v184
	v_mul_f32_e32 v183, v122, v200
	v_mul_f32_e32 v123, v123, v185
	v_cvt_pk_bf16_f32 v120, v124, v125
	v_cvt_pk_bf16_f32 v121, v126, v127
	v_cvt_pk_bf16_f32 v122, v181, v182
	v_cvt_pk_bf16_f32 v123, v183, v123
	global_store_dwordx4 v[198:199], v[120:123], off
	v_lshlrev_b32_e32 v203, 16, v188
	v_and_b32_e32 v188, 0xffff0000, v188
	v_add_f32_e32 v120, 1.0, v186
	v_add_f32_e32 v121, 1.0, v202
	v_mul_f32_e32 v122, 0xbfb8aa3b, v187
	v_rcp_f32_e32 v120, v120
	v_rcp_f32_e32 v121, v121
	v_exp_f32_e32 v122, v122
	v_lshlrev_b32_e32 v204, 16, v189
	v_mul_f32_e32 v117, v117, v120
	v_mul_f32_e32 v118, v118, v121
	v_add_f32_e32 v120, 1.0, v122
	v_mul_f32_e32 v121, 0xbfb8aa3b, v203
	v_mul_f32_e32 v122, 0xbfb8aa3b, v188
	v_rcp_f32_e32 v120, v120
	v_exp_f32_e32 v121, v121
	v_exp_f32_e32 v122, v122
	v_and_b32_e32 v189, 0xffff0000, v189
	v_mul_f32_e32 v123, 0xbfb8aa3b, v189
	v_mul_f32_e32 v201, 0xbfb8aa3b, v201
	v_mul_f32_e32 v119, v119, v120
	v_add_f32_e32 v120, 1.0, v121
	v_add_f32_e32 v121, 1.0, v122
	v_mul_f32_e32 v122, 0xbfb8aa3b, v204
	v_exp_f32_e32 v123, v123
	v_exp_f32_e32 v201, v201
	v_exp_f32_e32 v122, v122
	v_rcp_f32_e32 v120, v120
	v_add_f32_e32 v123, 1.0, v123
	v_add_f32_e32 v201, 1.0, v201
	v_add_f32_e32 v122, 1.0, v122
	v_rcp_f32_e32 v123, v123
	v_rcp_f32_e32 v201, v201
	v_rcp_f32_e32 v121, v121
	v_rcp_f32_e32 v122, v122
	v_mul_f32_e32 v115, v115, v123
	v_mul_f32_e32 v116, v116, v201
	v_mul_f32_e32 v120, v112, v120
	v_mul_f32_e32 v121, v113, v121
	v_mul_f32_e32 v122, v114, v122
	v_cvt_pk_bf16_f32 v112, v116, v117
	v_cvt_pk_bf16_f32 v113, v118, v119
	v_cvt_pk_bf16_f32 v114, v120, v121
	v_cvt_pk_bf16_f32 v115, v122, v115
	global_store_dwordx4 v[198:199], v[112:115], off offset:256
	v_lshlrev_b32_e32 v116, 16, v191
	v_mul_f32_e32 v116, 0xbfb8aa3b, v116
	v_lshlrev_b32_e32 v114, 16, v190
	v_and_b32_e32 v115, 0xffff0000, v190
	v_mul_f32_e32 v114, 0xbfb8aa3b, v114
	v_mul_f32_e32 v115, 0xbfb8aa3b, v115
	v_exp_f32_e32 v114, v114
	v_exp_f32_e32 v115, v115
	v_exp_f32_e32 v116, v116
	v_and_b32_e32 v117, 0xffff0000, v191
	v_add_f32_e32 v114, 1.0, v114
	v_add_f32_e32 v115, 1.0, v115
	v_add_f32_e32 v116, 1.0, v116
	v_mul_f32_e32 v117, 0xbfb8aa3b, v117
	v_rcp_f32_e32 v114, v114
	v_rcp_f32_e32 v115, v115
	v_rcp_f32_e32 v116, v116
	v_exp_f32_e32 v117, v117
	v_lshlrev_b32_e32 v118, 16, v192
	v_and_b32_e32 v119, 0xffff0000, v192
	v_mul_f32_e32 v108, v108, v114
	v_mul_f32_e32 v109, v109, v115
	v_mul_f32_e32 v110, v110, v116
	v_add_f32_e32 v114, 1.0, v117
	v_mul_f32_e32 v115, 0xbfb8aa3b, v118
	v_mul_f32_e32 v116, 0xbfb8aa3b, v119
	v_rcp_f32_e32 v114, v114
	v_exp_f32_e32 v115, v115
	v_exp_f32_e32 v116, v116
	v_lshlrev_b32_e32 v120, 16, v193
	v_and_b32_e32 v121, 0xffff0000, v193
	v_mul_f32_e32 v111, v111, v114
	v_add_f32_e32 v114, 1.0, v115
	v_add_f32_e32 v115, 1.0, v116
	v_mul_f32_e32 v116, 0xbfb8aa3b, v120
	v_mul_f32_e32 v117, 0xbfb8aa3b, v121
	v_exp_f32_e32 v116, v116
	v_exp_f32_e32 v117, v117
	v_rcp_f32_e32 v114, v114
	v_rcp_f32_e32 v115, v115
	v_add_f32_e32 v116, 1.0, v116
	v_add_f32_e32 v117, 1.0, v117
	v_rcp_f32_e32 v116, v116
	v_rcp_f32_e32 v117, v117
	v_lshl_add_u64 v[112:113], s[46:47], 0, v[194:195]
	v_lshl_add_u64 v[112:113], v[112:113], 0, v[164:165]
	v_mul_f32_e32 v114, v104, v114
	v_mul_f32_e32 v115, v105, v115
	v_mul_f32_e32 v116, v106, v116
	v_mul_f32_e32 v107, v107, v117
	v_cvt_pk_bf16_f32 v104, v108, v109
	v_cvt_pk_bf16_f32 v105, v110, v111
	v_cvt_pk_bf16_f32 v106, v114, v115
	v_cvt_pk_bf16_f32 v107, v116, v107
	global_store_dwordx4 v[112:113], v[104:107], off
	v_lshlrev_b32_e32 v108, 16, v146
	v_and_b32_e32 v109, 0xffff0000, v146
	v_lshlrev_b32_e32 v104, 16, v144
	v_and_b32_e32 v105, 0xffff0000, v144
	v_lshlrev_b32_e32 v106, 16, v145
	v_mul_f32_e32 v104, 0xbfb8aa3b, v104
	v_mul_f32_e32 v105, 0xbfb8aa3b, v105
	v_mul_f32_e32 v106, 0xbfb8aa3b, v106
	v_exp_f32_e32 v104, v104
	v_exp_f32_e32 v105, v105
	v_exp_f32_e32 v106, v106
	v_and_b32_e32 v107, 0xffff0000, v145
; __device__ __forceinline__ float sigmoidf_(float x) { return __builtin_amdgcn_rcpf(1.0f + __expf(-x)); }
; __device__ __forceinline__ u32x4 pack8(const float (&f)[8]) { u32x4 w; w.x = cvt_pk_bf16(f[0], f[1]); w.y = cvt_pk_bf16(f[2], f[3]); w.z = cvt_pk_bf16(f[4], f[5]); w.w = cvt_pk_bf16(f[6], f[7]); return w; }
;     __device__ __forceinline__ void operator()(const f32x4 (&acc)[2][2][4][2], const pg8::Unit& u, int wr, int wc, int fr, int fq) const {
;     ...
;                     float a[8], gt[8], o[8];
;                     unpack8(la[m][bj], a);
;                     if (mode == 0) {
; #pragma unroll
;                         for (int n = 0; n < 2; ++n)
; #pragma unroll
;                             for (int i = 0; i < 4; ++i) o[n * 4 + i] = sigmoidf_(a[n * 4 + i]) * acc[ai][bj][m][n][i];
;                     } else {
;                         unpack8(lg[m][bj], gt);
; #pragma unroll
;                         for (int n = 0; n < 2; ++n)
; #pragma unroll
;                             for (int i = 0; i < 4; ++i) o[n * 4 + i] = a[n * 4 + i] + sigmoidf_(gt[n * 4 + i]) * acc[ai][bj][m][n][i];
;                     }
;                     *(u32x4*)p = pack8(o);
	v_add_f32_e32 v104, 1.0, v104
	v_add_f32_e32 v105, 1.0, v105
	v_add_f32_e32 v106, 1.0, v106
	v_mul_f32_e32 v107, 0xbfb8aa3b, v107
	v_rcp_f32_e32 v104, v104
	v_rcp_f32_e32 v105, v105
	v_rcp_f32_e32 v106, v106
	v_exp_f32_e32 v107, v107
	v_mul_f32_e32 v100, v100, v104
	v_mul_f32_e32 v101, v101, v105
	v_mul_f32_e32 v102, v102, v106
	v_add_f32_e32 v104, 1.0, v107
	v_mul_f32_e32 v105, 0xbfb8aa3b, v108
	v_mul_f32_e32 v106, 0xbfb8aa3b, v109
	v_rcp_f32_e32 v104, v104
	v_exp_f32_e32 v105, v105
	v_exp_f32_e32 v106, v106
	v_and_b32_e32 v111, 0xffff0000, v147
	v_lshlrev_b32_e32 v110, 16, v147
	v_mul_f32_e32 v107, 0xbfb8aa3b, v111
	v_mul_f32_e32 v103, v103, v104
	v_add_f32_e32 v104, 1.0, v105
	v_add_f32_e32 v105, 1.0, v106
	v_mul_f32_e32 v106, 0xbfb8aa3b, v110
	v_exp_f32_e32 v107, v107
	v_exp_f32_e32 v106, v106
	v_rcp_f32_e32 v104, v104
	v_rcp_f32_e32 v105, v105
	v_add_f32_e32 v107, 1.0, v107
	v_add_f32_e32 v106, 1.0, v106
	v_rcp_f32_e32 v107, v107
	v_rcp_f32_e32 v106, v106
	v_mul_f32_e32 v104, v96, v104
	v_mul_f32_e32 v105, v97, v105
	v_mul_f32_e32 v99, v99, v107
	v_mul_f32_e32 v106, v98, v106
	v_cvt_pk_bf16_f32 v96, v100, v101
	v_cvt_pk_bf16_f32 v97, v102, v103
	v_cvt_pk_bf16_f32 v98, v104, v105
	v_cvt_pk_bf16_f32 v99, v106, v99
	global_store_dwordx4 v[112:113], v[96:99], off offset:256
	v_lshlrev_b32_e32 v100, 16, v141
	v_mul_f32_e32 v100, 0xbfb8aa3b, v100
	v_lshlrev_b32_e32 v98, 16, v140
	v_and_b32_e32 v99, 0xffff0000, v140
	v_mul_f32_e32 v98, 0xbfb8aa3b, v98
	v_mul_f32_e32 v99, 0xbfb8aa3b, v99
	v_exp_f32_e32 v98, v98
	v_exp_f32_e32 v99, v99
	v_exp_f32_e32 v100, v100
	v_and_b32_e32 v101, 0xffff0000, v141
	v_add_f32_e32 v98, 1.0, v98
	v_add_f32_e32 v99, 1.0, v99
	v_add_f32_e32 v100, 1.0, v100
	v_mul_f32_e32 v101, 0xbfb8aa3b, v101
	v_rcp_f32_e32 v98, v98
	v_rcp_f32_e32 v99, v99
	v_rcp_f32_e32 v100, v100
	v_exp_f32_e32 v101, v101
	v_lshlrev_b32_e32 v102, 16, v142
	v_and_b32_e32 v103, 0xffff0000, v142
	v_mul_f32_e32 v92, v92, v98
	v_mul_f32_e32 v93, v93, v99
	v_mul_f32_e32 v94, v94, v100
	v_add_f32_e32 v98, 1.0, v101
	v_mul_f32_e32 v99, 0xbfb8aa3b, v102
	v_mul_f32_e32 v100, 0xbfb8aa3b, v103
	v_rcp_f32_e32 v98, v98
	v_exp_f32_e32 v99, v99
	v_exp_f32_e32 v100, v100
	v_lshlrev_b32_e32 v104, 16, v143
	v_and_b32_e32 v105, 0xffff0000, v143
	v_mul_f32_e32 v95, v95, v98
	v_add_f32_e32 v98, 1.0, v99
	v_add_f32_e32 v99, 1.0, v100
	v_mul_f32_e32 v100, 0xbfb8aa3b, v104
	v_mul_f32_e32 v101, 0xbfb8aa3b, v105
	v_exp_f32_e32 v100, v100
	v_exp_f32_e32 v101, v101
	v_rcp_f32_e32 v98, v98
	v_rcp_f32_e32 v99, v99
	v_add_f32_e32 v100, 1.0, v100
	v_add_f32_e32 v101, 1.0, v101
	v_rcp_f32_e32 v100, v100
	v_rcp_f32_e32 v101, v101
	v_lshl_add_u64 v[96:97], s[46:47], 0, v[174:175]
	v_lshl_add_u64 v[96:97], v[96:97], 0, v[164:165]
	v_mul_f32_e32 v98, v88, v98
	v_mul_f32_e32 v99, v89, v99
	v_mul_f32_e32 v100, v90, v100
	v_mul_f32_e32 v91, v91, v101
	v_cvt_pk_bf16_f32 v88, v92, v93
	v_cvt_pk_bf16_f32 v89, v94, v95
	v_cvt_pk_bf16_f32 v90, v98, v99
	v_cvt_pk_bf16_f32 v91, v100, v91
	global_store_dwordx4 v[96:97], v[88:91], off
	v_lshlrev_b32_e32 v92, 16, v138
	v_and_b32_e32 v93, 0xffff0000, v138
	v_lshlrev_b32_e32 v88, 16, v136
	v_and_b32_e32 v89, 0xffff0000, v136
	v_lshlrev_b32_e32 v90, 16, v137
	v_mul_f32_e32 v88, 0xbfb8aa3b, v88
	v_mul_f32_e32 v89, 0xbfb8aa3b, v89
	v_mul_f32_e32 v90, 0xbfb8aa3b, v90
	v_exp_f32_e32 v88, v88
	v_exp_f32_e32 v89, v89
	v_exp_f32_e32 v90, v90
	v_and_b32_e32 v91, 0xffff0000, v137
	v_add_f32_e32 v88, 1.0, v88
	v_add_f32_e32 v89, 1.0, v89
	v_add_f32_e32 v90, 1.0, v90
	v_mul_f32_e32 v91, 0xbfb8aa3b, v91
	v_rcp_f32_e32 v88, v88
	v_rcp_f32_e32 v89, v89
	v_rcp_f32_e32 v90, v90
	v_exp_f32_e32 v91, v91
	v_mul_f32_e32 v84, v84, v88
	v_mul_f32_e32 v85, v85, v89
	v_mul_f32_e32 v86, v86, v90
	v_add_f32_e32 v88, 1.0, v91
	v_mul_f32_e32 v89, 0xbfb8aa3b, v92
	v_mul_f32_e32 v90, 0xbfb8aa3b, v93
	v_rcp_f32_e32 v88, v88
	v_exp_f32_e32 v89, v89
	v_exp_f32_e32 v90, v90
	v_and_b32_e32 v95, 0xffff0000, v139
	v_lshlrev_b32_e32 v94, 16, v139
	v_mul_f32_e32 v91, 0xbfb8aa3b, v95
	v_mul_f32_e32 v87, v87, v88
	v_add_f32_e32 v88, 1.0, v89
	v_add_f32_e32 v89, 1.0, v90
	v_mul_f32_e32 v90, 0xbfb8aa3b, v94
	v_exp_f32_e32 v91, v91
	v_exp_f32_e32 v90, v90
	v_rcp_f32_e32 v88, v88
	v_rcp_f32_e32 v89, v89
	v_add_f32_e32 v91, 1.0, v91
	v_add_f32_e32 v90, 1.0, v90
	v_rcp_f32_e32 v91, v91
	v_rcp_f32_e32 v90, v90
	v_mul_f32_e32 v88, v80, v88
	v_mul_f32_e32 v89, v81, v89
	v_mul_f32_e32 v83, v83, v91
	v_mul_f32_e32 v90, v82, v90
	v_cvt_pk_bf16_f32 v80, v84, v85
	v_cvt_pk_bf16_f32 v81, v86, v87
	v_cvt_pk_bf16_f32 v82, v88, v89
	v_cvt_pk_bf16_f32 v83, v90, v83
	global_store_dwordx4 v[96:97], v[80:83], off offset:256
	v_lshlrev_b32_e32 v84, 16, v133
	v_mul_f32_e32 v84, 0xbfb8aa3b, v84
	v_lshlrev_b32_e32 v82, 16, v132
	v_and_b32_e32 v83, 0xffff0000, v132
	v_mul_f32_e32 v82, 0xbfb8aa3b, v82
	v_mul_f32_e32 v83, 0xbfb8aa3b, v83
	v_exp_f32_e32 v82, v82
	v_exp_f32_e32 v83, v83
	v_exp_f32_e32 v84, v84
	v_and_b32_e32 v85, 0xffff0000, v133
	v_add_f32_e32 v82, 1.0, v82
	v_add_f32_e32 v83, 1.0, v83
	v_add_f32_e32 v84, 1.0, v84
	v_mul_f32_e32 v85, 0xbfb8aa3b, v85
	v_rcp_f32_e32 v82, v82
	v_rcp_f32_e32 v83, v83
	v_rcp_f32_e32 v84, v84
	v_exp_f32_e32 v85, v85
	v_lshlrev_b32_e32 v86, 16, v134
	v_and_b32_e32 v87, 0xffff0000, v134
	v_mul_f32_e32 v76, v76, v82
	v_mul_f32_e32 v77, v77, v83
	v_mul_f32_e32 v78, v78, v84
	v_add_f32_e32 v82, 1.0, v85
	v_mul_f32_e32 v83, 0xbfb8aa3b, v86
	v_mul_f32_e32 v84, 0xbfb8aa3b, v87
	v_rcp_f32_e32 v82, v82
	v_exp_f32_e32 v83, v83
	v_exp_f32_e32 v84, v84
	v_lshlrev_b32_e32 v88, 16, v135
	v_and_b32_e32 v89, 0xffff0000, v135
	v_mul_f32_e32 v79, v79, v82
	v_add_f32_e32 v82, 1.0, v83
; __device__ __forceinline__ float sigmoidf_(float x) { return __builtin_amdgcn_rcpf(1.0f + __expf(-x)); }
; __device__ __forceinline__ u32x4 pack8(const float (&f)[8]) { u32x4 w; w.x = cvt_pk_bf16(f[0], f[1]); w.y = cvt_pk_bf16(f[2], f[3]); w.z = cvt_pk_bf16(f[4], f[5]); w.w = cvt_pk_bf16(f[6], f[7]); return w; }
;     __device__ __forceinline__ void operator()(const f32x4 (&acc)[2][2][4][2], const pg8::Unit& u, int wr, int wc, int fr, int fq) const {
;     ...
;         for (int ai = 0; ai < 2; ++ai) {
;             u32x4 la[4][2], lg[4][2];
; #pragma unroll
;             for (int m = 0; m < 4; ++m)
; #pragma unroll
;                 for (int bj = 0; bj < 2; ++bj) { const bf16_t* p = G + (size_t)(row0 + ai * 128 + m * 16) * LDG + col0 + bj * 128;
;                     la[m][bj] = *(const u32x4*)p; if (mode != 0) lg[m][bj] = *(const u32x4*)(p + 2048); else lg[m][bj] = la[m][bj]; }
; #pragma unroll
;             for (int m = 0; m < 4; ++m)
; #pragma unroll
;                 for (int bj = 0; bj < 2; ++bj) {
;                     bf16_t* p = G + (size_t)(row0 + ai * 128 + m * 16) * LDG + col0 + bj * 128;
;                     float a[8], gt[8], o[8];
;                     unpack8(la[m][bj], a);
;                     if (mode == 0) {
; #pragma unroll
;                         for (int n = 0; n < 2; ++n)
; #pragma unroll
;                             for (int i = 0; i < 4; ++i) o[n * 4 + i] = sigmoidf_(a[n * 4 + i]) * acc[ai][bj][m][n][i];
;                     } else {
;                         unpack8(lg[m][bj], gt);
; #pragma unroll
;                         for (int n = 0; n < 2; ++n)
; #pragma unroll
;                             for (int i = 0; i < 4; ++i) o[n * 4 + i] = a[n * 4 + i] + sigmoidf_(gt[n * 4 + i]) * acc[ai][bj][m][n][i];
;                     }
;                     *(u32x4*)p = pack8(o);
	v_add_f32_e32 v83, 1.0, v84
	v_mul_f32_e32 v84, 0xbfb8aa3b, v88
	v_mul_f32_e32 v85, 0xbfb8aa3b, v89
	v_exp_f32_e32 v84, v84
	v_exp_f32_e32 v85, v85
	v_rcp_f32_e32 v82, v82
	v_rcp_f32_e32 v83, v83
	v_add_f32_e32 v84, 1.0, v84
	v_add_f32_e32 v85, 1.0, v85
	v_rcp_f32_e32 v84, v84
	v_rcp_f32_e32 v85, v85
	v_lshl_add_u64 v[80:81], s[46:47], 0, v[172:173]
	v_lshl_add_u64 v[80:81], v[80:81], 0, v[164:165]
	v_mul_f32_e32 v82, v72, v82
	v_mul_f32_e32 v83, v73, v83
	v_mul_f32_e32 v84, v74, v84
	v_mul_f32_e32 v75, v75, v85
	v_cvt_pk_bf16_f32 v72, v76, v77
	v_cvt_pk_bf16_f32 v73, v78, v79
	v_cvt_pk_bf16_f32 v74, v82, v83
	v_cvt_pk_bf16_f32 v75, v84, v75
	global_store_dwordx4 v[80:81], v[72:75], off
	v_lshlrev_b32_e32 v76, 16, v130
	v_and_b32_e32 v77, 0xffff0000, v130
	v_lshlrev_b32_e32 v72, 16, v128
	v_and_b32_e32 v73, 0xffff0000, v128
	v_lshlrev_b32_e32 v74, 16, v129
	v_mul_f32_e32 v72, 0xbfb8aa3b, v72
	v_mul_f32_e32 v73, 0xbfb8aa3b, v73
	v_mul_f32_e32 v74, 0xbfb8aa3b, v74
	v_exp_f32_e32 v72, v72
	v_exp_f32_e32 v73, v73
	v_exp_f32_e32 v74, v74
	v_and_b32_e32 v75, 0xffff0000, v129
	v_add_f32_e32 v72, 1.0, v72
	v_add_f32_e32 v73, 1.0, v73
	v_add_f32_e32 v74, 1.0, v74
	v_mul_f32_e32 v75, 0xbfb8aa3b, v75
	v_rcp_f32_e32 v72, v72
	v_rcp_f32_e32 v73, v73
	v_rcp_f32_e32 v74, v74
	v_exp_f32_e32 v75, v75
	v_mul_f32_e32 v68, v68, v72
	v_mul_f32_e32 v69, v69, v73
	v_mul_f32_e32 v70, v70, v74
	v_add_f32_e32 v72, 1.0, v75
	v_mul_f32_e32 v73, 0xbfb8aa3b, v76
	v_mul_f32_e32 v74, 0xbfb8aa3b, v77
	v_rcp_f32_e32 v72, v72
	v_exp_f32_e32 v73, v73
	v_exp_f32_e32 v74, v74
	v_and_b32_e32 v79, 0xffff0000, v131
	v_lshlrev_b32_e32 v78, 16, v131
	v_mul_f32_e32 v75, 0xbfb8aa3b, v79
	v_mul_f32_e32 v71, v71, v72
	v_add_f32_e32 v72, 1.0, v73
	v_add_f32_e32 v73, 1.0, v74
	v_mul_f32_e32 v74, 0xbfb8aa3b, v78
	v_exp_f32_e32 v75, v75
	v_exp_f32_e32 v74, v74
	v_rcp_f32_e32 v72, v72
	v_rcp_f32_e32 v73, v73
	v_add_f32_e32 v75, 1.0, v75
	v_add_f32_e32 v74, 1.0, v74
	v_rcp_f32_e32 v75, v75
	v_rcp_f32_e32 v74, v74
	v_lshl_add_u64 v[100:101], v[170:171], 0, s[4:5]
	v_mul_f32_e32 v72, v64, v72
	v_mul_f32_e32 v67, v67, v75
	v_cvt_pk_bf16_f32 v64, v68, v69
	v_lshl_add_u64 v[68:69], v[166:167], 0, v[100:101]
	v_mul_f32_e32 v73, v65, v73
	v_mul_f32_e32 v74, v66, v74
	v_cvt_pk_bf16_f32 v65, v70, v71
	v_cvt_pk_bf16_f32 v66, v72, v73
	v_cvt_pk_bf16_f32 v67, v74, v67
	global_load_dwordx4 v[84:87], v[68:69], off
	global_load_dwordx4 v[88:91], v[68:69], off offset:256
	v_lshl_add_u64 v[102:103], v[170:171], 0, s[6:7]
	global_store_dwordx4 v[80:81], v[64:67], off offset:256
	v_lshl_add_u64 v[82:83], v[170:171], 0, s[8:9]
	v_lshl_add_u64 v[80:81], v[170:171], 0, s[10:11]
	v_lshl_add_u64 v[64:65], v[166:167], 0, v[102:103]
	global_load_dwordx4 v[92:95], v[64:65], off
	global_load_dwordx4 v[96:99], v[64:65], off offset:256
	v_lshl_add_u64 v[64:65], v[166:167], 0, v[82:83]
	global_load_dwordx4 v[76:79], v[64:65], off
	global_load_dwordx4 v[72:75], v[64:65], off offset:256
	v_lshl_add_u64 v[64:65], v[166:167], 0, v[80:81]
	v_lshl_add_u64 v[100:101], s[46:47], 0, v[100:101]
	global_load_dwordx4 v[68:71], v[64:65], off
	s_nop 0
	global_load_dwordx4 v[64:67], v[64:65], off offset:256
	v_lshl_add_u64 v[100:101], v[100:101], 0, v[164:165]
	s_waitcnt vmcnt(0)
	v_lshlrev_b32_e32 v104, 16, v84
	v_and_b32_e32 v84, 0xffff0000, v84
	v_mul_f32_e32 v84, 0xbfb8aa3b, v84
	v_exp_f32_e32 v84, v84
	v_lshlrev_b32_e32 v105, 16, v85
	v_and_b32_e32 v85, 0xffff0000, v85
	v_mul_f32_e32 v85, 0xbfb8aa3b, v85
	v_add_f32_e32 v84, 1.0, v84
	v_rcp_f32_e32 v84, v84
	v_exp_f32_e32 v85, v85
	v_lshlrev_b32_e32 v106, 16, v86
	v_and_b32_e32 v86, 0xffff0000, v86
	v_mul_f32_e32 v61, v61, v84
	v_add_f32_e32 v84, 1.0, v85
	v_mul_f32_e32 v85, 0xbfb8aa3b, v106
	v_mul_f32_e32 v86, 0xbfb8aa3b, v86
	v_rcp_f32_e32 v84, v84
	v_exp_f32_e32 v85, v85
	v_exp_f32_e32 v86, v86
	v_lshlrev_b32_e32 v107, 16, v87
	v_and_b32_e32 v87, 0xffff0000, v87
	v_mul_f32_e32 v104, 0xbfb8aa3b, v104
	v_mul_f32_e32 v105, 0xbfb8aa3b, v105
	v_mul_f32_e32 v63, v63, v84
	v_add_f32_e32 v84, 1.0, v85
	v_add_f32_e32 v85, 1.0, v86
	v_mul_f32_e32 v86, 0xbfb8aa3b, v107
	v_mul_f32_e32 v87, 0xbfb8aa3b, v87
	v_exp_f32_e32 v104, v104
	v_exp_f32_e32 v105, v105
	v_exp_f32_e32 v86, v86
	v_exp_f32_e32 v87, v87
	v_add_f32_e32 v104, 1.0, v104
	v_add_f32_e32 v105, 1.0, v105
	v_add_f32_e32 v86, 1.0, v86
	v_add_f32_e32 v87, 1.0, v87
	v_rcp_f32_e32 v104, v104
	v_rcp_f32_e32 v105, v105
	v_rcp_f32_e32 v84, v84
	v_rcp_f32_e32 v85, v85
	v_rcp_f32_e32 v86, v86
	v_rcp_f32_e32 v87, v87
	v_mul_f32_e32 v60, v60, v104
	v_mul_f32_e32 v62, v62, v105
	v_mul_f32_e32 v84, v56, v84
	v_mul_f32_e32 v85, v57, v85
	v_mul_f32_e32 v86, v58, v86
	v_mul_f32_e32 v59, v59, v87
	v_cvt_pk_bf16_f32 v56, v60, v61
	v_cvt_pk_bf16_f32 v57, v62, v63
	v_cvt_pk_bf16_f32 v58, v84, v85
	v_cvt_pk_bf16_f32 v59, v86, v59
	global_store_dwordx4 v[100:101], v[56:59], off
	v_lshlrev_b32_e32 v60, 16, v90
	v_and_b32_e32 v61, 0xffff0000, v90
	v_lshlrev_b32_e32 v56, 16, v88
	v_and_b32_e32 v57, 0xffff0000, v88
	v_lshlrev_b32_e32 v58, 16, v89
	v_mul_f32_e32 v56, 0xbfb8aa3b, v56
	v_mul_f32_e32 v57, 0xbfb8aa3b, v57
	v_mul_f32_e32 v58, 0xbfb8aa3b, v58
	v_exp_f32_e32 v56, v56
	v_exp_f32_e32 v57, v57
	v_exp_f32_e32 v58, v58
	v_and_b32_e32 v59, 0xffff0000, v89
	v_add_f32_e32 v56, 1.0, v56
	v_add_f32_e32 v57, 1.0, v57
	v_add_f32_e32 v58, 1.0, v58
	v_mul_f32_e32 v59, 0xbfb8aa3b, v59
	v_rcp_f32_e32 v56, v56
	v_rcp_f32_e32 v57, v57
	v_rcp_f32_e32 v58, v58
	v_exp_f32_e32 v59, v59
	v_mul_f32_e32 v52, v52, v56
	v_mul_f32_e32 v53, v53, v57
	v_mul_f32_e32 v54, v54, v58
	v_add_f32_e32 v56, 1.0, v59
	v_mul_f32_e32 v57, 0xbfb8aa3b, v60
	v_mul_f32_e32 v58, 0xbfb8aa3b, v61
; __device__ __forceinline__ float sigmoidf_(float x) { return __builtin_amdgcn_rcpf(1.0f + __expf(-x)); }
; __device__ __forceinline__ u32x4 pack8(const float (&f)[8]) { u32x4 w; w.x = cvt_pk_bf16(f[0], f[1]); w.y = cvt_pk_bf16(f[2], f[3]); w.z = cvt_pk_bf16(f[4], f[5]); w.w = cvt_pk_bf16(f[6], f[7]); return w; }
;     __device__ __forceinline__ void operator()(const f32x4 (&acc)[2][2][4][2], const pg8::Unit& u, int wr, int wc, int fr, int fq) const {
;     ...
;             for (int m = 0; m < 4; ++m)
; #pragma unroll
;                 for (int bj = 0; bj < 2; ++bj) {
;                     bf16_t* p = G + (size_t)(row0 + ai * 128 + m * 16) * LDG + col0 + bj * 128;
;                     float a[8], gt[8], o[8];
;                     unpack8(la[m][bj], a);
;                     if (mode == 0) {
; #pragma unroll
;                         for (int n = 0; n < 2; ++n)
; #pragma unroll
;                             for (int i = 0; i < 4; ++i) o[n * 4 + i] = sigmoidf_(a[n * 4 + i]) * acc[ai][bj][m][n][i];
;                     } else {
;                         unpack8(lg[m][bj], gt);
; #pragma unroll
;                         for (int n = 0; n < 2; ++n)
; #pragma unroll
;                             for (int i = 0; i < 4; ++i) o[n * 4 + i] = a[n * 4 + i] + sigmoidf_(gt[n * 4 + i]) * acc[ai][bj][m][n][i];
;                     }
;                     *(u32x4*)p = pack8(o);
	v_rcp_f32_e32 v56, v56
	v_exp_f32_e32 v57, v57
	v_exp_f32_e32 v58, v58
	v_and_b32_e32 v63, 0xffff0000, v91
	v_lshlrev_b32_e32 v62, 16, v91
	v_mul_f32_e32 v59, 0xbfb8aa3b, v63
	v_mul_f32_e32 v55, v55, v56
	v_add_f32_e32 v56, 1.0, v57
	v_add_f32_e32 v57, 1.0, v58
	v_mul_f32_e32 v58, 0xbfb8aa3b, v62
	v_exp_f32_e32 v59, v59
	v_exp_f32_e32 v58, v58
	v_rcp_f32_e32 v56, v56
	v_rcp_f32_e32 v57, v57
	v_add_f32_e32 v59, 1.0, v59
	v_add_f32_e32 v58, 1.0, v58
	v_rcp_f32_e32 v59, v59
	v_rcp_f32_e32 v58, v58
	v_mul_f32_e32 v56, v48, v56
	v_mul_f32_e32 v57, v49, v57
	v_mul_f32_e32 v51, v51, v59
	v_mul_f32_e32 v58, v50, v58
	v_cvt_pk_bf16_f32 v48, v52, v53
	v_cvt_pk_bf16_f32 v49, v54, v55
	v_cvt_pk_bf16_f32 v50, v56, v57
	v_cvt_pk_bf16_f32 v51, v58, v51
	global_store_dwordx4 v[100:101], v[48:51], off offset:256
	v_lshlrev_b32_e32 v52, 16, v93
	v_mul_f32_e32 v52, 0xbfb8aa3b, v52
	v_lshlrev_b32_e32 v50, 16, v92
	v_and_b32_e32 v51, 0xffff0000, v92
	v_mul_f32_e32 v50, 0xbfb8aa3b, v50
	v_mul_f32_e32 v51, 0xbfb8aa3b, v51
	v_exp_f32_e32 v50, v50
	v_exp_f32_e32 v51, v51
	v_exp_f32_e32 v52, v52
	v_and_b32_e32 v53, 0xffff0000, v93
	v_add_f32_e32 v50, 1.0, v50
	v_add_f32_e32 v51, 1.0, v51
	v_add_f32_e32 v52, 1.0, v52
	v_mul_f32_e32 v53, 0xbfb8aa3b, v53
	v_rcp_f32_e32 v50, v50
	v_rcp_f32_e32 v51, v51
	v_rcp_f32_e32 v52, v52
	v_exp_f32_e32 v53, v53
	v_lshlrev_b32_e32 v54, 16, v94
	v_and_b32_e32 v55, 0xffff0000, v94
	v_mul_f32_e32 v44, v44, v50
	v_mul_f32_e32 v45, v45, v51
	v_mul_f32_e32 v46, v46, v52
	v_add_f32_e32 v50, 1.0, v53
	v_mul_f32_e32 v51, 0xbfb8aa3b, v54
	v_mul_f32_e32 v52, 0xbfb8aa3b, v55
	v_rcp_f32_e32 v50, v50
	v_exp_f32_e32 v51, v51
	v_exp_f32_e32 v52, v52
	v_lshlrev_b32_e32 v56, 16, v95
	v_and_b32_e32 v57, 0xffff0000, v95
	v_mul_f32_e32 v47, v47, v50
	v_add_f32_e32 v50, 1.0, v51
	v_add_f32_e32 v51, 1.0, v52
	v_mul_f32_e32 v52, 0xbfb8aa3b, v56
	v_mul_f32_e32 v53, 0xbfb8aa3b, v57
	v_exp_f32_e32 v52, v52
	v_exp_f32_e32 v53, v53
	v_rcp_f32_e32 v50, v50
	v_rcp_f32_e32 v51, v51
	v_add_f32_e32 v52, 1.0, v52
	v_add_f32_e32 v53, 1.0, v53
	v_rcp_f32_e32 v52, v52
	v_rcp_f32_e32 v53, v53
	v_lshl_add_u64 v[48:49], s[46:47], 0, v[102:103]
	v_lshl_add_u64 v[48:49], v[48:49], 0, v[164:165]
	v_mul_f32_e32 v50, v40, v50
	v_mul_f32_e32 v51, v41, v51
	v_mul_f32_e32 v52, v42, v52
	v_mul_f32_e32 v43, v43, v53
	v_cvt_pk_bf16_f32 v40, v44, v45
	v_cvt_pk_bf16_f32 v41, v46, v47
	v_cvt_pk_bf16_f32 v42, v50, v51
	v_cvt_pk_bf16_f32 v43, v52, v43
	global_store_dwordx4 v[48:49], v[40:43], off
	v_lshlrev_b32_e32 v44, 16, v98
	v_and_b32_e32 v45, 0xffff0000, v98
	v_lshlrev_b32_e32 v40, 16, v96
	v_and_b32_e32 v41, 0xffff0000, v96
	v_lshlrev_b32_e32 v42, 16, v97
	v_mul_f32_e32 v40, 0xbfb8aa3b, v40
	v_mul_f32_e32 v41, 0xbfb8aa3b, v41
	v_mul_f32_e32 v42, 0xbfb8aa3b, v42
	v_exp_f32_e32 v40, v40
	v_exp_f32_e32 v41, v41
	v_exp_f32_e32 v42, v42
	v_and_b32_e32 v43, 0xffff0000, v97
	v_add_f32_e32 v40, 1.0, v40
	v_add_f32_e32 v41, 1.0, v41
	v_add_f32_e32 v42, 1.0, v42
	v_mul_f32_e32 v43, 0xbfb8aa3b, v43
	v_rcp_f32_e32 v40, v40
	v_rcp_f32_e32 v41, v41
	v_rcp_f32_e32 v42, v42
	v_exp_f32_e32 v43, v43
	v_mul_f32_e32 v36, v36, v40
	v_mul_f32_e32 v37, v37, v41
	v_mul_f32_e32 v38, v38, v42
	v_add_f32_e32 v40, 1.0, v43
	v_mul_f32_e32 v41, 0xbfb8aa3b, v44
	v_mul_f32_e32 v42, 0xbfb8aa3b, v45
	v_rcp_f32_e32 v40, v40
	v_exp_f32_e32 v41, v41
	v_exp_f32_e32 v42, v42
	v_and_b32_e32 v47, 0xffff0000, v99
	v_lshlrev_b32_e32 v46, 16, v99
	v_mul_f32_e32 v43, 0xbfb8aa3b, v47
	v_mul_f32_e32 v39, v39, v40
	v_add_f32_e32 v40, 1.0, v41
	v_add_f32_e32 v41, 1.0, v42
	v_mul_f32_e32 v42, 0xbfb8aa3b, v46
	v_exp_f32_e32 v43, v43
	v_exp_f32_e32 v42, v42
	v_rcp_f32_e32 v40, v40
	v_rcp_f32_e32 v41, v41
	v_add_f32_e32 v43, 1.0, v43
	v_add_f32_e32 v42, 1.0, v42
	v_rcp_f32_e32 v43, v43
	v_rcp_f32_e32 v42, v42
	v_mul_f32_e32 v40, v32, v40
	v_mul_f32_e32 v41, v33, v41
	v_mul_f32_e32 v35, v35, v43
	v_mul_f32_e32 v42, v34, v42
	v_cvt_pk_bf16_f32 v32, v36, v37
	v_cvt_pk_bf16_f32 v33, v38, v39
	v_cvt_pk_bf16_f32 v34, v40, v41
	v_cvt_pk_bf16_f32 v35, v42, v35
	global_store_dwordx4 v[48:49], v[32:35], off offset:256
	v_lshlrev_b32_e32 v36, 16, v77
	v_mul_f32_e32 v36, 0xbfb8aa3b, v36
	v_lshlrev_b32_e32 v34, 16, v76
	v_and_b32_e32 v35, 0xffff0000, v76
	v_mul_f32_e32 v34, 0xbfb8aa3b, v34
	v_mul_f32_e32 v35, 0xbfb8aa3b, v35
	v_exp_f32_e32 v34, v34
	v_exp_f32_e32 v35, v35
	v_exp_f32_e32 v36, v36
	v_and_b32_e32 v37, 0xffff0000, v77
	v_add_f32_e32 v34, 1.0, v34
	v_add_f32_e32 v35, 1.0, v35
	v_add_f32_e32 v36, 1.0, v36
	v_mul_f32_e32 v37, 0xbfb8aa3b, v37
	v_rcp_f32_e32 v34, v34
	v_rcp_f32_e32 v35, v35
	v_rcp_f32_e32 v36, v36
	v_exp_f32_e32 v37, v37
	v_lshlrev_b32_e32 v38, 16, v78
	v_and_b32_e32 v39, 0xffff0000, v78
	v_mul_f32_e32 v28, v28, v34
	v_mul_f32_e32 v29, v29, v35
	v_mul_f32_e32 v30, v30, v36
	v_add_f32_e32 v34, 1.0, v37
	v_mul_f32_e32 v35, 0xbfb8aa3b, v38
	v_mul_f32_e32 v36, 0xbfb8aa3b, v39
	v_rcp_f32_e32 v34, v34
	v_exp_f32_e32 v35, v35
	v_exp_f32_e32 v36, v36
	v_lshlrev_b32_e32 v40, 16, v79
	v_and_b32_e32 v41, 0xffff0000, v79
	v_mul_f32_e32 v31, v31, v34
	v_add_f32_e32 v34, 1.0, v35
	v_add_f32_e32 v35, 1.0, v36
	v_mul_f32_e32 v36, 0xbfb8aa3b, v40
	v_mul_f32_e32 v37, 0xbfb8aa3b, v41
	v_exp_f32_e32 v36, v36
	v_exp_f32_e32 v37, v37
	v_rcp_f32_e32 v34, v34
	v_rcp_f32_e32 v35, v35
	v_add_f32_e32 v36, 1.0, v36
	v_add_f32_e32 v37, 1.0, v37
; __device__ __forceinline__ float sigmoidf_(float x) { return __builtin_amdgcn_rcpf(1.0f + __expf(-x)); }
; __device__ __forceinline__ u32x4 pack8(const float (&f)[8]) { u32x4 w; w.x = cvt_pk_bf16(f[0], f[1]); w.y = cvt_pk_bf16(f[2], f[3]); w.z = cvt_pk_bf16(f[4], f[5]); w.w = cvt_pk_bf16(f[6], f[7]); return w; }
; #define PG8_WAIT_V(n) asm volatile("s_waitcnt vmcnt(" #n ")" ::: "memory")
; #define PG8_BAR __builtin_amdgcn_s_barrier()
; template <class Epi>
; __device__ __forceinline__ void gemm_phase(PG8_LAS unsigned char* lds, const Gemm g, const StaticOrder& S, const Epi& E) {
;     ...
;         if (!has_next) break;
; #pragma unroll
;         for (int a = 0; a < 2; ++a)
; #pragma unroll
;             for (int b = 0; b < 2; ++b)
; #pragma unroll
;                 for (int m = 0; m < 4; ++m)
; #pragma unroll
;                     for (int n = 0; n < 2; ++n) acc[a][b][m][n] = (f32x4){0.f, 0.f, 0.f, 0.f};
;         cur = nxt; cA = nA; cB = nB; ++ui;
;     }
;     PG8_WAIT_V(0);
;     if (wr == 0) PG8_BAR;
;     PG8_BAR;
;     __device__ __forceinline__ void operator()(const f32x4 (&acc)[2][2][4][2], const pg8::Unit& u, int wr, int wc, int fr, int fq) const {
;     ...
;             for (int m = 0; m < 4; ++m)
; #pragma unroll
;                 for (int bj = 0; bj < 2; ++bj) {
;                     bf16_t* p = G + (size_t)(row0 + ai * 128 + m * 16) * LDG + col0 + bj * 128;
;                     float a[8], gt[8], o[8];
;                     unpack8(la[m][bj], a);
;                     if (mode == 0) {
; #pragma unroll
;                         for (int n = 0; n < 2; ++n)
; #pragma unroll
;                             for (int i = 0; i < 4; ++i) o[n * 4 + i] = sigmoidf_(a[n * 4 + i]) * acc[ai][bj][m][n][i];
;                     } else {
;                         unpack8(lg[m][bj], gt);
; #pragma unroll
;                         for (int n = 0; n < 2; ++n)
; #pragma unroll
;                             for (int i = 0; i < 4; ++i) o[n * 4 + i] = a[n * 4 + i] + sigmoidf_(gt[n * 4 + i]) * acc[ai][bj][m][n][i];
;                     }
;                     *(u32x4*)p = pack8(o);
	v_rcp_f32_e32 v36, v36
	v_rcp_f32_e32 v37, v37
	v_lshl_add_u64 v[32:33], s[46:47], 0, v[82:83]
	v_lshl_add_u64 v[32:33], v[32:33], 0, v[164:165]
	v_mul_f32_e32 v34, v24, v34
	v_mul_f32_e32 v35, v25, v35
	v_mul_f32_e32 v36, v26, v36
	v_mul_f32_e32 v27, v27, v37
	v_cvt_pk_bf16_f32 v24, v28, v29
	v_cvt_pk_bf16_f32 v25, v30, v31
	v_cvt_pk_bf16_f32 v26, v34, v35
	v_cvt_pk_bf16_f32 v27, v36, v27
	global_store_dwordx4 v[32:33], v[24:27], off
	v_lshlrev_b32_e32 v28, 16, v74
	v_and_b32_e32 v29, 0xffff0000, v74
	v_lshlrev_b32_e32 v24, 16, v72
	v_and_b32_e32 v25, 0xffff0000, v72
	v_lshlrev_b32_e32 v26, 16, v73
	v_mul_f32_e32 v24, 0xbfb8aa3b, v24
	v_mul_f32_e32 v25, 0xbfb8aa3b, v25
	v_mul_f32_e32 v26, 0xbfb8aa3b, v26
	v_exp_f32_e32 v24, v24
	v_exp_f32_e32 v25, v25
	v_exp_f32_e32 v26, v26
	v_and_b32_e32 v27, 0xffff0000, v73
	v_add_f32_e32 v24, 1.0, v24
	v_add_f32_e32 v25, 1.0, v25
	v_add_f32_e32 v26, 1.0, v26
	v_mul_f32_e32 v27, 0xbfb8aa3b, v27
	v_rcp_f32_e32 v24, v24
	v_rcp_f32_e32 v25, v25
	v_rcp_f32_e32 v26, v26
	v_exp_f32_e32 v27, v27
	v_mul_f32_e32 v20, v20, v24
	v_mul_f32_e32 v21, v21, v25
	v_mul_f32_e32 v22, v22, v26
	v_add_f32_e32 v24, 1.0, v27
	v_mul_f32_e32 v25, 0xbfb8aa3b, v28
	v_mul_f32_e32 v26, 0xbfb8aa3b, v29
	v_rcp_f32_e32 v24, v24
	v_exp_f32_e32 v25, v25
	v_exp_f32_e32 v26, v26
	v_and_b32_e32 v31, 0xffff0000, v75
	v_lshlrev_b32_e32 v30, 16, v75
	v_mul_f32_e32 v27, 0xbfb8aa3b, v31
	v_mul_f32_e32 v23, v23, v24
	v_add_f32_e32 v24, 1.0, v25
	v_add_f32_e32 v25, 1.0, v26
	v_mul_f32_e32 v26, 0xbfb8aa3b, v30
	v_exp_f32_e32 v27, v27
	v_exp_f32_e32 v26, v26
	v_rcp_f32_e32 v24, v24
	v_rcp_f32_e32 v25, v25
	v_add_f32_e32 v27, 1.0, v27
	v_add_f32_e32 v26, 1.0, v26
	v_rcp_f32_e32 v27, v27
	v_rcp_f32_e32 v26, v26
	v_mul_f32_e32 v24, v16, v24
	v_mul_f32_e32 v25, v17, v25
	v_mul_f32_e32 v19, v19, v27
	v_mul_f32_e32 v26, v18, v26
	v_cvt_pk_bf16_f32 v16, v20, v21
	v_cvt_pk_bf16_f32 v17, v22, v23
	v_cvt_pk_bf16_f32 v18, v24, v25
	v_cvt_pk_bf16_f32 v19, v26, v19
	global_store_dwordx4 v[32:33], v[16:19], off offset:256
	v_lshlrev_b32_e32 v20, 16, v69
	v_mul_f32_e32 v20, 0xbfb8aa3b, v20
	v_lshlrev_b32_e32 v18, 16, v68
	v_and_b32_e32 v19, 0xffff0000, v68
	v_mul_f32_e32 v18, 0xbfb8aa3b, v18
	v_mul_f32_e32 v19, 0xbfb8aa3b, v19
	v_exp_f32_e32 v18, v18
	v_exp_f32_e32 v19, v19
	v_exp_f32_e32 v20, v20
	v_and_b32_e32 v21, 0xffff0000, v69
	v_add_f32_e32 v18, 1.0, v18
	v_add_f32_e32 v19, 1.0, v19
	v_add_f32_e32 v20, 1.0, v20
	v_mul_f32_e32 v21, 0xbfb8aa3b, v21
	v_rcp_f32_e32 v18, v18
	v_rcp_f32_e32 v19, v19
	v_rcp_f32_e32 v20, v20
	v_exp_f32_e32 v21, v21
	v_lshlrev_b32_e32 v22, 16, v70
	v_and_b32_e32 v23, 0xffff0000, v70
	v_mul_f32_e32 v12, v12, v18
	v_mul_f32_e32 v13, v13, v19
	v_mul_f32_e32 v14, v14, v20
	v_add_f32_e32 v18, 1.0, v21
	v_mul_f32_e32 v19, 0xbfb8aa3b, v22
	v_mul_f32_e32 v20, 0xbfb8aa3b, v23
	v_rcp_f32_e32 v18, v18
	v_exp_f32_e32 v19, v19
	v_exp_f32_e32 v20, v20
	v_lshlrev_b32_e32 v24, 16, v71
	v_and_b32_e32 v25, 0xffff0000, v71
	v_mul_f32_e32 v15, v15, v18
	v_add_f32_e32 v18, 1.0, v19
	v_add_f32_e32 v19, 1.0, v20
	v_mul_f32_e32 v20, 0xbfb8aa3b, v24
	v_mul_f32_e32 v21, 0xbfb8aa3b, v25
	v_exp_f32_e32 v20, v20
	v_exp_f32_e32 v21, v21
	v_rcp_f32_e32 v18, v18
	v_rcp_f32_e32 v19, v19
	v_add_f32_e32 v20, 1.0, v20
	v_add_f32_e32 v21, 1.0, v21
	v_rcp_f32_e32 v20, v20
	v_rcp_f32_e32 v21, v21
	v_lshl_add_u64 v[16:17], s[46:47], 0, v[80:81]
	v_lshl_add_u64 v[16:17], v[16:17], 0, v[164:165]
	v_mul_f32_e32 v18, v8, v18
	v_mul_f32_e32 v19, v9, v19
	v_mul_f32_e32 v20, v10, v20
	v_mul_f32_e32 v11, v11, v21
	v_cvt_pk_bf16_f32 v8, v12, v13
	v_cvt_pk_bf16_f32 v9, v14, v15
	v_cvt_pk_bf16_f32 v10, v18, v19
	v_cvt_pk_bf16_f32 v11, v20, v11
	global_store_dwordx4 v[16:17], v[8:11], off
	v_lshlrev_b32_e32 v12, 16, v66
	v_and_b32_e32 v13, 0xffff0000, v66
	v_lshlrev_b32_e32 v8, 16, v64
	v_and_b32_e32 v9, 0xffff0000, v64
	v_lshlrev_b32_e32 v10, 16, v65
	v_mul_f32_e32 v8, 0xbfb8aa3b, v8
	v_mul_f32_e32 v9, 0xbfb8aa3b, v9
	v_mul_f32_e32 v10, 0xbfb8aa3b, v10
	v_exp_f32_e32 v8, v8
	v_exp_f32_e32 v9, v9
	v_exp_f32_e32 v10, v10
	v_and_b32_e32 v11, 0xffff0000, v65
	v_add_f32_e32 v8, 1.0, v8
	v_add_f32_e32 v9, 1.0, v9
	v_add_f32_e32 v10, 1.0, v10
	v_mul_f32_e32 v11, 0xbfb8aa3b, v11
	v_rcp_f32_e32 v8, v8
	v_rcp_f32_e32 v9, v9
	v_rcp_f32_e32 v10, v10
	v_exp_f32_e32 v11, v11
	v_mul_f32_e32 v4, v4, v8
	v_mul_f32_e32 v5, v5, v9
	v_mul_f32_e32 v6, v6, v10
	v_add_f32_e32 v8, 1.0, v11
	v_mul_f32_e32 v9, 0xbfb8aa3b, v12
	v_mul_f32_e32 v10, 0xbfb8aa3b, v13
	v_rcp_f32_e32 v8, v8
	v_exp_f32_e32 v9, v9
	v_exp_f32_e32 v10, v10
	v_and_b32_e32 v15, 0xffff0000, v67
	v_lshlrev_b32_e32 v14, 16, v67
	v_mul_f32_e32 v11, 0xbfb8aa3b, v15
	v_mul_f32_e32 v7, v7, v8
	v_add_f32_e32 v8, 1.0, v9
	v_add_f32_e32 v9, 1.0, v10
	v_mul_f32_e32 v10, 0xbfb8aa3b, v14
	v_exp_f32_e32 v11, v11
	v_exp_f32_e32 v10, v10
	v_rcp_f32_e32 v8, v8
	v_rcp_f32_e32 v9, v9
	v_add_f32_e32 v11, 1.0, v11
	v_add_f32_e32 v10, 1.0, v10
	v_rcp_f32_e32 v11, v11
	v_rcp_f32_e32 v10, v10
	v_mul_f32_e32 v8, v0, v8
	v_mul_f32_e32 v9, v1, v9
	v_mul_f32_e32 v3, v3, v11
	v_mul_f32_e32 v10, v2, v10
	v_cvt_pk_bf16_f32 v0, v4, v5
	v_cvt_pk_bf16_f32 v1, v6, v7
	v_cvt_pk_bf16_f32 v2, v8, v9
	v_cvt_pk_bf16_f32 v3, v10, v3
	global_store_dwordx4 v[16:17], v[0:3], off offset:256
	s_cbranch_vccz .LBB0_897
	s_waitcnt vmcnt(0)
	s_cmpk_gt_u32 s34, 0xff
	s_cbranch_scc1 .LBB0_908
	s_barrier

; #define PG8_STAGE(bufoff, gbase, voff) do { _Pragma("unroll") for (int _i = 0; _i < 2; ++_i) \
;         __builtin_amdgcn_global_load_lds((const unsigned*)((const char*)(gbase) + (voff)[_i]), (PG8_LAS unsigned*)(lds + (bufoff) + ldsw + _i * 8192), 16, 0, 0); } while (0)
; #define PG8_LDA(dst, b, h) do { _Pragma("unroll") for (int m = 0; m < 4; ++m) _Pragma("unroll") for (int k = 0; k < 2; ++k) dst[m][k] = *(const PG8_LAS bf16x8*)(lds + PG8_SA(b, h) + aoff + m * 2048 + k * 1024); } while (0)
; #define PG8_LDB(dst, b, h) do { _Pragma("unroll") for (int n = 0; n < 2; ++n) _Pragma("unroll") for (int k = 0; k < 2; ++k) dst[n][k] = *(const PG8_LAS bf16x8*)(lds + PG8_SB(b, h) + boff + n * 2048 + k * 1024); } while (0)
; #define PG8_MMA(ai, bj, At, Bt) do { __builtin_amdgcn_s_setprio(1); _Pragma("unroll") for (int m = 0; m < 4; ++m) _Pragma("unroll") for (int n = 0; n < 2; ++n) _Pragma("unroll") for (int k = 0; k < 2; ++k) \
;         acc[ai][bj][m][n] = __builtin_amdgcn_mfma_f32_16x16x32_bf16(Bt[n][k], At[m][k], acc[ai][bj][m][n], 0, 0, 0); __builtin_amdgcn_s_setprio(0); } while (0)
; #define PG8_BAR __builtin_amdgcn_s_barrier()
; template <class Epi>
; __device__ __forceinline__ void gemm_phase(PG8_LAS unsigned char* lds, const Gemm g, const StaticOrder& S, const Epi& E) {
;     ...
;             const char* a1 = cA + (size_t)(t + 1) * kstep;
;             const char* a2 = last ? nA : cA + (size_t)(t + 2) * kstep; const char* b2 = last ? nB : cB + (size_t)(t + 2) * kstep;
;             const char* a3 = a2 + kstep; const char* b3 = b2 + kstep;
;             PG8_LDB(B0, 0, 0); PG8_SCHED; PG8_LDA(At, 0, 0); PG8_STAGE(PG8_SA(1, 1), a1 + hstepA, voffA);
;             PG8_WAIT_L(8); PG8_BAR; PG8_WAIT_L(0); PG8_MMA(0, 0, At, B0); PG8_BAR; PG8_SCHED;
;             PG8_LDB(B1, 0, 1); PG8_STAGE(PG8_SB(0, 0), b2, voffB);
;             PG8_BAR; PG8_WAIT_L(0); PG8_MMA(0, 1, At, B1); PG8_BAR;
;             PG8_LDA(At, 0, 1); PG8_STAGE(PG8_SA(0, 0), a2, voffA);
;             PG8_BAR; PG8_WAIT_L(0); PG8_MMA(1, 0, At, B0); PG8_BAR; PG8_SCHED;
;             PG8_STAGE(PG8_SB(0, 1), b2 + hstepB, voffB);
;             PG8_WAIT_V(6); PG8_BAR; PG8_MMA(1, 1, At, B1); PG8_BAR;
;             PG8_LDB(B0, 1, 0); PG8_SCHED; PG8_LDA(At, 1, 0); PG8_STAGE(PG8_SA(0, 1), a2 + hstepA, voffA);
;             PG8_WAIT_L(8); PG8_BAR; PG8_WAIT_L(0); PG8_MMA(0, 0, At, B0); PG8_BAR; PG8_SCHED;
.Lsp_4:
.LBB0_925:
	ds_read_b128 v[128:131], v198
	ds_read_b128 v[132:135], v198 offset:1024
	ds_read_b128 v[136:139], v198 offset:2048
	ds_read_b128 v[140:143], v198 offset:3072
	ds_read_b128 v[144:147], v199
	ds_read_b128 v[148:151], v199 offset:1024
	ds_read_b128 v[152:155], v199 offset:2048
	ds_read_b128 v[156:159], v199 offset:3072
	ds_read_b128 v[160:163], v199 offset:4096
	ds_read_b128 v[164:167], v199 offset:5120
	ds_read_b128 v[186:189], v199 offset:6144
	ds_read_b128 v[190:193], v199 offset:7168
	ds_read_b128 v[202:205], v200
	ds_read_b128 v[206:209], v200 offset:1024
	ds_read_b128 v[210:213], v200 offset:2048
	ds_read_b128 v[214:217], v200 offset:3072
	s_add_u32 s22, s30, 0xfffc0080
	s_addc_u32 s23, s31, -1
	s_cmp_eq_u32 s61, 12
	s_cselect_b32 s35, s17, s23
	s_cselect_b32 s34, s57, s22
	s_cselect_b32 s23, s15, s60
	s_cselect_b32 s22, s58, s59
	v_lshl_add_u64 v[194:195], s[30:31], 0, v[178:179]
	s_add_i32 m0, s29, 0xc000
	s_nop 0
	global_load_lds_dwordx4 v[194:195], off
	v_lshl_add_u64 v[194:195], s[30:31], 0, v[180:181]
	s_add_i32 m0, s29, 0xe000
	s_nop 0
	global_load_lds_dwordx4 v[194:195], off
	s_waitcnt lgkmcnt(0)
	s_waitcnt vmcnt(8)
	s_barrier
	v_mfma_f32_16x16x32_bf16 v[124:127], v[128:131], v[144:147], v[124:127]
	v_mfma_f32_16x16x32_bf16 v[120:123], v[136:139], v[144:147], v[120:123]
	v_mfma_f32_16x16x32_bf16 v[108:111], v[128:131], v[152:155], v[108:111]
	v_mfma_f32_16x16x32_bf16 v[104:107], v[136:139], v[152:155], v[104:107]
	v_mfma_f32_16x16x32_bf16 v[92:95], v[128:131], v[160:163], v[92:95]
	v_mfma_f32_16x16x32_bf16 v[88:91], v[136:139], v[160:163], v[88:91]
	v_mfma_f32_16x16x32_bf16 v[76:79], v[128:131], v[186:189], v[76:79]
	v_mfma_f32_16x16x32_bf16 v[72:75], v[136:139], v[186:189], v[72:75]
	v_mfma_f32_16x16x32_bf16 v[124:127], v[132:135], v[148:151], v[124:127]
	v_mfma_f32_16x16x32_bf16 v[120:123], v[140:143], v[148:151], v[120:123]
	v_mfma_f32_16x16x32_bf16 v[108:111], v[132:135], v[156:159], v[108:111]
	v_mfma_f32_16x16x32_bf16 v[104:107], v[140:143], v[156:159], v[104:107]
	v_mfma_f32_16x16x32_bf16 v[92:95], v[132:135], v[164:167], v[92:95]
	v_mfma_f32_16x16x32_bf16 v[88:91], v[140:143], v[164:167], v[88:91]
	v_mfma_f32_16x16x32_bf16 v[76:79], v[132:135], v[190:193], v[76:79]
	v_mfma_f32_16x16x32_bf16 v[72:75], v[140:143], v[190:193], v[72:75]
	v_mfma_f32_16x16x32_bf16 v[116:119], v[202:205], v[144:147], v[116:119]
	v_mfma_f32_16x16x32_bf16 v[112:115], v[210:213], v[144:147], v[112:115]
	v_mfma_f32_16x16x32_bf16 v[100:103], v[202:205], v[152:155], v[100:103]
	v_mfma_f32_16x16x32_bf16 v[96:99], v[210:213], v[152:155], v[96:99]
	v_mfma_f32_16x16x32_bf16 v[84:87], v[202:205], v[160:163], v[84:87]
	v_mfma_f32_16x16x32_bf16 v[80:83], v[210:213], v[160:163], v[80:83]
	v_mfma_f32_16x16x32_bf16 v[68:71], v[202:205], v[186:189], v[68:71]
	v_mfma_f32_16x16x32_bf16 v[64:67], v[210:213], v[186:189], v[64:67]
	v_mfma_f32_16x16x32_bf16 v[116:119], v[206:209], v[148:151], v[116:119]
	v_mfma_f32_16x16x32_bf16 v[112:115], v[214:217], v[148:151], v[112:115]
	v_mfma_f32_16x16x32_bf16 v[100:103], v[206:209], v[156:159], v[100:103]
	v_mfma_f32_16x16x32_bf16 v[96:99], v[214:217], v[156:159], v[96:99]
	v_mfma_f32_16x16x32_bf16 v[84:87], v[206:209], v[164:167], v[84:87]
	v_mfma_f32_16x16x32_bf16 v[80:83], v[214:217], v[164:167], v[80:83]
	v_mfma_f32_16x16x32_bf16 v[68:71], v[206:209], v[190:193], v[68:71]
	v_mfma_f32_16x16x32_bf16 v[64:67], v[214:217], v[190:193], v[64:67]
	s_barrier
	ds_read_b128 v[144:147], v199 offset:16384
	ds_read_b128 v[148:151], v199 offset:17408
	ds_read_b128 v[152:155], v199 offset:18432
	ds_read_b128 v[156:159], v199 offset:19456
	ds_read_b128 v[160:163], v199 offset:20480
	ds_read_b128 v[164:167], v199 offset:21504
	ds_read_b128 v[186:189], v199 offset:22528
	ds_read_b128 v[190:193], v199 offset:23552
	s_add_i32 s62, s53, s38
	v_lshl_add_u64 v[194:195], s[22:23], 0, v[172:173]
	s_mov_b32 m0, s62
	s_nop 0
	global_load_lds_dwordx4 v[194:195], off
	v_lshl_add_u64 v[218:219], s[22:23], 0, v[176:177]
	s_add_i32 m0, s62, 0x2000
	s_nop 0
	global_load_lds_dwordx4 v[218:219], off
	s_mov_b32 m0, s29
	v_lshl_add_u64 v[220:221], s[34:35], 0, v[170:171]
	global_load_lds_dwordx4 v[220:221], off
	v_lshl_add_u64 v[222:223], s[34:35], 0, v[174:175]
	s_mov_b32 m0, s39
	s_nop 0
	global_load_lds_dwordx4 v[222:223], off
	s_add_u32 s62, s22, 0x40000
	s_addc_u32 s63, s23, 0
	s_add_i32 s64, s54, s38
	v_lshl_add_u64 v[224:225], s[62:63], 0, v[172:173]
	s_mov_b32 m0, s64
	s_nop 0
	global_load_lds_dwordx4 v[224:225], off
	v_lshl_add_u64 v[224:225], s[62:63], 0, v[176:177]
	s_add_i32 m0, s64, 0x2000
	s_nop 0
	global_load_lds_dwordx4 v[224:225], off
	s_waitcnt lgkmcnt(0)
	s_waitcnt vmcnt(8)
	s_barrier
; #define PG8_STAGE(bufoff, gbase, voff) do { _Pragma("unroll") for (int _i = 0; _i < 2; ++_i) \
;         __builtin_amdgcn_global_load_lds((const unsigned*)((const char*)(gbase) + (voff)[_i]), (PG8_LAS unsigned*)(lds + (bufoff) + ldsw + _i * 8192), 16, 0, 0); } while (0)
; #define PG8_LDA(dst, b, h) do { _Pragma("unroll") for (int m = 0; m < 4; ++m) _Pragma("unroll") for (int k = 0; k < 2; ++k) dst[m][k] = *(const PG8_LAS bf16x8*)(lds + PG8_SA(b, h) + aoff + m * 2048 + k * 1024); } while (0)
; #define PG8_LDB(dst, b, h) do { _Pragma("unroll") for (int n = 0; n < 2; ++n) _Pragma("unroll") for (int k = 0; k < 2; ++k) dst[n][k] = *(const PG8_LAS bf16x8*)(lds + PG8_SB(b, h) + boff + n * 2048 + k * 1024); } while (0)
; #define PG8_MMA(ai, bj, At, Bt) do { __builtin_amdgcn_s_setprio(1); _Pragma("unroll") for (int m = 0; m < 4; ++m) _Pragma("unroll") for (int n = 0; n < 2; ++n) _Pragma("unroll") for (int k = 0; k < 2; ++k) \
;         acc[ai][bj][m][n] = __builtin_amdgcn_mfma_f32_16x16x32_bf16(Bt[n][k], At[m][k], acc[ai][bj][m][n], 0, 0, 0); __builtin_amdgcn_s_setprio(0); } while (0)
; #define PG8_WAIT_V(n) asm volatile("s_waitcnt vmcnt(" #n ")" ::: "memory")
; #define PG8_WAIT_L(n) asm volatile("s_waitcnt lgkmcnt(" #n ")" ::: "memory")
; #define PG8_BAR __builtin_amdgcn_s_barrier()
; #define PG8_SCHED __builtin_amdgcn_sched_barrier(0)
; template <class Epi>
; __device__ __forceinline__ void gemm_phase(PG8_LAS unsigned char* lds, const Gemm g, const StaticOrder& S, const Epi& E) {
;     ...
;             PG8_BAR; PG8_WAIT_L(0); PG8_MMA(0, 1, At, B1); PG8_BAR;
;             PG8_LDA(At, 0, 1); PG8_STAGE(PG8_SA(0, 0), a2, voffA);
;             PG8_BAR; PG8_WAIT_L(0); PG8_MMA(1, 0, At, B0); PG8_BAR; PG8_SCHED;
;             PG8_STAGE(PG8_SB(0, 1), b2 + hstepB, voffB);
;             PG8_WAIT_V(6); PG8_BAR; PG8_MMA(1, 1, At, B1); PG8_BAR;
;             PG8_LDB(B0, 1, 0); PG8_SCHED; PG8_LDA(At, 1, 0); PG8_STAGE(PG8_SA(0, 1), a2 + hstepA, voffA);
;             PG8_WAIT_L(8); PG8_BAR; PG8_WAIT_L(0); PG8_MMA(0, 0, At, B0); PG8_BAR; PG8_SCHED;
	v_mfma_f32_16x16x32_bf16 v[60:63], v[128:131], v[144:147], v[60:63]
	v_mfma_f32_16x16x32_bf16 v[56:59], v[136:139], v[144:147], v[56:59]
	v_mfma_f32_16x16x32_bf16 v[44:47], v[128:131], v[152:155], v[44:47]
	v_mfma_f32_16x16x32_bf16 v[40:43], v[136:139], v[152:155], v[40:43]
	v_mfma_f32_16x16x32_bf16 v[28:31], v[128:131], v[160:163], v[28:31]
	v_mfma_f32_16x16x32_bf16 v[24:27], v[136:139], v[160:163], v[24:27]
	v_mfma_f32_16x16x32_bf16 v[12:15], v[128:131], v[186:189], v[12:15]
	v_mfma_f32_16x16x32_bf16 v[8:11], v[136:139], v[186:189], v[8:11]
	v_mfma_f32_16x16x32_bf16 v[60:63], v[132:135], v[148:151], v[60:63]
	v_mfma_f32_16x16x32_bf16 v[56:59], v[140:143], v[148:151], v[56:59]
	v_mfma_f32_16x16x32_bf16 v[44:47], v[132:135], v[156:159], v[44:47]
	v_mfma_f32_16x16x32_bf16 v[40:43], v[140:143], v[156:159], v[40:43]
	v_mfma_f32_16x16x32_bf16 v[28:31], v[132:135], v[164:167], v[28:31]
	v_mfma_f32_16x16x32_bf16 v[24:27], v[140:143], v[164:167], v[24:27]
	v_mfma_f32_16x16x32_bf16 v[12:15], v[132:135], v[190:193], v[12:15]
	v_mfma_f32_16x16x32_bf16 v[8:11], v[140:143], v[190:193], v[8:11]
	v_mfma_f32_16x16x32_bf16 v[52:55], v[202:205], v[144:147], v[52:55]
	v_mfma_f32_16x16x32_bf16 v[48:51], v[210:213], v[144:147], v[48:51]
	v_mfma_f32_16x16x32_bf16 v[36:39], v[202:205], v[152:155], v[36:39]
	v_mfma_f32_16x16x32_bf16 v[32:35], v[210:213], v[152:155], v[32:35]
	v_mfma_f32_16x16x32_bf16 v[20:23], v[202:205], v[160:163], v[20:23]
	v_mfma_f32_16x16x32_bf16 v[16:19], v[210:213], v[160:163], v[16:19]
	v_mfma_f32_16x16x32_bf16 v[4:7], v[202:205], v[186:189], v[4:7]
	v_mfma_f32_16x16x32_bf16 v[0:3], v[210:213], v[186:189], v[0:3]
	v_mfma_f32_16x16x32_bf16 v[52:55], v[206:209], v[148:151], v[52:55]
	v_mfma_f32_16x16x32_bf16 v[48:51], v[214:217], v[148:151], v[48:51]
	v_mfma_f32_16x16x32_bf16 v[36:39], v[206:209], v[156:159], v[36:39]
	v_mfma_f32_16x16x32_bf16 v[32:35], v[214:217], v[156:159], v[32:35]
	v_mfma_f32_16x16x32_bf16 v[20:23], v[206:209], v[164:167], v[20:23]
	v_mfma_f32_16x16x32_bf16 v[16:19], v[214:217], v[164:167], v[16:19]
	v_mfma_f32_16x16x32_bf16 v[4:7], v[206:209], v[190:193], v[4:7]
	v_mfma_f32_16x16x32_bf16 v[0:3], v[214:217], v[190:193], v[0:3]
	s_add_i32 s62, 0, 0x18000
	v_add_u32_e32 v140, s62, v196
	s_barrier
	ds_read_b128 v[128:131], v140
	ds_read_b128 v[132:135], v140 offset:1024
	ds_read_b128 v[136:139], v140 offset:2048
	ds_read_b128 v[140:143], v140 offset:3072
	ds_read_b128 v[144:147], v199 offset:32768
	ds_read_b128 v[148:151], v199 offset:33792
	ds_read_b128 v[152:155], v199 offset:34816
	ds_read_b128 v[156:159], v199 offset:35840
	ds_read_b128 v[160:163], v199 offset:36864
	ds_read_b128 v[164:167], v199 offset:37888
	ds_read_b128 v[186:189], v199 offset:38912
	ds_read_b128 v[190:193], v199 offset:39936
	v_add_u32_e32 v201, 0x1c000, v196
	ds_read_b128 v[202:205], v201
	ds_read_b128 v[206:209], v201 offset:1024
	ds_read_b128 v[210:213], v201 offset:2048
	ds_read_b128 v[214:217], v201 offset:3072
	s_add_u32 s34, s34, 0x40000
	s_addc_u32 s35, s35, 0
	s_mov_b32 m0, s40
	v_lshl_add_u64 v[224:225], s[34:35], 0, v[170:171]
	global_load_lds_dwordx4 v[224:225], off
	v_lshl_add_u64 v[224:225], s[34:35], 0, v[174:175]
	s_mov_b32 m0, s41
	s_nop 0
	global_load_lds_dwordx4 v[224:225], off
	s_waitcnt lgkmcnt(0)
	s_waitcnt vmcnt(8)
	s_barrier
	v_mfma_f32_16x16x32_bf16 v[124:127], v[128:131], v[144:147], v[124:127]
	v_mfma_f32_16x16x32_bf16 v[120:123], v[136:139], v[144:147], v[120:123]
	v_mfma_f32_16x16x32_bf16 v[108:111], v[128:131], v[152:155], v[108:111]
	v_mfma_f32_16x16x32_bf16 v[104:107], v[136:139], v[152:155], v[104:107]
	v_mfma_f32_16x16x32_bf16 v[92:95], v[128:131], v[160:163], v[92:95]
	v_mfma_f32_16x16x32_bf16 v[88:91], v[136:139], v[160:163], v[88:91]
	v_mfma_f32_16x16x32_bf16 v[76:79], v[128:131], v[186:189], v[76:79]
	v_mfma_f32_16x16x32_bf16 v[72:75], v[136:139], v[186:189], v[72:75]
	v_mfma_f32_16x16x32_bf16 v[124:127], v[132:135], v[148:151], v[124:127]
	v_mfma_f32_16x16x32_bf16 v[120:123], v[140:143], v[148:151], v[120:123]
	v_mfma_f32_16x16x32_bf16 v[108:111], v[132:135], v[156:159], v[108:111]
	v_mfma_f32_16x16x32_bf16 v[104:107], v[140:143], v[156:159], v[104:107]
	v_mfma_f32_16x16x32_bf16 v[92:95], v[132:135], v[164:167], v[92:95]
	v_mfma_f32_16x16x32_bf16 v[88:91], v[140:143], v[164:167], v[88:91]
	v_mfma_f32_16x16x32_bf16 v[76:79], v[132:135], v[190:193], v[76:79]
	v_mfma_f32_16x16x32_bf16 v[72:75], v[140:143], v[190:193], v[72:75]
	v_mfma_f32_16x16x32_bf16 v[116:119], v[202:205], v[144:147], v[116:119]
	v_mfma_f32_16x16x32_bf16 v[112:115], v[210:213], v[144:147], v[112:115]
	v_mfma_f32_16x16x32_bf16 v[100:103], v[202:205], v[152:155], v[100:103]
	v_mfma_f32_16x16x32_bf16 v[96:99], v[210:213], v[152:155], v[96:99]
	v_mfma_f32_16x16x32_bf16 v[84:87], v[202:205], v[160:163], v[84:87]
	v_mfma_f32_16x16x32_bf16 v[80:83], v[210:213], v[160:163], v[80:83]
	v_mfma_f32_16x16x32_bf16 v[68:71], v[202:205], v[186:189], v[68:71]
	v_mfma_f32_16x16x32_bf16 v[64:67], v[210:213], v[186:189], v[64:67]
	v_mfma_f32_16x16x32_bf16 v[116:119], v[206:209], v[148:151], v[116:119]
	v_mfma_f32_16x16x32_bf16 v[112:115], v[214:217], v[148:151], v[112:115]
	v_mfma_f32_16x16x32_bf16 v[100:103], v[206:209], v[156:159], v[100:103]
	v_mfma_f32_16x16x32_bf16 v[96:99], v[214:217], v[156:159], v[96:99]
	v_mfma_f32_16x16x32_bf16 v[84:87], v[206:209], v[164:167], v[84:87]
	v_mfma_f32_16x16x32_bf16 v[80:83], v[214:217], v[164:167], v[80:83]
	v_mfma_f32_16x16x32_bf16 v[68:71], v[206:209], v[190:193], v[68:71]
	v_mfma_f32_16x16x32_bf16 v[64:67], v[214:217], v[190:193], v[64:67]
	s_barrier
; #define PG8_STAGE(bufoff, gbase, voff) do { _Pragma("unroll") for (int _i = 0; _i < 2; ++_i) \
;         __builtin_amdgcn_global_load_lds((const unsigned*)((const char*)(gbase) + (voff)[_i]), (PG8_LAS unsigned*)(lds + (bufoff) + ldsw + _i * 8192), 16, 0, 0); } while (0)
; #define PG8_MMA(ai, bj, At, Bt) do { __builtin_amdgcn_s_setprio(1); _Pragma("unroll") for (int m = 0; m < 4; ++m) _Pragma("unroll") for (int n = 0; n < 2; ++n) _Pragma("unroll") for (int k = 0; k < 2; ++k) \
;         acc[ai][bj][m][n] = __builtin_amdgcn_mfma_f32_16x16x32_bf16(Bt[n][k], At[m][k], acc[ai][bj][m][n], 0, 0, 0); __builtin_amdgcn_s_setprio(0); } while (0)
; #define PG8_WAIT_V(n) asm volatile("s_waitcnt vmcnt(" #n ")" ::: "memory")
; #define PG8_WAIT_L(n) asm volatile("s_waitcnt lgkmcnt(" #n ")" ::: "memory")
; #define PG8_BAR __builtin_amdgcn_s_barrier()
; #define PG8_SCHED __builtin_amdgcn_sched_barrier(0)
; template <class Epi>
; __device__ __forceinline__ void gemm_phase(PG8_LAS unsigned char* lds, const Gemm g, const StaticOrder& S, const Epi& E) {
;     ...
;             PG8_BAR; PG8_WAIT_L(0); PG8_MMA(1, 0, At, B0); PG8_BAR; PG8_SCHED;
;             PG8_STAGE(PG8_SB(1, 1), b3 + hstepB, voffB);
;             PG8_WAIT_V(6); PG8_BAR; PG8_MMA(1, 1, At, B1); PG8_BAR;
;         }
;         E(acc, cur, wr, wc, fr, fq);
;         if (!has_next) break;
;     __device__ __forceinline__ void operator()(const f32x4 (&acc)[2][2][4][2], const pg8::Unit& u, int wr, int wc, int fr, int fq) const {
;         const int row0 = u.pm * 256 + wr * 64 + fr, col0 = u.pn * 256 + wc * 32 + 8 * fq;
; #pragma unroll
;         for (int ai = 0; ai < 2; ++ai) {
;             u32x4 la[4][2], lg[4][2];
; #pragma unroll
;             for (int m = 0; m < 4; ++m)
; #pragma unroll
;                 for (int bj = 0; bj < 2; ++bj) { const bf16_t* p = G + (size_t)(row0 + ai * 128 + m * 16) * LDG + col0 + bj * 128;
;                     la[m][bj] = *(const u32x4*)p; if (mode != 0) lg[m][bj] = *(const u32x4*)(p + 2048); else lg[m][bj] = la[m][bj]; }
	ds_read_b128 v[144:147], v199 offset:49152
	ds_read_b128 v[148:151], v199 offset:50176
	ds_read_b128 v[152:155], v199 offset:51200
	ds_read_b128 v[156:159], v199 offset:52224
	ds_read_b128 v[160:163], v199 offset:53248
	ds_read_b128 v[164:167], v199 offset:54272
	ds_read_b128 v[186:189], v199 offset:55296
	ds_read_b128 v[190:193], v199 offset:56320
	s_add_i32 s34, 0, 0x1c000
	s_add_i32 s35, s62, s38
	v_lshl_add_u64 v[194:195], v[194:195], 0, s[4:5]
	s_mov_b32 m0, s35
	s_nop 0
	global_load_lds_dwordx4 v[194:195], off
	v_lshl_add_u64 v[194:195], v[218:219], 0, s[4:5]
	s_add_i32 m0, s35, 0x2000
	s_nop 0
	global_load_lds_dwordx4 v[194:195], off
	s_mov_b32 m0, s43
	v_lshl_add_u64 v[194:195], v[220:221], 0, s[4:5]
	global_load_lds_dwordx4 v[194:195], off
	v_lshl_add_u64 v[194:195], v[222:223], 0, s[4:5]
	s_mov_b32 m0, s50
	s_nop 0
	global_load_lds_dwordx4 v[194:195], off
	s_add_u32 s22, s22, 0x40080
	s_addc_u32 s23, s23, 0
	s_add_i32 s34, s34, s38
	v_lshl_add_u64 v[224:225], s[22:23], 0, v[172:173]
	s_mov_b32 m0, s34
	s_nop 0
	global_load_lds_dwordx4 v[224:225], off
	v_lshl_add_u64 v[224:225], s[22:23], 0, v[176:177]
	s_add_i32 m0, s34, 0x2000
	s_nop 0
	global_load_lds_dwordx4 v[224:225], off
	s_waitcnt lgkmcnt(0)
	s_waitcnt vmcnt(8)
	s_barrier
	v_mfma_f32_16x16x32_bf16 v[60:63], v[128:131], v[144:147], v[60:63]
	v_mfma_f32_16x16x32_bf16 v[56:59], v[136:139], v[144:147], v[56:59]
	v_mfma_f32_16x16x32_bf16 v[44:47], v[128:131], v[152:155], v[44:47]
	v_mfma_f32_16x16x32_bf16 v[40:43], v[136:139], v[152:155], v[40:43]
	v_mfma_f32_16x16x32_bf16 v[28:31], v[128:131], v[160:163], v[28:31]
	v_mfma_f32_16x16x32_bf16 v[24:27], v[136:139], v[160:163], v[24:27]
	v_mfma_f32_16x16x32_bf16 v[12:15], v[128:131], v[186:189], v[12:15]
	v_mfma_f32_16x16x32_bf16 v[8:11], v[136:139], v[186:189], v[8:11]
	v_mfma_f32_16x16x32_bf16 v[60:63], v[132:135], v[148:151], v[60:63]
	v_mfma_f32_16x16x32_bf16 v[56:59], v[140:143], v[148:151], v[56:59]
	v_mfma_f32_16x16x32_bf16 v[44:47], v[132:135], v[156:159], v[44:47]
	v_mfma_f32_16x16x32_bf16 v[40:43], v[140:143], v[156:159], v[40:43]
	v_mfma_f32_16x16x32_bf16 v[28:31], v[132:135], v[164:167], v[28:31]
	v_mfma_f32_16x16x32_bf16 v[24:27], v[140:143], v[164:167], v[24:27]
	v_mfma_f32_16x16x32_bf16 v[12:15], v[132:135], v[190:193], v[12:15]
	v_mfma_f32_16x16x32_bf16 v[8:11], v[140:143], v[190:193], v[8:11]
	v_mfma_f32_16x16x32_bf16 v[52:55], v[202:205], v[144:147], v[52:55]
	v_mfma_f32_16x16x32_bf16 v[48:51], v[210:213], v[144:147], v[48:51]
	v_mfma_f32_16x16x32_bf16 v[36:39], v[202:205], v[152:155], v[36:39]
	v_mfma_f32_16x16x32_bf16 v[32:35], v[210:213], v[152:155], v[32:35]
	v_mfma_f32_16x16x32_bf16 v[20:23], v[202:205], v[160:163], v[20:23]
	v_mfma_f32_16x16x32_bf16 v[16:19], v[210:213], v[160:163], v[16:19]
	v_mfma_f32_16x16x32_bf16 v[4:7], v[202:205], v[186:189], v[4:7]
	v_mfma_f32_16x16x32_bf16 v[0:3], v[210:213], v[186:189], v[0:3]
	v_mfma_f32_16x16x32_bf16 v[52:55], v[206:209], v[148:151], v[52:55]
	v_mfma_f32_16x16x32_bf16 v[48:51], v[214:217], v[148:151], v[48:51]
	v_mfma_f32_16x16x32_bf16 v[36:39], v[206:209], v[156:159], v[36:39]
	v_mfma_f32_16x16x32_bf16 v[32:35], v[214:217], v[156:159], v[32:35]
	v_mfma_f32_16x16x32_bf16 v[20:23], v[206:209], v[164:167], v[20:23]
	v_mfma_f32_16x16x32_bf16 v[16:19], v[214:217], v[164:167], v[16:19]
	v_mfma_f32_16x16x32_bf16 v[4:7], v[206:209], v[190:193], v[4:7]
	v_mfma_f32_16x16x32_bf16 v[0:3], v[214:217], v[190:193], v[0:3]
	s_add_i32 s61, s61, 2
	s_add_u32 s30, s30, 0x100
	s_addc_u32 s31, s31, 0
	s_add_u32 s59, s59, 0x100
	s_addc_u32 s60, s60, 0
	s_cmp_gt_u32 s61, 13
	s_barrier
	s_cbranch_scc0 .LBB0_925
	v_lshl_or_b32 v130, s56, 8, v197
	v_lshl_add_u32 v128, s28, 8, v169
	v_ashrrev_i32_e32 v131, 31, v130
	v_lshlrev_b64 v[186:187], 1, v[130:131]
	v_ashrrev_i32_e32 v129, 31, v128
	v_lshl_add_u64 v[188:189], s[46:47], 0, v[186:187]
	v_lshlrev_b64 v[190:191], 13, v[128:129]
	v_lshl_add_u64 v[130:131], v[188:189], 0, v[190:191]
	v_add_co_u32_e32 v132, vcc, 0x1000, v130
	global_load_dwordx4 v[202:205], v[130:131], off
	s_nop 0
	v_addc_co_u32_e32 v133, vcc, 0, v131, vcc
	global_load_dwordx4 v[206:209], v[132:133], off
	v_or_b32_e32 v134, 16, v128
	v_or_b32_e32 v136, 32, v128
	v_or_b32_e32 v128, 48, v128
	v_ashrrev_i32_e32 v135, 31, v134
	v_ashrrev_i32_e32 v137, 31, v136
	v_ashrrev_i32_e32 v129, 31, v128
	v_lshlrev_b64 v[226:227], 13, v[134:135]
	v_lshlrev_b64 v[194:195], 13, v[136:137]
	v_lshlrev_b64 v[192:193], 13, v[128:129]
	v_lshl_add_u64 v[128:129], s[46:47], 0, v[190:191]
	v_lshl_add_u64 v[134:135], v[188:189], 0, v[226:227]
	v_lshl_add_u64 v[140:141], v[188:189], 0, v[194:195]
	v_lshl_add_u64 v[142:143], v[188:189], 0, v[192:193]
	v_lshl_add_u64 v[228:229], v[128:129], 0, v[186:187]
	global_load_dwordx4 v[210:213], v[130:131], off offset:256
	global_load_dwordx4 v[214:217], v[134:135], off
	global_load_dwordx4 v[164:167], v[134:135], off offset:256
	global_load_dwordx4 v[152:155], v[140:141], off
	global_load_dwordx4 v[144:147], v[140:141], off offset:256
	global_load_dwordx4 v[136:139], v[142:143], off
	global_load_dwordx4 v[128:131], v[142:143], off offset:256
	global_load_dwordx4 v[218:221], v[132:133], off offset:256
	v_add_co_u32_e32 v134, vcc, 0x1000, v134
	s_mov_b32 s56, s14
	s_nop 0
	v_addc_co_u32_e32 v135, vcc, 0, v135, vcc
	global_load_dwordx4 v[222:225], v[134:135], off
	global_load_dwordx4 v[160:163], v[134:135], off offset:256
	v_add_co_u32_e32 v132, vcc, 0x1000, v140
	s_mov_b32 s28, s16
	s_nop 0
	v_addc_co_u32_e32 v133, vcc, 0, v141, vcc
	global_load_dwordx4 v[156:159], v[132:133], off
	global_load_dwordx4 v[148:151], v[132:133], off offset:256
	v_add_co_u32_e32 v134, vcc, 0x1000, v142
	s_mov_b64 s[22:23], s[20:21]
	s_nop 0
	v_addc_co_u32_e32 v135, vcc, 0, v143, vcc
	global_load_dwordx4 v[140:143], v[134:135], off
	s_nop 0
	global_load_dwordx4 v[132:135], v[134:135], off offset:256
	s_mov_b64 s[30:31], s[18:19]
	s_waitcnt vmcnt(0)
; __device__ __forceinline__ float sigmoidf_(float x) { return __builtin_amdgcn_rcpf(1.0f + __expf(-x)); }
; __device__ __forceinline__ u32x4 pack8(const float (&f)[8]) { u32x4 w; w.x = cvt_pk_bf16(f[0], f[1]); w.y = cvt_pk_bf16(f[2], f[3]); w.z = cvt_pk_bf16(f[4], f[5]); w.w = cvt_pk_bf16(f[6], f[7]); return w; }
;     __device__ __forceinline__ void operator()(const f32x4 (&acc)[2][2][4][2], const pg8::Unit& u, int wr, int wc, int fr, int fq) const {
;     ...
;                     float a[8], gt[8], o[8];
;                     unpack8(la[m][bj], a);
;                     if (mode == 0) {
; #pragma unroll
;                         for (int n = 0; n < 2; ++n)
; #pragma unroll
;                             for (int i = 0; i < 4; ++i) o[n * 4 + i] = sigmoidf_(a[n * 4 + i]) * acc[ai][bj][m][n][i];
;                     } else {
;                         unpack8(lg[m][bj], gt);
; #pragma unroll
;                         for (int n = 0; n < 2; ++n)
; #pragma unroll
;                             for (int i = 0; i < 4; ++i) o[n * 4 + i] = a[n * 4 + i] + sigmoidf_(gt[n * 4 + i]) * acc[ai][bj][m][n][i];
;                     }
;                     *(u32x4*)p = pack8(o);
	v_lshlrev_b32_e32 v201, 16, v202
	v_and_b32_e32 v202, 0xffff0000, v202
	v_lshlrev_b32_e32 v230, 16, v203
	v_lshlrev_b32_e32 v233, 16, v206
	v_and_b32_e32 v206, 0xffff0000, v206
	v_lshlrev_b32_e32 v234, 16, v207
	v_mul_f32_e32 v206, 0xbfb8aa3b, v206
	v_mul_f32_e32 v234, 0xbfb8aa3b, v234
	v_mul_f32_e32 v233, 0xbfb8aa3b, v233
	v_exp_f32_e32 v206, v206
	v_exp_f32_e32 v234, v234
	v_exp_f32_e32 v233, v233
	v_and_b32_e32 v207, 0xffff0000, v207
	v_lshlrev_b32_e32 v235, 16, v208
	v_and_b32_e32 v208, 0xffff0000, v208
	v_mul_f32_e32 v207, 0xbfb8aa3b, v207
	v_mul_f32_e32 v235, 0xbfb8aa3b, v235
	v_mul_f32_e32 v208, 0xbfb8aa3b, v208
	v_exp_f32_e32 v207, v207
	v_add_f32_e32 v206, 1.0, v206
	v_add_f32_e32 v234, 1.0, v234
	v_exp_f32_e32 v235, v235
	v_exp_f32_e32 v208, v208
	v_add_f32_e32 v233, 1.0, v233
	v_rcp_f32_e32 v206, v206
	v_rcp_f32_e32 v234, v234
	v_rcp_f32_e32 v233, v233
	v_lshlrev_b32_e32 v236, 16, v209
	v_add_f32_e32 v207, 1.0, v207
	v_add_f32_e32 v235, 1.0, v235
	v_rcp_f32_e32 v207, v207
	v_fmac_f32_e32 v202, v125, v206
	v_fmac_f32_e32 v230, v126, v234
	v_add_f32_e32 v125, 1.0, v208
	v_mul_f32_e32 v126, 0xbfb8aa3b, v236
	v_fmac_f32_e32 v201, v124, v233
	v_rcp_f32_e32 v124, v235
	v_exp_f32_e32 v126, v126
	v_rcp_f32_e32 v125, v125
	v_and_b32_e32 v203, 0xffff0000, v203
	v_and_b32_e32 v209, 0xffff0000, v209
	v_lshlrev_b32_e32 v231, 16, v204
	v_and_b32_e32 v204, 0xffff0000, v204
	v_fmac_f32_e32 v203, v127, v207
	v_mul_f32_e32 v127, 0xbfb8aa3b, v209
	v_exp_f32_e32 v127, v127
	v_add_f32_e32 v126, 1.0, v126
	v_fmac_f32_e32 v231, v120, v124
	v_fmac_f32_e32 v204, v121, v125
	v_cvt_pk_bf16_f32 v120, v201, v202
	v_cvt_pk_bf16_f32 v121, v230, v203
	v_lshlrev_b32_e32 v201, 16, v218
	v_and_b32_e32 v202, 0xffff0000, v218
	v_lshlrev_b32_e32 v203, 16, v219
	v_rcp_f32_e32 v126, v126
	v_mul_f32_e32 v201, 0xbfb8aa3b, v201
	v_mul_f32_e32 v202, 0xbfb8aa3b, v202
	v_mul_f32_e32 v203, 0xbfb8aa3b, v203
	v_exp_f32_e32 v201, v201
	v_exp_f32_e32 v202, v202
	v_exp_f32_e32 v203, v203
	v_lshlrev_b32_e32 v232, 16, v205
	v_add_f32_e32 v127, 1.0, v127
	v_rcp_f32_e32 v127, v127
	v_fmac_f32_e32 v232, v122, v126
	v_cvt_pk_bf16_f32 v122, v231, v204
	v_and_b32_e32 v204, 0xffff0000, v219
	v_add_f32_e32 v201, 1.0, v201
	v_add_f32_e32 v202, 1.0, v202
	v_add_f32_e32 v203, 1.0, v203
	v_mul_f32_e32 v204, 0xbfb8aa3b, v204
	v_rcp_f32_e32 v201, v201
	v_rcp_f32_e32 v202, v202
	v_rcp_f32_e32 v203, v203
	v_exp_f32_e32 v204, v204
	v_and_b32_e32 v205, 0xffff0000, v205
	v_fmac_f32_e32 v205, v123, v127
	v_cvt_pk_bf16_f32 v123, v232, v205
	global_store_dwordx4 v[228:229], v[120:123], off
	v_lshlrev_b32_e32 v205, 16, v220
	v_and_b32_e32 v206, 0xffff0000, v220
	v_lshlrev_b32_e32 v120, 16, v210
	v_and_b32_e32 v121, 0xffff0000, v210
	v_lshlrev_b32_e32 v122, 16, v211
	v_fmac_f32_e32 v120, v116, v201
	v_fmac_f32_e32 v121, v117, v202
	v_fmac_f32_e32 v122, v118, v203
	v_add_f32_e32 v116, 1.0, v204
	v_mul_f32_e32 v117, 0xbfb8aa3b, v205
	v_mul_f32_e32 v118, 0xbfb8aa3b, v206
	v_rcp_f32_e32 v116, v116
	v_exp_f32_e32 v117, v117
	v_exp_f32_e32 v118, v118
	v_and_b32_e32 v123, 0xffff0000, v211
	v_lshlrev_b32_e32 v207, 16, v221
	v_fmac_f32_e32 v123, v119, v116
	v_add_f32_e32 v116, 1.0, v117
	v_add_f32_e32 v117, 1.0, v118
	v_mul_f32_e32 v118, 0xbfb8aa3b, v207
	v_exp_f32_e32 v118, v118
	v_rcp_f32_e32 v116, v116
	v_rcp_f32_e32 v117, v117
	v_lshlrev_b32_e32 v124, 16, v212
	v_add_f32_e32 v118, 1.0, v118
	v_rcp_f32_e32 v118, v118
	v_and_b32_e32 v208, 0xffff0000, v221
	v_and_b32_e32 v125, 0xffff0000, v212
	v_lshlrev_b32_e32 v126, 16, v213
	v_mul_f32_e32 v119, 0xbfb8aa3b, v208
	v_fmac_f32_e32 v124, v112, v116
	v_exp_f32_e32 v119, v119
	v_fmac_f32_e32 v125, v113, v117
	v_fmac_f32_e32 v126, v114, v118
	v_cvt_pk_bf16_f32 v112, v120, v121
	v_cvt_pk_bf16_f32 v113, v122, v123
	v_cvt_pk_bf16_f32 v114, v124, v125
	v_lshlrev_b32_e32 v122, 16, v222
	v_and_b32_e32 v123, 0xffff0000, v222
	v_lshlrev_b32_e32 v124, 16, v223
	v_mul_f32_e32 v122, 0xbfb8aa3b, v122
	v_mul_f32_e32 v123, 0xbfb8aa3b, v123
	v_mul_f32_e32 v124, 0xbfb8aa3b, v124
	v_exp_f32_e32 v122, v122
	v_exp_f32_e32 v123, v123
	v_exp_f32_e32 v124, v124
	v_add_f32_e32 v119, 1.0, v119
	v_rcp_f32_e32 v119, v119
	v_and_b32_e32 v125, 0xffff0000, v223
	v_add_f32_e32 v122, 1.0, v122
	v_add_f32_e32 v123, 1.0, v123
	v_add_f32_e32 v124, 1.0, v124
	v_mul_f32_e32 v125, 0xbfb8aa3b, v125
	v_rcp_f32_e32 v122, v122
	v_rcp_f32_e32 v123, v123
	v_rcp_f32_e32 v124, v124
	v_exp_f32_e32 v125, v125
	v_and_b32_e32 v127, 0xffff0000, v213
	v_fmac_f32_e32 v127, v115, v119
	v_cvt_pk_bf16_f32 v115, v126, v127
	global_store_dwordx4 v[228:229], v[112:115], off offset:256
	v_lshlrev_b32_e32 v116, 16, v215
	v_lshlrev_b32_e32 v126, 16, v224
	v_lshlrev_b32_e32 v114, 16, v214
	v_and_b32_e32 v115, 0xffff0000, v214
	v_and_b32_e32 v127, 0xffff0000, v224
	v_fmac_f32_e32 v114, v108, v122
	v_fmac_f32_e32 v115, v109, v123
	v_fmac_f32_e32 v116, v110, v124
	v_add_f32_e32 v108, 1.0, v125
	v_mul_f32_e32 v109, 0xbfb8aa3b, v126
	v_mul_f32_e32 v110, 0xbfb8aa3b, v127
	v_rcp_f32_e32 v108, v108
	v_exp_f32_e32 v109, v109
	v_exp_f32_e32 v110, v110
	v_and_b32_e32 v117, 0xffff0000, v215
	v_fmac_f32_e32 v117, v111, v108
	v_add_f32_e32 v108, 1.0, v109
	v_add_f32_e32 v109, 1.0, v110
	v_rcp_f32_e32 v108, v108
	v_rcp_f32_e32 v109, v109
	v_lshlrev_b32_e32 v201, 16, v225
	v_lshlrev_b32_e32 v118, 16, v216
	v_and_b32_e32 v119, 0xffff0000, v216
	v_and_b32_e32 v202, 0xffff0000, v225
	v_mul_f32_e32 v110, 0xbfb8aa3b, v201
	v_exp_f32_e32 v110, v110
	v_mul_f32_e32 v111, 0xbfb8aa3b, v202
	v_fmac_f32_e32 v118, v104, v108
	v_fmac_f32_e32 v119, v105, v109
	v_cvt_pk_bf16_f32 v104, v114, v115
	v_cvt_pk_bf16_f32 v105, v116, v117
	v_lshlrev_b32_e32 v114, 16, v160
; __device__ __forceinline__ float sigmoidf_(float x) { return __builtin_amdgcn_rcpf(1.0f + __expf(-x)); }
; __device__ __forceinline__ u32x4 pack8(const float (&f)[8]) { u32x4 w; w.x = cvt_pk_bf16(f[0], f[1]); w.y = cvt_pk_bf16(f[2], f[3]); w.z = cvt_pk_bf16(f[4], f[5]); w.w = cvt_pk_bf16(f[6], f[7]); return w; }
;     __device__ __forceinline__ void operator()(const f32x4 (&acc)[2][2][4][2], const pg8::Unit& u, int wr, int wc, int fr, int fq) const {
;     ...
;                     float a[8], gt[8], o[8];
;                     unpack8(la[m][bj], a);
;                     if (mode == 0) {
; #pragma unroll
;                         for (int n = 0; n < 2; ++n)
; #pragma unroll
;                             for (int i = 0; i < 4; ++i) o[n * 4 + i] = sigmoidf_(a[n * 4 + i]) * acc[ai][bj][m][n][i];
;                     } else {
;                         unpack8(lg[m][bj], gt);
; #pragma unroll
;                         for (int n = 0; n < 2; ++n)
; #pragma unroll
;                             for (int i = 0; i < 4; ++i) o[n * 4 + i] = a[n * 4 + i] + sigmoidf_(gt[n * 4 + i]) * acc[ai][bj][m][n][i];
;                     }
;                     *(u32x4*)p = pack8(o);
	v_and_b32_e32 v115, 0xffff0000, v160
	v_lshlrev_b32_e32 v116, 16, v161
	v_exp_f32_e32 v111, v111
	v_mul_f32_e32 v114, 0xbfb8aa3b, v114
	v_mul_f32_e32 v115, 0xbfb8aa3b, v115
	v_mul_f32_e32 v116, 0xbfb8aa3b, v116
	v_exp_f32_e32 v114, v114
	v_exp_f32_e32 v115, v115
	v_exp_f32_e32 v116, v116
	v_add_f32_e32 v110, 1.0, v110
	v_rcp_f32_e32 v110, v110
	v_add_f32_e32 v111, 1.0, v111
	v_and_b32_e32 v117, 0xffff0000, v161
	v_rcp_f32_e32 v111, v111
	v_add_f32_e32 v114, 1.0, v114
	v_add_f32_e32 v115, 1.0, v115
	v_add_f32_e32 v116, 1.0, v116
	v_mul_f32_e32 v117, 0xbfb8aa3b, v117
	v_rcp_f32_e32 v114, v114
	v_rcp_f32_e32 v115, v115
	v_rcp_f32_e32 v116, v116
	v_exp_f32_e32 v117, v117
	v_lshl_add_u64 v[112:113], s[46:47], 0, v[226:227]
	v_lshlrev_b32_e32 v120, 16, v217
	v_lshl_add_u64 v[112:113], v[112:113], 0, v[186:187]
	v_and_b32_e32 v121, 0xffff0000, v217
	v_fmac_f32_e32 v120, v106, v110
	v_cvt_pk_bf16_f32 v106, v118, v119
	v_fmac_f32_e32 v121, v107, v111
	v_cvt_pk_bf16_f32 v107, v120, v121
	global_store_dwordx4 v[112:113], v[104:107], off
	v_lshlrev_b32_e32 v118, 16, v162
	v_and_b32_e32 v119, 0xffff0000, v162
	v_lshlrev_b32_e32 v104, 16, v164
	v_and_b32_e32 v105, 0xffff0000, v164
	v_lshlrev_b32_e32 v106, 16, v165
	v_fmac_f32_e32 v104, v100, v114
	v_fmac_f32_e32 v105, v101, v115
	v_fmac_f32_e32 v106, v102, v116
	v_add_f32_e32 v100, 1.0, v117
	v_mul_f32_e32 v101, 0xbfb8aa3b, v118
	v_mul_f32_e32 v102, 0xbfb8aa3b, v119
	v_rcp_f32_e32 v100, v100
	v_exp_f32_e32 v101, v101
	v_exp_f32_e32 v102, v102
	v_and_b32_e32 v107, 0xffff0000, v165
	v_lshlrev_b32_e32 v120, 16, v163
	v_fmac_f32_e32 v107, v103, v100
	v_add_f32_e32 v100, 1.0, v101
	v_add_f32_e32 v101, 1.0, v102
	v_mul_f32_e32 v102, 0xbfb8aa3b, v120
	v_exp_f32_e32 v102, v102
	v_rcp_f32_e32 v100, v100
	v_rcp_f32_e32 v101, v101
	v_lshlrev_b32_e32 v108, 16, v166
	v_add_f32_e32 v102, 1.0, v102
	v_rcp_f32_e32 v102, v102
	v_and_b32_e32 v121, 0xffff0000, v163
	v_and_b32_e32 v109, 0xffff0000, v166
	v_lshlrev_b32_e32 v110, 16, v167
	v_mul_f32_e32 v103, 0xbfb8aa3b, v121
	v_fmac_f32_e32 v108, v96, v100
	v_exp_f32_e32 v103, v103
	v_fmac_f32_e32 v109, v97, v101
	v_fmac_f32_e32 v110, v98, v102
	v_cvt_pk_bf16_f32 v96, v104, v105
	v_cvt_pk_bf16_f32 v97, v106, v107
	v_cvt_pk_bf16_f32 v98, v108, v109
	v_lshlrev_b32_e32 v106, 16, v156
	v_and_b32_e32 v107, 0xffff0000, v156
	v_lshlrev_b32_e32 v108, 16, v157
	v_mul_f32_e32 v106, 0xbfb8aa3b, v106
	v_mul_f32_e32 v107, 0xbfb8aa3b, v107
	v_mul_f32_e32 v108, 0xbfb8aa3b, v108
	v_exp_f32_e32 v106, v106
	v_exp_f32_e32 v107, v107
	v_exp_f32_e32 v108, v108
	v_add_f32_e32 v103, 1.0, v103
	v_rcp_f32_e32 v103, v103
	v_and_b32_e32 v109, 0xffff0000, v157
	v_add_f32_e32 v106, 1.0, v106
	v_add_f32_e32 v107, 1.0, v107
	v_add_f32_e32 v108, 1.0, v108
	v_mul_f32_e32 v109, 0xbfb8aa3b, v109
	v_rcp_f32_e32 v106, v106
	v_rcp_f32_e32 v107, v107
	v_rcp_f32_e32 v108, v108
	v_exp_f32_e32 v109, v109
	v_and_b32_e32 v111, 0xffff0000, v167
	v_fmac_f32_e32 v111, v99, v103
	v_cvt_pk_bf16_f32 v99, v110, v111
	global_store_dwordx4 v[112:113], v[96:99], off offset:256
	v_lshlrev_b32_e32 v100, 16, v153
	v_lshlrev_b32_e32 v110, 16, v158
	v_lshlrev_b32_e32 v98, 16, v152
	v_and_b32_e32 v99, 0xffff0000, v152
	v_and_b32_e32 v111, 0xffff0000, v158
	v_fmac_f32_e32 v98, v92, v106
	v_fmac_f32_e32 v99, v93, v107
	v_fmac_f32_e32 v100, v94, v108
	v_add_f32_e32 v92, 1.0, v109
	v_mul_f32_e32 v93, 0xbfb8aa3b, v110
	v_mul_f32_e32 v94, 0xbfb8aa3b, v111
	v_rcp_f32_e32 v92, v92
	v_exp_f32_e32 v93, v93
	v_exp_f32_e32 v94, v94
	v_and_b32_e32 v101, 0xffff0000, v153
	v_fmac_f32_e32 v101, v95, v92
	v_add_f32_e32 v92, 1.0, v93
	v_add_f32_e32 v93, 1.0, v94
	v_rcp_f32_e32 v92, v92
	v_rcp_f32_e32 v93, v93
	v_lshlrev_b32_e32 v112, 16, v159
	v_lshlrev_b32_e32 v102, 16, v154
	v_and_b32_e32 v103, 0xffff0000, v154
	v_and_b32_e32 v113, 0xffff0000, v159
	v_mul_f32_e32 v94, 0xbfb8aa3b, v112
	v_exp_f32_e32 v94, v94
	v_mul_f32_e32 v95, 0xbfb8aa3b, v113
	v_fmac_f32_e32 v102, v88, v92
	v_fmac_f32_e32 v103, v89, v93
	v_cvt_pk_bf16_f32 v88, v98, v99
	v_cvt_pk_bf16_f32 v89, v100, v101
	v_lshlrev_b32_e32 v98, 16, v148
	v_and_b32_e32 v99, 0xffff0000, v148
	v_lshlrev_b32_e32 v100, 16, v149
	v_exp_f32_e32 v95, v95
	v_mul_f32_e32 v98, 0xbfb8aa3b, v98
	v_mul_f32_e32 v99, 0xbfb8aa3b, v99
	v_mul_f32_e32 v100, 0xbfb8aa3b, v100
	v_exp_f32_e32 v98, v98
	v_exp_f32_e32 v99, v99
	v_exp_f32_e32 v100, v100
	v_add_f32_e32 v94, 1.0, v94
	v_rcp_f32_e32 v94, v94
	v_add_f32_e32 v95, 1.0, v95
	v_and_b32_e32 v101, 0xffff0000, v149
	v_rcp_f32_e32 v95, v95
	v_add_f32_e32 v98, 1.0, v98
	v_add_f32_e32 v99, 1.0, v99
	v_add_f32_e32 v100, 1.0, v100
	v_mul_f32_e32 v101, 0xbfb8aa3b, v101
	v_rcp_f32_e32 v98, v98
	v_rcp_f32_e32 v99, v99
	v_rcp_f32_e32 v100, v100
	v_exp_f32_e32 v101, v101
	v_lshl_add_u64 v[96:97], s[46:47], 0, v[194:195]
	v_lshlrev_b32_e32 v104, 16, v155
	v_lshl_add_u64 v[96:97], v[96:97], 0, v[186:187]
	v_and_b32_e32 v105, 0xffff0000, v155
	v_fmac_f32_e32 v104, v90, v94
	v_cvt_pk_bf16_f32 v90, v102, v103
	v_fmac_f32_e32 v105, v91, v95
	v_cvt_pk_bf16_f32 v91, v104, v105
	global_store_dwordx4 v[96:97], v[88:91], off
	v_lshlrev_b32_e32 v102, 16, v150
	v_and_b32_e32 v103, 0xffff0000, v150
	v_lshlrev_b32_e32 v88, 16, v144
	v_and_b32_e32 v89, 0xffff0000, v144
	v_lshlrev_b32_e32 v90, 16, v145
	v_fmac_f32_e32 v88, v84, v98
	v_fmac_f32_e32 v89, v85, v99
	v_fmac_f32_e32 v90, v86, v100
	v_add_f32_e32 v84, 1.0, v101
	v_mul_f32_e32 v85, 0xbfb8aa3b, v102
	v_mul_f32_e32 v86, 0xbfb8aa3b, v103
	v_rcp_f32_e32 v84, v84
	v_exp_f32_e32 v85, v85
	v_exp_f32_e32 v86, v86
	v_and_b32_e32 v91, 0xffff0000, v145
	v_lshlrev_b32_e32 v104, 16, v151
	v_fmac_f32_e32 v91, v87, v84
	v_add_f32_e32 v84, 1.0, v85
; __device__ __forceinline__ float sigmoidf_(float x) { return __builtin_amdgcn_rcpf(1.0f + __expf(-x)); }
; __device__ __forceinline__ u32x4 pack8(const float (&f)[8]) { u32x4 w; w.x = cvt_pk_bf16(f[0], f[1]); w.y = cvt_pk_bf16(f[2], f[3]); w.z = cvt_pk_bf16(f[4], f[5]); w.w = cvt_pk_bf16(f[6], f[7]); return w; }
;     __device__ __forceinline__ void operator()(const f32x4 (&acc)[2][2][4][2], const pg8::Unit& u, int wr, int wc, int fr, int fq) const {
;     ...
;         for (int ai = 0; ai < 2; ++ai) {
;             u32x4 la[4][2], lg[4][2];
; #pragma unroll
;             for (int m = 0; m < 4; ++m)
; #pragma unroll
;                 for (int bj = 0; bj < 2; ++bj) { const bf16_t* p = G + (size_t)(row0 + ai * 128 + m * 16) * LDG + col0 + bj * 128;
;                     la[m][bj] = *(const u32x4*)p; if (mode != 0) lg[m][bj] = *(const u32x4*)(p + 2048); else lg[m][bj] = la[m][bj]; }
; #pragma unroll
;             for (int m = 0; m < 4; ++m)
; #pragma unroll
;                 for (int bj = 0; bj < 2; ++bj) {
;                     bf16_t* p = G + (size_t)(row0 + ai * 128 + m * 16) * LDG + col0 + bj * 128;
;                     float a[8], gt[8], o[8];
;                     unpack8(la[m][bj], a);
;                     if (mode == 0) {
; #pragma unroll
;                         for (int n = 0; n < 2; ++n)
; #pragma unroll
;                             for (int i = 0; i < 4; ++i) o[n * 4 + i] = sigmoidf_(a[n * 4 + i]) * acc[ai][bj][m][n][i];
;                     } else {
;                         unpack8(lg[m][bj], gt);
; #pragma unroll
;                         for (int n = 0; n < 2; ++n)
; #pragma unroll
;                             for (int i = 0; i < 4; ++i) o[n * 4 + i] = a[n * 4 + i] + sigmoidf_(gt[n * 4 + i]) * acc[ai][bj][m][n][i];
;                     }
;                     *(u32x4*)p = pack8(o);
	v_add_f32_e32 v85, 1.0, v86
	v_mul_f32_e32 v86, 0xbfb8aa3b, v104
	v_exp_f32_e32 v86, v86
	v_rcp_f32_e32 v84, v84
	v_rcp_f32_e32 v85, v85
	v_lshlrev_b32_e32 v92, 16, v146
	v_add_f32_e32 v86, 1.0, v86
	v_rcp_f32_e32 v86, v86
	v_and_b32_e32 v105, 0xffff0000, v151
	v_and_b32_e32 v93, 0xffff0000, v146
	v_lshlrev_b32_e32 v94, 16, v147
	v_mul_f32_e32 v87, 0xbfb8aa3b, v105
	v_fmac_f32_e32 v92, v80, v84
	v_exp_f32_e32 v87, v87
	v_fmac_f32_e32 v93, v81, v85
	v_fmac_f32_e32 v94, v82, v86
	v_cvt_pk_bf16_f32 v80, v88, v89
	v_cvt_pk_bf16_f32 v81, v90, v91
	v_cvt_pk_bf16_f32 v82, v92, v93
	v_lshlrev_b32_e32 v90, 16, v140
	v_and_b32_e32 v91, 0xffff0000, v140
	v_lshlrev_b32_e32 v92, 16, v141
	v_mul_f32_e32 v90, 0xbfb8aa3b, v90
	v_mul_f32_e32 v91, 0xbfb8aa3b, v91
	v_mul_f32_e32 v92, 0xbfb8aa3b, v92
	v_exp_f32_e32 v90, v90
	v_exp_f32_e32 v91, v91
	v_exp_f32_e32 v92, v92
	v_add_f32_e32 v87, 1.0, v87
	v_rcp_f32_e32 v87, v87
	v_and_b32_e32 v93, 0xffff0000, v141
	v_add_f32_e32 v90, 1.0, v90
	v_add_f32_e32 v91, 1.0, v91
	v_add_f32_e32 v92, 1.0, v92
	v_mul_f32_e32 v93, 0xbfb8aa3b, v93
	v_rcp_f32_e32 v90, v90
	v_rcp_f32_e32 v91, v91
	v_rcp_f32_e32 v92, v92
	v_exp_f32_e32 v93, v93
	v_and_b32_e32 v95, 0xffff0000, v147
	v_fmac_f32_e32 v95, v83, v87
	v_cvt_pk_bf16_f32 v83, v94, v95
	global_store_dwordx4 v[96:97], v[80:83], off offset:256
	v_lshlrev_b32_e32 v84, 16, v137
	v_lshlrev_b32_e32 v94, 16, v142
	v_lshlrev_b32_e32 v82, 16, v136
	v_and_b32_e32 v83, 0xffff0000, v136
	v_and_b32_e32 v95, 0xffff0000, v142
	v_fmac_f32_e32 v82, v76, v90
	v_fmac_f32_e32 v83, v77, v91
	v_fmac_f32_e32 v84, v78, v92
	v_add_f32_e32 v76, 1.0, v93
	v_mul_f32_e32 v77, 0xbfb8aa3b, v94
	v_mul_f32_e32 v78, 0xbfb8aa3b, v95
	v_rcp_f32_e32 v76, v76
	v_exp_f32_e32 v77, v77
	v_exp_f32_e32 v78, v78
	v_and_b32_e32 v85, 0xffff0000, v137
	v_fmac_f32_e32 v85, v79, v76
	v_add_f32_e32 v76, 1.0, v77
	v_add_f32_e32 v77, 1.0, v78
	v_rcp_f32_e32 v76, v76
	v_rcp_f32_e32 v77, v77
	v_lshlrev_b32_e32 v96, 16, v143
	v_lshlrev_b32_e32 v86, 16, v138
	v_and_b32_e32 v87, 0xffff0000, v138
	v_and_b32_e32 v97, 0xffff0000, v143
	v_mul_f32_e32 v78, 0xbfb8aa3b, v96
	v_exp_f32_e32 v78, v78
	v_mul_f32_e32 v79, 0xbfb8aa3b, v97
	v_fmac_f32_e32 v86, v72, v76
	v_fmac_f32_e32 v87, v73, v77
	v_cvt_pk_bf16_f32 v72, v82, v83
	v_cvt_pk_bf16_f32 v73, v84, v85
	v_lshlrev_b32_e32 v82, 16, v132
	v_and_b32_e32 v83, 0xffff0000, v132
	v_lshlrev_b32_e32 v84, 16, v133
	v_exp_f32_e32 v79, v79
	v_mul_f32_e32 v82, 0xbfb8aa3b, v82
	v_mul_f32_e32 v83, 0xbfb8aa3b, v83
	v_mul_f32_e32 v84, 0xbfb8aa3b, v84
	v_exp_f32_e32 v82, v82
	v_exp_f32_e32 v83, v83
	v_exp_f32_e32 v84, v84
	v_add_f32_e32 v78, 1.0, v78
	v_rcp_f32_e32 v78, v78
	v_add_f32_e32 v79, 1.0, v79
	v_and_b32_e32 v85, 0xffff0000, v133
	v_rcp_f32_e32 v79, v79
	v_add_f32_e32 v82, 1.0, v82
	v_add_f32_e32 v83, 1.0, v83
	v_add_f32_e32 v84, 1.0, v84
	v_mul_f32_e32 v85, 0xbfb8aa3b, v85
	v_rcp_f32_e32 v82, v82
	v_rcp_f32_e32 v83, v83
	v_rcp_f32_e32 v84, v84
	v_exp_f32_e32 v85, v85
	v_lshl_add_u64 v[80:81], s[46:47], 0, v[192:193]
	v_lshlrev_b32_e32 v88, 16, v139
	v_lshl_add_u64 v[80:81], v[80:81], 0, v[186:187]
	v_and_b32_e32 v89, 0xffff0000, v139
	v_fmac_f32_e32 v88, v74, v78
	v_cvt_pk_bf16_f32 v74, v86, v87
	v_fmac_f32_e32 v89, v75, v79
	v_cvt_pk_bf16_f32 v75, v88, v89
	global_store_dwordx4 v[80:81], v[72:75], off
	v_lshlrev_b32_e32 v86, 16, v134
	v_and_b32_e32 v87, 0xffff0000, v134
	v_lshlrev_b32_e32 v72, 16, v128
	v_and_b32_e32 v73, 0xffff0000, v128
	v_lshlrev_b32_e32 v74, 16, v129
	v_fmac_f32_e32 v72, v68, v82
	v_fmac_f32_e32 v73, v69, v83
	v_fmac_f32_e32 v74, v70, v84
	v_add_f32_e32 v68, 1.0, v85
	v_mul_f32_e32 v69, 0xbfb8aa3b, v86
	v_mul_f32_e32 v70, 0xbfb8aa3b, v87
	v_rcp_f32_e32 v68, v68
	v_exp_f32_e32 v69, v69
	v_exp_f32_e32 v70, v70
	v_and_b32_e32 v75, 0xffff0000, v129
	v_lshlrev_b32_e32 v88, 16, v135
	v_and_b32_e32 v89, 0xffff0000, v135
	v_fmac_f32_e32 v75, v71, v68
	v_add_f32_e32 v68, 1.0, v69
	v_add_f32_e32 v69, 1.0, v70
	v_mul_f32_e32 v70, 0xbfb8aa3b, v88
	v_exp_f32_e32 v70, v70
	v_mul_f32_e32 v71, 0xbfb8aa3b, v89
	v_exp_f32_e32 v71, v71
	v_rcp_f32_e32 v68, v68
	v_rcp_f32_e32 v69, v69
	v_add_f32_e32 v70, 1.0, v70
	v_rcp_f32_e32 v70, v70
	v_add_f32_e32 v71, 1.0, v71
	v_rcp_f32_e32 v71, v71
	v_lshlrev_b32_e32 v76, 16, v130
	v_and_b32_e32 v77, 0xffff0000, v130
	v_lshl_add_u64 v[132:133], v[190:191], 0, s[6:7]
	v_lshlrev_b32_e32 v78, 16, v131
	v_fmac_f32_e32 v76, v64, v68
	v_fmac_f32_e32 v77, v65, v69
	v_lshl_add_u64 v[68:69], v[188:189], 0, v[132:133]
	v_and_b32_e32 v79, 0xffff0000, v131
	v_fmac_f32_e32 v78, v66, v70
	v_add_co_u32_e32 v70, vcc, s55, v68
	v_fmac_f32_e32 v79, v67, v71
	s_nop 0
	v_addc_co_u32_e32 v71, vcc, 0, v69, vcc
	v_cvt_pk_bf16_f32 v64, v72, v73
	v_cvt_pk_bf16_f32 v65, v74, v75
	v_cvt_pk_bf16_f32 v66, v76, v77
	v_cvt_pk_bf16_f32 v67, v78, v79
	global_load_dwordx4 v[108:111], v[68:69], off
	global_load_dwordx4 v[112:115], v[70:71], off
	v_lshl_add_u64 v[134:135], v[190:191], 0, s[8:9]
	global_store_dwordx4 v[80:81], v[64:67], off offset:256
	global_load_dwordx4 v[116:119], v[68:69], off offset:256
	global_load_dwordx4 v[120:123], v[70:71], off offset:256
	v_lshl_add_u64 v[64:65], v[188:189], 0, v[134:135]
	v_add_co_u32_e32 v66, vcc, s55, v64
	v_lshl_add_u64 v[106:107], v[190:191], 0, s[10:11]
	s_nop 0
	v_addc_co_u32_e32 v67, vcc, 0, v65, vcc
	global_load_dwordx4 v[124:127], v[64:65], off
	global_load_dwordx4 v[100:103], v[64:65], off offset:256
	global_load_dwordx4 v[128:131], v[66:67], off
	global_load_dwordx4 v[96:99], v[66:67], off offset:256
	v_lshl_add_u64 v[64:65], v[188:189], 0, v[106:107]
	v_add_co_u32_e32 v66, vcc, s55, v64
	v_lshl_add_u64 v[104:105], v[190:191], 0, s[12:13]
	s_nop 0
	v_addc_co_u32_e32 v67, vcc, 0, v65, vcc
	global_load_dwordx4 v[92:95], v[64:65], off
	global_load_dwordx4 v[84:87], v[64:65], off offset:256
	global_load_dwordx4 v[88:91], v[66:67], off
	global_load_dwordx4 v[80:83], v[66:67], off offset:256
	v_lshl_add_u64 v[64:65], v[188:189], 0, v[104:105]
	v_add_co_u32_e32 v66, vcc, s55, v64
	v_lshl_add_u64 v[132:133], s[46:47], 0, v[132:133]
	s_nop 0
	v_addc_co_u32_e32 v67, vcc, 0, v65, vcc
	global_load_dwordx4 v[76:79], v[64:65], off
	global_load_dwordx4 v[68:71], v[64:65], off offset:256
	global_load_dwordx4 v[72:75], v[66:67], off
	s_nop 0
	global_load_dwordx4 v[64:67], v[66:67], off offset:256
	v_lshl_add_u64 v[132:133], v[132:133], 0, v[186:187]
	s_and_b64 vcc, exec, s[2:3]
	s_waitcnt vmcnt(0)
; __device__ __forceinline__ float sigmoidf_(float x) { return __builtin_amdgcn_rcpf(1.0f + __expf(-x)); }
; __device__ __forceinline__ u32x4 pack8(const float (&f)[8]) { u32x4 w; w.x = cvt_pk_bf16(f[0], f[1]); w.y = cvt_pk_bf16(f[2], f[3]); w.z = cvt_pk_bf16(f[4], f[5]); w.w = cvt_pk_bf16(f[6], f[7]); return w; }
;     __device__ __forceinline__ void operator()(const f32x4 (&acc)[2][2][4][2], const pg8::Unit& u, int wr, int wc, int fr, int fq) const {
;     ...
;                     float a[8], gt[8], o[8];
;                     unpack8(la[m][bj], a);
;                     if (mode == 0) {
; #pragma unroll
;                         for (int n = 0; n < 2; ++n)
; #pragma unroll
;                             for (int i = 0; i < 4; ++i) o[n * 4 + i] = sigmoidf_(a[n * 4 + i]) * acc[ai][bj][m][n][i];
;                     } else {
;                         unpack8(lg[m][bj], gt);
; #pragma unroll
;                         for (int n = 0; n < 2; ++n)
; #pragma unroll
;                             for (int i = 0; i < 4; ++i) o[n * 4 + i] = a[n * 4 + i] + sigmoidf_(gt[n * 4 + i]) * acc[ai][bj][m][n][i];
;                     }
;                     *(u32x4*)p = pack8(o);
	v_lshlrev_b32_e32 v136, 16, v108
	v_lshlrev_b32_e32 v140, 16, v112
	v_and_b32_e32 v112, 0xffff0000, v112
	v_lshlrev_b32_e32 v141, 16, v113
	v_mul_f32_e32 v140, 0xbfb8aa3b, v140
	v_mul_f32_e32 v112, 0xbfb8aa3b, v112
	v_mul_f32_e32 v141, 0xbfb8aa3b, v141
	v_exp_f32_e32 v140, v140
	v_exp_f32_e32 v112, v112
	v_exp_f32_e32 v141, v141
	v_and_b32_e32 v113, 0xffff0000, v113
	v_add_f32_e32 v140, 1.0, v140
	v_add_f32_e32 v112, 1.0, v112
	v_add_f32_e32 v141, 1.0, v141
	v_mul_f32_e32 v113, 0xbfb8aa3b, v113
	v_rcp_f32_e32 v140, v140
	v_rcp_f32_e32 v112, v112
	v_rcp_f32_e32 v141, v141
	v_exp_f32_e32 v113, v113
	v_and_b32_e32 v108, 0xffff0000, v108
	v_lshlrev_b32_e32 v137, 16, v109
	v_lshlrev_b32_e32 v142, 16, v114
	v_and_b32_e32 v114, 0xffff0000, v114
	v_fmac_f32_e32 v136, v60, v140
	v_fmac_f32_e32 v108, v61, v112
	v_fmac_f32_e32 v137, v62, v141
	v_add_f32_e32 v60, 1.0, v113
	v_mul_f32_e32 v61, 0xbfb8aa3b, v142
	v_mul_f32_e32 v62, 0xbfb8aa3b, v114
	v_rcp_f32_e32 v60, v60
	v_exp_f32_e32 v61, v61
	v_exp_f32_e32 v62, v62
	v_and_b32_e32 v109, 0xffff0000, v109
	v_lshlrev_b32_e32 v143, 16, v115
	v_fmac_f32_e32 v109, v63, v60
	v_add_f32_e32 v60, 1.0, v61
	v_add_f32_e32 v61, 1.0, v62
	v_mul_f32_e32 v62, 0xbfb8aa3b, v143
	v_exp_f32_e32 v62, v62
	v_and_b32_e32 v115, 0xffff0000, v115
	v_mul_f32_e32 v63, 0xbfb8aa3b, v115
	v_exp_f32_e32 v63, v63
	v_rcp_f32_e32 v61, v61
	v_add_f32_e32 v62, 1.0, v62
	v_rcp_f32_e32 v60, v60
	v_rcp_f32_e32 v62, v62
	v_lshlrev_b32_e32 v138, 16, v110
	v_and_b32_e32 v110, 0xffff0000, v110
	v_lshlrev_b32_e32 v139, 16, v111
	v_add_f32_e32 v63, 1.0, v63
	v_fmac_f32_e32 v110, v57, v61
	v_rcp_f32_e32 v63, v63
	v_fmac_f32_e32 v138, v56, v60
	v_fmac_f32_e32 v139, v58, v62
	v_cvt_pk_bf16_f32 v56, v136, v108
	v_cvt_pk_bf16_f32 v57, v137, v109
	v_cvt_pk_bf16_f32 v58, v138, v110
	v_lshlrev_b32_e32 v108, 16, v120
	v_and_b32_e32 v109, 0xffff0000, v120
	v_lshlrev_b32_e32 v110, 16, v121
	v_mul_f32_e32 v108, 0xbfb8aa3b, v108
	v_mul_f32_e32 v109, 0xbfb8aa3b, v109
	v_mul_f32_e32 v110, 0xbfb8aa3b, v110
	v_exp_f32_e32 v108, v108
	v_exp_f32_e32 v109, v109
	v_exp_f32_e32 v110, v110
	v_and_b32_e32 v111, 0xffff0000, v111
	v_fmac_f32_e32 v111, v59, v63
	v_cvt_pk_bf16_f32 v59, v139, v111
	v_and_b32_e32 v111, 0xffff0000, v121
	v_add_f32_e32 v108, 1.0, v108
	v_add_f32_e32 v109, 1.0, v109
	v_add_f32_e32 v110, 1.0, v110
	v_mul_f32_e32 v111, 0xbfb8aa3b, v111
	v_rcp_f32_e32 v108, v108
	v_rcp_f32_e32 v109, v109
	v_rcp_f32_e32 v110, v110
	v_exp_f32_e32 v111, v111
	global_store_dwordx4 v[132:133], v[56:59], off
	v_lshlrev_b32_e32 v112, 16, v122
	v_and_b32_e32 v113, 0xffff0000, v122
	v_lshlrev_b32_e32 v56, 16, v116
	v_and_b32_e32 v57, 0xffff0000, v116
	v_lshlrev_b32_e32 v58, 16, v117
	v_fmac_f32_e32 v56, v52, v108
	v_fmac_f32_e32 v57, v53, v109
	v_fmac_f32_e32 v58, v54, v110
	v_add_f32_e32 v52, 1.0, v111
	v_mul_f32_e32 v53, 0xbfb8aa3b, v112
	v_mul_f32_e32 v54, 0xbfb8aa3b, v113
	v_rcp_f32_e32 v52, v52
	v_exp_f32_e32 v53, v53
	v_exp_f32_e32 v54, v54
	v_and_b32_e32 v59, 0xffff0000, v117
	v_lshlrev_b32_e32 v114, 16, v123
	v_fmac_f32_e32 v59, v55, v52
	v_add_f32_e32 v52, 1.0, v53
	v_add_f32_e32 v53, 1.0, v54
	v_mul_f32_e32 v54, 0xbfb8aa3b, v114
	v_exp_f32_e32 v54, v54
	v_rcp_f32_e32 v52, v52
	v_rcp_f32_e32 v53, v53
	v_lshlrev_b32_e32 v60, 16, v118
	v_add_f32_e32 v54, 1.0, v54
	v_rcp_f32_e32 v54, v54
	v_and_b32_e32 v115, 0xffff0000, v123
	v_and_b32_e32 v61, 0xffff0000, v118
	v_lshlrev_b32_e32 v62, 16, v119
	v_mul_f32_e32 v55, 0xbfb8aa3b, v115
	v_fmac_f32_e32 v60, v48, v52
	v_exp_f32_e32 v55, v55
	v_fmac_f32_e32 v61, v49, v53
	v_fmac_f32_e32 v62, v50, v54
	v_cvt_pk_bf16_f32 v48, v56, v57
	v_cvt_pk_bf16_f32 v49, v58, v59
	v_cvt_pk_bf16_f32 v50, v60, v61
	v_lshlrev_b32_e32 v58, 16, v128
	v_and_b32_e32 v59, 0xffff0000, v128
	v_lshlrev_b32_e32 v60, 16, v129
	v_mul_f32_e32 v58, 0xbfb8aa3b, v58
	v_mul_f32_e32 v59, 0xbfb8aa3b, v59
	v_mul_f32_e32 v60, 0xbfb8aa3b, v60
	v_exp_f32_e32 v58, v58
	v_exp_f32_e32 v59, v59
	v_exp_f32_e32 v60, v60
	v_add_f32_e32 v55, 1.0, v55
	v_rcp_f32_e32 v55, v55
	v_and_b32_e32 v61, 0xffff0000, v129
	v_add_f32_e32 v58, 1.0, v58
	v_add_f32_e32 v59, 1.0, v59
	v_add_f32_e32 v60, 1.0, v60
	v_mul_f32_e32 v61, 0xbfb8aa3b, v61
	v_rcp_f32_e32 v58, v58
	v_rcp_f32_e32 v59, v59
	v_rcp_f32_e32 v60, v60
	v_exp_f32_e32 v61, v61
	v_and_b32_e32 v63, 0xffff0000, v119
	v_fmac_f32_e32 v63, v51, v55
	v_cvt_pk_bf16_f32 v51, v62, v63
	global_store_dwordx4 v[132:133], v[48:51], off offset:256
	v_lshlrev_b32_e32 v52, 16, v125
	v_lshlrev_b32_e32 v62, 16, v130
	v_lshlrev_b32_e32 v50, 16, v124
	v_and_b32_e32 v51, 0xffff0000, v124
	v_and_b32_e32 v63, 0xffff0000, v130
	v_fmac_f32_e32 v50, v44, v58
	v_fmac_f32_e32 v51, v45, v59
	v_fmac_f32_e32 v52, v46, v60
	v_add_f32_e32 v44, 1.0, v61
	v_mul_f32_e32 v45, 0xbfb8aa3b, v62
	v_mul_f32_e32 v46, 0xbfb8aa3b, v63
	v_rcp_f32_e32 v44, v44
	v_exp_f32_e32 v45, v45
	v_exp_f32_e32 v46, v46
	v_and_b32_e32 v53, 0xffff0000, v125
	v_fmac_f32_e32 v53, v47, v44
	v_add_f32_e32 v44, 1.0, v45
	v_add_f32_e32 v45, 1.0, v46
	v_rcp_f32_e32 v44, v44
	v_rcp_f32_e32 v45, v45
	v_lshlrev_b32_e32 v108, 16, v131
	v_lshlrev_b32_e32 v54, 16, v126
	v_and_b32_e32 v55, 0xffff0000, v126
	v_and_b32_e32 v109, 0xffff0000, v131
	v_mul_f32_e32 v46, 0xbfb8aa3b, v108
	v_exp_f32_e32 v46, v46
	v_mul_f32_e32 v47, 0xbfb8aa3b, v109
	v_fmac_f32_e32 v54, v40, v44
	v_fmac_f32_e32 v55, v41, v45
	v_cvt_pk_bf16_f32 v40, v50, v51
	v_cvt_pk_bf16_f32 v41, v52, v53
	v_lshlrev_b32_e32 v50, 16, v96
	v_and_b32_e32 v51, 0xffff0000, v96
	v_lshlrev_b32_e32 v52, 16, v97
	v_exp_f32_e32 v47, v47
	v_mul_f32_e32 v50, 0xbfb8aa3b, v50
	v_mul_f32_e32 v51, 0xbfb8aa3b, v51
	v_mul_f32_e32 v52, 0xbfb8aa3b, v52
; __device__ __forceinline__ float sigmoidf_(float x) { return __builtin_amdgcn_rcpf(1.0f + __expf(-x)); }
; __device__ __forceinline__ u32x4 pack8(const float (&f)[8]) { u32x4 w; w.x = cvt_pk_bf16(f[0], f[1]); w.y = cvt_pk_bf16(f[2], f[3]); w.z = cvt_pk_bf16(f[4], f[5]); w.w = cvt_pk_bf16(f[6], f[7]); return w; }
;     __device__ __forceinline__ void operator()(const f32x4 (&acc)[2][2][4][2], const pg8::Unit& u, int wr, int wc, int fr, int fq) const {
;     ...
;                     float a[8], gt[8], o[8];
;                     unpack8(la[m][bj], a);
;                     if (mode == 0) {
; #pragma unroll
;                         for (int n = 0; n < 2; ++n)
; #pragma unroll
;                             for (int i = 0; i < 4; ++i) o[n * 4 + i] = sigmoidf_(a[n * 4 + i]) * acc[ai][bj][m][n][i];
;                     } else {
;                         unpack8(lg[m][bj], gt);
; #pragma unroll
;                         for (int n = 0; n < 2; ++n)
; #pragma unroll
;                             for (int i = 0; i < 4; ++i) o[n * 4 + i] = a[n * 4 + i] + sigmoidf_(gt[n * 4 + i]) * acc[ai][bj][m][n][i];
;                     }
;                     *(u32x4*)p = pack8(o);
	v_exp_f32_e32 v50, v50
	v_exp_f32_e32 v51, v51
	v_exp_f32_e32 v52, v52
	v_add_f32_e32 v46, 1.0, v46
	v_rcp_f32_e32 v46, v46
	v_add_f32_e32 v47, 1.0, v47
	v_and_b32_e32 v53, 0xffff0000, v97
	v_rcp_f32_e32 v47, v47
	v_add_f32_e32 v50, 1.0, v50
	v_add_f32_e32 v51, 1.0, v51
	v_add_f32_e32 v52, 1.0, v52
	v_mul_f32_e32 v53, 0xbfb8aa3b, v53
	v_rcp_f32_e32 v50, v50
	v_rcp_f32_e32 v51, v51
	v_rcp_f32_e32 v52, v52
	v_exp_f32_e32 v53, v53
	v_lshl_add_u64 v[48:49], s[46:47], 0, v[134:135]
	v_lshlrev_b32_e32 v56, 16, v127
	v_lshl_add_u64 v[48:49], v[48:49], 0, v[186:187]
	v_and_b32_e32 v57, 0xffff0000, v127
	v_fmac_f32_e32 v56, v42, v46
	v_cvt_pk_bf16_f32 v42, v54, v55
	v_fmac_f32_e32 v57, v43, v47
	v_cvt_pk_bf16_f32 v43, v56, v57
	global_store_dwordx4 v[48:49], v[40:43], off
	v_lshlrev_b32_e32 v54, 16, v98
	v_and_b32_e32 v55, 0xffff0000, v98
	v_lshlrev_b32_e32 v40, 16, v100
	v_and_b32_e32 v41, 0xffff0000, v100
	v_lshlrev_b32_e32 v42, 16, v101
	v_fmac_f32_e32 v40, v36, v50
	v_fmac_f32_e32 v41, v37, v51
	v_fmac_f32_e32 v42, v38, v52
	v_add_f32_e32 v36, 1.0, v53
	v_mul_f32_e32 v37, 0xbfb8aa3b, v54
	v_mul_f32_e32 v38, 0xbfb8aa3b, v55
	v_rcp_f32_e32 v36, v36
	v_exp_f32_e32 v37, v37
	v_exp_f32_e32 v38, v38
	v_and_b32_e32 v43, 0xffff0000, v101
	v_lshlrev_b32_e32 v56, 16, v99
	v_fmac_f32_e32 v43, v39, v36
	v_add_f32_e32 v36, 1.0, v37
	v_add_f32_e32 v37, 1.0, v38
	v_mul_f32_e32 v38, 0xbfb8aa3b, v56
	v_exp_f32_e32 v38, v38
	v_rcp_f32_e32 v36, v36
	v_rcp_f32_e32 v37, v37
	v_lshlrev_b32_e32 v44, 16, v102
	v_add_f32_e32 v38, 1.0, v38
	v_rcp_f32_e32 v38, v38
	v_and_b32_e32 v57, 0xffff0000, v99
	v_and_b32_e32 v45, 0xffff0000, v102
	v_lshlrev_b32_e32 v46, 16, v103
	v_mul_f32_e32 v39, 0xbfb8aa3b, v57
	v_fmac_f32_e32 v44, v32, v36
	v_exp_f32_e32 v39, v39
	v_fmac_f32_e32 v45, v33, v37
	v_fmac_f32_e32 v46, v34, v38
	v_cvt_pk_bf16_f32 v32, v40, v41
	v_cvt_pk_bf16_f32 v33, v42, v43
	v_cvt_pk_bf16_f32 v34, v44, v45
	v_lshlrev_b32_e32 v42, 16, v88
	v_and_b32_e32 v43, 0xffff0000, v88
	v_lshlrev_b32_e32 v44, 16, v89
	v_mul_f32_e32 v42, 0xbfb8aa3b, v42
	v_mul_f32_e32 v43, 0xbfb8aa3b, v43
	v_mul_f32_e32 v44, 0xbfb8aa3b, v44
	v_exp_f32_e32 v42, v42
	v_exp_f32_e32 v43, v43
	v_exp_f32_e32 v44, v44
	v_add_f32_e32 v39, 1.0, v39
	v_rcp_f32_e32 v39, v39
	v_and_b32_e32 v45, 0xffff0000, v89
	v_add_f32_e32 v42, 1.0, v42
	v_add_f32_e32 v43, 1.0, v43
	v_add_f32_e32 v44, 1.0, v44
	v_mul_f32_e32 v45, 0xbfb8aa3b, v45
	v_rcp_f32_e32 v42, v42
	v_rcp_f32_e32 v43, v43
	v_rcp_f32_e32 v44, v44
	v_exp_f32_e32 v45, v45
	v_and_b32_e32 v47, 0xffff0000, v103
	v_fmac_f32_e32 v47, v35, v39
	v_cvt_pk_bf16_f32 v35, v46, v47
	global_store_dwordx4 v[48:49], v[32:35], off offset:256
	v_lshlrev_b32_e32 v36, 16, v93
	v_lshlrev_b32_e32 v46, 16, v90
	v_lshlrev_b32_e32 v34, 16, v92
	v_and_b32_e32 v35, 0xffff0000, v92
	v_and_b32_e32 v47, 0xffff0000, v90
	v_fmac_f32_e32 v34, v28, v42
	v_fmac_f32_e32 v35, v29, v43
	v_fmac_f32_e32 v36, v30, v44
	v_add_f32_e32 v28, 1.0, v45
	v_mul_f32_e32 v29, 0xbfb8aa3b, v46
	v_mul_f32_e32 v30, 0xbfb8aa3b, v47
	v_rcp_f32_e32 v28, v28
	v_exp_f32_e32 v29, v29
	v_exp_f32_e32 v30, v30
	v_and_b32_e32 v37, 0xffff0000, v93
	v_fmac_f32_e32 v37, v31, v28
	v_add_f32_e32 v28, 1.0, v29
	v_add_f32_e32 v29, 1.0, v30
	v_rcp_f32_e32 v28, v28
	v_rcp_f32_e32 v29, v29
	v_lshlrev_b32_e32 v48, 16, v91
	v_lshlrev_b32_e32 v38, 16, v94
	v_and_b32_e32 v39, 0xffff0000, v94
	v_and_b32_e32 v49, 0xffff0000, v91
	v_mul_f32_e32 v30, 0xbfb8aa3b, v48
	v_exp_f32_e32 v30, v30
	v_mul_f32_e32 v31, 0xbfb8aa3b, v49
	v_fmac_f32_e32 v38, v24, v28
	v_fmac_f32_e32 v39, v25, v29
	v_cvt_pk_bf16_f32 v24, v34, v35
	v_cvt_pk_bf16_f32 v25, v36, v37
	v_lshlrev_b32_e32 v34, 16, v80
	v_and_b32_e32 v35, 0xffff0000, v80
	v_lshlrev_b32_e32 v36, 16, v81
	v_exp_f32_e32 v31, v31
	v_mul_f32_e32 v34, 0xbfb8aa3b, v34
	v_mul_f32_e32 v35, 0xbfb8aa3b, v35
	v_mul_f32_e32 v36, 0xbfb8aa3b, v36
	v_exp_f32_e32 v34, v34
	v_exp_f32_e32 v35, v35
	v_exp_f32_e32 v36, v36
	v_add_f32_e32 v30, 1.0, v30
	v_rcp_f32_e32 v30, v30
	v_add_f32_e32 v31, 1.0, v31
	v_and_b32_e32 v37, 0xffff0000, v81
	v_rcp_f32_e32 v31, v31
	v_add_f32_e32 v34, 1.0, v34
	v_add_f32_e32 v35, 1.0, v35
	v_add_f32_e32 v36, 1.0, v36
	v_mul_f32_e32 v37, 0xbfb8aa3b, v37
	v_rcp_f32_e32 v34, v34
	v_rcp_f32_e32 v35, v35
	v_rcp_f32_e32 v36, v36
	v_exp_f32_e32 v37, v37
	v_lshl_add_u64 v[32:33], s[46:47], 0, v[106:107]
	v_lshlrev_b32_e32 v40, 16, v95
	v_lshl_add_u64 v[32:33], v[32:33], 0, v[186:187]
	v_and_b32_e32 v41, 0xffff0000, v95
	v_fmac_f32_e32 v40, v26, v30
	v_cvt_pk_bf16_f32 v26, v38, v39
	v_fmac_f32_e32 v41, v27, v31
	v_cvt_pk_bf16_f32 v27, v40, v41
	global_store_dwordx4 v[32:33], v[24:27], off
	v_lshlrev_b32_e32 v38, 16, v82
	v_and_b32_e32 v39, 0xffff0000, v82
	v_lshlrev_b32_e32 v24, 16, v84
	v_and_b32_e32 v25, 0xffff0000, v84
	v_lshlrev_b32_e32 v26, 16, v85
	v_fmac_f32_e32 v24, v20, v34
	v_fmac_f32_e32 v25, v21, v35
	v_fmac_f32_e32 v26, v22, v36
	v_add_f32_e32 v20, 1.0, v37
; __device__ __forceinline__ float sigmoidf_(float x) { return __builtin_amdgcn_rcpf(1.0f + __expf(-x)); }
; __device__ __forceinline__ u32x4 pack8(const float (&f)[8]) { u32x4 w; w.x = cvt_pk_bf16(f[0], f[1]); w.y = cvt_pk_bf16(f[2], f[3]); w.z = cvt_pk_bf16(f[4], f[5]); w.w = cvt_pk_bf16(f[6], f[7]); return w; }
; #define PG8_WAIT_V(n) asm volatile("s_waitcnt vmcnt(" #n ")" ::: "memory")
; #define PG8_BAR __builtin_amdgcn_s_barrier()
; template <class Epi>
; __device__ __forceinline__ void gemm_phase(PG8_LAS unsigned char* lds, const Gemm g, const StaticOrder& S, const Epi& E) {
;     ...
;         if (!has_next) break;
; #pragma unroll
;         for (int a = 0; a < 2; ++a)
; #pragma unroll
;             for (int b = 0; b < 2; ++b)
; #pragma unroll
;                 for (int m = 0; m < 4; ++m)
; #pragma unroll
;                     for (int n = 0; n < 2; ++n) acc[a][b][m][n] = (f32x4){0.f, 0.f, 0.f, 0.f};
;         cur = nxt; cA = nA; cB = nB; ++ui;
;     }
;     PG8_WAIT_V(0);
;     if (wr == 0) PG8_BAR;
;     PG8_BAR;
;     __device__ __forceinline__ void operator()(const f32x4 (&acc)[2][2][4][2], const pg8::Unit& u, int wr, int wc, int fr, int fq) const {
;     ...
;                     float a[8], gt[8], o[8];
;                     unpack8(la[m][bj], a);
;                     if (mode == 0) {
; #pragma unroll
;                         for (int n = 0; n < 2; ++n)
; #pragma unroll
;                             for (int i = 0; i < 4; ++i) o[n * 4 + i] = sigmoidf_(a[n * 4 + i]) * acc[ai][bj][m][n][i];
;                     } else {
;                         unpack8(lg[m][bj], gt);
; #pragma unroll
;                         for (int n = 0; n < 2; ++n)
; #pragma unroll
;                             for (int i = 0; i < 4; ++i) o[n * 4 + i] = a[n * 4 + i] + sigmoidf_(gt[n * 4 + i]) * acc[ai][bj][m][n][i];
;                     }
;                     *(u32x4*)p = pack8(o);
	v_mul_f32_e32 v21, 0xbfb8aa3b, v38
	v_mul_f32_e32 v22, 0xbfb8aa3b, v39
	v_rcp_f32_e32 v20, v20
	v_exp_f32_e32 v21, v21
	v_exp_f32_e32 v22, v22
	v_and_b32_e32 v27, 0xffff0000, v85
	v_lshlrev_b32_e32 v40, 16, v83
	v_fmac_f32_e32 v27, v23, v20
	v_add_f32_e32 v20, 1.0, v21
	v_add_f32_e32 v21, 1.0, v22
	v_mul_f32_e32 v22, 0xbfb8aa3b, v40
	v_exp_f32_e32 v22, v22
	v_rcp_f32_e32 v20, v20
	v_rcp_f32_e32 v21, v21
	v_lshlrev_b32_e32 v28, 16, v86
	v_add_f32_e32 v22, 1.0, v22
	v_rcp_f32_e32 v22, v22
	v_and_b32_e32 v41, 0xffff0000, v83
	v_and_b32_e32 v29, 0xffff0000, v86
	v_lshlrev_b32_e32 v30, 16, v87
	v_mul_f32_e32 v23, 0xbfb8aa3b, v41
	v_fmac_f32_e32 v28, v16, v20
	v_exp_f32_e32 v23, v23
	v_fmac_f32_e32 v29, v17, v21
	v_fmac_f32_e32 v30, v18, v22
	v_cvt_pk_bf16_f32 v16, v24, v25
	v_cvt_pk_bf16_f32 v17, v26, v27
	v_cvt_pk_bf16_f32 v18, v28, v29
	v_lshlrev_b32_e32 v26, 16, v72
	v_and_b32_e32 v27, 0xffff0000, v72
	v_lshlrev_b32_e32 v28, 16, v73
	v_mul_f32_e32 v26, 0xbfb8aa3b, v26
	v_mul_f32_e32 v27, 0xbfb8aa3b, v27
	v_mul_f32_e32 v28, 0xbfb8aa3b, v28
	v_exp_f32_e32 v26, v26
	v_exp_f32_e32 v27, v27
	v_exp_f32_e32 v28, v28
	v_add_f32_e32 v23, 1.0, v23
	v_rcp_f32_e32 v23, v23
	v_and_b32_e32 v29, 0xffff0000, v73
	v_add_f32_e32 v26, 1.0, v26
	v_add_f32_e32 v27, 1.0, v27
	v_add_f32_e32 v28, 1.0, v28
	v_mul_f32_e32 v29, 0xbfb8aa3b, v29
	v_rcp_f32_e32 v26, v26
	v_rcp_f32_e32 v27, v27
	v_rcp_f32_e32 v28, v28
	v_exp_f32_e32 v29, v29
	v_and_b32_e32 v31, 0xffff0000, v87
	v_fmac_f32_e32 v31, v19, v23
	v_cvt_pk_bf16_f32 v19, v30, v31
	global_store_dwordx4 v[32:33], v[16:19], off offset:256
	v_lshlrev_b32_e32 v20, 16, v77
	v_lshlrev_b32_e32 v30, 16, v74
	v_lshlrev_b32_e32 v18, 16, v76
	v_and_b32_e32 v19, 0xffff0000, v76
	v_and_b32_e32 v31, 0xffff0000, v74
	v_fmac_f32_e32 v18, v12, v26
	v_fmac_f32_e32 v19, v13, v27
	v_fmac_f32_e32 v20, v14, v28
	v_add_f32_e32 v12, 1.0, v29
	v_mul_f32_e32 v13, 0xbfb8aa3b, v30
	v_mul_f32_e32 v14, 0xbfb8aa3b, v31
	v_rcp_f32_e32 v12, v12
	v_exp_f32_e32 v13, v13
	v_exp_f32_e32 v14, v14
	v_and_b32_e32 v21, 0xffff0000, v77
	v_fmac_f32_e32 v21, v15, v12
	v_add_f32_e32 v12, 1.0, v13
	v_add_f32_e32 v13, 1.0, v14
	v_rcp_f32_e32 v12, v12
	v_rcp_f32_e32 v13, v13
	v_lshlrev_b32_e32 v32, 16, v75
	v_lshlrev_b32_e32 v22, 16, v78
	v_and_b32_e32 v23, 0xffff0000, v78
	v_and_b32_e32 v33, 0xffff0000, v75
	v_mul_f32_e32 v14, 0xbfb8aa3b, v32
	v_exp_f32_e32 v14, v14
	v_mul_f32_e32 v15, 0xbfb8aa3b, v33
	v_fmac_f32_e32 v22, v8, v12
	v_fmac_f32_e32 v23, v9, v13
	v_cvt_pk_bf16_f32 v8, v18, v19
	v_cvt_pk_bf16_f32 v9, v20, v21
	v_lshlrev_b32_e32 v18, 16, v64
	v_and_b32_e32 v19, 0xffff0000, v64
	v_lshlrev_b32_e32 v20, 16, v65
	v_exp_f32_e32 v15, v15
	v_mul_f32_e32 v18, 0xbfb8aa3b, v18
	v_mul_f32_e32 v19, 0xbfb8aa3b, v19
	v_mul_f32_e32 v20, 0xbfb8aa3b, v20
	v_exp_f32_e32 v18, v18
	v_exp_f32_e32 v19, v19
	v_exp_f32_e32 v20, v20
	v_add_f32_e32 v14, 1.0, v14
	v_rcp_f32_e32 v14, v14
	v_add_f32_e32 v15, 1.0, v15
	v_and_b32_e32 v21, 0xffff0000, v65
	v_rcp_f32_e32 v15, v15
	v_add_f32_e32 v18, 1.0, v18
	v_add_f32_e32 v19, 1.0, v19
	v_add_f32_e32 v20, 1.0, v20
	v_mul_f32_e32 v21, 0xbfb8aa3b, v21
	v_rcp_f32_e32 v18, v18
	v_rcp_f32_e32 v19, v19
	v_rcp_f32_e32 v20, v20
	v_exp_f32_e32 v21, v21
	v_lshl_add_u64 v[16:17], s[46:47], 0, v[104:105]
	v_lshlrev_b32_e32 v24, 16, v79
	v_lshl_add_u64 v[16:17], v[16:17], 0, v[186:187]
	v_and_b32_e32 v25, 0xffff0000, v79
	v_fmac_f32_e32 v24, v10, v14
	v_cvt_pk_bf16_f32 v10, v22, v23
	v_fmac_f32_e32 v25, v11, v15
	v_cvt_pk_bf16_f32 v11, v24, v25
	global_store_dwordx4 v[16:17], v[8:11], off
	v_lshlrev_b32_e32 v22, 16, v66
	v_and_b32_e32 v23, 0xffff0000, v66
	v_lshlrev_b32_e32 v8, 16, v68
	v_and_b32_e32 v9, 0xffff0000, v68
	v_lshlrev_b32_e32 v10, 16, v69
	v_fmac_f32_e32 v8, v4, v18
	v_fmac_f32_e32 v9, v5, v19
	v_fmac_f32_e32 v10, v6, v20
	v_add_f32_e32 v4, 1.0, v21
	v_mul_f32_e32 v5, 0xbfb8aa3b, v22
	v_mul_f32_e32 v6, 0xbfb8aa3b, v23
	v_rcp_f32_e32 v4, v4
	v_exp_f32_e32 v5, v5
	v_exp_f32_e32 v6, v6
	v_and_b32_e32 v11, 0xffff0000, v69
	v_lshlrev_b32_e32 v24, 16, v67
	v_and_b32_e32 v25, 0xffff0000, v67
	v_fmac_f32_e32 v11, v7, v4
	v_add_f32_e32 v4, 1.0, v5
	v_add_f32_e32 v5, 1.0, v6
	v_mul_f32_e32 v6, 0xbfb8aa3b, v24
	v_mul_f32_e32 v7, 0xbfb8aa3b, v25
	v_exp_f32_e32 v6, v6
	v_exp_f32_e32 v7, v7
	v_rcp_f32_e32 v4, v4
	v_rcp_f32_e32 v5, v5
	v_add_f32_e32 v6, 1.0, v6
	v_add_f32_e32 v7, 1.0, v7
	v_rcp_f32_e32 v6, v6
	v_rcp_f32_e32 v7, v7
	v_lshlrev_b32_e32 v12, 16, v70
	v_and_b32_e32 v13, 0xffff0000, v70
	v_lshlrev_b32_e32 v14, 16, v71
	v_and_b32_e32 v15, 0xffff0000, v71
	v_fmac_f32_e32 v12, v0, v4
	v_fmac_f32_e32 v13, v1, v5
	v_fmac_f32_e32 v14, v2, v6
	v_fmac_f32_e32 v15, v3, v7
	v_cvt_pk_bf16_f32 v0, v8, v9
	v_cvt_pk_bf16_f32 v1, v10, v11
	v_cvt_pk_bf16_f32 v2, v12, v13
	v_cvt_pk_bf16_f32 v3, v14, v15
	global_store_dwordx4 v[16:17], v[0:3], off offset:256
	s_cbranch_vccz .LBB0_918
	s_waitcnt vmcnt(0)
	s_cmpk_gt_u32 s36, 0xff
	s_cbranch_scc1 .LBB0_929
	s_barrier

; __device__ __forceinline__ unsigned xb_ld(unsigned* p)              { return __hip_atomic_load(p, __ATOMIC_RELAXED, __HIP_MEMORY_SCOPE_AGENT); }
; __device__ __forceinline__ void xcd_barrier_complete(unsigned* bar, unsigned x, unsigned& nloc, unsigned& nx) {
;     const unsigned G = gridDim.x * gridDim.y * gridDim.z;
;     unsigned sum, cnt, mine, sp = 0u;
;     for (;;) {
;         sum = 0u; cnt = 0u; mine = 0u;
; #pragma unroll
;         for (unsigned j = 0; j < 16; ++j) { const unsigned c = xb_ld(&bar[XB_XCNT(j)]); sum += c; cnt += (c > 0u) ? 1u : 0u; mine = (j == x) ? c : mine; }
; __device__ __forceinline__ void xcd_barrier(const XcdBarrier& b) {
;     asm volatile("s_waitcnt vmcnt(0)" ::: "memory");
;     __syncthreads();
;     if (threadIdx.x == 0) {
;         unsigned* bar = b.bar;
;         __builtin_amdgcn_s_waitcnt(0);
;         unsigned nloc = b.st[0], nx = b.st[1];
;         if (nloc == 0u) { xcd_barrier_complete(bar, b.x, nloc, nx); b.st[0] = nloc; b.st[1] = nx; }
.LBB0_930:
	s_setprio 0
	s_cmp_gt_i32 s75, 8
	s_cselect_b64 s[2:3], -1, 0
	s_and_b64 s[0:1], s[0:1], s[2:3]
	s_andn2_b64 vcc, exec, s[0:1]
	s_cbranch_vccnz .LBB0_984
	s_waitcnt vmcnt(0)
	s_waitcnt vmcnt(0) lgkmcnt(0)
	s_barrier
	s_mov_b64 s[0:1], exec
	v_readlane_b32 s4, v253, 8
	v_readlane_b32 s5, v253, 9
	s_and_b64 s[4:5], s[0:1], s[4:5]
	s_mov_b64 exec, s[4:5]
	s_cbranch_execz .LBB0_983
	s_add_i32 s4, 0, 0x24000
	v_mov_b32_e32 v0, s4
	s_waitcnt vmcnt(0) expcnt(0) lgkmcnt(0)
	ds_read_b32 v2, v0
	s_add_i32 s4, 0, 0x24004
	v_mov_b32_e32 v0, s4
	ds_read_b32 v0, v0
	s_waitcnt lgkmcnt(1)
	v_cmp_ne_u32_e32 vcc, 0, v2
	s_cbranch_vccnz .LBB0_947
	s_add_u32 s4, s80, 0x1e7fae00
	s_addc_u32 s5, s81, 0
	s_add_u32 s6, s80, 0x1e7fb000
	s_addc_u32 s7, s81, 0
	s_add_u32 s8, s80, 0x1e7fb100
	s_addc_u32 s9, s81, 0
	s_add_u32 s10, s80, 0x1e7fb200
	s_addc_u32 s11, s81, 0
	s_add_u32 s12, s80, 0x1e7fb300
	s_addc_u32 s13, s81, 0
	s_add_u32 s14, s80, 0x1e7fb400
	s_addc_u32 s15, s81, 0
	s_add_u32 s16, s80, 0x1e7fb500
	s_addc_u32 s17, s81, 0
	s_add_u32 s18, s80, 0x1e7fb600
	s_addc_u32 s19, s81, 0
	s_add_u32 s20, s80, 0x1e7fb700
	s_addc_u32 s21, s81, 0
	s_add_u32 s22, s80, 0x1e7fb800
	s_addc_u32 s23, s81, 0
	s_add_u32 s28, s80, 0x1e7fb900
	s_addc_u32 s29, s81, 0
	s_add_u32 s30, s80, 0x1e7fba00
	s_addc_u32 s31, s81, 0
	s_add_u32 s34, s80, 0x1e7fbb00
	s_addc_u32 s35, s81, 0
	s_add_u32 s36, s80, 0x1e7fbc00
	s_addc_u32 s37, s81, 0
	s_add_u32 s38, s80, 0x1e7fbd00
	s_addc_u32 s39, s81, 0
	s_add_u32 s40, s80, 0x1e7fbe00
	s_addc_u32 s41, s81, 0
	s_mul_i32 s54, s27, s33
	s_add_u32 s42, s80, 0x1e7fbf00
	s_mul_i32 s54, s54, s26
	s_addc_u32 s43, s81, 0
	s_mov_b32 s55, 1
	v_mov_b32_e32 v16, 0
	s_branch .LBB0_935

; #define PG8_STAGE(bufoff, gbase, voff) do { _Pragma("unroll") for (int _i = 0; _i < 2; ++_i) \
;         __builtin_amdgcn_global_load_lds((const unsigned*)((const char*)(gbase) + (voff)[_i]), (PG8_LAS unsigned*)(lds + (bufoff) + ldsw + _i * 8192), 16, 0, 0); } while (0)
; #define PG8_LDA(dst, b, h) do { _Pragma("unroll") for (int m = 0; m < 4; ++m) _Pragma("unroll") for (int k = 0; k < 2; ++k) dst[m][k] = *(const PG8_LAS bf16x8*)(lds + PG8_SA(b, h) + aoff + m * 2048 + k * 1024); } while (0)
; #define PG8_LDB(dst, b, h) do { _Pragma("unroll") for (int n = 0; n < 2; ++n) _Pragma("unroll") for (int k = 0; k < 2; ++k) dst[n][k] = *(const PG8_LAS bf16x8*)(lds + PG8_SB(b, h) + boff + n * 2048 + k * 1024); } while (0)
; #define PG8_MMA(ai, bj, At, Bt) do { __builtin_amdgcn_s_setprio(1); _Pragma("unroll") for (int m = 0; m < 4; ++m) _Pragma("unroll") for (int n = 0; n < 2; ++n) _Pragma("unroll") for (int k = 0; k < 2; ++k) \
;         acc[ai][bj][m][n] = __builtin_amdgcn_mfma_f32_16x16x32_bf16(Bt[n][k], At[m][k], acc[ai][bj][m][n], 0, 0, 0); __builtin_amdgcn_s_setprio(0); } while (0)
; #define PG8_BAR __builtin_amdgcn_s_barrier()
; template <class Epi>
; __device__ __forceinline__ void gemm_phase(PG8_LAS unsigned char* lds, const Gemm g, const StaticOrder& S, const Epi& E) {
;     ...
;             const char* a1 = cA + (size_t)(t + 1) * kstep;
;             const char* a2 = last ? nA : cA + (size_t)(t + 2) * kstep; const char* b2 = last ? nB : cB + (size_t)(t + 2) * kstep;
;             const char* a3 = a2 + kstep; const char* b3 = b2 + kstep;
;             PG8_LDB(B0, 0, 0); PG8_SCHED; PG8_LDA(At, 0, 0); PG8_STAGE(PG8_SA(1, 1), a1 + hstepA, voffA);
;             PG8_WAIT_L(8); PG8_BAR; PG8_WAIT_L(0); PG8_MMA(0, 0, At, B0); PG8_BAR; PG8_SCHED;
;             PG8_LDB(B1, 0, 1); PG8_STAGE(PG8_SB(0, 0), b2, voffB);
;             PG8_BAR; PG8_WAIT_L(0); PG8_MMA(0, 1, At, B1); PG8_BAR;
;             PG8_LDA(At, 0, 1); PG8_STAGE(PG8_SA(0, 0), a2, voffA);
;             PG8_BAR; PG8_WAIT_L(0); PG8_MMA(1, 0, At, B0); PG8_BAR; PG8_SCHED;
;             PG8_STAGE(PG8_SB(0, 1), b2 + hstepB, voffB);
;             PG8_WAIT_V(6); PG8_BAR; PG8_MMA(1, 1, At, B1); PG8_BAR;
;             PG8_LDB(B0, 1, 0); PG8_SCHED; PG8_LDA(At, 1, 0); PG8_STAGE(PG8_SA(0, 1), a2 + hstepA, voffA);
;             PG8_WAIT_L(8); PG8_BAR; PG8_WAIT_L(0); PG8_MMA(0, 0, At, B0); PG8_BAR; PG8_SCHED;
.Lsp_5:
.LBB0_1003:
	ds_read_b128 v[128:131], v190
	ds_read_b128 v[132:135], v190 offset:1024
	ds_read_b128 v[136:139], v190 offset:2048
	ds_read_b128 v[140:143], v190 offset:3072
	ds_read_b128 v[144:147], v191
	ds_read_b128 v[148:151], v191 offset:1024
	ds_read_b128 v[170:173], v191 offset:2048
	ds_read_b128 v[174:177], v191 offset:3072
	ds_read_b128 v[178:181], v191 offset:4096
	ds_read_b128 v[182:185], v191 offset:5120
	ds_read_b128 v[194:197], v191 offset:6144
	ds_read_b128 v[198:201], v191 offset:7168
	ds_read_b128 v[202:205], v192
	ds_read_b128 v[206:209], v192 offset:1024
	ds_read_b128 v[210:213], v192 offset:2048
	ds_read_b128 v[214:217], v192 offset:3072
	s_add_u32 s22, s28, 0xfff00080
	s_addc_u32 s23, s29, -1
	s_cmp_eq_u32 s56, 28
	s_cselect_b32 s31, s15, s23
	s_cselect_b32 s30, s21, s22
	s_cselect_b32 s23, s13, s55
	s_cselect_b32 s22, s53, s54
	v_lshl_add_u64 v[186:187], s[28:29], 0, v[160:161]
	s_add_i32 m0, s36, 0xc000
	s_nop 0
	global_load_lds_dwordx4 v[186:187], off
	v_lshl_add_u64 v[186:187], s[28:29], 0, v[162:163]
	s_add_i32 m0, s36, 0xe000
	s_nop 0
	global_load_lds_dwordx4 v[186:187], off
	s_waitcnt lgkmcnt(0)
	s_waitcnt vmcnt(8)
	s_barrier
	v_mfma_f32_16x16x32_bf16 v[124:127], v[128:131], v[144:147], v[124:127]
	v_mfma_f32_16x16x32_bf16 v[120:123], v[136:139], v[144:147], v[120:123]
	v_mfma_f32_16x16x32_bf16 v[104:107], v[128:131], v[170:173], v[104:107]
	v_mfma_f32_16x16x32_bf16 v[108:111], v[136:139], v[170:173], v[108:111]
	v_mfma_f32_16x16x32_bf16 v[88:91], v[128:131], v[178:181], v[88:91]
	v_mfma_f32_16x16x32_bf16 v[92:95], v[136:139], v[178:181], v[92:95]
	v_mfma_f32_16x16x32_bf16 v[72:75], v[128:131], v[194:197], v[72:75]
	v_mfma_f32_16x16x32_bf16 v[76:79], v[136:139], v[194:197], v[76:79]
	v_mfma_f32_16x16x32_bf16 v[124:127], v[132:135], v[148:151], v[124:127]
	v_mfma_f32_16x16x32_bf16 v[120:123], v[140:143], v[148:151], v[120:123]
	v_mfma_f32_16x16x32_bf16 v[104:107], v[132:135], v[174:177], v[104:107]
	v_mfma_f32_16x16x32_bf16 v[108:111], v[140:143], v[174:177], v[108:111]
	v_mfma_f32_16x16x32_bf16 v[88:91], v[132:135], v[182:185], v[88:91]
	v_mfma_f32_16x16x32_bf16 v[92:95], v[140:143], v[182:185], v[92:95]
	v_mfma_f32_16x16x32_bf16 v[72:75], v[132:135], v[198:201], v[72:75]
	v_mfma_f32_16x16x32_bf16 v[76:79], v[140:143], v[198:201], v[76:79]
	v_mfma_f32_16x16x32_bf16 v[116:119], v[202:205], v[144:147], v[116:119]
	v_mfma_f32_16x16x32_bf16 v[112:115], v[210:213], v[144:147], v[112:115]
	v_mfma_f32_16x16x32_bf16 v[100:103], v[202:205], v[170:173], v[100:103]
	v_mfma_f32_16x16x32_bf16 v[96:99], v[210:213], v[170:173], v[96:99]
	v_mfma_f32_16x16x32_bf16 v[84:87], v[202:205], v[178:181], v[84:87]
	v_mfma_f32_16x16x32_bf16 v[80:83], v[210:213], v[178:181], v[80:83]
	v_mfma_f32_16x16x32_bf16 v[68:71], v[202:205], v[194:197], v[68:71]
	v_mfma_f32_16x16x32_bf16 v[64:67], v[210:213], v[194:197], v[64:67]
	v_mfma_f32_16x16x32_bf16 v[116:119], v[206:209], v[148:151], v[116:119]
	v_mfma_f32_16x16x32_bf16 v[112:115], v[214:217], v[148:151], v[112:115]
	v_mfma_f32_16x16x32_bf16 v[100:103], v[206:209], v[174:177], v[100:103]
	v_mfma_f32_16x16x32_bf16 v[96:99], v[214:217], v[174:177], v[96:99]
	v_mfma_f32_16x16x32_bf16 v[84:87], v[206:209], v[182:185], v[84:87]
	v_mfma_f32_16x16x32_bf16 v[80:83], v[214:217], v[182:185], v[80:83]
	v_mfma_f32_16x16x32_bf16 v[68:71], v[206:209], v[198:201], v[68:71]
	v_mfma_f32_16x16x32_bf16 v[64:67], v[214:217], v[198:201], v[64:67]
	s_barrier
	ds_read_b128 v[144:147], v191 offset:16384
	ds_read_b128 v[148:151], v191 offset:17408
	ds_read_b128 v[170:173], v191 offset:18432
	ds_read_b128 v[174:177], v191 offset:19456
	ds_read_b128 v[178:181], v191 offset:20480
	ds_read_b128 v[182:185], v191 offset:21504
	ds_read_b128 v[194:197], v191 offset:22528
	ds_read_b128 v[198:201], v191 offset:23552
	s_add_i32 s57, s50, s35
	v_lshl_add_u64 v[186:187], s[22:23], 0, v[154:155]
	s_mov_b32 m0, s57
	s_nop 0
	global_load_lds_dwordx4 v[186:187], off
	v_lshl_add_u64 v[218:219], s[22:23], 0, v[158:159]
	s_add_i32 m0, s57, 0x2000
	s_nop 0
	global_load_lds_dwordx4 v[218:219], off
	s_mov_b32 m0, s36
	v_lshl_add_u64 v[220:221], s[30:31], 0, v[152:153]
	global_load_lds_dwordx4 v[220:221], off
	v_lshl_add_u64 v[222:223], s[30:31], 0, v[156:157]
	s_mov_b32 m0, s37
	s_nop 0
	global_load_lds_dwordx4 v[222:223], off
	s_add_u32 s58, s22, 0x80000
	s_addc_u32 s59, s23, 0
	s_add_i32 s57, s51, s35
	v_lshl_add_u64 v[224:225], s[58:59], 0, v[154:155]
	s_mov_b32 m0, s57
	s_nop 0
	global_load_lds_dwordx4 v[224:225], off
	v_lshl_add_u64 v[224:225], s[58:59], 0, v[158:159]
	s_add_i32 m0, s57, 0x2000
	s_nop 0
	global_load_lds_dwordx4 v[224:225], off
	s_waitcnt lgkmcnt(0)
	s_waitcnt vmcnt(8)
	s_barrier
; #define PG8_STAGE(bufoff, gbase, voff) do { _Pragma("unroll") for (int _i = 0; _i < 2; ++_i) \
;         __builtin_amdgcn_global_load_lds((const unsigned*)((const char*)(gbase) + (voff)[_i]), (PG8_LAS unsigned*)(lds + (bufoff) + ldsw + _i * 8192), 16, 0, 0); } while (0)
; #define PG8_LDA(dst, b, h) do { _Pragma("unroll") for (int m = 0; m < 4; ++m) _Pragma("unroll") for (int k = 0; k < 2; ++k) dst[m][k] = *(const PG8_LAS bf16x8*)(lds + PG8_SA(b, h) + aoff + m * 2048 + k * 1024); } while (0)
; #define PG8_LDB(dst, b, h) do { _Pragma("unroll") for (int n = 0; n < 2; ++n) _Pragma("unroll") for (int k = 0; k < 2; ++k) dst[n][k] = *(const PG8_LAS bf16x8*)(lds + PG8_SB(b, h) + boff + n * 2048 + k * 1024); } while (0)
; #define PG8_MMA(ai, bj, At, Bt) do { __builtin_amdgcn_s_setprio(1); _Pragma("unroll") for (int m = 0; m < 4; ++m) _Pragma("unroll") for (int n = 0; n < 2; ++n) _Pragma("unroll") for (int k = 0; k < 2; ++k) \
;         acc[ai][bj][m][n] = __builtin_amdgcn_mfma_f32_16x16x32_bf16(Bt[n][k], At[m][k], acc[ai][bj][m][n], 0, 0, 0); __builtin_amdgcn_s_setprio(0); } while (0)
; #define PG8_WAIT_V(n) asm volatile("s_waitcnt vmcnt(" #n ")" ::: "memory")
; #define PG8_WAIT_L(n) asm volatile("s_waitcnt lgkmcnt(" #n ")" ::: "memory")
; #define PG8_BAR __builtin_amdgcn_s_barrier()
; #define PG8_SCHED __builtin_amdgcn_sched_barrier(0)
; template <class Epi>
; __device__ __forceinline__ void gemm_phase(PG8_LAS unsigned char* lds, const Gemm g, const StaticOrder& S, const Epi& E) {
;     ...
;             PG8_BAR; PG8_WAIT_L(0); PG8_MMA(0, 1, At, B1); PG8_BAR;
;             PG8_LDA(At, 0, 1); PG8_STAGE(PG8_SA(0, 0), a2, voffA);
;             PG8_BAR; PG8_WAIT_L(0); PG8_MMA(1, 0, At, B0); PG8_BAR; PG8_SCHED;
;             PG8_STAGE(PG8_SB(0, 1), b2 + hstepB, voffB);
;             PG8_WAIT_V(6); PG8_BAR; PG8_MMA(1, 1, At, B1); PG8_BAR;
;             PG8_LDB(B0, 1, 0); PG8_SCHED; PG8_LDA(At, 1, 0); PG8_STAGE(PG8_SA(0, 1), a2 + hstepA, voffA);
;             PG8_WAIT_L(8); PG8_BAR; PG8_WAIT_L(0); PG8_MMA(0, 0, At, B0); PG8_BAR; PG8_SCHED;
	v_mfma_f32_16x16x32_bf16 v[60:63], v[128:131], v[144:147], v[60:63]
	v_mfma_f32_16x16x32_bf16 v[56:59], v[136:139], v[144:147], v[56:59]
	v_mfma_f32_16x16x32_bf16 v[40:43], v[128:131], v[170:173], v[40:43]
	v_mfma_f32_16x16x32_bf16 v[44:47], v[136:139], v[170:173], v[44:47]
	v_mfma_f32_16x16x32_bf16 v[24:27], v[128:131], v[178:181], v[24:27]
	v_mfma_f32_16x16x32_bf16 v[28:31], v[136:139], v[178:181], v[28:31]
	v_mfma_f32_16x16x32_bf16 v[8:11], v[128:131], v[194:197], v[8:11]
	v_mfma_f32_16x16x32_bf16 v[12:15], v[136:139], v[194:197], v[12:15]
	v_mfma_f32_16x16x32_bf16 v[60:63], v[132:135], v[148:151], v[60:63]
	v_mfma_f32_16x16x32_bf16 v[56:59], v[140:143], v[148:151], v[56:59]
	v_mfma_f32_16x16x32_bf16 v[40:43], v[132:135], v[174:177], v[40:43]
	v_mfma_f32_16x16x32_bf16 v[44:47], v[140:143], v[174:177], v[44:47]
	v_mfma_f32_16x16x32_bf16 v[24:27], v[132:135], v[182:185], v[24:27]
	v_mfma_f32_16x16x32_bf16 v[28:31], v[140:143], v[182:185], v[28:31]
	v_mfma_f32_16x16x32_bf16 v[8:11], v[132:135], v[198:201], v[8:11]
	v_mfma_f32_16x16x32_bf16 v[12:15], v[140:143], v[198:201], v[12:15]
	v_mfma_f32_16x16x32_bf16 v[52:55], v[202:205], v[144:147], v[52:55]
	v_mfma_f32_16x16x32_bf16 v[48:51], v[210:213], v[144:147], v[48:51]
	v_mfma_f32_16x16x32_bf16 v[36:39], v[202:205], v[170:173], v[36:39]
	v_mfma_f32_16x16x32_bf16 v[32:35], v[210:213], v[170:173], v[32:35]
	v_mfma_f32_16x16x32_bf16 v[20:23], v[202:205], v[178:181], v[20:23]
	v_mfma_f32_16x16x32_bf16 v[16:19], v[210:213], v[178:181], v[16:19]
	v_mfma_f32_16x16x32_bf16 v[4:7], v[202:205], v[194:197], v[4:7]
	v_mfma_f32_16x16x32_bf16 v[0:3], v[210:213], v[194:197], v[0:3]
	v_mfma_f32_16x16x32_bf16 v[52:55], v[206:209], v[148:151], v[52:55]
	v_mfma_f32_16x16x32_bf16 v[48:51], v[214:217], v[148:151], v[48:51]
	v_mfma_f32_16x16x32_bf16 v[36:39], v[206:209], v[174:177], v[36:39]
	v_mfma_f32_16x16x32_bf16 v[32:35], v[214:217], v[174:177], v[32:35]
	v_mfma_f32_16x16x32_bf16 v[20:23], v[206:209], v[182:185], v[20:23]
	v_mfma_f32_16x16x32_bf16 v[16:19], v[214:217], v[182:185], v[16:19]
	v_mfma_f32_16x16x32_bf16 v[4:7], v[206:209], v[198:201], v[4:7]
	v_mfma_f32_16x16x32_bf16 v[0:3], v[214:217], v[198:201], v[0:3]
	s_add_i32 s57, 0, 0x18000
	v_add_u32_e32 v140, s57, v188
	s_barrier
	ds_read_b128 v[128:131], v140
	ds_read_b128 v[132:135], v140 offset:1024
	ds_read_b128 v[136:139], v140 offset:2048
	ds_read_b128 v[140:143], v140 offset:3072
	ds_read_b128 v[144:147], v191 offset:32768
	ds_read_b128 v[148:151], v191 offset:33792
	ds_read_b128 v[170:173], v191 offset:34816
	ds_read_b128 v[174:177], v191 offset:35840
	ds_read_b128 v[178:181], v191 offset:36864
	ds_read_b128 v[182:185], v191 offset:37888
	ds_read_b128 v[194:197], v191 offset:38912
	ds_read_b128 v[198:201], v191 offset:39936
	v_add_u32_e32 v214, 0x1c000, v188
	ds_read_b128 v[202:205], v214
	ds_read_b128 v[206:209], v214 offset:1024
	ds_read_b128 v[210:213], v214 offset:2048
	ds_read_b128 v[214:217], v214 offset:3072
	s_add_u32 s30, s30, 0x100000
	s_addc_u32 s31, s31, 0
	s_mov_b32 m0, s38
	v_lshl_add_u64 v[224:225], s[30:31], 0, v[152:153]
	global_load_lds_dwordx4 v[224:225], off
	v_lshl_add_u64 v[224:225], s[30:31], 0, v[156:157]
	s_mov_b32 m0, s39
	s_nop 0
	global_load_lds_dwordx4 v[224:225], off
	s_waitcnt lgkmcnt(0)
	s_waitcnt vmcnt(8)
	s_barrier
	v_mfma_f32_16x16x32_bf16 v[124:127], v[128:131], v[144:147], v[124:127]
	v_mfma_f32_16x16x32_bf16 v[120:123], v[136:139], v[144:147], v[120:123]
	v_mfma_f32_16x16x32_bf16 v[104:107], v[128:131], v[170:173], v[104:107]
	v_mfma_f32_16x16x32_bf16 v[108:111], v[136:139], v[170:173], v[108:111]
	v_mfma_f32_16x16x32_bf16 v[88:91], v[128:131], v[178:181], v[88:91]
	v_mfma_f32_16x16x32_bf16 v[92:95], v[136:139], v[178:181], v[92:95]
	v_mfma_f32_16x16x32_bf16 v[72:75], v[128:131], v[194:197], v[72:75]
	v_mfma_f32_16x16x32_bf16 v[76:79], v[136:139], v[194:197], v[76:79]
	v_mfma_f32_16x16x32_bf16 v[124:127], v[132:135], v[148:151], v[124:127]
	v_mfma_f32_16x16x32_bf16 v[120:123], v[140:143], v[148:151], v[120:123]
	v_mfma_f32_16x16x32_bf16 v[104:107], v[132:135], v[174:177], v[104:107]
	v_mfma_f32_16x16x32_bf16 v[108:111], v[140:143], v[174:177], v[108:111]
	v_mfma_f32_16x16x32_bf16 v[88:91], v[132:135], v[182:185], v[88:91]
	v_mfma_f32_16x16x32_bf16 v[92:95], v[140:143], v[182:185], v[92:95]
	v_mfma_f32_16x16x32_bf16 v[72:75], v[132:135], v[198:201], v[72:75]
	v_mfma_f32_16x16x32_bf16 v[76:79], v[140:143], v[198:201], v[76:79]
	v_mfma_f32_16x16x32_bf16 v[116:119], v[202:205], v[144:147], v[116:119]
	v_mfma_f32_16x16x32_bf16 v[112:115], v[210:213], v[144:147], v[112:115]
	v_mfma_f32_16x16x32_bf16 v[100:103], v[202:205], v[170:173], v[100:103]
	v_mfma_f32_16x16x32_bf16 v[96:99], v[210:213], v[170:173], v[96:99]
	v_mfma_f32_16x16x32_bf16 v[84:87], v[202:205], v[178:181], v[84:87]
	v_mfma_f32_16x16x32_bf16 v[80:83], v[210:213], v[178:181], v[80:83]
	v_mfma_f32_16x16x32_bf16 v[68:71], v[202:205], v[194:197], v[68:71]
	v_mfma_f32_16x16x32_bf16 v[64:67], v[210:213], v[194:197], v[64:67]
	v_mfma_f32_16x16x32_bf16 v[116:119], v[206:209], v[148:151], v[116:119]
	v_mfma_f32_16x16x32_bf16 v[112:115], v[214:217], v[148:151], v[112:115]
	v_mfma_f32_16x16x32_bf16 v[100:103], v[206:209], v[174:177], v[100:103]
	v_mfma_f32_16x16x32_bf16 v[96:99], v[214:217], v[174:177], v[96:99]
	v_mfma_f32_16x16x32_bf16 v[84:87], v[206:209], v[182:185], v[84:87]
	v_mfma_f32_16x16x32_bf16 v[80:83], v[214:217], v[182:185], v[80:83]
	v_mfma_f32_16x16x32_bf16 v[68:71], v[206:209], v[198:201], v[68:71]
	v_mfma_f32_16x16x32_bf16 v[64:67], v[214:217], v[198:201], v[64:67]
	s_barrier
; #define PG8_STAGE(bufoff, gbase, voff) do { _Pragma("unroll") for (int _i = 0; _i < 2; ++_i) \
;         __builtin_amdgcn_global_load_lds((const unsigned*)((const char*)(gbase) + (voff)[_i]), (PG8_LAS unsigned*)(lds + (bufoff) + ldsw + _i * 8192), 16, 0, 0); } while (0)
; #define PG8_LDA(dst, b, h) do { _Pragma("unroll") for (int m = 0; m < 4; ++m) _Pragma("unroll") for (int k = 0; k < 2; ++k) dst[m][k] = *(const PG8_LAS bf16x8*)(lds + PG8_SA(b, h) + aoff + m * 2048 + k * 1024); } while (0)
; #define PG8_LDB(dst, b, h) do { _Pragma("unroll") for (int n = 0; n < 2; ++n) _Pragma("unroll") for (int k = 0; k < 2; ++k) dst[n][k] = *(const PG8_LAS bf16x8*)(lds + PG8_SB(b, h) + boff + n * 2048 + k * 1024); } while (0)
; #define PG8_MMA(ai, bj, At, Bt) do { __builtin_amdgcn_s_setprio(1); _Pragma("unroll") for (int m = 0; m < 4; ++m) _Pragma("unroll") for (int n = 0; n < 2; ++n) _Pragma("unroll") for (int k = 0; k < 2; ++k) \
;         acc[ai][bj][m][n] = __builtin_amdgcn_mfma_f32_16x16x32_bf16(Bt[n][k], At[m][k], acc[ai][bj][m][n], 0, 0, 0); __builtin_amdgcn_s_setprio(0); } while (0)
; #define PG8_WAIT_V(n) asm volatile("s_waitcnt vmcnt(" #n ")" ::: "memory")
; #define PG8_WAIT_L(n) asm volatile("s_waitcnt lgkmcnt(" #n ")" ::: "memory")
; #define PG8_BAR __builtin_amdgcn_s_barrier()
; #define PG8_SCHED __builtin_amdgcn_sched_barrier(0)
; template <class Epi>
; __device__ __forceinline__ void gemm_phase(PG8_LAS unsigned char* lds, const Gemm g, const StaticOrder& S, const Epi& E) {
;     ...
;             PG8_LDB(B1, 1, 1); PG8_STAGE(PG8_SB(1, 0), b3, voffB);
;             PG8_BAR; PG8_WAIT_L(0); PG8_MMA(0, 1, At, B1); PG8_BAR;
;             PG8_LDA(At, 1, 1); PG8_STAGE(PG8_SA(1, 0), a3, voffA);
;             PG8_BAR; PG8_WAIT_L(0); PG8_MMA(1, 0, At, B0); PG8_BAR; PG8_SCHED;
;             PG8_STAGE(PG8_SB(1, 1), b3 + hstepB, voffB);
;             PG8_WAIT_V(6); PG8_BAR; PG8_MMA(1, 1, At, B1); PG8_BAR;
	ds_read_b128 v[144:147], v191 offset:49152
	ds_read_b128 v[148:151], v191 offset:50176
	ds_read_b128 v[170:173], v191 offset:51200
	ds_read_b128 v[174:177], v191 offset:52224
	ds_read_b128 v[178:181], v191 offset:53248
	ds_read_b128 v[182:185], v191 offset:54272
	ds_read_b128 v[194:197], v191 offset:55296
	ds_read_b128 v[198:201], v191 offset:56320
	s_add_i32 s30, 0, 0x1c000
	s_add_i32 s31, s57, s35
	v_lshl_add_u64 v[186:187], v[186:187], 0, s[10:11]
	s_mov_b32 m0, s31
	s_nop 0
	global_load_lds_dwordx4 v[186:187], off
	v_lshl_add_u64 v[186:187], v[218:219], 0, s[10:11]
	s_add_i32 m0, s31, 0x2000
	s_nop 0
	global_load_lds_dwordx4 v[186:187], off
	s_mov_b32 m0, s41
	v_lshl_add_u64 v[186:187], v[220:221], 0, s[10:11]
	global_load_lds_dwordx4 v[186:187], off
	v_lshl_add_u64 v[186:187], v[222:223], 0, s[10:11]
	s_mov_b32 m0, s42
	s_nop 0
	global_load_lds_dwordx4 v[186:187], off
	s_add_u32 s22, s22, 0x80080
	s_addc_u32 s23, s23, 0
	s_add_i32 s30, s30, s35
	v_lshl_add_u64 v[224:225], s[22:23], 0, v[154:155]
	s_mov_b32 m0, s30
	s_nop 0
	global_load_lds_dwordx4 v[224:225], off
	v_lshl_add_u64 v[224:225], s[22:23], 0, v[158:159]
	s_add_i32 m0, s30, 0x2000
	s_nop 0
	global_load_lds_dwordx4 v[224:225], off
	s_waitcnt lgkmcnt(0)
	s_waitcnt vmcnt(8)
	s_barrier
	v_mfma_f32_16x16x32_bf16 v[60:63], v[128:131], v[144:147], v[60:63]
	v_mfma_f32_16x16x32_bf16 v[56:59], v[136:139], v[144:147], v[56:59]
	v_mfma_f32_16x16x32_bf16 v[40:43], v[128:131], v[170:173], v[40:43]
	v_mfma_f32_16x16x32_bf16 v[44:47], v[136:139], v[170:173], v[44:47]
	v_mfma_f32_16x16x32_bf16 v[24:27], v[128:131], v[178:181], v[24:27]
	v_mfma_f32_16x16x32_bf16 v[28:31], v[136:139], v[178:181], v[28:31]
	v_mfma_f32_16x16x32_bf16 v[8:11], v[128:131], v[194:197], v[8:11]
	v_mfma_f32_16x16x32_bf16 v[12:15], v[136:139], v[194:197], v[12:15]
	v_mfma_f32_16x16x32_bf16 v[60:63], v[132:135], v[148:151], v[60:63]
	v_mfma_f32_16x16x32_bf16 v[56:59], v[140:143], v[148:151], v[56:59]
	v_mfma_f32_16x16x32_bf16 v[40:43], v[132:135], v[174:177], v[40:43]
	v_mfma_f32_16x16x32_bf16 v[44:47], v[140:143], v[174:177], v[44:47]
	v_mfma_f32_16x16x32_bf16 v[24:27], v[132:135], v[182:185], v[24:27]
	v_mfma_f32_16x16x32_bf16 v[28:31], v[140:143], v[182:185], v[28:31]
	v_mfma_f32_16x16x32_bf16 v[8:11], v[132:135], v[198:201], v[8:11]
	v_mfma_f32_16x16x32_bf16 v[12:15], v[140:143], v[198:201], v[12:15]
	v_mfma_f32_16x16x32_bf16 v[52:55], v[202:205], v[144:147], v[52:55]
	v_mfma_f32_16x16x32_bf16 v[48:51], v[210:213], v[144:147], v[48:51]
	v_mfma_f32_16x16x32_bf16 v[36:39], v[202:205], v[170:173], v[36:39]
	v_mfma_f32_16x16x32_bf16 v[32:35], v[210:213], v[170:173], v[32:35]
	v_mfma_f32_16x16x32_bf16 v[20:23], v[202:205], v[178:181], v[20:23]
	v_mfma_f32_16x16x32_bf16 v[16:19], v[210:213], v[178:181], v[16:19]
	v_mfma_f32_16x16x32_bf16 v[4:7], v[202:205], v[194:197], v[4:7]
	v_mfma_f32_16x16x32_bf16 v[0:3], v[210:213], v[194:197], v[0:3]
	v_mfma_f32_16x16x32_bf16 v[52:55], v[206:209], v[148:151], v[52:55]
	v_mfma_f32_16x16x32_bf16 v[48:51], v[214:217], v[148:151], v[48:51]
	v_mfma_f32_16x16x32_bf16 v[36:39], v[206:209], v[174:177], v[36:39]
	v_mfma_f32_16x16x32_bf16 v[32:35], v[214:217], v[174:177], v[32:35]
	v_mfma_f32_16x16x32_bf16 v[20:23], v[206:209], v[182:185], v[20:23]
	v_mfma_f32_16x16x32_bf16 v[16:19], v[214:217], v[182:185], v[16:19]
	v_mfma_f32_16x16x32_bf16 v[4:7], v[206:209], v[198:201], v[4:7]
	v_mfma_f32_16x16x32_bf16 v[0:3], v[214:217], v[198:201], v[0:3]
	s_add_i32 s56, s56, 2
	s_add_u32 s28, s28, 0x100
	s_addc_u32 s29, s29, 0
	s_add_u32 s54, s54, 0x100
	s_addc_u32 s55, s55, 0
	s_cmp_gt_u32 s56, 29
	s_barrier
	s_cbranch_scc0 .LBB0_1003
; __device__ __forceinline__ u32x4 pack8(const float (&f)[8]) { u32x4 w; w.x = cvt_pk_bf16(f[0], f[1]); w.y = cvt_pk_bf16(f[2], f[3]); w.z = cvt_pk_bf16(f[4], f[5]); w.w = cvt_pk_bf16(f[6], f[7]); return w; }
;     __device__ __forceinline__ void operator()(const f32x4 (&acc)[2][2][4][2], const pg8::Unit& u, int wr, int wc, int fr, int fq) const {
;         const int row0 = u.pm * 256 + wr * 64 + fr, col0 = u.pn * 256 + wc * 32 + 8 * fq;
; #pragma unroll
;         for (int ai = 0; ai < 2; ++ai) {
;             u32x4 rb[4][2];
; #pragma unroll
;             for (int m = 0; m < 4; ++m)
; #pragma unroll
;                 for (int bj = 0; bj < 2; ++bj) rb[m][bj] = *(const u32x4*)(resb + (size_t)(row0 + ai * 128 + m * 16) * DM + col0 + bj * 128);
; #pragma unroll
;             for (int m = 0; m < 4; ++m) {
;                 const int r = row0 + ai * 128 + m * 16; float ss = 0.f;
; #pragma unroll
;                 for (int bj = 0; bj < 2; ++bj) {
;                     const size_t off = (size_t)r * DM + col0 + bj * 128;
;                     float rv[8], o[8]; unpack8(rb[m][bj], rv);
; #pragma unroll
;                     for (int n = 0; n < 2; ++n)
; #pragma unroll
;                         for (int i = 0; i < 4; ++i) o[n * 4 + i] = rv[n * 4 + i] + coef * acc[ai][bj][m][n][i];
;                     if (outf) { *(f32x4*)(outf + off) = (f32x4){o[0], o[1], o[2], o[3]}; *(f32x4*)(outf + off + 4) = (f32x4){o[4], o[5], o[6], o[7]}; }
;                     if (hb) { *(u32x4*)(hb + off) = pack8(o);
; #pragma unroll
;                         for (int i = 0; i < 8; ++i) ss += o[i] * o[i]; }
;                 }
;                 if (hb) { ss += __shfl_xor(ss, 16); ss += __shfl_xor(ss, 32); if (fq == 0) part[(size_t)r * 32 + u.pn * 4 + wc] = ss; }
	v_lshl_or_b32 v170, s8, 8, v189
	v_lshl_add_u32 v172, s20, 8, v169
	v_ashrrev_i32_e32 v171, 31, v170
	v_lshlrev_b64 v[204:205], 1, v[170:171]
	v_ashrrev_i32_e32 v173, 31, v172
	v_lshl_add_u64 v[174:175], s[76:77], 0, v[204:205]
	v_lshlrev_b64 v[194:195], 12, v[172:173]
	v_lshl_add_u64 v[128:129], v[174:175], 0, v[194:195]
	global_load_dwordx4 v[196:199], v[128:129], off
	global_load_dwordx4 v[200:203], v[128:129], off offset:256
	v_or_b32_e32 v184, 16, v172
	v_or_b32_e32 v180, 32, v172
	v_or_b32_e32 v176, 48, v172
	v_ashrrev_i32_e32 v185, 31, v184
	v_ashrrev_i32_e32 v181, 31, v180
	v_ashrrev_i32_e32 v177, 31, v176
	v_lshlrev_b64 v[186:187], 12, v[184:185]
	v_lshlrev_b64 v[182:183], 12, v[180:181]
	v_lshlrev_b64 v[178:179], 12, v[176:177]
	v_lshl_add_u64 v[128:129], v[174:175], 0, v[186:187]
	v_lshl_add_u64 v[130:131], v[174:175], 0, v[182:183]
	v_lshl_add_u64 v[206:207], v[174:175], 0, v[178:179]
	global_load_dwordx4 v[148:151], v[128:129], off
	global_load_dwordx4 v[144:147], v[128:129], off offset:256
	global_load_dwordx4 v[140:143], v[130:131], off
	global_load_dwordx4 v[136:139], v[130:131], off offset:256
	global_load_dwordx4 v[132:135], v[206:207], off
	s_nop 0
	global_load_dwordx4 v[128:131], v[206:207], off offset:256
	v_and_b32_e32 v207, 64, v193
	v_xor_b32_e32 v206, 16, v193
	v_add_u32_e32 v207, 64, v207
	v_xor_b32_e32 v208, 32, v193
	v_cmp_lt_i32_e32 vcc, v206, v207
	s_lshl_b32 s20, s8, 2
	s_ashr_i32 s21, s20, 31
	v_cndmask_b32_e32 v209, v193, v206, vcc
	v_cmp_lt_i32_e32 vcc, v208, v207
	v_lshl_add_u64 v[206:207], s[76:77], 0, v[194:195]
	v_lshl_add_u64 v[204:205], v[206:207], 0, v[204:205]
	v_lshlrev_b32_e32 v194, 2, v209
	v_cndmask_b32_e32 v208, v193, v208, vcc
	s_waitcnt vmcnt(0)
	v_lshlrev_b32_e32 v195, 16, v196
	v_and_b32_e32 v196, 0xffff0000, v196
	v_lshlrev_b32_e32 v212, 16, v202
	v_add_f32_e32 v125, v125, v196
	v_lshlrev_b32_e32 v206, 16, v197
	v_add_f32_e32 v124, v124, v195
	v_add_f32_e32 v195, v112, v212
	v_cvt_pk_bf16_f32 v112, v124, v125
	v_mul_f32_e32 v125, v125, v125
	v_and_b32_e32 v197, 0xffff0000, v197
	v_add_f32_e32 v126, v126, v206
	v_fmac_f32_e32 v125, v124, v124
	v_lshlrev_b32_e32 v207, 16, v198
	v_add_f32_e32 v127, v127, v197
	v_fmac_f32_e32 v125, v126, v126
	v_and_b32_e32 v198, 0xffff0000, v198
	v_add_f32_e32 v120, v120, v207
	v_fmac_f32_e32 v125, v127, v127
	v_lshlrev_b32_e32 v209, 16, v199
	v_add_f32_e32 v121, v121, v198
	v_fmac_f32_e32 v125, v120, v120
	v_and_b32_e32 v199, 0xffff0000, v199
	v_add_f32_e32 v122, v122, v209
	v_fmac_f32_e32 v125, v121, v121
	v_lshlrev_b32_e32 v210, 16, v200
	v_add_f32_e32 v123, v123, v199
	v_fmac_f32_e32 v125, v122, v122
	v_and_b32_e32 v200, 0xffff0000, v200
	v_add_f32_e32 v116, v116, v210
	v_fmac_f32_e32 v125, v123, v123
	v_lshlrev_b32_e32 v211, 16, v201
	v_add_f32_e32 v117, v117, v200
	v_fmac_f32_e32 v125, v116, v116
	v_and_b32_e32 v201, 0xffff0000, v201
	v_add_f32_e32 v118, v118, v211
	v_fmac_f32_e32 v125, v117, v117
	v_add_f32_e32 v119, v119, v201
	v_fmac_f32_e32 v125, v118, v118
	v_and_b32_e32 v202, 0xffff0000, v202
	v_fmac_f32_e32 v125, v119, v119
	v_lshlrev_b32_e32 v213, 16, v203
	v_add_f32_e32 v196, v113, v202
	v_fmac_f32_e32 v125, v195, v195
	v_and_b32_e32 v203, 0xffff0000, v203
	v_add_f32_e32 v197, v114, v213
	v_fmac_f32_e32 v125, v196, v196
	v_add_f32_e32 v198, v115, v203
	v_fmac_f32_e32 v125, v197, v197
	v_fmac_f32_e32 v125, v198, v198
	ds_bpermute_b32 v124, v194, v125
	v_cvt_pk_bf16_f32 v113, v126, v127
	v_cvt_pk_bf16_f32 v114, v120, v121
	v_cvt_pk_bf16_f32 v115, v122, v123
	global_store_dwordx4 v[204:205], v[112:115], off
	v_cvt_pk_bf16_f32 v116, v116, v117
	v_cvt_pk_bf16_f32 v117, v118, v119
	v_cvt_pk_bf16_f32 v118, v195, v196
	v_cvt_pk_bf16_f32 v119, v197, v198
	global_store_dwordx4 v[204:205], v[116:119], off offset:256
	s_waitcnt lgkmcnt(0)
	v_add_f32_e32 v113, v125, v124
	v_lshlrev_b32_e32 v112, 2, v208
	ds_bpermute_b32 v114, v112, v113
	s_and_saveexec_b64 s[22:23], s[2:3]
	s_cbranch_execz .LBB0_1006
	v_lshlrev_b64 v[116:117], 7, v[172:173]
	v_lshl_add_u64 v[116:117], s[0:1], 0, v[116:117]
	v_lshl_add_u64 v[116:117], s[20:21], 2, v[116:117]
	s_lshl_b32 s8, s40, 2
	v_lshl_add_u64 v[116:117], v[116:117], 0, s[8:9]
	s_waitcnt lgkmcnt(0)
	v_add_f32_e32 v113, v113, v114
	global_store_dword v[116:117], v113, off

; __device__ __forceinline__ unsigned xb_ld(unsigned* p)              { return __hip_atomic_load(p, __ATOMIC_RELAXED, __HIP_MEMORY_SCOPE_AGENT); }
; __device__ __forceinline__ void xcd_barrier_complete(unsigned* bar, unsigned x, unsigned& nloc, unsigned& nx) {
;     const unsigned G = gridDim.x * gridDim.y * gridDim.z;
;     unsigned sum, cnt, mine, sp = 0u;
;     for (;;) {
;         sum = 0u; cnt = 0u; mine = 0u;
; #pragma unroll
;         for (unsigned j = 0; j < 16; ++j) { const unsigned c = xb_ld(&bar[XB_XCNT(j)]); sum += c; cnt += (c > 0u) ? 1u : 0u; mine = (j == x) ? c : mine; }
; __device__ __forceinline__ void xcd_barrier(const XcdBarrier& b) {
;     asm volatile("s_waitcnt vmcnt(0)" ::: "memory");
;     __syncthreads();
;     if (threadIdx.x == 0) {
;         unsigned* bar = b.bar;
;         __builtin_amdgcn_s_waitcnt(0);
;         unsigned nloc = b.st[0], nx = b.st[1];
;         if (nloc == 0u) { xcd_barrier_complete(bar, b.x, nloc, nx); b.st[0] = nloc; b.st[1] = nx; }
.LBB0_1023:
	s_setprio 0
	s_cmp_gt_i32 s75, 9
	s_cselect_b64 s[2:3], -1, 0
	s_and_b64 s[4:5], s[6:7], s[2:3]
	s_andn2_b64 vcc, exec, s[4:5]
	s_cbranch_vccnz .LBB0_1077
	s_waitcnt vmcnt(0)
	s_waitcnt vmcnt(0) lgkmcnt(0)
	s_barrier
	s_mov_b64 s[4:5], exec
	v_readlane_b32 s6, v253, 8
	v_readlane_b32 s7, v253, 9
	s_and_b64 s[6:7], s[4:5], s[6:7]
	s_mov_b64 exec, s[6:7]
	s_cbranch_execz .LBB0_1076
	s_add_i32 s6, 0, 0x24000
	v_mov_b32_e32 v0, s6
	s_waitcnt vmcnt(0) expcnt(0) lgkmcnt(0)
	ds_read_b32 v2, v0
	s_add_i32 s6, 0, 0x24004
	v_mov_b32_e32 v0, s6
	ds_read_b32 v0, v0
	s_waitcnt lgkmcnt(1)
	v_cmp_ne_u32_e32 vcc, 0, v2
	s_cbranch_vccnz .LBB0_1040
	s_add_u32 s6, s80, 0x1e7fae00
	s_addc_u32 s7, s81, 0
	s_add_u32 s8, s80, 0x1e7fb000
	s_addc_u32 s9, s81, 0
	s_add_u32 s10, s80, 0x1e7fb100
	s_addc_u32 s11, s81, 0
	s_add_u32 s12, s80, 0x1e7fb200
	s_addc_u32 s13, s81, 0
	s_add_u32 s14, s80, 0x1e7fb300
	s_addc_u32 s15, s81, 0
	s_add_u32 s16, s80, 0x1e7fb400
	s_addc_u32 s17, s81, 0
	s_add_u32 s18, s80, 0x1e7fb500
	s_addc_u32 s19, s81, 0
	s_add_u32 s20, s80, 0x1e7fb600
	s_addc_u32 s21, s81, 0
	s_add_u32 s22, s80, 0x1e7fb700
	s_addc_u32 s23, s81, 0
	s_add_u32 s28, s80, 0x1e7fb800
	s_addc_u32 s29, s81, 0
	s_add_u32 s30, s80, 0x1e7fb900
	s_addc_u32 s31, s81, 0
	s_add_u32 s34, s80, 0x1e7fba00
	s_addc_u32 s35, s81, 0
	s_add_u32 s36, s80, 0x1e7fbb00
	s_addc_u32 s37, s81, 0
	s_add_u32 s38, s80, 0x1e7fbc00
	s_addc_u32 s39, s81, 0
	s_add_u32 s40, s80, 0x1e7fbd00
	s_addc_u32 s41, s81, 0
	s_add_u32 s42, s80, 0x1e7fbe00
	s_addc_u32 s43, s81, 0
	s_mul_i32 s54, s27, s33
	s_add_u32 s46, s80, 0x1e7fbf00
	s_mul_i32 s54, s54, s26
	s_addc_u32 s47, s81, 0
	s_mov_b32 s55, 1
	v_mov_b32_e32 v16, 0
	s_branch .LBB0_1028

; #define PG8_STAGE(bufoff, gbase, voff) do { _Pragma("unroll") for (int _i = 0; _i < 2; ++_i) \
;         __builtin_amdgcn_global_load_lds((const unsigned*)((const char*)(gbase) + (voff)[_i]), (PG8_LAS unsigned*)(lds + (bufoff) + ldsw + _i * 8192), 16, 0, 0); } while (0)
; #define PG8_LDA(dst, b, h) do { _Pragma("unroll") for (int m = 0; m < 4; ++m) _Pragma("unroll") for (int k = 0; k < 2; ++k) dst[m][k] = *(const PG8_LAS bf16x8*)(lds + PG8_SA(b, h) + aoff + m * 2048 + k * 1024); } while (0)
; #define PG8_LDB(dst, b, h) do { _Pragma("unroll") for (int n = 0; n < 2; ++n) _Pragma("unroll") for (int k = 0; k < 2; ++k) dst[n][k] = *(const PG8_LAS bf16x8*)(lds + PG8_SB(b, h) + boff + n * 2048 + k * 1024); } while (0)
; #define PG8_MMA(ai, bj, At, Bt) do { __builtin_amdgcn_s_setprio(1); _Pragma("unroll") for (int m = 0; m < 4; ++m) _Pragma("unroll") for (int n = 0; n < 2; ++n) _Pragma("unroll") for (int k = 0; k < 2; ++k) \
;         acc[ai][bj][m][n] = __builtin_amdgcn_mfma_f32_16x16x32_bf16(Bt[n][k], At[m][k], acc[ai][bj][m][n], 0, 0, 0); __builtin_amdgcn_s_setprio(0); } while (0)
; #define PG8_WAIT_V(n) asm volatile("s_waitcnt vmcnt(" #n ")" ::: "memory")
; #define PG8_WAIT_L(n) asm volatile("s_waitcnt lgkmcnt(" #n ")" ::: "memory")
; #define PG8_BAR __builtin_amdgcn_s_barrier()
; #define PG8_SCHED __builtin_amdgcn_sched_barrier(0)
; template <class Epi>
; __device__ __forceinline__ void gemm_phase(PG8_LAS unsigned char* lds, const Gemm g, const StaticOrder& S, const Epi& E) {
;     ...
;             PG8_LDB(B0, 0, 0); PG8_SCHED; PG8_LDA(At, 0, 0); PG8_STAGE(PG8_SA(1, 1), a1 + hstepA, voffA);
;             PG8_WAIT_L(8); PG8_BAR; PG8_WAIT_L(0); PG8_MMA(0, 0, At, B0); PG8_BAR; PG8_SCHED;
;             PG8_LDB(B1, 0, 1); PG8_STAGE(PG8_SB(0, 0), b2, voffB);
;             PG8_BAR; PG8_WAIT_L(0); PG8_MMA(0, 1, At, B1); PG8_BAR;
;             PG8_LDA(At, 0, 1); PG8_STAGE(PG8_SA(0, 0), a2, voffA);
;             PG8_BAR; PG8_WAIT_L(0); PG8_MMA(1, 0, At, B0); PG8_BAR; PG8_SCHED;
;             PG8_STAGE(PG8_SB(0, 1), b2 + hstepB, voffB);
;             PG8_WAIT_V(6); PG8_BAR; PG8_MMA(1, 1, At, B1); PG8_BAR;
.Lsp_6:
.LBB0_1086:
	ds_read_b128 v[0:3], v173
	ds_read_b128 v[4:7], v173 offset:1024
	ds_read_b128 v[154:157], v173 offset:2048
	ds_read_b128 v[158:161], v173 offset:3072
	ds_read_b128 v[162:165], v174
	ds_read_b128 v[178:181], v174 offset:1024
	ds_read_b128 v[182:185], v174 offset:2048
	ds_read_b128 v[186:189], v174 offset:3072
	ds_read_b128 v[190:193], v174 offset:4096
	ds_read_b128 v[194:197], v174 offset:5120
	ds_read_b128 v[198:201], v174 offset:6144
	ds_read_b128 v[202:205], v174 offset:7168
	ds_read_b128 v[206:209], v175
	ds_read_b128 v[210:213], v175 offset:1024
	ds_read_b128 v[214:217], v175 offset:2048
	ds_read_b128 v[218:221], v175 offset:3072
	s_add_u32 s4, s0, 0xfff80080
	s_addc_u32 s5, s1, -1
	s_cmp_eq_u32 s63, 28
	s_cselect_b32 s7, s39, s5
	s_cselect_b32 s6, s59, s4
	s_cselect_b32 s5, s37, s62
	s_cselect_b32 s4, s60, s61
	v_lshl_add_u64 v[166:167], s[0:1], 0, v[146:147]
	s_add_i32 m0, s11, 0xc000
	s_nop 0
	global_load_lds_dwordx4 v[166:167], off
	v_lshl_add_u64 v[166:167], s[0:1], 0, v[148:149]
	s_add_i32 m0, s11, 0xe000
	s_nop 0
	global_load_lds_dwordx4 v[166:167], off
	s_waitcnt lgkmcnt(0)
	s_waitcnt vmcnt(8)
	s_barrier
	v_mfma_f32_16x16x32_bf16 v[132:135], v[0:3], v[162:165], v[132:135]
	v_mfma_f32_16x16x32_bf16 v[124:127], v[154:157], v[162:165], v[124:127]
	v_mfma_f32_16x16x32_bf16 v[116:119], v[0:3], v[182:185], v[116:119]
	v_mfma_f32_16x16x32_bf16 v[108:111], v[154:157], v[182:185], v[108:111]
	v_mfma_f32_16x16x32_bf16 v[100:103], v[0:3], v[190:193], v[100:103]
	v_mfma_f32_16x16x32_bf16 v[92:95], v[154:157], v[190:193], v[92:95]
	v_mfma_f32_16x16x32_bf16 v[84:87], v[0:3], v[198:201], v[84:87]
	v_mfma_f32_16x16x32_bf16 v[76:79], v[154:157], v[198:201], v[76:79]
	v_mfma_f32_16x16x32_bf16 v[132:135], v[4:7], v[178:181], v[132:135]
	v_mfma_f32_16x16x32_bf16 v[124:127], v[158:161], v[178:181], v[124:127]
	v_mfma_f32_16x16x32_bf16 v[116:119], v[4:7], v[186:189], v[116:119]
	v_mfma_f32_16x16x32_bf16 v[108:111], v[158:161], v[186:189], v[108:111]
	v_mfma_f32_16x16x32_bf16 v[100:103], v[4:7], v[194:197], v[100:103]
	v_mfma_f32_16x16x32_bf16 v[92:95], v[158:161], v[194:197], v[92:95]
	v_mfma_f32_16x16x32_bf16 v[84:87], v[4:7], v[202:205], v[84:87]
	v_mfma_f32_16x16x32_bf16 v[76:79], v[158:161], v[202:205], v[76:79]
	v_mfma_f32_16x16x32_bf16 v[128:131], v[206:209], v[162:165], v[128:131]
	v_mfma_f32_16x16x32_bf16 v[120:123], v[214:217], v[162:165], v[120:123]
	v_mfma_f32_16x16x32_bf16 v[112:115], v[206:209], v[182:185], v[112:115]
	v_mfma_f32_16x16x32_bf16 v[104:107], v[214:217], v[182:185], v[104:107]
	v_mfma_f32_16x16x32_bf16 v[96:99], v[206:209], v[190:193], v[96:99]
	v_mfma_f32_16x16x32_bf16 v[88:91], v[214:217], v[190:193], v[88:91]
	v_mfma_f32_16x16x32_bf16 v[80:83], v[206:209], v[198:201], v[80:83]
	v_mfma_f32_16x16x32_bf16 v[72:75], v[214:217], v[198:201], v[72:75]
	v_mfma_f32_16x16x32_bf16 v[128:131], v[210:213], v[178:181], v[128:131]
	v_mfma_f32_16x16x32_bf16 v[120:123], v[218:221], v[178:181], v[120:123]
	v_mfma_f32_16x16x32_bf16 v[112:115], v[210:213], v[186:189], v[112:115]
	v_mfma_f32_16x16x32_bf16 v[104:107], v[218:221], v[186:189], v[104:107]
	v_mfma_f32_16x16x32_bf16 v[96:99], v[210:213], v[194:197], v[96:99]
	v_mfma_f32_16x16x32_bf16 v[88:91], v[218:221], v[194:197], v[88:91]
	v_mfma_f32_16x16x32_bf16 v[80:83], v[210:213], v[202:205], v[80:83]
	v_mfma_f32_16x16x32_bf16 v[72:75], v[218:221], v[202:205], v[72:75]
	s_barrier
	ds_read_b128 v[162:165], v174 offset:16384
	ds_read_b128 v[178:181], v174 offset:17408
	ds_read_b128 v[182:185], v174 offset:18432
	ds_read_b128 v[186:189], v174 offset:19456
	ds_read_b128 v[190:193], v174 offset:20480
	ds_read_b128 v[194:197], v174 offset:21504
	ds_read_b128 v[198:201], v174 offset:22528
	ds_read_b128 v[202:205], v174 offset:23552
	s_add_i32 s64, s52, s22
	v_lshl_add_u64 v[166:167], s[4:5], 0, v[140:141]
	s_mov_b32 m0, s64
	s_nop 0
	global_load_lds_dwordx4 v[166:167], off
	v_lshl_add_u64 v[222:223], s[4:5], 0, v[136:137]
	s_add_i32 m0, s64, 0x2000
	s_nop 0
	global_load_lds_dwordx4 v[222:223], off
	s_mov_b32 m0, s11
	v_lshl_add_u64 v[224:225], s[6:7], 0, v[142:143]
	global_load_lds_dwordx4 v[224:225], off
	v_lshl_add_u64 v[226:227], s[6:7], 0, v[138:139]
	s_mov_b32 m0, s31
	s_nop 0
	global_load_lds_dwordx4 v[226:227], off
	s_add_u32 s64, s4, 0x80000
	s_addc_u32 s65, s5, 0
	s_add_i32 s66, s53, s22
	v_lshl_add_u64 v[228:229], s[64:65], 0, v[140:141]
	s_mov_b32 m0, s66
	s_nop 0
	global_load_lds_dwordx4 v[228:229], off
	v_lshl_add_u64 v[228:229], s[64:65], 0, v[136:137]
	s_add_i32 m0, s66, 0x2000
	s_nop 0
	global_load_lds_dwordx4 v[228:229], off
	s_waitcnt lgkmcnt(0)
	s_waitcnt vmcnt(8)
	s_barrier
; #define PG8_STAGE(bufoff, gbase, voff) do { _Pragma("unroll") for (int _i = 0; _i < 2; ++_i) \
;         __builtin_amdgcn_global_load_lds((const unsigned*)((const char*)(gbase) + (voff)[_i]), (PG8_LAS unsigned*)(lds + (bufoff) + ldsw + _i * 8192), 16, 0, 0); } while (0)
; #define PG8_LDA(dst, b, h) do { _Pragma("unroll") for (int m = 0; m < 4; ++m) _Pragma("unroll") for (int k = 0; k < 2; ++k) dst[m][k] = *(const PG8_LAS bf16x8*)(lds + PG8_SA(b, h) + aoff + m * 2048 + k * 1024); } while (0)
; #define PG8_LDB(dst, b, h) do { _Pragma("unroll") for (int n = 0; n < 2; ++n) _Pragma("unroll") for (int k = 0; k < 2; ++k) dst[n][k] = *(const PG8_LAS bf16x8*)(lds + PG8_SB(b, h) + boff + n * 2048 + k * 1024); } while (0)
; #define PG8_MMA(ai, bj, At, Bt) do { __builtin_amdgcn_s_setprio(1); _Pragma("unroll") for (int m = 0; m < 4; ++m) _Pragma("unroll") for (int n = 0; n < 2; ++n) _Pragma("unroll") for (int k = 0; k < 2; ++k) \
;         acc[ai][bj][m][n] = __builtin_amdgcn_mfma_f32_16x16x32_bf16(Bt[n][k], At[m][k], acc[ai][bj][m][n], 0, 0, 0); __builtin_amdgcn_s_setprio(0); } while (0)
; #define PG8_WAIT_V(n) asm volatile("s_waitcnt vmcnt(" #n ")" ::: "memory")
; #define PG8_WAIT_L(n) asm volatile("s_waitcnt lgkmcnt(" #n ")" ::: "memory")
; #define PG8_BAR __builtin_amdgcn_s_barrier()
; #define PG8_SCHED __builtin_amdgcn_sched_barrier(0)
; template <class Epi>
; __device__ __forceinline__ void gemm_phase(PG8_LAS unsigned char* lds, const Gemm g, const StaticOrder& S, const Epi& E) {
;     ...
;             PG8_BAR; PG8_WAIT_L(0); PG8_MMA(1, 0, At, B0); PG8_BAR; PG8_SCHED;
;             PG8_STAGE(PG8_SB(0, 1), b2 + hstepB, voffB);
;             PG8_WAIT_V(6); PG8_BAR; PG8_MMA(1, 1, At, B1); PG8_BAR;
;             PG8_LDB(B0, 1, 0); PG8_SCHED; PG8_LDA(At, 1, 0); PG8_STAGE(PG8_SA(0, 1), a2 + hstepA, voffA);
;             PG8_WAIT_L(8); PG8_BAR; PG8_WAIT_L(0); PG8_MMA(0, 0, At, B0); PG8_BAR; PG8_SCHED;
;             PG8_LDB(B1, 1, 1); PG8_STAGE(PG8_SB(1, 0), b3, voffB);
;             PG8_BAR; PG8_WAIT_L(0); PG8_MMA(0, 1, At, B1); PG8_BAR;
	v_mfma_f32_16x16x32_bf16 v[68:71], v[0:3], v[162:165], v[68:71]
	v_mfma_f32_16x16x32_bf16 v[60:63], v[154:157], v[162:165], v[60:63]
	v_mfma_f32_16x16x32_bf16 v[52:55], v[0:3], v[182:185], v[52:55]
	v_mfma_f32_16x16x32_bf16 v[44:47], v[154:157], v[182:185], v[44:47]
	v_mfma_f32_16x16x32_bf16 v[36:39], v[0:3], v[190:193], v[36:39]
	v_mfma_f32_16x16x32_bf16 v[28:31], v[154:157], v[190:193], v[28:31]
	v_mfma_f32_16x16x32_bf16 v[0:3], v[0:3], v[198:201], v[20:23]
	v_mfma_f32_16x16x32_bf16 v[68:71], v[4:7], v[178:181], v[68:71]
	v_mfma_f32_16x16x32_bf16 v[60:63], v[158:161], v[178:181], v[60:63]
	v_mfma_f32_16x16x32_bf16 v[52:55], v[4:7], v[186:189], v[52:55]
	v_mfma_f32_16x16x32_bf16 v[44:47], v[158:161], v[186:189], v[44:47]
	v_mfma_f32_16x16x32_bf16 v[36:39], v[4:7], v[194:197], v[36:39]
	v_mfma_f32_16x16x32_bf16 v[28:31], v[158:161], v[194:197], v[28:31]
	v_mfma_f32_16x16x32_bf16 v[0:3], v[4:7], v[202:205], v[0:3]
	v_mfma_f32_16x16x32_bf16 v[4:7], v[154:157], v[198:201], v[12:15]
	v_mfma_f32_16x16x32_bf16 v[4:7], v[158:161], v[202:205], v[4:7]
	v_mfma_f32_16x16x32_bf16 v[12:15], v[206:209], v[162:165], v[64:67]
	v_mfma_f32_16x16x32_bf16 v[64:67], v[210:213], v[178:181], v[12:15]
	v_mfma_f32_16x16x32_bf16 v[12:15], v[214:217], v[162:165], v[56:59]
	v_mfma_f32_16x16x32_bf16 v[56:59], v[218:221], v[178:181], v[12:15]
	v_mfma_f32_16x16x32_bf16 v[12:15], v[206:209], v[182:185], v[48:51]
	v_mfma_f32_16x16x32_bf16 v[48:51], v[210:213], v[186:189], v[12:15]
	v_mfma_f32_16x16x32_bf16 v[12:15], v[214:217], v[182:185], v[40:43]
	v_mfma_f32_16x16x32_bf16 v[40:43], v[218:221], v[186:189], v[12:15]
	v_mfma_f32_16x16x32_bf16 v[12:15], v[206:209], v[190:193], v[32:35]
	v_mfma_f32_16x16x32_bf16 v[32:35], v[210:213], v[194:197], v[12:15]
	v_mfma_f32_16x16x32_bf16 v[12:15], v[214:217], v[190:193], v[24:27]
	v_mfma_f32_16x16x32_bf16 v[24:27], v[218:221], v[194:197], v[12:15]
	v_mfma_f32_16x16x32_bf16 v[12:15], v[206:209], v[198:201], v[16:19]
	v_mfma_f32_16x16x32_bf16 v[8:11], v[214:217], v[198:201], v[8:11]
	v_mfma_f32_16x16x32_bf16 v[16:19], v[210:213], v[202:205], v[12:15]
	v_mfma_f32_16x16x32_bf16 v[8:11], v[218:221], v[202:205], v[8:11]
	s_add_i32 s64, 0, 0x18000
	v_add_u32_e32 v158, s64, v170
	s_barrier
	s_nop 0
	s_nop 0
	ds_read_b128 v[12:15], v158
	ds_read_b128 v[20:23], v158 offset:1024
	ds_read_b128 v[154:157], v158 offset:2048
	ds_read_b128 v[158:161], v158 offset:3072
	ds_read_b128 v[162:165], v174 offset:32768
	ds_read_b128 v[178:181], v174 offset:33792
	ds_read_b128 v[182:185], v174 offset:34816
	ds_read_b128 v[186:189], v174 offset:35840
	ds_read_b128 v[190:193], v174 offset:36864
	ds_read_b128 v[194:197], v174 offset:37888
	ds_read_b128 v[198:201], v174 offset:38912
	ds_read_b128 v[202:205], v174 offset:39936
	v_add_u32_e32 v177, 0x1c000, v170
	ds_read_b128 v[206:209], v177
	ds_read_b128 v[210:213], v177 offset:1024
	ds_read_b128 v[214:217], v177 offset:2048
	ds_read_b128 v[218:221], v177 offset:3072
	s_add_u32 s6, s6, 0x80000
	s_addc_u32 s7, s7, 0
	s_mov_b32 m0, s34
	v_lshl_add_u64 v[228:229], s[6:7], 0, v[142:143]
	global_load_lds_dwordx4 v[228:229], off
	v_lshl_add_u64 v[228:229], s[6:7], 0, v[138:139]
	s_mov_b32 m0, s35
	s_nop 0
	global_load_lds_dwordx4 v[228:229], off
	s_waitcnt lgkmcnt(0)
	s_waitcnt vmcnt(8)
	s_barrier
	v_mfma_f32_16x16x32_bf16 v[132:135], v[12:15], v[162:165], v[132:135]
	v_mfma_f32_16x16x32_bf16 v[124:127], v[154:157], v[162:165], v[124:127]
	v_mfma_f32_16x16x32_bf16 v[116:119], v[12:15], v[182:185], v[116:119]
	v_mfma_f32_16x16x32_bf16 v[108:111], v[154:157], v[182:185], v[108:111]
	v_mfma_f32_16x16x32_bf16 v[100:103], v[12:15], v[190:193], v[100:103]
	v_mfma_f32_16x16x32_bf16 v[92:95], v[154:157], v[190:193], v[92:95]
	v_mfma_f32_16x16x32_bf16 v[84:87], v[12:15], v[198:201], v[84:87]
	v_mfma_f32_16x16x32_bf16 v[76:79], v[154:157], v[198:201], v[76:79]
	v_mfma_f32_16x16x32_bf16 v[132:135], v[20:23], v[178:181], v[132:135]
	v_mfma_f32_16x16x32_bf16 v[124:127], v[158:161], v[178:181], v[124:127]
	v_mfma_f32_16x16x32_bf16 v[116:119], v[20:23], v[186:189], v[116:119]
	v_mfma_f32_16x16x32_bf16 v[108:111], v[158:161], v[186:189], v[108:111]
	v_mfma_f32_16x16x32_bf16 v[100:103], v[20:23], v[194:197], v[100:103]
	v_mfma_f32_16x16x32_bf16 v[92:95], v[158:161], v[194:197], v[92:95]
	v_mfma_f32_16x16x32_bf16 v[84:87], v[20:23], v[202:205], v[84:87]
	v_mfma_f32_16x16x32_bf16 v[76:79], v[158:161], v[202:205], v[76:79]
	v_mfma_f32_16x16x32_bf16 v[128:131], v[206:209], v[162:165], v[128:131]
	v_mfma_f32_16x16x32_bf16 v[120:123], v[214:217], v[162:165], v[120:123]
	v_mfma_f32_16x16x32_bf16 v[112:115], v[206:209], v[182:185], v[112:115]
	v_mfma_f32_16x16x32_bf16 v[104:107], v[214:217], v[182:185], v[104:107]
	v_mfma_f32_16x16x32_bf16 v[96:99], v[206:209], v[190:193], v[96:99]
	v_mfma_f32_16x16x32_bf16 v[88:91], v[214:217], v[190:193], v[88:91]
	v_mfma_f32_16x16x32_bf16 v[80:83], v[206:209], v[198:201], v[80:83]
	v_mfma_f32_16x16x32_bf16 v[72:75], v[214:217], v[198:201], v[72:75]
	v_mfma_f32_16x16x32_bf16 v[128:131], v[210:213], v[178:181], v[128:131]
	v_mfma_f32_16x16x32_bf16 v[120:123], v[218:221], v[178:181], v[120:123]
	v_mfma_f32_16x16x32_bf16 v[112:115], v[210:213], v[186:189], v[112:115]
	v_mfma_f32_16x16x32_bf16 v[104:107], v[218:221], v[186:189], v[104:107]
	v_mfma_f32_16x16x32_bf16 v[96:99], v[210:213], v[194:197], v[96:99]
	v_mfma_f32_16x16x32_bf16 v[88:91], v[218:221], v[194:197], v[88:91]
	v_mfma_f32_16x16x32_bf16 v[80:83], v[210:213], v[202:205], v[80:83]
	v_mfma_f32_16x16x32_bf16 v[72:75], v[218:221], v[202:205], v[72:75]
	s_barrier
; #define PG8_LAS __attribute__((address_space(3)))
; #define PG8_STAGE(bufoff, gbase, voff) do { _Pragma("unroll") for (int _i = 0; _i < 2; ++_i) \
;         __builtin_amdgcn_global_load_lds((const unsigned*)((const char*)(gbase) + (voff)[_i]), (PG8_LAS unsigned*)(lds + (bufoff) + ldsw + _i * 8192), 16, 0, 0); } while (0)
; #define PG8_LDA(dst, b, h) do { _Pragma("unroll") for (int m = 0; m < 4; ++m) _Pragma("unroll") for (int k = 0; k < 2; ++k) dst[m][k] = *(const PG8_LAS bf16x8*)(lds + PG8_SA(b, h) + aoff + m * 2048 + k * 1024); } while (0)
; #define PG8_MMA(ai, bj, At, Bt) do { __builtin_amdgcn_s_setprio(1); _Pragma("unroll") for (int m = 0; m < 4; ++m) _Pragma("unroll") for (int n = 0; n < 2; ++n) _Pragma("unroll") for (int k = 0; k < 2; ++k) \
;         acc[ai][bj][m][n] = __builtin_amdgcn_mfma_f32_16x16x32_bf16(Bt[n][k], At[m][k], acc[ai][bj][m][n], 0, 0, 0); __builtin_amdgcn_s_setprio(0); } while (0)
; #define PG8_WAIT_V(n) asm volatile("s_waitcnt vmcnt(" #n ")" ::: "memory")
; #define PG8_WAIT_L(n) asm volatile("s_waitcnt lgkmcnt(" #n ")" ::: "memory")
; #define PG8_BAR __builtin_amdgcn_s_barrier()
; #define PG8_SCHED __builtin_amdgcn_sched_barrier(0)
; template <class Epi>
; __device__ __forceinline__ void gemm_phase(PG8_LAS unsigned char* lds, const Gemm g, const StaticOrder& S, const Epi& E) {
;     ...
;             PG8_LDA(At, 1, 1); PG8_STAGE(PG8_SA(1, 0), a3, voffA);
;             PG8_BAR; PG8_WAIT_L(0); PG8_MMA(1, 0, At, B0); PG8_BAR; PG8_SCHED;
;             PG8_STAGE(PG8_SB(1, 1), b3 + hstepB, voffB);
;             PG8_WAIT_V(6); PG8_BAR; PG8_MMA(1, 1, At, B1); PG8_BAR;
;         }
;         E(acc, cur, wr, wc, fr, fq);
;     __device__ __forceinline__ void operator()(const f32x4 (&acc)[2][2][4][2], const pg8::Unit& u, int wr, int wc, int fr, int fq) const {
;         const int row0 = u.pm * 256 + wr * 64 + fr, col0 = u.pn * 128 + wc * 32 + 8 * fq;
;         float rsv[8]; PG8_LAS float* mine = rs_lds + (wr * 4 + wc) * 512 + fq * 16 + fr;
;         if (u.pm != cached_pm) { rstd8(part, row0, fq, rsv);
	ds_read_b128 v[162:165], v174 offset:49152
	ds_read_b128 v[178:181], v174 offset:50176
	ds_read_b128 v[182:185], v174 offset:51200
	ds_read_b128 v[186:189], v174 offset:52224
	ds_read_b128 v[190:193], v174 offset:53248
	ds_read_b128 v[194:197], v174 offset:54272
	ds_read_b128 v[198:201], v174 offset:55296
	ds_read_b128 v[202:205], v174 offset:56320
	s_add_i32 s6, 0, 0x1c000
	s_add_i32 s7, s64, s22
	v_lshl_add_u64 v[166:167], v[166:167], 0, s[12:13]
	s_mov_b32 m0, s7
	s_nop 0
	global_load_lds_dwordx4 v[166:167], off
	v_lshl_add_u64 v[166:167], v[222:223], 0, s[12:13]
	s_add_i32 m0, s7, 0x2000
	s_nop 0
	global_load_lds_dwordx4 v[166:167], off
	s_mov_b32 m0, s48
	v_lshl_add_u64 v[166:167], v[224:225], 0, s[12:13]
	global_load_lds_dwordx4 v[166:167], off
	v_lshl_add_u64 v[166:167], v[226:227], 0, s[12:13]
	s_mov_b32 m0, s49
	s_nop 0
	global_load_lds_dwordx4 v[166:167], off
	s_add_u32 s4, s4, 0x80080
	s_addc_u32 s5, s5, 0
	s_add_i32 s6, s6, s22
	v_lshl_add_u64 v[228:229], s[4:5], 0, v[140:141]
	s_mov_b32 m0, s6
	s_nop 0
	global_load_lds_dwordx4 v[228:229], off
	v_lshl_add_u64 v[228:229], s[4:5], 0, v[136:137]
	s_add_i32 m0, s6, 0x2000
	s_nop 0
	global_load_lds_dwordx4 v[228:229], off
	s_waitcnt lgkmcnt(0)
	s_waitcnt vmcnt(8)
	s_barrier
	v_mfma_f32_16x16x32_bf16 v[68:71], v[12:15], v[162:165], v[68:71]
	v_mfma_f32_16x16x32_bf16 v[52:55], v[12:15], v[182:185], v[52:55]
	v_mfma_f32_16x16x32_bf16 v[36:39], v[12:15], v[190:193], v[36:39]
	v_mfma_f32_16x16x32_bf16 v[0:3], v[12:15], v[198:201], v[0:3]
	v_mfma_f32_16x16x32_bf16 v[68:71], v[20:23], v[178:181], v[68:71]
	v_mfma_f32_16x16x32_bf16 v[60:63], v[154:157], v[162:165], v[60:63]
	v_mfma_f32_16x16x32_bf16 v[52:55], v[20:23], v[186:189], v[52:55]
	v_mfma_f32_16x16x32_bf16 v[44:47], v[154:157], v[182:185], v[44:47]
	v_mfma_f32_16x16x32_bf16 v[36:39], v[20:23], v[194:197], v[36:39]
	v_mfma_f32_16x16x32_bf16 v[28:31], v[154:157], v[190:193], v[28:31]
	v_mfma_f32_16x16x32_bf16 v[20:23], v[20:23], v[202:205], v[0:3]
	v_mfma_f32_16x16x32_bf16 v[0:3], v[154:157], v[198:201], v[4:7]
	v_mfma_f32_16x16x32_bf16 v[60:63], v[158:161], v[178:181], v[60:63]
	v_mfma_f32_16x16x32_bf16 v[44:47], v[158:161], v[186:189], v[44:47]
	v_mfma_f32_16x16x32_bf16 v[28:31], v[158:161], v[194:197], v[28:31]
	v_mfma_f32_16x16x32_bf16 v[12:15], v[158:161], v[202:205], v[0:3]
	v_mfma_f32_16x16x32_bf16 v[0:3], v[206:209], v[162:165], v[64:67]
	v_mfma_f32_16x16x32_bf16 v[64:67], v[210:213], v[178:181], v[0:3]
	v_mfma_f32_16x16x32_bf16 v[0:3], v[214:217], v[162:165], v[56:59]
	v_mfma_f32_16x16x32_bf16 v[56:59], v[218:221], v[178:181], v[0:3]
	v_mfma_f32_16x16x32_bf16 v[0:3], v[206:209], v[182:185], v[48:51]
	v_mfma_f32_16x16x32_bf16 v[48:51], v[210:213], v[186:189], v[0:3]
	v_mfma_f32_16x16x32_bf16 v[0:3], v[214:217], v[182:185], v[40:43]
	v_mfma_f32_16x16x32_bf16 v[40:43], v[218:221], v[186:189], v[0:3]
	v_mfma_f32_16x16x32_bf16 v[0:3], v[206:209], v[190:193], v[32:35]
	v_mfma_f32_16x16x32_bf16 v[32:35], v[210:213], v[194:197], v[0:3]
	v_mfma_f32_16x16x32_bf16 v[0:3], v[214:217], v[190:193], v[24:27]
	v_mfma_f32_16x16x32_bf16 v[24:27], v[218:221], v[194:197], v[0:3]
	v_mfma_f32_16x16x32_bf16 v[0:3], v[206:209], v[198:201], v[16:19]
	v_mfma_f32_16x16x32_bf16 v[16:19], v[210:213], v[202:205], v[0:3]
	v_mfma_f32_16x16x32_bf16 v[0:3], v[214:217], v[198:201], v[8:11]
	v_mfma_f32_16x16x32_bf16 v[8:11], v[218:221], v[202:205], v[0:3]
	s_add_i32 s63, s63, 2
	s_add_u32 s0, s0, 0x100
	s_addc_u32 s1, s1, 0
	s_add_u32 s61, s61, 0x100
	s_addc_u32 s62, s62, 0
	s_cmp_gt_u32 s63, 29
	s_barrier
	s_cbranch_scc0 .LBB0_1086
	v_lshl_add_u32 v164, s10, 8, v169
	v_or_b32_e32 v160, 16, v164
	v_or_b32_e32 v158, 32, v164
	v_or_b32_e32 v156, 48, v164
	s_mov_b64 s[0:1], -1
	s_cmp_lg_u32 s10, s58
	v_ashrrev_i32_e32 v165, 31, v164
	v_ashrrev_i32_e32 v161, 31, v160
	v_ashrrev_i32_e32 v159, 31, v158
	v_ashrrev_i32_e32 v157, 31, v156
	v_add_u32_e32 v166, 0x80, v164
	s_cbranch_scc0 .LBB0_1089
	v_lshlrev_b64 v[0:1], 7, v[164:165]
	v_lshlrev_b64 v[4:5], 7, v[160:161]
	v_lshl_add_u64 v[162:163], v[144:145], 0, v[0:1]
	v_lshl_add_u64 v[154:155], v[144:145], 0, v[4:5]
	global_load_dwordx4 v[0:3], v[162:163], off
	global_load_dwordx4 v[4:7], v[154:155], off
	global_load_dwordx4 v[178:181], v[162:163], off offset:16
	global_load_dwordx4 v[182:185], v[154:155], off offset:16
	v_lshlrev_b64 v[154:155], 7, v[158:159]
	v_lshlrev_b64 v[186:187], 7, v[156:157]
	v_lshl_add_u64 v[154:155], v[144:145], 0, v[154:155]
	v_lshl_add_u64 v[198:199], v[144:145], 0, v[186:187]
	global_load_dwordx4 v[186:189], v[154:155], off
	global_load_dwordx4 v[190:193], v[198:199], off
	global_load_dwordx4 v[194:197], v[154:155], off offset:16
	s_nop 0
	global_load_dwordx4 v[198:201], v[198:199], off offset:16
	v_add_u32_e32 v154, 0x80, v164
	v_ashrrev_i32_e32 v155, 31, v154
	v_lshlrev_b64 v[202:203], 7, v[154:155]
	v_add_co_u32_e32 v204, vcc, s47, v162
	v_lshl_add_u64 v[210:211], v[144:145], 0, v[202:203]
	s_nop 0
	v_addc_co_u32_e32 v205, vcc, 0, v163, vcc
	global_load_dwordx4 v[202:205], v[204:205], off offset:2048
	s_nop 0
	global_load_dwordx4 v[206:209], v[210:211], off offset:16
	s_nop 0
	global_load_dwordx4 v[210:213], v[210:211], off
	v_and_b32_e32 v177, 64, v176
	v_add_co_u32_e32 v226, vcc, s54, v162
	v_xor_b32_e32 v167, 16, v176
	v_add_u32_e32 v177, 64, v177
	v_addc_co_u32_e32 v227, vcc, 0, v163, vcc
	v_xor_b32_e32 v216, 32, v176
	v_cmp_lt_i32_e32 vcc, v167, v177
	v_lshl_add_u64 v[214:215], v[162:163], 0, s[14:15]
	v_lshl_add_u64 v[222:223], v[162:163], 0, s[16:17]
	v_cndmask_b32_e32 v167, v176, v167, vcc
	v_cmp_lt_i32_e32 vcc, v216, v177
	v_lshl_add_u64 v[162:163], v[162:163], 0, s[18:19]
	v_lshlrev_b32_e32 v167, 2, v167
	v_cndmask_b32_e32 v177, v176, v216, vcc
	global_load_dwordx4 v[214:217], v[214:215], off offset:16
	s_nop 0
	global_load_dwordx4 v[218:221], v[226:227], off
	s_nop 0
	global_load_dwordx4 v[222:225], v[222:223], off offset:16
	s_nop 0
	global_load_dwordx4 v[226:229], v[226:227], off offset:2048
	s_nop 0
	global_load_dwordx4 v[230:233], v[162:163], off offset:16
	v_lshlrev_b32_e32 v177, 2, v177
	v_mov_b64_e32 v[234:235], s[28:29]
	s_waitcnt vmcnt(0)
; __device__ __forceinline__ void rstd8(const float* part, int row0, int fq, float (&rs)[8]) {
;     f32x4 v[8][2];
; #pragma unroll
;     for (int k = 0; k < 8; ++k) { const f32x4* p = (const f32x4*)(part + (size_t)(row0 + (k >> 2) * 128 + (k & 3) * 16) * 32 + fq * 8); v[k][0] = p[0]; v[k][1] = p[1]; }
; #pragma unroll
;     for (int k = 0; k < 8; ++k) { float s = ((v[k][0][0] + v[k][0][1]) + (v[k][0][2] + v[k][0][3])) + ((v[k][1][0] + v[k][1][1]) + (v[k][1][2] + v[k][1][3]));
;         s += __shfl_xor(s, 16); s += __shfl_xor(s, 32); rs[k] = rsqrtf(s * (1.0f / 2048.0f) + EPS); }
;     __device__ __forceinline__ void operator()(const f32x4 (&acc)[2][2][4][2], const pg8::Unit& u, int wr, int wc, int fr, int fq) const {
;     ...
;         if (u.pm != cached_pm) { rstd8(part, row0, fq, rsv);
; #pragma unroll
;             for (int k = 0; k < 8; ++k) mine[k * 64] = rsv[k];
;             cached_pm = u.pm; }
	v_mov_b32_e32 v163, v4
	v_mov_b32_e32 v162, v0
	v_mov_b32_e32 v4, v1
	v_mov_b32_e32 v0, v2
	v_mov_b32_e32 v1, v6
	v_mov_b32_e32 v6, v3
	v_mov_b32_e32 v2, v178
	v_mov_b32_e32 v3, v182
	v_mov_b32_e32 v182, v179
	v_mov_b32_e32 v178, v180
	v_mov_b32_e32 v179, v184
	v_mov_b32_e32 v184, v181
	v_pk_add_f32 v[4:5], v[162:163], v[4:5]
	v_pk_add_f32 v[0:1], v[0:1], v[6:7]
	v_pk_add_f32 v[2:3], v[2:3], v[182:183]
	v_pk_add_f32 v[6:7], v[178:179], v[184:185]
	v_pk_add_f32 v[0:1], v[4:5], v[0:1]
	v_pk_add_f32 v[2:3], v[2:3], v[6:7]
	v_mov_b32_e32 v180, v186
	v_pk_add_f32 v[0:1], v[0:1], v[2:3]
	ds_bpermute_b32 v2, v167, v0
	ds_bpermute_b32 v3, v167, v1
	v_mov_b32_e32 v181, v190
	v_mov_b32_e32 v190, v187
	v_mov_b32_e32 v186, v188
	v_mov_b32_e32 v187, v192
	v_mov_b32_e32 v192, v189
	v_mov_b32_e32 v188, v194
	v_mov_b32_e32 v189, v198
	v_mov_b32_e32 v198, v195
	v_mov_b32_e32 v194, v196
	v_mov_b32_e32 v195, v200
	v_mov_b32_e32 v200, v197
	s_waitcnt lgkmcnt(0)
	v_pk_add_f32 v[0:1], v[0:1], v[2:3]
	v_pk_add_f32 v[162:163], v[180:181], v[190:191]
	v_pk_add_f32 v[4:5], v[186:187], v[192:193]
	v_pk_add_f32 v[6:7], v[188:189], v[198:199]
	v_pk_add_f32 v[178:179], v[194:195], v[200:201]
	ds_bpermute_b32 v2, v177, v0
	ds_bpermute_b32 v3, v177, v1
	v_pk_add_f32 v[4:5], v[162:163], v[4:5]
	v_pk_add_f32 v[6:7], v[6:7], v[178:179]
	v_mov_b32_e32 v162, v212
	v_pk_add_f32 v[4:5], v[4:5], v[6:7]
	ds_bpermute_b32 v6, v167, v4
	ds_bpermute_b32 v7, v167, v5
	s_waitcnt lgkmcnt(2)
	v_pk_add_f32 v[0:1], v[0:1], v[2:3]
	v_mov_b32_e32 v163, v204
	v_pk_fma_f32 v[0:1], v[0:1], s[20:21], v[234:235] op_sel_hi:[1,0,0]
	v_mov_b32_e32 v204, v213
	v_mul_f32_e32 v2, 0x4b800000, v0
	v_mul_f32_e32 v3, 0x4b800000, v1
	v_cmp_gt_f32_e32 vcc, s55, v0
	v_cmp_gt_f32_e64 s[0:1], s55, v1
	v_pk_add_f32 v[162:163], v[162:163], v[204:205]
	v_cndmask_b32_e32 v0, v0, v2, vcc
	v_cndmask_b32_e64 v1, v1, v3, s[0:1]
	s_waitcnt lgkmcnt(0)
	v_pk_add_f32 v[2:3], v[4:5], v[6:7]
	ds_bpermute_b32 v4, v177, v2
	ds_bpermute_b32 v5, v177, v3
	v_rsq_f32_e32 v0, v0
	v_rsq_f32_e32 v1, v1
	v_mov_b32_e32 v178, v208
	v_mov_b32_e32 v179, v216
	s_waitcnt lgkmcnt(0)
	v_pk_add_f32 v[2:3], v[2:3], v[4:5]
	v_pk_mul_f32 v[6:7], v[0:1], s[30:31] op_sel_hi:[1,0]
	v_pk_fma_f32 v[2:3], v[2:3], s[20:21], v[234:235] op_sel_hi:[1,0,0]
	v_cndmask_b32_e64 v1, v1, v7, s[0:1]
	v_mul_f32_e32 v4, 0x4b800000, v2
	v_cmp_gt_f32_e64 s[0:1], s55, v2
	v_mov_b32_e32 v5, v202
	v_mov_b32_e32 v202, v211
	v_cndmask_b32_e64 v2, v2, v4, s[0:1]
	v_mov_b32_e32 v4, v210
	v_pk_add_f32 v[4:5], v[4:5], v[202:203]
	v_mov_b32_e32 v216, v209
	v_pk_add_f32 v[4:5], v[4:5], v[162:163]
	v_mov_b32_e32 v162, v206
	v_mov_b32_e32 v163, v214
	v_mov_b32_e32 v214, v207
	v_pk_add_f32 v[162:163], v[162:163], v[214:215]
	v_pk_add_f32 v[178:179], v[178:179], v[216:217]
	v_mul_f32_e32 v7, 0x4b800000, v3
	v_pk_add_f32 v[162:163], v[162:163], v[178:179]
	v_cmp_gt_f32_e64 s[4:5], s55, v3
	v_pk_add_f32 v[4:5], v[4:5], v[162:163]
	ds_bpermute_b32 v162, v167, v4
	ds_bpermute_b32 v163, v167, v5
	v_cndmask_b32_e64 v3, v3, v7, s[4:5]
	v_rsq_f32_e32 v2, v2
	v_rsq_f32_e32 v3, v3
	v_cndmask_b32_e32 v0, v0, v6, vcc
	s_waitcnt lgkmcnt(0)
	v_pk_add_f32 v[4:5], v[4:5], v[162:163]
	ds_bpermute_b32 v162, v177, v4
	ds_bpermute_b32 v163, v177, v5
	v_pk_mul_f32 v[6:7], v[2:3], s[30:31] op_sel_hi:[1,0]
	v_mov_b32_e32 v178, v226
	v_cndmask_b32_e64 v3, v3, v7, s[4:5]
	v_cndmask_b32_e64 v2, v2, v6, s[0:1]
	s_waitcnt lgkmcnt(0)
	v_pk_add_f32 v[4:5], v[4:5], v[162:163]
	v_mov_b32_e32 v6, v219
	v_mov_b32_e32 v7, v220
	v_mov_b32_e32 v219, v221
	v_mov_b32_e32 v162, v223
	v_mov_b32_e32 v163, v224
	v_mov_b32_e32 v223, v225
	v_mov_b32_e32 v179, v230
	v_mov_b32_e32 v230, v227
	v_mov_b32_e32 v180, v228
	v_mov_b32_e32 v181, v232
	v_mov_b32_e32 v232, v229
	v_pk_add_f32 v[6:7], v[6:7], v[218:219]
	v_pk_add_f32 v[162:163], v[162:163], v[222:223]
	v_pk_add_f32 v[178:179], v[178:179], v[230:231]
	v_pk_add_f32 v[180:181], v[180:181], v[232:233]
	v_pk_add_f32 v[6:7], v[6:7], v[6:7] op_sel:[0,1] op_sel_hi:[1,0]
	v_pk_add_f32 v[162:163], v[162:163], v[162:163] op_sel:[0,1] op_sel_hi:[1,0]
	v_pk_add_f32 v[178:179], v[178:179], v[180:181]
	v_pk_fma_f32 v[4:5], v[4:5], s[20:21], v[234:235] op_sel_hi:[1,0,0]
	v_mov_b32_e32 v7, v178
	v_mov_b32_e32 v163, v179
	v_pk_add_f32 v[6:7], v[6:7], v[162:163]
	ds_bpermute_b32 v162, v167, v6
	ds_bpermute_b32 v163, v167, v7
	v_mul_f32_e32 v167, 0x4b800000, v4
	v_cmp_gt_f32_e32 vcc, s55, v4
	v_cmp_gt_f32_e64 s[0:1], s55, v5
	s_waitcnt lgkmcnt(0)
	v_pk_add_f32 v[6:7], v[6:7], v[162:163]
	ds_bpermute_b32 v162, v177, v6
	ds_bpermute_b32 v163, v177, v7
	v_cndmask_b32_e32 v4, v4, v167, vcc
	v_mul_f32_e32 v167, 0x4b800000, v5
	v_cndmask_b32_e64 v5, v5, v167, s[0:1]
	v_rsq_f32_e32 v4, v4
	s_waitcnt lgkmcnt(0)
	v_pk_add_f32 v[6:7], v[6:7], v[162:163]
	v_rsq_f32_e32 v5, v5
	v_pk_fma_f32 v[6:7], v[6:7], s[20:21], v[234:235] op_sel_hi:[1,0,0]
	s_nop 0
	v_mul_f32_e32 v162, 0x4b800000, v6
	v_cmp_gt_f32_e64 s[4:5], s55, v6
	v_cmp_gt_f32_e64 s[6:7], s55, v7
	s_nop 0
	v_cndmask_b32_e64 v6, v6, v162, s[4:5]
	v_mul_f32_e32 v162, 0x4b800000, v7
	v_cndmask_b32_e64 v7, v7, v162, s[6:7]
	v_rsq_f32_e32 v6, v6
	v_rsq_f32_e32 v7, v7
	v_pk_mul_f32 v[162:163], v[4:5], s[30:31] op_sel_hi:[1,0]
	s_nop 0
	v_cndmask_b32_e64 v5, v5, v163, s[0:1]
	v_cndmask_b32_e32 v4, v4, v162, vcc
	v_pk_mul_f32 v[162:163], v[6:7], s[30:31] op_sel_hi:[1,0]
	s_mov_b64 s[0:1], 0
	v_cndmask_b32_e64 v7, v7, v163, s[6:7]
	v_cndmask_b32_e64 v6, v6, v162, s[4:5]
	ds_write2st64_b32 v171, v0, v1 offset1:1
	ds_write2st64_b32 v171, v2, v3 offset0:2 offset1:3
	ds_write2st64_b32 v171, v4, v5 offset0:4 offset1:5
	ds_write2st64_b32 v171, v6, v7 offset0:6 offset1:7
	v_mov_b64_e32 v[162:163], v[154:155]

; __device__ __forceinline__ unsigned xb_ld(unsigned* p)              { return __hip_atomic_load(p, __ATOMIC_RELAXED, __HIP_MEMORY_SCOPE_AGENT); }
; __device__ __forceinline__ void xcd_barrier_complete(unsigned* bar, unsigned x, unsigned& nloc, unsigned& nx) {
;     const unsigned G = gridDim.x * gridDim.y * gridDim.z;
;     unsigned sum, cnt, mine, sp = 0u;
;     for (;;) {
;         sum = 0u; cnt = 0u; mine = 0u;
; #pragma unroll
;         for (unsigned j = 0; j < 16; ++j) { const unsigned c = xb_ld(&bar[XB_XCNT(j)]); sum += c; cnt += (c > 0u) ? 1u : 0u; mine = (j == x) ? c : mine; }
; __device__ __forceinline__ void xcd_barrier(const XcdBarrier& b) {
;     asm volatile("s_waitcnt vmcnt(0)" ::: "memory");
;     __syncthreads();
;     if (threadIdx.x == 0) {
;         unsigned* bar = b.bar;
;         __builtin_amdgcn_s_waitcnt(0);
;         unsigned nloc = b.st[0], nx = b.st[1];
;         if (nloc == 0u) { xcd_barrier_complete(bar, b.x, nloc, nx); b.st[0] = nloc; b.st[1] = nx; }
.LBB0_1094:
	s_setprio 0
	s_cmp_gt_i32 s75, 10
	s_cselect_b64 s[0:1], -1, 0
	s_and_b64 s[2:3], s[8:9], s[0:1]
	s_andn2_b64 vcc, exec, s[2:3]
	s_cbranch_vccnz .LBB0_1148
	s_waitcnt vmcnt(0)
	s_waitcnt vmcnt(0) lgkmcnt(0)
	s_barrier
	s_mov_b64 s[2:3], exec
	v_readlane_b32 s4, v253, 8
	v_readlane_b32 s5, v253, 9
	s_and_b64 s[4:5], s[2:3], s[4:5]
	s_mov_b64 exec, s[4:5]
	s_cbranch_execz .LBB0_1147
	s_add_i32 s4, 0, 0x24000
	v_mov_b32_e32 v0, s4
	s_waitcnt vmcnt(0) expcnt(0) lgkmcnt(0)
	ds_read_b32 v2, v0
	s_add_i32 s4, 0, 0x24004
	v_mov_b32_e32 v0, s4
	ds_read_b32 v0, v0
	s_waitcnt lgkmcnt(1)
	v_cmp_ne_u32_e32 vcc, 0, v2
	s_cbranch_vccnz .LBB0_1111
	s_add_u32 s4, s80, 0x1e7fae00
	s_addc_u32 s5, s81, 0
	s_add_u32 s6, s80, 0x1e7fb000
	s_addc_u32 s7, s81, 0
	s_add_u32 s8, s80, 0x1e7fb100
	s_addc_u32 s9, s81, 0
	s_add_u32 s10, s80, 0x1e7fb200
	s_addc_u32 s11, s81, 0
	s_add_u32 s12, s80, 0x1e7fb300
	s_addc_u32 s13, s81, 0
	s_add_u32 s14, s80, 0x1e7fb400
	s_addc_u32 s15, s81, 0
	s_add_u32 s16, s80, 0x1e7fb500
	s_addc_u32 s17, s81, 0
	s_add_u32 s18, s80, 0x1e7fb600
	s_addc_u32 s19, s81, 0
	s_add_u32 s20, s80, 0x1e7fb700
	s_addc_u32 s21, s81, 0
	s_add_u32 s22, s80, 0x1e7fb800
	s_addc_u32 s23, s81, 0
	s_add_u32 s28, s80, 0x1e7fb900
	s_addc_u32 s29, s81, 0
	s_add_u32 s30, s80, 0x1e7fba00
	s_addc_u32 s31, s81, 0
	s_add_u32 s34, s80, 0x1e7fbb00
	s_addc_u32 s35, s81, 0
	s_add_u32 s36, s80, 0x1e7fbc00
	s_addc_u32 s37, s81, 0
	s_add_u32 s38, s80, 0x1e7fbd00
	s_addc_u32 s39, s81, 0
	s_add_u32 s40, s80, 0x1e7fbe00
	s_addc_u32 s41, s81, 0
	s_mul_i32 s27, s27, s33
	s_add_u32 s42, s80, 0x1e7fbf00
	s_mul_i32 s27, s27, s26
	s_addc_u32 s43, s81, 0
	s_mov_b32 s33, 1
	v_mov_b32_e32 v16, 0
	s_branch .LBB0_1099

; #define PG8_STAGE(bufoff, gbase, voff) do { _Pragma("unroll") for (int _i = 0; _i < 2; ++_i) \
;         __builtin_amdgcn_global_load_lds((const unsigned*)((const char*)(gbase) + (voff)[_i]), (PG8_LAS unsigned*)(lds + (bufoff) + ldsw + _i * 8192), 16, 0, 0); } while (0)
; #define PG8_LDA(dst, b, h) do { _Pragma("unroll") for (int m = 0; m < 4; ++m) _Pragma("unroll") for (int k = 0; k < 2; ++k) dst[m][k] = *(const PG8_LAS bf16x8*)(lds + PG8_SA(b, h) + aoff + m * 2048 + k * 1024); } while (0)
; #define PG8_LDB(dst, b, h) do { _Pragma("unroll") for (int n = 0; n < 2; ++n) _Pragma("unroll") for (int k = 0; k < 2; ++k) dst[n][k] = *(const PG8_LAS bf16x8*)(lds + PG8_SB(b, h) + boff + n * 2048 + k * 1024); } while (0)
; #define PG8_MMA(ai, bj, At, Bt) do { __builtin_amdgcn_s_setprio(1); _Pragma("unroll") for (int m = 0; m < 4; ++m) _Pragma("unroll") for (int n = 0; n < 2; ++n) _Pragma("unroll") for (int k = 0; k < 2; ++k) \
;         acc[ai][bj][m][n] = __builtin_amdgcn_mfma_f32_16x16x32_bf16(Bt[n][k], At[m][k], acc[ai][bj][m][n], 0, 0, 0); __builtin_amdgcn_s_setprio(0); } while (0)
; #define PG8_WAIT_V(n) asm volatile("s_waitcnt vmcnt(" #n ")" ::: "memory")
; #define PG8_WAIT_L(n) asm volatile("s_waitcnt lgkmcnt(" #n ")" ::: "memory")
; #define PG8_BAR __builtin_amdgcn_s_barrier()
; #define PG8_SCHED __builtin_amdgcn_sched_barrier(0)
; template <class Epi>
; __device__ __forceinline__ void gemm_phase(PG8_LAS unsigned char* lds, const Gemm g, const StaticOrder& S, const Epi& E) {
;     ...
;             PG8_LDB(B0, 0, 0); PG8_SCHED; PG8_LDA(At, 0, 0); PG8_STAGE(PG8_SA(1, 1), a1 + hstepA, voffA);
;             PG8_WAIT_L(8); PG8_BAR; PG8_WAIT_L(0); PG8_MMA(0, 0, At, B0); PG8_BAR; PG8_SCHED;
;             PG8_LDB(B1, 0, 1); PG8_STAGE(PG8_SB(0, 0), b2, voffB);
;             PG8_BAR; PG8_WAIT_L(0); PG8_MMA(0, 1, At, B1); PG8_BAR;
;             PG8_LDA(At, 0, 1); PG8_STAGE(PG8_SA(0, 0), a2, voffA);
;             PG8_BAR; PG8_WAIT_L(0); PG8_MMA(1, 0, At, B0); PG8_BAR; PG8_SCHED;
;             PG8_STAGE(PG8_SB(0, 1), b2 + hstepB, voffB);
;             PG8_WAIT_V(6); PG8_BAR; PG8_MMA(1, 1, At, B1); PG8_BAR;
.Lsp_7:
.LBB0_1170:
	ds_read_b128 v[144:147], v155
	ds_read_b128 v[148:151], v155 offset:1024
	ds_read_b128 v[158:161], v155 offset:2048
	ds_read_b128 v[162:165], v155 offset:3072
	ds_read_b128 v[166:169], v156
	ds_read_b128 v[170:173], v156 offset:1024
	ds_read_b128 v[174:177], v156 offset:2048
	ds_read_b128 v[178:181], v156 offset:3072
	ds_read_b128 v[182:185], v156 offset:4096
	ds_read_b128 v[186:189], v156 offset:5120
	ds_read_b128 v[190:193], v156 offset:6144
	ds_read_b128 v[194:197], v156 offset:7168
	ds_read_b128 v[198:201], v157
	ds_read_b128 v[202:205], v157 offset:1024
	ds_read_b128 v[206:209], v157 offset:2048
	ds_read_b128 v[210:213], v157 offset:3072
	s_add_u32 s12, s10, 0xffea0080
	s_addc_u32 s13, s11, -1
	s_cmpk_eq_i32 s38, 0x54
	s_cselect_b32 s15, s3, s13
	s_cselect_b32 s14, s2, s12
	s_cselect_b32 s13, s5, s37
	s_cselect_b32 s12, s4, s36
	v_lshl_add_u64 v[222:223], s[10:11], 0, v[136:137]
	s_add_i32 m0, s19, 0xc000
	s_nop 0
	global_load_lds_dwordx4 v[222:223], off
	v_lshl_add_u64 v[222:223], s[10:11], 0, v[138:139]
	s_add_i32 m0, s19, 0xe000
	s_nop 0
	global_load_lds_dwordx4 v[222:223], off
	s_waitcnt lgkmcnt(0)
	s_waitcnt vmcnt(8)
	s_barrier
	v_mfma_f32_16x16x32_bf16 v[124:127], v[144:147], v[166:169], v[124:127]
	v_mfma_f32_16x16x32_bf16 v[120:123], v[158:161], v[166:169], v[120:123]
	v_mfma_f32_16x16x32_bf16 v[108:111], v[144:147], v[174:177], v[108:111]
	v_mfma_f32_16x16x32_bf16 v[104:107], v[158:161], v[174:177], v[104:107]
	v_mfma_f32_16x16x32_bf16 v[88:91], v[144:147], v[182:185], v[88:91]
	v_mfma_f32_16x16x32_bf16 v[92:95], v[158:161], v[182:185], v[92:95]
	v_mfma_f32_16x16x32_bf16 v[72:75], v[144:147], v[190:193], v[72:75]
	v_mfma_f32_16x16x32_bf16 v[76:79], v[158:161], v[190:193], v[76:79]
	v_mfma_f32_16x16x32_bf16 v[124:127], v[148:151], v[170:173], v[124:127]
	v_mfma_f32_16x16x32_bf16 v[120:123], v[162:165], v[170:173], v[120:123]
	v_mfma_f32_16x16x32_bf16 v[108:111], v[148:151], v[178:181], v[108:111]
	v_mfma_f32_16x16x32_bf16 v[104:107], v[162:165], v[178:181], v[104:107]
	v_mfma_f32_16x16x32_bf16 v[88:91], v[148:151], v[186:189], v[88:91]
	v_mfma_f32_16x16x32_bf16 v[92:95], v[162:165], v[186:189], v[92:95]
	v_mfma_f32_16x16x32_bf16 v[72:75], v[148:151], v[194:197], v[72:75]
	v_mfma_f32_16x16x32_bf16 v[76:79], v[162:165], v[194:197], v[76:79]
	v_mfma_f32_16x16x32_bf16 v[116:119], v[198:201], v[166:169], v[116:119]
	v_mfma_f32_16x16x32_bf16 v[112:115], v[206:209], v[166:169], v[112:115]
	v_mfma_f32_16x16x32_bf16 v[100:103], v[198:201], v[174:177], v[100:103]
	v_mfma_f32_16x16x32_bf16 v[96:99], v[206:209], v[174:177], v[96:99]
	v_mfma_f32_16x16x32_bf16 v[80:83], v[198:201], v[182:185], v[80:83]
	v_mfma_f32_16x16x32_bf16 v[84:87], v[206:209], v[182:185], v[84:87]
	v_mfma_f32_16x16x32_bf16 v[64:67], v[198:201], v[190:193], v[64:67]
	v_mfma_f32_16x16x32_bf16 v[68:71], v[206:209], v[190:193], v[68:71]
	v_mfma_f32_16x16x32_bf16 v[116:119], v[202:205], v[170:173], v[116:119]
	v_mfma_f32_16x16x32_bf16 v[112:115], v[210:213], v[170:173], v[112:115]
	v_mfma_f32_16x16x32_bf16 v[100:103], v[202:205], v[178:181], v[100:103]
	v_mfma_f32_16x16x32_bf16 v[96:99], v[210:213], v[178:181], v[96:99]
	v_mfma_f32_16x16x32_bf16 v[80:83], v[202:205], v[186:189], v[80:83]
	v_mfma_f32_16x16x32_bf16 v[84:87], v[210:213], v[186:189], v[84:87]
	v_mfma_f32_16x16x32_bf16 v[64:67], v[202:205], v[194:197], v[64:67]
	v_mfma_f32_16x16x32_bf16 v[68:71], v[210:213], v[194:197], v[68:71]
	s_barrier
	ds_read_b128 v[166:169], v156 offset:16384
	ds_read_b128 v[170:173], v156 offset:17408
	ds_read_b128 v[174:177], v156 offset:18432
	ds_read_b128 v[178:181], v156 offset:19456
	ds_read_b128 v[182:185], v156 offset:20480
	ds_read_b128 v[186:189], v156 offset:21504
	ds_read_b128 v[190:193], v156 offset:22528
	ds_read_b128 v[194:197], v156 offset:23552
	s_add_i32 s39, s29, s18
	v_lshl_add_u64 v[214:215], s[12:13], 0, v[130:131]
	s_mov_b32 m0, s39
	s_nop 0
	global_load_lds_dwordx4 v[214:215], off
	v_lshl_add_u64 v[216:217], s[12:13], 0, v[134:135]
	s_add_i32 m0, s39, 0x2000
	s_nop 0
	global_load_lds_dwordx4 v[216:217], off
	s_mov_b32 m0, s19
	v_lshl_add_u64 v[218:219], s[14:15], 0, v[128:129]
	global_load_lds_dwordx4 v[218:219], off
	v_lshl_add_u64 v[220:221], s[14:15], 0, v[132:133]
	s_mov_b32 m0, s20
	s_nop 0
	global_load_lds_dwordx4 v[220:221], off
	s_add_u32 s40, s12, 0x160000
	s_addc_u32 s41, s13, 0
	s_add_i32 s39, s30, s18
	v_lshl_add_u64 v[222:223], s[40:41], 0, v[130:131]
	s_mov_b32 m0, s39
	s_nop 0
	global_load_lds_dwordx4 v[222:223], off
	v_lshl_add_u64 v[222:223], s[40:41], 0, v[134:135]
	s_add_i32 m0, s39, 0x2000
	s_nop 0
	global_load_lds_dwordx4 v[222:223], off
	s_waitcnt lgkmcnt(0)
	s_waitcnt vmcnt(8)
	s_barrier
; #define PG8_STAGE(bufoff, gbase, voff) do { _Pragma("unroll") for (int _i = 0; _i < 2; ++_i) \
;         __builtin_amdgcn_global_load_lds((const unsigned*)((const char*)(gbase) + (voff)[_i]), (PG8_LAS unsigned*)(lds + (bufoff) + ldsw + _i * 8192), 16, 0, 0); } while (0)
; #define PG8_LDA(dst, b, h) do { _Pragma("unroll") for (int m = 0; m < 4; ++m) _Pragma("unroll") for (int k = 0; k < 2; ++k) dst[m][k] = *(const PG8_LAS bf16x8*)(lds + PG8_SA(b, h) + aoff + m * 2048 + k * 1024); } while (0)
; #define PG8_LDB(dst, b, h) do { _Pragma("unroll") for (int n = 0; n < 2; ++n) _Pragma("unroll") for (int k = 0; k < 2; ++k) dst[n][k] = *(const PG8_LAS bf16x8*)(lds + PG8_SB(b, h) + boff + n * 2048 + k * 1024); } while (0)
; #define PG8_MMA(ai, bj, At, Bt) do { __builtin_amdgcn_s_setprio(1); _Pragma("unroll") for (int m = 0; m < 4; ++m) _Pragma("unroll") for (int n = 0; n < 2; ++n) _Pragma("unroll") for (int k = 0; k < 2; ++k) \
;         acc[ai][bj][m][n] = __builtin_amdgcn_mfma_f32_16x16x32_bf16(Bt[n][k], At[m][k], acc[ai][bj][m][n], 0, 0, 0); __builtin_amdgcn_s_setprio(0); } while (0)
; #define PG8_WAIT_V(n) asm volatile("s_waitcnt vmcnt(" #n ")" ::: "memory")
; #define PG8_WAIT_L(n) asm volatile("s_waitcnt lgkmcnt(" #n ")" ::: "memory")
; #define PG8_BAR __builtin_amdgcn_s_barrier()
; #define PG8_SCHED __builtin_amdgcn_sched_barrier(0)
; template <class Epi>
; __device__ __forceinline__ void gemm_phase(PG8_LAS unsigned char* lds, const Gemm g, const StaticOrder& S, const Epi& E) {
;     ...
;             PG8_BAR; PG8_WAIT_L(0); PG8_MMA(1, 0, At, B0); PG8_BAR; PG8_SCHED;
;             PG8_STAGE(PG8_SB(0, 1), b2 + hstepB, voffB);
;             PG8_WAIT_V(6); PG8_BAR; PG8_MMA(1, 1, At, B1); PG8_BAR;
;             PG8_LDB(B0, 1, 0); PG8_SCHED; PG8_LDA(At, 1, 0); PG8_STAGE(PG8_SA(0, 1), a2 + hstepA, voffA);
;             PG8_WAIT_L(8); PG8_BAR; PG8_WAIT_L(0); PG8_MMA(0, 0, At, B0); PG8_BAR; PG8_SCHED;
;             PG8_LDB(B1, 1, 1); PG8_STAGE(PG8_SB(1, 0), b3, voffB);
;             PG8_BAR; PG8_WAIT_L(0); PG8_MMA(0, 1, At, B1); PG8_BAR;
	v_mfma_f32_16x16x32_bf16 v[56:59], v[144:147], v[166:169], v[56:59]
	v_mfma_f32_16x16x32_bf16 v[60:63], v[158:161], v[166:169], v[60:63]
	v_mfma_f32_16x16x32_bf16 v[40:43], v[144:147], v[174:177], v[40:43]
	v_mfma_f32_16x16x32_bf16 v[44:47], v[158:161], v[174:177], v[44:47]
	v_mfma_f32_16x16x32_bf16 v[24:27], v[144:147], v[182:185], v[24:27]
	v_mfma_f32_16x16x32_bf16 v[28:31], v[158:161], v[182:185], v[28:31]
	v_mfma_f32_16x16x32_bf16 v[8:11], v[144:147], v[190:193], v[8:11]
	v_mfma_f32_16x16x32_bf16 v[12:15], v[158:161], v[190:193], v[12:15]
	v_mfma_f32_16x16x32_bf16 v[56:59], v[148:151], v[170:173], v[56:59]
	v_mfma_f32_16x16x32_bf16 v[60:63], v[162:165], v[170:173], v[60:63]
	v_mfma_f32_16x16x32_bf16 v[40:43], v[148:151], v[178:181], v[40:43]
	v_mfma_f32_16x16x32_bf16 v[44:47], v[162:165], v[178:181], v[44:47]
	v_mfma_f32_16x16x32_bf16 v[24:27], v[148:151], v[186:189], v[24:27]
	v_mfma_f32_16x16x32_bf16 v[28:31], v[162:165], v[186:189], v[28:31]
	v_mfma_f32_16x16x32_bf16 v[8:11], v[148:151], v[194:197], v[8:11]
	v_mfma_f32_16x16x32_bf16 v[12:15], v[162:165], v[194:197], v[12:15]
	v_mfma_f32_16x16x32_bf16 v[48:51], v[198:201], v[166:169], v[48:51]
	v_mfma_f32_16x16x32_bf16 v[52:55], v[206:209], v[166:169], v[52:55]
	v_mfma_f32_16x16x32_bf16 v[32:35], v[198:201], v[174:177], v[32:35]
	v_mfma_f32_16x16x32_bf16 v[36:39], v[206:209], v[174:177], v[36:39]
	v_mfma_f32_16x16x32_bf16 v[16:19], v[198:201], v[182:185], v[16:19]
	v_mfma_f32_16x16x32_bf16 v[20:23], v[206:209], v[182:185], v[20:23]
	v_mfma_f32_16x16x32_bf16 v[0:3], v[198:201], v[190:193], v[0:3]
	v_mfma_f32_16x16x32_bf16 v[4:7], v[206:209], v[190:193], v[4:7]
	v_mfma_f32_16x16x32_bf16 v[48:51], v[202:205], v[170:173], v[48:51]
	v_mfma_f32_16x16x32_bf16 v[52:55], v[210:213], v[170:173], v[52:55]
	v_mfma_f32_16x16x32_bf16 v[32:35], v[202:205], v[178:181], v[32:35]
	v_mfma_f32_16x16x32_bf16 v[36:39], v[210:213], v[178:181], v[36:39]
	v_mfma_f32_16x16x32_bf16 v[16:19], v[202:205], v[186:189], v[16:19]
	v_mfma_f32_16x16x32_bf16 v[20:23], v[210:213], v[186:189], v[20:23]
	v_mfma_f32_16x16x32_bf16 v[0:3], v[202:205], v[194:197], v[0:3]
	v_mfma_f32_16x16x32_bf16 v[4:7], v[210:213], v[194:197], v[4:7]
	s_add_i32 s39, 0, 0x18000
	v_add_u32_e32 v162, s39, v153
	s_barrier
	ds_read_b128 v[144:147], v162
	ds_read_b128 v[148:151], v162 offset:1024
	ds_read_b128 v[158:161], v162 offset:2048
	ds_read_b128 v[162:165], v162 offset:3072
	ds_read_b128 v[166:169], v156 offset:32768
	ds_read_b128 v[170:173], v156 offset:33792
	ds_read_b128 v[174:177], v156 offset:34816
	ds_read_b128 v[178:181], v156 offset:35840
	ds_read_b128 v[182:185], v156 offset:36864
	ds_read_b128 v[186:189], v156 offset:37888
	ds_read_b128 v[190:193], v156 offset:38912
	ds_read_b128 v[194:197], v156 offset:39936
	v_add_u32_e32 v210, 0x1c000, v153
	ds_read_b128 v[198:201], v210
	ds_read_b128 v[202:205], v210 offset:1024
	ds_read_b128 v[206:209], v210 offset:2048
	ds_read_b128 v[210:213], v210 offset:3072
	s_add_u32 s14, s14, 0x160000
	s_addc_u32 s15, s15, 0
	s_mov_b32 m0, s21
	v_lshl_add_u64 v[222:223], s[14:15], 0, v[128:129]
	global_load_lds_dwordx4 v[222:223], off
	v_lshl_add_u64 v[222:223], s[14:15], 0, v[132:133]
	s_mov_b32 m0, s22
	s_nop 0
	global_load_lds_dwordx4 v[222:223], off
	s_waitcnt lgkmcnt(0)
	s_waitcnt vmcnt(8)
	s_barrier
	v_mfma_f32_16x16x32_bf16 v[124:127], v[144:147], v[166:169], v[124:127]
	v_mfma_f32_16x16x32_bf16 v[120:123], v[158:161], v[166:169], v[120:123]
	v_mfma_f32_16x16x32_bf16 v[108:111], v[144:147], v[174:177], v[108:111]
	v_mfma_f32_16x16x32_bf16 v[104:107], v[158:161], v[174:177], v[104:107]
	v_mfma_f32_16x16x32_bf16 v[88:91], v[144:147], v[182:185], v[88:91]
	v_mfma_f32_16x16x32_bf16 v[92:95], v[158:161], v[182:185], v[92:95]
	v_mfma_f32_16x16x32_bf16 v[72:75], v[144:147], v[190:193], v[72:75]
	v_mfma_f32_16x16x32_bf16 v[76:79], v[158:161], v[190:193], v[76:79]
	v_mfma_f32_16x16x32_bf16 v[124:127], v[148:151], v[170:173], v[124:127]
	v_mfma_f32_16x16x32_bf16 v[120:123], v[162:165], v[170:173], v[120:123]
	v_mfma_f32_16x16x32_bf16 v[108:111], v[148:151], v[178:181], v[108:111]
	v_mfma_f32_16x16x32_bf16 v[104:107], v[162:165], v[178:181], v[104:107]
	v_mfma_f32_16x16x32_bf16 v[88:91], v[148:151], v[186:189], v[88:91]
	v_mfma_f32_16x16x32_bf16 v[92:95], v[162:165], v[186:189], v[92:95]
	v_mfma_f32_16x16x32_bf16 v[72:75], v[148:151], v[194:197], v[72:75]
	v_mfma_f32_16x16x32_bf16 v[76:79], v[162:165], v[194:197], v[76:79]
	v_mfma_f32_16x16x32_bf16 v[116:119], v[198:201], v[166:169], v[116:119]
	v_mfma_f32_16x16x32_bf16 v[112:115], v[206:209], v[166:169], v[112:115]
	v_mfma_f32_16x16x32_bf16 v[100:103], v[198:201], v[174:177], v[100:103]
	v_mfma_f32_16x16x32_bf16 v[96:99], v[206:209], v[174:177], v[96:99]
	v_mfma_f32_16x16x32_bf16 v[80:83], v[198:201], v[182:185], v[80:83]
	v_mfma_f32_16x16x32_bf16 v[84:87], v[206:209], v[182:185], v[84:87]
	v_mfma_f32_16x16x32_bf16 v[64:67], v[198:201], v[190:193], v[64:67]
	v_mfma_f32_16x16x32_bf16 v[68:71], v[206:209], v[190:193], v[68:71]
	v_mfma_f32_16x16x32_bf16 v[116:119], v[202:205], v[170:173], v[116:119]
	v_mfma_f32_16x16x32_bf16 v[112:115], v[210:213], v[170:173], v[112:115]
	v_mfma_f32_16x16x32_bf16 v[100:103], v[202:205], v[178:181], v[100:103]
	v_mfma_f32_16x16x32_bf16 v[96:99], v[210:213], v[178:181], v[96:99]
	v_mfma_f32_16x16x32_bf16 v[80:83], v[202:205], v[186:189], v[80:83]
	v_mfma_f32_16x16x32_bf16 v[84:87], v[210:213], v[186:189], v[84:87]
	v_mfma_f32_16x16x32_bf16 v[64:67], v[202:205], v[194:197], v[64:67]
	v_mfma_f32_16x16x32_bf16 v[68:71], v[210:213], v[194:197], v[68:71]
	s_barrier
; #define PG8_STAGE(bufoff, gbase, voff) do { _Pragma("unroll") for (int _i = 0; _i < 2; ++_i) \
;         __builtin_amdgcn_global_load_lds((const unsigned*)((const char*)(gbase) + (voff)[_i]), (PG8_LAS unsigned*)(lds + (bufoff) + ldsw + _i * 8192), 16, 0, 0); } while (0)
; #define PG8_LDA(dst, b, h) do { _Pragma("unroll") for (int m = 0; m < 4; ++m) _Pragma("unroll") for (int k = 0; k < 2; ++k) dst[m][k] = *(const PG8_LAS bf16x8*)(lds + PG8_SA(b, h) + aoff + m * 2048 + k * 1024); } while (0)
; #define PG8_MMA(ai, bj, At, Bt) do { __builtin_amdgcn_s_setprio(1); _Pragma("unroll") for (int m = 0; m < 4; ++m) _Pragma("unroll") for (int n = 0; n < 2; ++n) _Pragma("unroll") for (int k = 0; k < 2; ++k) \
;         acc[ai][bj][m][n] = __builtin_amdgcn_mfma_f32_16x16x32_bf16(Bt[n][k], At[m][k], acc[ai][bj][m][n], 0, 0, 0); __builtin_amdgcn_s_setprio(0); } while (0)
; #define PG8_WAIT_V(n) asm volatile("s_waitcnt vmcnt(" #n ")" ::: "memory")
; #define PG8_WAIT_L(n) asm volatile("s_waitcnt lgkmcnt(" #n ")" ::: "memory")
; #define PG8_BAR __builtin_amdgcn_s_barrier()
; #define PG8_SCHED __builtin_amdgcn_sched_barrier(0)
; template <class Epi>
; __device__ __forceinline__ void gemm_phase(PG8_LAS unsigned char* lds, const Gemm g, const StaticOrder& S, const Epi& E) {
;     ...
;             PG8_LDA(At, 1, 1); PG8_STAGE(PG8_SA(1, 0), a3, voffA);
;             PG8_BAR; PG8_WAIT_L(0); PG8_MMA(1, 0, At, B0); PG8_BAR; PG8_SCHED;
;             PG8_STAGE(PG8_SB(1, 1), b3 + hstepB, voffB);
;             PG8_WAIT_V(6); PG8_BAR; PG8_MMA(1, 1, At, B1); PG8_BAR;
;         }
;         E(acc, cur, wr, wc, fr, fq);
;     __device__ __forceinline__ void operator()(const f32x4 (&acc)[2][2][4][2], const pg8::Unit& u, int wr, int wc, int fr, int fq) const {
;         const int row0 = u.pm * 256 + wr * 64 + fr, col0 = u.pn * 256 + wc * 32 + 8 * fq;
; #pragma unroll
;         for (int ai = 0; ai < 2; ++ai) {
;             u32x4 rb[4][2];
; #pragma unroll
;             for (int m = 0; m < 4; ++m)
; #pragma unroll
;                 for (int bj = 0; bj < 2; ++bj) rb[m][bj] = *(const u32x4*)(resb + (size_t)(row0 + ai * 128 + m * 16) * DM + col0 + bj * 128);
	ds_read_b128 v[166:169], v156 offset:49152
	ds_read_b128 v[170:173], v156 offset:50176
	ds_read_b128 v[174:177], v156 offset:51200
	ds_read_b128 v[178:181], v156 offset:52224
	ds_read_b128 v[182:185], v156 offset:53248
	ds_read_b128 v[186:189], v156 offset:54272
	ds_read_b128 v[190:193], v156 offset:55296
	ds_read_b128 v[194:197], v156 offset:56320
	s_add_i32 s14, 0, 0x1c000
	s_add_i32 s15, s39, s18
	v_lshl_add_u64 v[214:215], v[214:215], 0, s[6:7]
	s_mov_b32 m0, s15
	s_nop 0
	global_load_lds_dwordx4 v[214:215], off
	v_lshl_add_u64 v[214:215], v[216:217], 0, s[6:7]
	s_add_i32 m0, s15, 0x2000
	s_nop 0
	global_load_lds_dwordx4 v[214:215], off
	s_mov_b32 m0, s25
	v_lshl_add_u64 v[214:215], v[218:219], 0, s[6:7]
	global_load_lds_dwordx4 v[214:215], off
	v_lshl_add_u64 v[214:215], v[220:221], 0, s[6:7]
	s_mov_b32 m0, s27
	s_nop 0
	global_load_lds_dwordx4 v[214:215], off
	s_add_u32 s12, s12, 0x160080
	s_addc_u32 s13, s13, 0
	s_add_i32 s14, s14, s18
	v_lshl_add_u64 v[222:223], s[12:13], 0, v[130:131]
	s_mov_b32 m0, s14
	s_nop 0
	global_load_lds_dwordx4 v[222:223], off
	v_lshl_add_u64 v[222:223], s[12:13], 0, v[134:135]
	s_add_i32 m0, s14, 0x2000
	s_nop 0
	global_load_lds_dwordx4 v[222:223], off
	s_waitcnt lgkmcnt(0)
	s_waitcnt vmcnt(8)
	s_barrier
	v_mfma_f32_16x16x32_bf16 v[56:59], v[144:147], v[166:169], v[56:59]
	v_mfma_f32_16x16x32_bf16 v[60:63], v[158:161], v[166:169], v[60:63]
	v_mfma_f32_16x16x32_bf16 v[40:43], v[144:147], v[174:177], v[40:43]
	v_mfma_f32_16x16x32_bf16 v[44:47], v[158:161], v[174:177], v[44:47]
	v_mfma_f32_16x16x32_bf16 v[24:27], v[144:147], v[182:185], v[24:27]
	v_mfma_f32_16x16x32_bf16 v[28:31], v[158:161], v[182:185], v[28:31]
	v_mfma_f32_16x16x32_bf16 v[8:11], v[144:147], v[190:193], v[8:11]
	v_mfma_f32_16x16x32_bf16 v[12:15], v[158:161], v[190:193], v[12:15]
	v_mfma_f32_16x16x32_bf16 v[56:59], v[148:151], v[170:173], v[56:59]
	v_mfma_f32_16x16x32_bf16 v[60:63], v[162:165], v[170:173], v[60:63]
	v_mfma_f32_16x16x32_bf16 v[40:43], v[148:151], v[178:181], v[40:43]
	v_mfma_f32_16x16x32_bf16 v[44:47], v[162:165], v[178:181], v[44:47]
	v_mfma_f32_16x16x32_bf16 v[24:27], v[148:151], v[186:189], v[24:27]
	v_mfma_f32_16x16x32_bf16 v[28:31], v[162:165], v[186:189], v[28:31]
	v_mfma_f32_16x16x32_bf16 v[8:11], v[148:151], v[194:197], v[8:11]
	v_mfma_f32_16x16x32_bf16 v[12:15], v[162:165], v[194:197], v[12:15]
	v_mfma_f32_16x16x32_bf16 v[48:51], v[198:201], v[166:169], v[48:51]
	v_mfma_f32_16x16x32_bf16 v[52:55], v[206:209], v[166:169], v[52:55]
	v_mfma_f32_16x16x32_bf16 v[32:35], v[198:201], v[174:177], v[32:35]
	v_mfma_f32_16x16x32_bf16 v[36:39], v[206:209], v[174:177], v[36:39]
	v_mfma_f32_16x16x32_bf16 v[16:19], v[198:201], v[182:185], v[16:19]
	v_mfma_f32_16x16x32_bf16 v[20:23], v[206:209], v[182:185], v[20:23]
	v_mfma_f32_16x16x32_bf16 v[0:3], v[198:201], v[190:193], v[0:3]
	v_mfma_f32_16x16x32_bf16 v[4:7], v[206:209], v[190:193], v[4:7]
	v_mfma_f32_16x16x32_bf16 v[48:51], v[202:205], v[170:173], v[48:51]
	v_mfma_f32_16x16x32_bf16 v[52:55], v[210:213], v[170:173], v[52:55]
	v_mfma_f32_16x16x32_bf16 v[32:35], v[202:205], v[178:181], v[32:35]
	v_mfma_f32_16x16x32_bf16 v[36:39], v[210:213], v[178:181], v[36:39]
	v_mfma_f32_16x16x32_bf16 v[16:19], v[202:205], v[186:189], v[16:19]
	v_mfma_f32_16x16x32_bf16 v[20:23], v[210:213], v[186:189], v[20:23]
	v_mfma_f32_16x16x32_bf16 v[0:3], v[202:205], v[194:197], v[0:3]
	v_mfma_f32_16x16x32_bf16 v[4:7], v[210:213], v[194:197], v[4:7]
	s_add_i32 s38, s38, 2
	s_add_u32 s10, s10, 0x100
	s_addc_u32 s11, s11, 0
	s_add_u32 s36, s36, 0x100
	s_addc_u32 s37, s37, 0
	s_cmpk_gt_u32 s38, 0x55
	s_barrier
	s_cbranch_scc0 .LBB0_1170
	s_andn2_b64 vcc, exec, s[8:9]
	s_cbranch_vccnz .LBB0_1158
	v_lshl_or_b32 v144, s35, 8, v154
	v_lshl_add_u32 v148, s34, 8, v152
	v_ashrrev_i32_e32 v145, 31, v144
	v_ashrrev_i32_e32 v149, 31, v148
	v_lshl_add_u64 v[146:147], v[144:145], 1, s[76:77]
	v_lshlrev_b64 v[150:151], 12, v[148:149]
	v_or_b32_e32 v182, 16, v148
	v_lshl_add_u64 v[150:151], v[146:147], 0, v[150:151]
	v_ashrrev_i32_e32 v183, 31, v182
	global_load_dwordx4 v[158:161], v[150:151], off
	global_load_dwordx4 v[162:165], v[150:151], off offset:256
	v_lshlrev_b64 v[150:151], 12, v[182:183]
	v_lshl_add_u64 v[150:151], v[146:147], 0, v[150:151]
	v_or_b32_e32 v190, 32, v148
	global_load_dwordx4 v[166:169], v[150:151], off
	global_load_dwordx4 v[170:173], v[150:151], off offset:256
	v_ashrrev_i32_e32 v191, 31, v190
	v_lshlrev_b64 v[150:151], 12, v[190:191]
	v_lshl_add_u64 v[150:151], v[146:147], 0, v[150:151]
	global_load_dwordx4 v[174:177], v[150:151], off
	global_load_dwordx4 v[178:181], v[150:151], off offset:256
	v_or_b32_e32 v150, 48, v148
	v_ashrrev_i32_e32 v151, 31, v150
	v_lshlrev_b64 v[184:185], 13, v[148:149]
	v_lshlrev_b64 v[186:187], 12, v[150:151]
	v_lshlrev_b64 v[144:145], 2, v[144:145]
	v_lshl_add_u64 v[184:185], s[42:43], 0, v[184:185]
	v_lshlrev_b64 v[182:183], 13, v[182:183]
	v_lshl_add_u64 v[186:187], v[146:147], 0, v[186:187]
	v_lshl_add_u64 v[192:193], v[184:185], 0, v[144:145]
	v_lshl_add_u64 v[194:195], s[42:43], 0, v[182:183]
	global_load_dwordx4 v[182:185], v[186:187], off offset:256
	s_nop 0
	global_load_dwordx4 v[186:189], v[186:187], off
	v_lshl_add_u64 v[194:195], v[194:195], 0, v[144:145]
	s_waitcnt vmcnt(0)
;     __device__ __forceinline__ void operator()(const f32x4 (&acc)[2][2][4][2], const pg8::Unit& u, int wr, int wc, int fr, int fq) const {
;     ...
;         for (int ai = 0; ai < 2; ++ai) {
;             u32x4 rb[4][2];
; #pragma unroll
;             for (int m = 0; m < 4; ++m)
; #pragma unroll
;                 for (int bj = 0; bj < 2; ++bj) rb[m][bj] = *(const u32x4*)(resb + (size_t)(row0 + ai * 128 + m * 16) * DM + col0 + bj * 128);
; #pragma unroll
;             for (int m = 0; m < 4; ++m) {
;                 const int r = row0 + ai * 128 + m * 16; float ss = 0.f;
; #pragma unroll
;                 for (int bj = 0; bj < 2; ++bj) {
;                     const size_t off = (size_t)r * DM + col0 + bj * 128;
;                     float rv[8], o[8]; unpack8(rb[m][bj], rv);
; #pragma unroll
;                     for (int n = 0; n < 2; ++n)
; #pragma unroll
;                         for (int i = 0; i < 4; ++i) o[n * 4 + i] = rv[n * 4 + i] + coef * acc[ai][bj][m][n][i];
;                     if (outf) { *(f32x4*)(outf + off) = (f32x4){o[0], o[1], o[2], o[3]}; *(f32x4*)(outf + off + 4) = (f32x4){o[4], o[5], o[6], o[7]}; }
	v_lshlrev_b32_e32 v196, 16, v160
	v_and_b32_e32 v197, 0xffff0000, v160
	v_lshlrev_b32_e32 v160, 16, v161
	v_and_b32_e32 v161, 0xffff0000, v161
	v_lshlrev_b32_e32 v198, 16, v158
	v_and_b32_e32 v199, 0xffff0000, v158
	v_lshlrev_b32_e32 v158, 16, v159
	v_and_b32_e32 v159, 0xffff0000, v159
	v_lshlrev_b32_e32 v200, 16, v164
	v_and_b32_e32 v201, 0xffff0000, v164
	v_lshlrev_b32_e32 v164, 16, v165
	v_and_b32_e32 v165, 0xffff0000, v165
	v_lshlrev_b32_e32 v202, 16, v162
	v_and_b32_e32 v203, 0xffff0000, v162
	v_lshlrev_b32_e32 v162, 16, v163
	v_and_b32_e32 v163, 0xffff0000, v163
	v_pk_fma_f32 v[122:123], v[122:123], 0.5, v[160:161] op_sel_hi:[1,0,1]
	v_pk_fma_f32 v[126:127], v[126:127], 0.5, v[158:159] op_sel_hi:[1,0,1]
	v_pk_fma_f32 v[114:115], v[114:115], 0.5, v[164:165] op_sel_hi:[1,0,1]
	v_pk_fma_f32 v[118:119], v[118:119], 0.5, v[162:163] op_sel_hi:[1,0,1]
	v_lshlrev_b32_e32 v158, 16, v168
	v_and_b32_e32 v159, 0xffff0000, v168
	v_lshlrev_b32_e32 v160, 16, v169
	v_and_b32_e32 v161, 0xffff0000, v169
	v_lshlrev_b32_e32 v162, 16, v166
	v_and_b32_e32 v163, 0xffff0000, v166
	v_lshlrev_b32_e32 v164, 16, v167
	v_and_b32_e32 v165, 0xffff0000, v167
	v_lshlrev_b32_e32 v168, 16, v173
	v_and_b32_e32 v169, 0xffff0000, v173
	v_pk_fma_f32 v[124:125], v[124:125], 0.5, v[198:199] op_sel_hi:[1,0,1]
	v_lshlrev_b32_e32 v166, 16, v172
	v_and_b32_e32 v167, 0xffff0000, v172
	v_lshlrev_b32_e32 v172, 16, v170
	v_and_b32_e32 v173, 0xffff0000, v170
	v_lshlrev_b32_e32 v170, 16, v171
	v_and_b32_e32 v171, 0xffff0000, v171
	v_pk_fma_f32 v[108:109], v[108:109], 0.5, v[162:163] op_sel_hi:[1,0,1]
	v_pk_fma_f32 v[110:111], v[110:111], 0.5, v[164:165] op_sel_hi:[1,0,1]
	v_pk_fma_f32 v[98:99], v[98:99], 0.5, v[168:169] op_sel_hi:[1,0,1]
	v_pk_fma_f32 v[120:121], v[120:121], 0.5, v[196:197] op_sel_hi:[1,0,1]
	v_pk_fma_f32 v[112:113], v[112:113], 0.5, v[200:201] op_sel_hi:[1,0,1]
	v_pk_fma_f32 v[116:117], v[116:117], 0.5, v[202:203] op_sel_hi:[1,0,1]
	global_store_dwordx4 v[192:193], v[124:127], off
	global_store_dwordx4 v[192:193], v[120:123], off offset:16
	global_store_dwordx4 v[192:193], v[116:119], off offset:512
	global_store_dwordx4 v[192:193], v[112:115], off offset:528
	v_pk_fma_f32 v[104:105], v[104:105], 0.5, v[158:159] op_sel_hi:[1,0,1]
	v_pk_fma_f32 v[106:107], v[106:107], 0.5, v[160:161] op_sel_hi:[1,0,1]
	v_pk_fma_f32 v[96:97], v[96:97], 0.5, v[166:167] op_sel_hi:[1,0,1]
	v_pk_fma_f32 v[100:101], v[100:101], 0.5, v[172:173] op_sel_hi:[1,0,1]
	v_pk_fma_f32 v[102:103], v[102:103], 0.5, v[170:171] op_sel_hi:[1,0,1]
	global_store_dwordx4 v[194:195], v[108:111], off
	global_store_dwordx4 v[194:195], v[104:107], off offset:16
	global_store_dwordx4 v[194:195], v[100:103], off offset:512
	global_store_dwordx4 v[194:195], v[96:99], off offset:528
	s_nop 0
	v_add_u32_e32 v100, 0xa0, v148
	v_lshlrev_b32_e32 v98, 16, v176
	v_and_b32_e32 v99, 0xffff0000, v176
	v_pk_fma_f32 v[92:93], v[92:93], 0.5, v[98:99] op_sel_hi:[1,0,1]
	v_lshlrev_b32_e32 v98, 16, v177
	v_and_b32_e32 v99, 0xffff0000, v177
	v_lshlrev_b64 v[96:97], 13, v[190:191]
	v_pk_fma_f32 v[94:95], v[94:95], 0.5, v[98:99] op_sel_hi:[1,0,1]
	v_lshlrev_b32_e32 v98, 16, v174
	v_and_b32_e32 v99, 0xffff0000, v174
	v_lshl_add_u64 v[96:97], s[42:43], 0, v[96:97]
	v_pk_fma_f32 v[88:89], v[88:89], 0.5, v[98:99] op_sel_hi:[1,0,1]
	v_lshlrev_b32_e32 v98, 16, v175
	v_and_b32_e32 v99, 0xffff0000, v175
	v_lshl_add_u64 v[96:97], v[96:97], 0, v[144:145]
	v_pk_fma_f32 v[90:91], v[90:91], 0.5, v[98:99] op_sel_hi:[1,0,1]
	global_store_dwordx4 v[96:97], v[88:91], off
	global_store_dwordx4 v[96:97], v[92:95], off offset:16
	v_add_u32_e32 v98, 0x90, v148
	v_lshlrev_b32_e32 v88, 16, v180
	v_and_b32_e32 v89, 0xffff0000, v180
	v_pk_fma_f32 v[84:85], v[84:85], 0.5, v[88:89] op_sel_hi:[1,0,1]
	v_lshlrev_b32_e32 v88, 16, v181
	v_and_b32_e32 v89, 0xffff0000, v181
	v_pk_fma_f32 v[86:87], v[86:87], 0.5, v[88:89] op_sel_hi:[1,0,1]
	v_lshlrev_b32_e32 v88, 16, v178
	v_and_b32_e32 v89, 0xffff0000, v178
	v_pk_fma_f32 v[80:81], v[80:81], 0.5, v[88:89] op_sel_hi:[1,0,1]
	v_lshlrev_b32_e32 v88, 16, v179
	v_and_b32_e32 v89, 0xffff0000, v179
	v_pk_fma_f32 v[82:83], v[82:83], 0.5, v[88:89] op_sel_hi:[1,0,1]
	global_store_dwordx4 v[96:97], v[80:83], off offset:512
	global_store_dwordx4 v[96:97], v[84:87], off offset:528
	v_add_u32_e32 v96, 0x80, v148
	v_lshlrev_b32_e32 v82, 16, v188
	v_and_b32_e32 v83, 0xffff0000, v188
	v_pk_fma_f32 v[76:77], v[76:77], 0.5, v[82:83] op_sel_hi:[1,0,1]
	v_lshlrev_b32_e32 v82, 16, v189
	v_and_b32_e32 v83, 0xffff0000, v189
	v_lshlrev_b64 v[80:81], 13, v[150:151]
	v_pk_fma_f32 v[78:79], v[78:79], 0.5, v[82:83] op_sel_hi:[1,0,1]
	v_lshlrev_b32_e32 v82, 16, v186
	v_and_b32_e32 v83, 0xffff0000, v186
	v_lshl_add_u64 v[80:81], s[42:43], 0, v[80:81]
	v_pk_fma_f32 v[72:73], v[72:73], 0.5, v[82:83] op_sel_hi:[1,0,1]
	v_lshlrev_b32_e32 v82, 16, v187
	v_and_b32_e32 v83, 0xffff0000, v187
	v_lshl_add_u64 v[80:81], v[80:81], 0, v[144:145]
	v_pk_fma_f32 v[74:75], v[74:75], 0.5, v[82:83] op_sel_hi:[1,0,1]
	global_store_dwordx4 v[80:81], v[72:75], off
	global_store_dwordx4 v[80:81], v[76:79], off offset:16
	v_ashrrev_i32_e32 v97, 31, v96
	v_lshlrev_b32_e32 v72, 16, v184
	v_and_b32_e32 v73, 0xffff0000, v184
	v_pk_fma_f32 v[68:69], v[68:69], 0.5, v[72:73] op_sel_hi:[1,0,1]
	v_lshlrev_b32_e32 v72, 16, v185
	v_and_b32_e32 v73, 0xffff0000, v185
	v_pk_fma_f32 v[70:71], v[70:71], 0.5, v[72:73] op_sel_hi:[1,0,1]
	v_lshlrev_b32_e32 v72, 16, v182
	v_and_b32_e32 v73, 0xffff0000, v182
	v_pk_fma_f32 v[64:65], v[64:65], 0.5, v[72:73] op_sel_hi:[1,0,1]
	v_lshlrev_b32_e32 v72, 16, v183
	v_and_b32_e32 v73, 0xffff0000, v183
	v_pk_fma_f32 v[66:67], v[66:67], 0.5, v[72:73] op_sel_hi:[1,0,1]
	global_store_dwordx4 v[80:81], v[64:67], off offset:512
	global_store_dwordx4 v[80:81], v[68:71], off offset:528
	v_ashrrev_i32_e32 v99, 31, v98
	v_lshlrev_b64 v[64:65], 12, v[96:97]
	v_lshl_add_u64 v[64:65], v[146:147], 0, v[64:65]
	global_load_dwordx4 v[68:71], v[64:65], off
	global_load_dwordx4 v[72:75], v[64:65], off offset:256
	v_lshlrev_b64 v[64:65], 12, v[98:99]
	v_lshl_add_u64 v[64:65], v[146:147], 0, v[64:65]
	global_load_dwordx4 v[76:79], v[64:65], off
	global_load_dwordx4 v[80:83], v[64:65], off offset:256
	v_ashrrev_i32_e32 v101, 31, v100
	v_lshlrev_b64 v[64:65], 12, v[100:101]
	v_lshl_add_u64 v[64:65], v[146:147], 0, v[64:65]
	global_load_dwordx4 v[84:87], v[64:65], off
	global_load_dwordx4 v[88:91], v[64:65], off offset:256
	v_add_u32_e32 v102, 0xb0, v148
	v_ashrrev_i32_e32 v103, 31, v102
	v_lshlrev_b64 v[64:65], 12, v[102:103]
	v_lshl_add_u64 v[92:93], v[146:147], 0, v[64:65]
	global_load_dwordx4 v[64:67], v[92:93], off offset:256
	s_nop 0
	global_load_dwordx4 v[92:95], v[92:93], off
	v_lshlrev_b64 v[96:97], 13, v[96:97]
	v_lshl_add_u64 v[96:97], s[42:43], 0, v[96:97]
	v_lshl_add_u64 v[96:97], v[96:97], 0, v[144:145]
	s_waitcnt vmcnt(0)
;     __device__ __forceinline__ void operator()(const f32x4 (&acc)[2][2][4][2], const pg8::Unit& u, int wr, int wc, int fr, int fq) const {
;     ...
;         for (int ai = 0; ai < 2; ++ai) {
;             u32x4 rb[4][2];
; #pragma unroll
;             for (int m = 0; m < 4; ++m)
; #pragma unroll
;                 for (int bj = 0; bj < 2; ++bj) rb[m][bj] = *(const u32x4*)(resb + (size_t)(row0 + ai * 128 + m * 16) * DM + col0 + bj * 128);
; #pragma unroll
;             for (int m = 0; m < 4; ++m) {
;                 const int r = row0 + ai * 128 + m * 16; float ss = 0.f;
; #pragma unroll
;                 for (int bj = 0; bj < 2; ++bj) {
;                     const size_t off = (size_t)r * DM + col0 + bj * 128;
;                     float rv[8], o[8]; unpack8(rb[m][bj], rv);
; #pragma unroll
;                     for (int n = 0; n < 2; ++n)
; #pragma unroll
;                         for (int i = 0; i < 4; ++i) o[n * 4 + i] = rv[n * 4 + i] + coef * acc[ai][bj][m][n][i];
;                     if (outf) { *(f32x4*)(outf + off) = (f32x4){o[0], o[1], o[2], o[3]}; *(f32x4*)(outf + off + 4) = (f32x4){o[4], o[5], o[6], o[7]}; }
	v_lshlrev_b32_e32 v104, 16, v70
	v_and_b32_e32 v105, 0xffff0000, v70
	v_lshlrev_b32_e32 v70, 16, v71
	v_and_b32_e32 v71, 0xffff0000, v71
	v_pk_fma_f32 v[62:63], v[62:63], 0.5, v[70:71] op_sel_hi:[1,0,1]
	v_lshlrev_b32_e32 v70, 16, v68
	v_and_b32_e32 v71, 0xffff0000, v68
	v_lshlrev_b32_e32 v68, 16, v69
	v_and_b32_e32 v69, 0xffff0000, v69
	v_pk_fma_f32 v[56:57], v[56:57], 0.5, v[70:71] op_sel_hi:[1,0,1]
	v_pk_fma_f32 v[58:59], v[58:59], 0.5, v[68:69] op_sel_hi:[1,0,1]
	v_pk_fma_f32 v[60:61], v[60:61], 0.5, v[104:105] op_sel_hi:[1,0,1]
	global_store_dwordx4 v[96:97], v[56:59], off
	global_store_dwordx4 v[96:97], v[60:63], off offset:16
	s_nop 0
	v_lshlrev_b32_e32 v56, 16, v74
	v_and_b32_e32 v57, 0xffff0000, v74
	v_pk_fma_f32 v[52:53], v[52:53], 0.5, v[56:57] op_sel_hi:[1,0,1]
	v_lshlrev_b32_e32 v56, 16, v75
	v_and_b32_e32 v57, 0xffff0000, v75
	v_pk_fma_f32 v[54:55], v[54:55], 0.5, v[56:57] op_sel_hi:[1,0,1]
	v_lshlrev_b32_e32 v56, 16, v72
	v_and_b32_e32 v57, 0xffff0000, v72
	v_pk_fma_f32 v[48:49], v[48:49], 0.5, v[56:57] op_sel_hi:[1,0,1]
	v_lshlrev_b32_e32 v56, 16, v73
	v_and_b32_e32 v57, 0xffff0000, v73
	v_pk_fma_f32 v[50:51], v[50:51], 0.5, v[56:57] op_sel_hi:[1,0,1]
	global_store_dwordx4 v[96:97], v[48:51], off offset:512
	global_store_dwordx4 v[96:97], v[52:55], off offset:528
	s_nop 0
	v_lshlrev_b32_e32 v50, 16, v78
	v_and_b32_e32 v51, 0xffff0000, v78
	v_pk_fma_f32 v[44:45], v[44:45], 0.5, v[50:51] op_sel_hi:[1,0,1]
	v_lshlrev_b32_e32 v50, 16, v79
	v_and_b32_e32 v51, 0xffff0000, v79
	v_lshlrev_b64 v[48:49], 13, v[98:99]
	v_pk_fma_f32 v[46:47], v[46:47], 0.5, v[50:51] op_sel_hi:[1,0,1]
	v_lshlrev_b32_e32 v50, 16, v76
	v_and_b32_e32 v51, 0xffff0000, v76
	v_lshl_add_u64 v[48:49], s[42:43], 0, v[48:49]
	v_pk_fma_f32 v[40:41], v[40:41], 0.5, v[50:51] op_sel_hi:[1,0,1]
	v_lshlrev_b32_e32 v50, 16, v77
	v_and_b32_e32 v51, 0xffff0000, v77
	v_lshl_add_u64 v[48:49], v[48:49], 0, v[144:145]
	v_pk_fma_f32 v[42:43], v[42:43], 0.5, v[50:51] op_sel_hi:[1,0,1]
	global_store_dwordx4 v[48:49], v[40:43], off
	global_store_dwordx4 v[48:49], v[44:47], off offset:16
	s_nop 0
	v_lshlrev_b32_e32 v40, 16, v82
	v_and_b32_e32 v41, 0xffff0000, v82
	v_pk_fma_f32 v[36:37], v[36:37], 0.5, v[40:41] op_sel_hi:[1,0,1]
	v_lshlrev_b32_e32 v40, 16, v83
	v_and_b32_e32 v41, 0xffff0000, v83
	v_pk_fma_f32 v[38:39], v[38:39], 0.5, v[40:41] op_sel_hi:[1,0,1]
	v_lshlrev_b32_e32 v40, 16, v80
	v_and_b32_e32 v41, 0xffff0000, v80
	v_pk_fma_f32 v[32:33], v[32:33], 0.5, v[40:41] op_sel_hi:[1,0,1]
	v_lshlrev_b32_e32 v40, 16, v81
	v_and_b32_e32 v41, 0xffff0000, v81
	v_pk_fma_f32 v[34:35], v[34:35], 0.5, v[40:41] op_sel_hi:[1,0,1]
	global_store_dwordx4 v[48:49], v[32:35], off offset:512
	global_store_dwordx4 v[48:49], v[36:39], off offset:528
	s_nop 0
	v_lshlrev_b32_e32 v34, 16, v86
	v_and_b32_e32 v35, 0xffff0000, v86
	v_pk_fma_f32 v[28:29], v[28:29], 0.5, v[34:35] op_sel_hi:[1,0,1]
	v_lshlrev_b32_e32 v34, 16, v87
	v_and_b32_e32 v35, 0xffff0000, v87
	v_lshlrev_b64 v[32:33], 13, v[100:101]
	v_pk_fma_f32 v[30:31], v[30:31], 0.5, v[34:35] op_sel_hi:[1,0,1]
	v_lshlrev_b32_e32 v34, 16, v84
	v_and_b32_e32 v35, 0xffff0000, v84
	v_lshl_add_u64 v[32:33], s[42:43], 0, v[32:33]
	v_pk_fma_f32 v[24:25], v[24:25], 0.5, v[34:35] op_sel_hi:[1,0,1]
	v_lshlrev_b32_e32 v34, 16, v85
	v_and_b32_e32 v35, 0xffff0000, v85
	v_lshl_add_u64 v[32:33], v[32:33], 0, v[144:145]
	v_pk_fma_f32 v[26:27], v[26:27], 0.5, v[34:35] op_sel_hi:[1,0,1]
	global_store_dwordx4 v[32:33], v[24:27], off
	global_store_dwordx4 v[32:33], v[28:31], off offset:16
	s_nop 0
	v_lshlrev_b32_e32 v24, 16, v90
	v_and_b32_e32 v25, 0xffff0000, v90
	v_pk_fma_f32 v[20:21], v[20:21], 0.5, v[24:25] op_sel_hi:[1,0,1]
	v_lshlrev_b32_e32 v24, 16, v91
	v_and_b32_e32 v25, 0xffff0000, v91
	v_pk_fma_f32 v[22:23], v[22:23], 0.5, v[24:25] op_sel_hi:[1,0,1]
	v_lshlrev_b32_e32 v24, 16, v88
	v_and_b32_e32 v25, 0xffff0000, v88
	v_pk_fma_f32 v[16:17], v[16:17], 0.5, v[24:25] op_sel_hi:[1,0,1]
	v_lshlrev_b32_e32 v24, 16, v89
	v_and_b32_e32 v25, 0xffff0000, v89
	v_pk_fma_f32 v[18:19], v[18:19], 0.5, v[24:25] op_sel_hi:[1,0,1]
	global_store_dwordx4 v[32:33], v[16:19], off offset:512
	global_store_dwordx4 v[32:33], v[20:23], off offset:528
	s_nop 0
	v_lshlrev_b32_e32 v18, 16, v94
	v_and_b32_e32 v19, 0xffff0000, v94
	v_pk_fma_f32 v[12:13], v[12:13], 0.5, v[18:19] op_sel_hi:[1,0,1]
	v_lshlrev_b32_e32 v18, 16, v95
	v_and_b32_e32 v19, 0xffff0000, v95
	v_lshlrev_b64 v[16:17], 13, v[102:103]
	v_pk_fma_f32 v[14:15], v[14:15], 0.5, v[18:19] op_sel_hi:[1,0,1]
	v_lshlrev_b32_e32 v18, 16, v92
	v_and_b32_e32 v19, 0xffff0000, v92
	v_lshl_add_u64 v[16:17], s[42:43], 0, v[16:17]
	v_pk_fma_f32 v[8:9], v[8:9], 0.5, v[18:19] op_sel_hi:[1,0,1]
	v_lshlrev_b32_e32 v18, 16, v93
	v_and_b32_e32 v19, 0xffff0000, v93
	v_lshl_add_u64 v[16:17], v[16:17], 0, v[144:145]
	v_pk_fma_f32 v[10:11], v[10:11], 0.5, v[18:19] op_sel_hi:[1,0,1]
	global_store_dwordx4 v[16:17], v[8:11], off
	global_store_dwordx4 v[16:17], v[12:15], off offset:16
	s_nop 0
	v_lshlrev_b32_e32 v8, 16, v66
	v_and_b32_e32 v9, 0xffff0000, v66
	v_pk_fma_f32 v[4:5], v[4:5], 0.5, v[8:9] op_sel_hi:[1,0,1]
	v_lshlrev_b32_e32 v8, 16, v67
	v_and_b32_e32 v9, 0xffff0000, v67
	v_pk_fma_f32 v[6:7], v[6:7], 0.5, v[8:9] op_sel_hi:[1,0,1]
	v_lshlrev_b32_e32 v8, 16, v64
	v_and_b32_e32 v9, 0xffff0000, v64
	v_pk_fma_f32 v[0:1], v[0:1], 0.5, v[8:9] op_sel_hi:[1,0,1]
	v_lshlrev_b32_e32 v8, 16, v65
	v_and_b32_e32 v9, 0xffff0000, v65
	v_pk_fma_f32 v[2:3], v[2:3], 0.5, v[8:9] op_sel_hi:[1,0,1]
	global_store_dwordx4 v[16:17], v[0:3], off offset:512
	global_store_dwordx4 v[16:17], v[4:7], off offset:528
	s_branch .LBB0_1158
